# fast-f32-reciprocal-division-in-epilogues-plus-defer2-loop-schedule
# speedup vs baseline: 1.0907x; 1.0229x over previous
.LBB0_71:
	s_and_b64 vcc, exec, s[0:1]
	s_cbranch_vccz .LBB0_73
	s_add_i32 s2, s8, 0xffffee86
	s_bfe_u32 s1, s2, 0x10003
	s_and_b32 s0, s2, 7
	s_lshr_b32 s2, s2, 4
	s_mul_i32 s3, s1, 24
	s_add_i32 s4, s2, s3
	s_lshl_b32 s3, s4, 6
	s_addk_i32 s3, 0xc00
	v_ashrrev_i32_e32 v0, 6, v32
	v_and_or_b32 v192, v32, 63, s3
	v_lshl_add_u32 v6, s0, 2, v0
	v_lshlrev_b64 v[0:1], 2, v[192:193]
	v_lshl_add_u64 v[2:3], s[54:55], 0, v[0:1]
	v_lshl_add_u64 v[0:1], s[56:57], 0, v[0:1]
	s_lshl_b32 s4, s4, 2
	global_load_dword v5, v[0:1], off
	v_mov_b32_e32 v0, s4
	global_load_dword v0, v0, s[58:59] offset:192
	s_mov_b32 s6, 0x3fb8aa3b
	global_load_dword v4, v[2:3], off
	s_mov_b32 s7, 0xc2ce8ed0
	s_mov_b32 s9, 0x42b17218
	s_cmp_eq_u32 s1, 0
	s_mov_b32 s4, 0x6dc9c883
	s_mov_b32 s5, 0x3fc45f30
	v_lshlrev_b32_e32 v14, 3, v32
	s_waitcnt vmcnt(1)
	v_mul_f32_e32 v1, 0x3fb8aa3b, v0
	v_fma_f32 v2, v0, s6, -v1
	v_rndne_f32_e32 v3, v1
	v_fmac_f32_e32 v2, 0x32a5705f, v0
	v_sub_f32_e32 v1, v1, v3
	v_add_f32_e32 v1, v1, v2
	v_exp_f32_e32 v1, v1
	v_cvt_i32_f32_e32 v2, v3
	v_cmp_ngt_f32_e32 vcc, s7, v0
	v_ldexp_f32 v1, v1, v2
	s_nop 0
	v_cndmask_b32_e32 v1, 0, v1, vcc
	v_cmp_nlt_f32_e32 vcc, s9, v0
	v_sub_u32_e32 v0, 31, v6
	s_nop 0
	v_cndmask_b32_e32 v10, v228, v1, vcc
	s_cselect_b64 vcc, -1, 0
	v_cndmask_b32_e32 v0, v6, v0, vcc
	v_cvt_f32_i32_e32 v1, v0
	v_cvt_f64_f32_e32 v[8:9], v10
	s_lshl_b32 s2, s2, 8
	s_lshl_b32 s1, s1, 7
	s_waitcnt vmcnt(0)
	v_mul_f32_e32 v1, v4, v1
	v_mul_f32_e32 v1, v1, v10
	v_mul_f32_e32 v2, 0x3fb8aa3b, v1
	v_fma_f32 v3, v1, s6, -v2
	v_rndne_f32_e32 v6, v2
	v_fmac_f32_e32 v3, 0x32a5705f, v1
	v_sub_f32_e32 v2, v2, v6
	v_add_f32_e32 v2, v2, v3
	v_exp_f32_e32 v2, v2
	v_cvt_i32_f32_e32 v3, v6
	v_cmp_ngt_f32_e32 vcc, s7, v1
	v_cvt_f64_f32_e32 v[6:7], v5
	s_or_b32 s1, s1, s2
	v_ldexp_f32 v2, v2, v3
	v_cndmask_b32_e32 v2, 0, v2, vcc
	v_cmp_nlt_f32_e32 vcc, s9, v1
	v_cvt_f64_i32_e32 v[0:1], v0
	v_mul_f64 v[0:1], v[0:1], v[6:7]
	v_mul_f64 v[0:1], v[0:1], v[8:9]
	v_cndmask_b32_e32 v11, v228, v2, vcc
	v_mul_f64 v[2:3], v[0:1], s[4:5]
	v_rndne_f64_e32 v[2:3], v[2:3]
	v_fma_f64 v[0:1], v[0:1], s[4:5], -v[2:3]
	v_cvt_f32_f64_e32 v1, v[0:1]
	v_cos_f32_e32 v0, v1
	v_sin_f32_e32 v1, v1
	v_mul_f64 v[6:7], v[6:7], v[8:9]
	v_mul_f64 v[8:9], v[6:7], s[4:5]
	v_mul_f32_e32 v0, v11, v0
	v_mul_f32_e32 v2, v11, v1
	v_mul_f32_e32 v1, v4, v10
	v_mul_f32_e32 v3, 0x3fb8aa3b, v1
	v_fma_f32 v10, v1, s6, -v3
	v_rndne_f32_e32 v11, v3
	v_fmac_f32_e32 v10, 0x32a5705f, v1
	v_sub_f32_e32 v3, v3, v11
	v_add_f32_e32 v3, v3, v10
	v_exp_f32_e32 v3, v3
	v_cvt_i32_f32_e32 v10, v11
	v_cmp_ngt_f32_e32 vcc, s7, v1
	v_rndne_f64_e32 v[8:9], v[8:9]
	v_fma_f64 v[6:7], v[6:7], s[4:5], -v[8:9]
	v_ldexp_f32 v3, v3, v10
	v_cndmask_b32_e32 v3, 0, v3, vcc
	v_cmp_nlt_f32_e32 vcc, s9, v1
	v_mov_b32_e32 v10, v5
	s_lshl_b32 s78, s0, 7
	v_cndmask_b32_e32 v1, v228, v3, vcc
	v_cvt_f32_f64_e32 v3, v[6:7]
	v_cos_f32_e32 v6, v3
	v_sin_f32_e32 v3, v3
	v_fma_f32 v8, v1, v6, -1.0
	v_mul_f32_e32 v9, v1, v3
	v_pk_mul_f32 v[6:7], v[4:5], v[4:5]
	v_pk_mul_f32 v[12:13], v[10:11], v[8:9] op_sel:[0,1] op_sel_hi:[0,0]
	v_pk_fma_f32 v[10:11], v[4:5], v[8:9], v[12:13]
	v_pk_fma_f32 v[8:9], v[4:5], v[8:9], v[12:13] op_sel_hi:[0,1,1] neg_lo:[0,0,1] neg_hi:[0,0,1]
	v_pk_add_f32 v[4:5], v[6:7], v[6:7] op_sel:[0,1] op_sel_hi:[0,1]
	v_rcp_f32_e32 v3, v5
	s_nop 0
	v_mul_f32_e32 v5, v9, v3
	v_div_scale_f32 v1, s[4:5], v4, v4, v10
	v_rcp_f32_e32 v3, v1
	s_nop 0
	v_fma_f32 v6, -v1, v3, 1.0
	v_fmac_f32_e32 v3, v6, v3
	v_div_scale_f32 v6, vcc, v10, v4, v10
	v_mul_f32_e32 v7, v6, v3
	v_fma_f32 v8, -v1, v7, v6
	v_fmac_f32_e32 v7, v8, v3
	v_fma_f32 v1, -v1, v7, v6
	v_div_fmas_f32 v1, v1, v3, v7
	v_div_fixup_f32 v4, v1, v4, v10
	v_pk_mul_f32 v[2:3], v[2:3], v[4:5] op_sel:[0,1] op_sel_hi:[0,0]
	v_pk_fma_f32 v[6:7], v[0:1], v[4:5], v[2:3] neg_lo:[0,0,1] neg_hi:[0,0,1]
	v_pk_fma_f32 v[0:1], v[0:1], v[4:5], v[2:3] op_sel_hi:[0,1,1]
	v_ashrrev_i32_e32 v2, 1, v32
	v_ashrrev_i32_e32 v5, 2, v32
	v_add_u32_e32 v2, s1, v2
	v_add_u32_e32 v0, s3, v5
	v_ashrrev_i32_e32 v3, 31, v2
	v_readlane_b32 s2, v253, 24
	v_lshlrev_b64 v[2:3], 10, v[2:3]
	v_readlane_b32 s3, v253, 25
	v_and_b32_e32 v4, 1, v32
	v_lshlrev_b32_e32 v192, 6, v4
	v_lshl_add_u64 v[2:3], s[2:3], 0, v[2:3]
	v_lshl_add_u64 v[2:3], v[2:3], 0, s[78:79]
	v_mov_b32_e32 v7, v1
	v_ashrrev_i32_e32 v1, 31, v0
	v_lshl_add_u64 v[34:35], v[2:3], 0, v[192:193]
	v_and_b32_e32 v2, 2, v32
	v_cmp_eq_u32_e32 vcc, 0, v2
	v_lshlrev_b32_e32 v2, 3, v5
	v_lshlrev_b64 v[0:1], 6, v[0:1]
	v_lshl_add_u32 v2, v4, 10, v2
	v_lshl_add_u64 v[38:39], s[60:61], 0, v[0:1]
	ds_write_b64 v14, v[6:7]
	s_waitcnt lgkmcnt(0)
	s_barrier
	v_lshl_add_u64 v[36:37], s[62:63], 0, v[0:1]
	ds_read2st64_b64 v[0:3], v2 offset1:1
	global_load_dwordx4 v[4:7], v[38:39], off offset:48
	global_load_dwordx4 v[12:15], v[38:39], off offset:32
	global_load_dwordx4 v[20:23], v[38:39], off offset:16
	global_load_dwordx4 v[28:31], v[38:39], off
	global_load_dwordx4 v[8:11], v[36:37], off offset:48
	global_load_dwordx4 v[16:19], v[36:37], off offset:32
	global_load_dwordx4 v[24:27], v[36:37], off offset:16
	global_load_dwordx4 v[40:43], v[36:37], off
	s_waitcnt vmcnt(4)
	v_mov_b32_e32 v44, v28
	v_mov_b32_e32 v45, v30
	v_mov_b32_e32 v49, v30
	v_mov_b32_e32 v30, v29
	s_waitcnt vmcnt(0)
	v_mov_b32_e32 v46, v40
	v_mov_b32_e32 v47, v42
	s_waitcnt lgkmcnt(0)
	v_pk_mul_f32 v[46:47], v[0:1], v[46:47] op_sel:[1,0]
	v_mov_b32_e32 v48, v40
	v_pk_fma_f32 v[44:45], v[0:1], v[44:45], v[46:47] op_sel_hi:[0,1,1] neg_lo:[0,0,1] neg_hi:[0,0,1]
	v_mov_b32_e32 v46, v28
	v_mov_b32_e32 v47, v42
	v_pk_mul_f32 v[46:47], v[0:1], v[46:47] op_sel:[1,0] op_sel_hi:[0,1]
	v_pk_fma_f32 v[46:47], v[0:1], v[48:49], v[46:47]
	v_mov_b32_e32 v42, v41
	v_cndmask_b32_e32 v33, v46, v44, vcc
	v_cndmask_b32_e32 v40, v47, v45, vcc
	v_pk_mul_f32 v[44:45], v[0:1], v[42:43] op_sel:[1,0]
	v_mov_b32_e32 v42, v29
	v_pk_fma_f32 v[44:45], v[0:1], v[30:31], v[44:45] op_sel_hi:[0,1,1] neg_lo:[0,0,1] neg_hi:[0,0,1]
	v_pk_mul_f32 v[28:29], v[0:1], v[42:43] op_sel:[1,0] op_sel_hi:[0,1]
	v_mov_b32_e32 v30, v41
	v_pk_fma_f32 v[28:29], v[0:1], v[30:31], v[28:29]
	v_and_b32_sdwa v30, v40, v218 dst_sel:DWORD dst_unused:UNUSED_PAD src0_sel:WORD_1 src1_sel:DWORD
	v_cndmask_b32_e32 v28, v28, v44, vcc
	v_cndmask_b32_e32 v29, v29, v45, vcc
	v_and_b32_sdwa v31, v33, v218 dst_sel:DWORD dst_unused:UNUSED_PAD src0_sel:WORD_1 src1_sel:DWORD
	v_add3_u32 v31, v33, v31, s80
	v_add3_u32 v30, v40, v30, s80
	v_and_b32_sdwa v33, v29, v218 dst_sel:DWORD dst_unused:UNUSED_PAD src0_sel:WORD_1 src1_sel:DWORD
	v_and_b32_sdwa v40, v28, v218 dst_sel:DWORD dst_unused:UNUSED_PAD src0_sel:WORD_1 src1_sel:DWORD
	v_add3_u32 v29, v29, v33, s80
	v_add3_u32 v28, v28, v40, s80
	v_and_b32_e32 v29, 0xffff0000, v29
	v_and_b32_e32 v28, 0xffff0000, v28
	v_mov_b32_e32 v40, v24
	v_mov_b32_e32 v41, v26
	v_or_b32_sdwa v29, v29, v30 dst_sel:DWORD dst_unused:UNUSED_PAD src0_sel:DWORD src1_sel:WORD_1
	v_or_b32_sdwa v28, v28, v31 dst_sel:DWORD dst_unused:UNUSED_PAD src0_sel:DWORD src1_sel:WORD_1
	v_mov_b32_e32 v30, v20
	v_mov_b32_e32 v31, v22
	v_pk_mul_f32 v[40:41], v[0:1], v[40:41] op_sel:[1,0]
	v_mov_b32_e32 v42, v24
	v_pk_fma_f32 v[30:31], v[0:1], v[30:31], v[40:41] op_sel_hi:[0,1,1] neg_lo:[0,0,1] neg_hi:[0,0,1]
	v_mov_b32_e32 v40, v20
	v_mov_b32_e32 v41, v26
	v_pk_mul_f32 v[40:41], v[0:1], v[40:41] op_sel:[1,0] op_sel_hi:[0,1]
	v_mov_b32_e32 v43, v22
	v_pk_fma_f32 v[40:41], v[0:1], v[42:43], v[40:41]
	v_mov_b32_e32 v26, v25
	v_cndmask_b32_e32 v24, v40, v30, vcc
	v_cndmask_b32_e32 v33, v41, v31, vcc
	v_mov_b32_e32 v22, v21
	v_pk_mul_f32 v[30:31], v[0:1], v[26:27] op_sel:[1,0]
	v_mov_b32_e32 v26, v21
	v_pk_fma_f32 v[30:31], v[0:1], v[22:23], v[30:31] op_sel_hi:[0,1,1] neg_lo:[0,0,1] neg_hi:[0,0,1]
	v_pk_mul_f32 v[20:21], v[0:1], v[26:27] op_sel:[1,0] op_sel_hi:[0,1]
	v_mov_b32_e32 v22, v25
	v_pk_fma_f32 v[20:21], v[0:1], v[22:23], v[20:21]
	v_and_b32_sdwa v23, v24, v218 dst_sel:DWORD dst_unused:UNUSED_PAD src0_sel:WORD_1 src1_sel:DWORD
	v_cndmask_b32_e32 v20, v20, v30, vcc
	v_cndmask_b32_e32 v21, v21, v31, vcc
	v_add3_u32 v23, v24, v23, s80
	v_and_b32_sdwa v24, v21, v218 dst_sel:DWORD dst_unused:UNUSED_PAD src0_sel:WORD_1 src1_sel:DWORD
	v_and_b32_sdwa v25, v20, v218 dst_sel:DWORD dst_unused:UNUSED_PAD src0_sel:WORD_1 src1_sel:DWORD
	v_and_b32_sdwa v22, v33, v218 dst_sel:DWORD dst_unused:UNUSED_PAD src0_sel:WORD_1 src1_sel:DWORD
	v_add3_u32 v21, v21, v24, s80
	v_add3_u32 v20, v20, v25, s80
	v_add3_u32 v22, v33, v22, s80
	v_and_b32_e32 v21, 0xffff0000, v21
	v_and_b32_e32 v20, 0xffff0000, v20
	v_or_b32_sdwa v31, v21, v22 dst_sel:DWORD dst_unused:UNUSED_PAD src0_sel:DWORD src1_sel:WORD_1
	v_or_b32_sdwa v30, v20, v23 dst_sel:DWORD dst_unused:UNUSED_PAD src0_sel:DWORD src1_sel:WORD_1
	v_mov_b32_e32 v22, v16
	v_mov_b32_e32 v23, v18
	v_mov_b32_e32 v20, v12
	v_mov_b32_e32 v21, v14
	v_pk_mul_f32 v[22:23], v[0:1], v[22:23] op_sel:[1,0]
	v_mov_b32_e32 v24, v16
	v_pk_fma_f32 v[20:21], v[0:1], v[20:21], v[22:23] op_sel_hi:[0,1,1] neg_lo:[0,0,1] neg_hi:[0,0,1]
	v_mov_b32_e32 v22, v12
	v_mov_b32_e32 v23, v18
	v_pk_mul_f32 v[22:23], v[0:1], v[22:23] op_sel:[1,0] op_sel_hi:[0,1]
	v_mov_b32_e32 v25, v14
	v_pk_fma_f32 v[22:23], v[0:1], v[24:25], v[22:23]
	v_mov_b32_e32 v18, v17
	v_cndmask_b32_e32 v16, v22, v20, vcc
	v_cndmask_b32_e32 v22, v23, v21, vcc
	v_mov_b32_e32 v14, v13
	v_pk_mul_f32 v[20:21], v[0:1], v[18:19] op_sel:[1,0]
	v_mov_b32_e32 v18, v13
	v_pk_fma_f32 v[20:21], v[0:1], v[14:15], v[20:21] op_sel_hi:[0,1,1] neg_lo:[0,0,1] neg_hi:[0,0,1]
	v_pk_mul_f32 v[12:13], v[0:1], v[18:19] op_sel:[1,0] op_sel_hi:[0,1]
	v_mov_b32_e32 v14, v17
	v_pk_fma_f32 v[12:13], v[0:1], v[14:15], v[12:13]
	v_and_b32_sdwa v15, v16, v218 dst_sel:DWORD dst_unused:UNUSED_PAD src0_sel:WORD_1 src1_sel:DWORD
	v_cndmask_b32_e32 v12, v12, v20, vcc
	v_cndmask_b32_e32 v13, v13, v21, vcc
	v_add3_u32 v15, v16, v15, s80
	v_and_b32_sdwa v16, v13, v218 dst_sel:DWORD dst_unused:UNUSED_PAD src0_sel:WORD_1 src1_sel:DWORD
	v_and_b32_sdwa v17, v12, v218 dst_sel:DWORD dst_unused:UNUSED_PAD src0_sel:WORD_1 src1_sel:DWORD
	v_and_b32_sdwa v14, v22, v218 dst_sel:DWORD dst_unused:UNUSED_PAD src0_sel:WORD_1 src1_sel:DWORD
	v_add3_u32 v13, v13, v16, s80
	v_add3_u32 v12, v12, v17, s80
	v_add3_u32 v14, v22, v14, s80
	v_and_b32_e32 v13, 0xffff0000, v13
	v_and_b32_e32 v12, 0xffff0000, v12
	v_mov_b32_e32 v16, v8
	v_mov_b32_e32 v17, v10
	v_or_b32_sdwa v13, v13, v14 dst_sel:DWORD dst_unused:UNUSED_PAD src0_sel:DWORD src1_sel:WORD_1
	v_or_b32_sdwa v12, v12, v15 dst_sel:DWORD dst_unused:UNUSED_PAD src0_sel:DWORD src1_sel:WORD_1
	v_mov_b32_e32 v14, v4
	v_mov_b32_e32 v15, v6
	v_pk_mul_f32 v[16:17], v[0:1], v[16:17] op_sel:[1,0]
	v_mov_b32_e32 v18, v8
	v_pk_fma_f32 v[14:15], v[0:1], v[14:15], v[16:17] op_sel_hi:[0,1,1] neg_lo:[0,0,1] neg_hi:[0,0,1]
	v_mov_b32_e32 v16, v4
	v_mov_b32_e32 v17, v10
	v_pk_mul_f32 v[16:17], v[0:1], v[16:17] op_sel:[1,0] op_sel_hi:[0,1]
	v_mov_b32_e32 v19, v6
	v_pk_fma_f32 v[16:17], v[0:1], v[18:19], v[16:17]
	v_mov_b32_e32 v10, v9
	v_cndmask_b32_e32 v8, v16, v14, vcc
	v_cndmask_b32_e32 v16, v17, v15, vcc
	v_mov_b32_e32 v6, v5
	v_pk_mul_f32 v[14:15], v[0:1], v[10:11] op_sel:[1,0]
	v_mov_b32_e32 v10, v5
	v_pk_fma_f32 v[14:15], v[0:1], v[6:7], v[14:15] op_sel_hi:[0,1,1] neg_lo:[0,0,1] neg_hi:[0,0,1]
	v_pk_mul_f32 v[4:5], v[0:1], v[10:11] op_sel:[1,0] op_sel_hi:[0,1]
	v_mov_b32_e32 v6, v9
	v_pk_fma_f32 v[0:1], v[0:1], v[6:7], v[4:5]
	v_and_b32_sdwa v4, v16, v218 dst_sel:DWORD dst_unused:UNUSED_PAD src0_sel:WORD_1 src1_sel:DWORD
	v_cndmask_b32_e32 v0, v0, v14, vcc
	v_cndmask_b32_e32 v1, v1, v15, vcc
	v_and_b32_sdwa v6, v1, v218 dst_sel:DWORD dst_unused:UNUSED_PAD src0_sel:WORD_1 src1_sel:DWORD
	v_and_b32_sdwa v7, v0, v218 dst_sel:DWORD dst_unused:UNUSED_PAD src0_sel:WORD_1 src1_sel:DWORD
	v_and_b32_sdwa v5, v8, v218 dst_sel:DWORD dst_unused:UNUSED_PAD src0_sel:WORD_1 src1_sel:DWORD
	v_add3_u32 v1, v1, v6, s80
	v_add3_u32 v0, v0, v7, s80
	v_add3_u32 v5, v8, v5, s80
	v_add3_u32 v4, v16, v4, s80
	v_and_b32_e32 v1, 0xffff0000, v1
	v_and_b32_e32 v0, 0xffff0000, v0
	v_or_b32_sdwa v15, v1, v4 dst_sel:DWORD dst_unused:UNUSED_PAD src0_sel:DWORD src1_sel:WORD_1
	v_or_b32_sdwa v14, v0, v5 dst_sel:DWORD dst_unused:UNUSED_PAD src0_sel:DWORD src1_sel:WORD_1
	global_store_dwordx4 v[34:35], v[28:31], off
	global_store_dwordx4 v[34:35], v[12:15], off offset:16
	global_load_dwordx4 v[4:7], v[38:39], off offset:48
	global_load_dwordx4 v[8:11], v[38:39], off offset:32
	s_nop 0
	global_load_dwordx4 v[12:15], v[38:39], off offset:16
	global_load_dwordx4 v[16:19], v[38:39], off
	global_load_dwordx4 v[20:23], v[36:37], off offset:48
	global_load_dwordx4 v[24:27], v[36:37], off offset:32
	global_load_dwordx4 v[28:31], v[36:37], off offset:16
	s_nop 0
	global_load_dwordx4 v[36:39], v[36:37], off
	s_waitcnt vmcnt(4)
	v_mov_b32_e32 v0, v16
	v_mov_b32_e32 v1, v18
	v_mov_b32_e32 v43, v18
	v_mov_b32_e32 v18, v17
	s_waitcnt vmcnt(0)
	v_mov_b32_e32 v40, v36
	v_mov_b32_e32 v41, v38
	v_pk_mul_f32 v[40:41], v[2:3], v[40:41] op_sel:[1,0]
	v_mov_b32_e32 v42, v36
	v_pk_fma_f32 v[0:1], v[2:3], v[0:1], v[40:41] op_sel_hi:[0,1,1] neg_lo:[0,0,1] neg_hi:[0,0,1]
	v_mov_b32_e32 v40, v16
	v_mov_b32_e32 v41, v38
	v_pk_mul_f32 v[40:41], v[2:3], v[40:41] op_sel:[1,0] op_sel_hi:[0,1]
	v_pk_fma_f32 v[40:41], v[2:3], v[42:43], v[40:41]
	v_mov_b32_e32 v38, v37
	v_cndmask_b32_e32 v33, v40, v0, vcc
	v_cndmask_b32_e32 v36, v41, v1, vcc
	v_pk_mul_f32 v[0:1], v[2:3], v[38:39] op_sel:[1,0]
	v_mov_b32_e32 v38, v17
	v_pk_fma_f32 v[0:1], v[2:3], v[18:19], v[0:1] op_sel_hi:[0,1,1] neg_lo:[0,0,1] neg_hi:[0,0,1]
	v_pk_mul_f32 v[16:17], v[2:3], v[38:39] op_sel:[1,0] op_sel_hi:[0,1]
	v_mov_b32_e32 v18, v37
	v_pk_fma_f32 v[16:17], v[2:3], v[18:19], v[16:17]
	v_mov_b32_e32 v37, v14
	v_cndmask_b32_e32 v0, v16, v0, vcc
	v_cndmask_b32_e32 v1, v17, v1, vcc
	v_and_b32_sdwa v17, v33, v218 dst_sel:DWORD dst_unused:UNUSED_PAD src0_sel:WORD_1 src1_sel:DWORD
	v_add3_u32 v18, v33, v17, s80
	v_and_b32_sdwa v17, v1, v218 dst_sel:DWORD dst_unused:UNUSED_PAD src0_sel:WORD_1 src1_sel:DWORD
	v_and_b32_sdwa v19, v0, v218 dst_sel:DWORD dst_unused:UNUSED_PAD src0_sel:WORD_1 src1_sel:DWORD
	v_and_b32_sdwa v16, v36, v218 dst_sel:DWORD dst_unused:UNUSED_PAD src0_sel:WORD_1 src1_sel:DWORD
	v_add3_u32 v1, v1, v17, s80
	v_add3_u32 v0, v0, v19, s80
	v_add3_u32 v16, v36, v16, s80
	v_and_b32_e32 v1, 0xffff0000, v1
	v_and_b32_e32 v0, 0xffff0000, v0
	v_or_b32_sdwa v17, v1, v16 dst_sel:DWORD dst_unused:UNUSED_PAD src0_sel:DWORD src1_sel:WORD_1
	v_or_b32_sdwa v16, v0, v18 dst_sel:DWORD dst_unused:UNUSED_PAD src0_sel:DWORD src1_sel:WORD_1
	v_mov_b32_e32 v18, v28
	v_mov_b32_e32 v19, v30
	v_mov_b32_e32 v0, v12
	v_mov_b32_e32 v1, v14
	v_pk_mul_f32 v[18:19], v[2:3], v[18:19] op_sel:[1,0]
	v_mov_b32_e32 v36, v28
	v_pk_fma_f32 v[0:1], v[2:3], v[0:1], v[18:19] op_sel_hi:[0,1,1] neg_lo:[0,0,1] neg_hi:[0,0,1]
	v_mov_b32_e32 v18, v12
	v_mov_b32_e32 v19, v30
	v_pk_mul_f32 v[18:19], v[2:3], v[18:19] op_sel:[1,0] op_sel_hi:[0,1]
	v_pk_fma_f32 v[18:19], v[2:3], v[36:37], v[18:19]
	v_mov_b32_e32 v30, v29
	v_cndmask_b32_e32 v18, v18, v0, vcc
	v_cndmask_b32_e32 v19, v19, v1, vcc
	v_mov_b32_e32 v14, v13
	v_pk_mul_f32 v[0:1], v[2:3], v[30:31] op_sel:[1,0]
	v_mov_b32_e32 v30, v13
	v_pk_fma_f32 v[0:1], v[2:3], v[14:15], v[0:1] op_sel_hi:[0,1,1] neg_lo:[0,0,1] neg_hi:[0,0,1]
	v_pk_mul_f32 v[12:13], v[2:3], v[30:31] op_sel:[1,0] op_sel_hi:[0,1]
	v_mov_b32_e32 v14, v29
	v_pk_fma_f32 v[12:13], v[2:3], v[14:15], v[12:13]
	s_nop 0
	v_cndmask_b32_e32 v0, v12, v0, vcc
	v_cndmask_b32_e32 v1, v13, v1, vcc
	v_and_b32_sdwa v14, v1, v218 dst_sel:DWORD dst_unused:UNUSED_PAD src0_sel:WORD_1 src1_sel:DWORD
	v_and_b32_sdwa v15, v0, v218 dst_sel:DWORD dst_unused:UNUSED_PAD src0_sel:WORD_1 src1_sel:DWORD
	v_and_b32_sdwa v12, v19, v218 dst_sel:DWORD dst_unused:UNUSED_PAD src0_sel:WORD_1 src1_sel:DWORD
	v_and_b32_sdwa v13, v18, v218 dst_sel:DWORD dst_unused:UNUSED_PAD src0_sel:WORD_1 src1_sel:DWORD
	v_add3_u32 v1, v1, v14, s80
	v_add3_u32 v0, v0, v15, s80
	v_add3_u32 v13, v18, v13, s80
	v_add3_u32 v12, v19, v12, s80
	v_and_b32_e32 v1, 0xffff0000, v1
	v_and_b32_e32 v0, 0xffff0000, v0
	v_or_b32_sdwa v19, v1, v12 dst_sel:DWORD dst_unused:UNUSED_PAD src0_sel:DWORD src1_sel:WORD_1
	v_or_b32_sdwa v18, v0, v13 dst_sel:DWORD dst_unused:UNUSED_PAD src0_sel:DWORD src1_sel:WORD_1
	v_mov_b32_e32 v12, v24
	v_mov_b32_e32 v13, v26
	v_mov_b32_e32 v0, v8
	v_mov_b32_e32 v1, v10
	v_pk_mul_f32 v[12:13], v[2:3], v[12:13] op_sel:[1,0]
	v_mov_b32_e32 v14, v24
	v_pk_fma_f32 v[0:1], v[2:3], v[0:1], v[12:13] op_sel_hi:[0,1,1] neg_lo:[0,0,1] neg_hi:[0,0,1]
	v_mov_b32_e32 v12, v8
	v_mov_b32_e32 v13, v26
	v_pk_mul_f32 v[12:13], v[2:3], v[12:13] op_sel:[1,0] op_sel_hi:[0,1]
	v_mov_b32_e32 v15, v10
	v_pk_fma_f32 v[12:13], v[2:3], v[14:15], v[12:13]
	v_mov_b32_e32 v26, v25
	v_cndmask_b32_e32 v12, v12, v0, vcc
	v_cndmask_b32_e32 v13, v13, v1, vcc
	v_mov_b32_e32 v10, v9
	v_pk_mul_f32 v[0:1], v[2:3], v[26:27] op_sel:[1,0]
	v_mov_b32_e32 v26, v9
	v_pk_fma_f32 v[0:1], v[2:3], v[10:11], v[0:1] op_sel_hi:[0,1,1] neg_lo:[0,0,1] neg_hi:[0,0,1]
	v_pk_mul_f32 v[8:9], v[2:3], v[26:27] op_sel:[1,0] op_sel_hi:[0,1]
	v_mov_b32_e32 v10, v25
	v_pk_fma_f32 v[8:9], v[2:3], v[10:11], v[8:9]
	s_nop 0
	v_cndmask_b32_e32 v0, v8, v0, vcc
	v_cndmask_b32_e32 v1, v9, v1, vcc
	v_and_b32_sdwa v10, v1, v218 dst_sel:DWORD dst_unused:UNUSED_PAD src0_sel:WORD_1 src1_sel:DWORD
	v_and_b32_sdwa v11, v0, v218 dst_sel:DWORD dst_unused:UNUSED_PAD src0_sel:WORD_1 src1_sel:DWORD
	v_and_b32_sdwa v8, v13, v218 dst_sel:DWORD dst_unused:UNUSED_PAD src0_sel:WORD_1 src1_sel:DWORD
	v_and_b32_sdwa v9, v12, v218 dst_sel:DWORD dst_unused:UNUSED_PAD src0_sel:WORD_1 src1_sel:DWORD
	v_add3_u32 v1, v1, v10, s80
	v_add3_u32 v0, v0, v11, s80
	v_add3_u32 v9, v12, v9, s80
	v_add3_u32 v8, v13, v8, s80
	v_and_b32_e32 v1, 0xffff0000, v1
	v_and_b32_e32 v0, 0xffff0000, v0
	v_mov_b32_e32 v10, v20
	v_mov_b32_e32 v11, v22
	v_or_b32_sdwa v1, v1, v8 dst_sel:DWORD dst_unused:UNUSED_PAD src0_sel:DWORD src1_sel:WORD_1
	v_or_b32_sdwa v0, v0, v9 dst_sel:DWORD dst_unused:UNUSED_PAD src0_sel:DWORD src1_sel:WORD_1
	v_mov_b32_e32 v8, v4
	v_mov_b32_e32 v9, v6
	v_pk_mul_f32 v[10:11], v[2:3], v[10:11] op_sel:[1,0]
	v_mov_b32_e32 v12, v20
	v_pk_fma_f32 v[8:9], v[2:3], v[8:9], v[10:11] op_sel_hi:[0,1,1] neg_lo:[0,0,1] neg_hi:[0,0,1]
	v_mov_b32_e32 v10, v4
	v_mov_b32_e32 v11, v22
	v_pk_mul_f32 v[10:11], v[2:3], v[10:11] op_sel:[1,0] op_sel_hi:[0,1]
	v_mov_b32_e32 v13, v6
	v_pk_fma_f32 v[10:11], v[2:3], v[12:13], v[10:11]
	v_mov_b32_e32 v22, v21
	v_cndmask_b32_e32 v10, v10, v8, vcc
	v_cndmask_b32_e32 v11, v11, v9, vcc
	v_mov_b32_e32 v6, v5
	v_pk_mul_f32 v[8:9], v[2:3], v[22:23] op_sel:[1,0]
	v_mov_b32_e32 v22, v5
	v_pk_fma_f32 v[8:9], v[2:3], v[6:7], v[8:9] op_sel_hi:[0,1,1] neg_lo:[0,0,1] neg_hi:[0,0,1]
	v_pk_mul_f32 v[4:5], v[2:3], v[22:23] op_sel:[1,0] op_sel_hi:[0,1]
	v_mov_b32_e32 v6, v21
	v_pk_fma_f32 v[2:3], v[2:3], v[6:7], v[4:5]
	v_and_b32_sdwa v4, v11, v218 dst_sel:DWORD dst_unused:UNUSED_PAD src0_sel:WORD_1 src1_sel:DWORD
	v_cndmask_b32_e32 v2, v2, v8, vcc
	v_cndmask_b32_e32 v3, v3, v9, vcc
	v_and_b32_sdwa v6, v3, v218 dst_sel:DWORD dst_unused:UNUSED_PAD src0_sel:WORD_1 src1_sel:DWORD
	v_and_b32_sdwa v7, v2, v218 dst_sel:DWORD dst_unused:UNUSED_PAD src0_sel:WORD_1 src1_sel:DWORD
	v_and_b32_sdwa v5, v10, v218 dst_sel:DWORD dst_unused:UNUSED_PAD src0_sel:WORD_1 src1_sel:DWORD
	v_add3_u32 v3, v3, v6, s80
	v_add3_u32 v2, v2, v7, s80
	v_add3_u32 v5, v10, v5, s80
	v_add3_u32 v4, v11, v4, s80
	v_and_b32_e32 v3, 0xffff0000, v3
	v_and_b32_e32 v2, 0xffff0000, v2
	v_or_b32_sdwa v3, v3, v4 dst_sel:DWORD dst_unused:UNUSED_PAD src0_sel:DWORD src1_sel:WORD_1
	v_or_b32_sdwa v2, v2, v5 dst_sel:DWORD dst_unused:UNUSED_PAD src0_sel:DWORD src1_sel:WORD_1
	global_store_dwordx4 v[34:35], v[16:19], off offset:32
	global_store_dwordx4 v[34:35], v[0:3], off offset:48
	s_barrier

.LBB0_80:
	s_andn2_b64 vcc, exec, s[0:1]
	s_cbranch_vccnz .LBB0_94
	s_add_i32 s78, s8, 0xfffffa6e
	s_and_b32 s0, s78, 0xffff
	s_mulk_i32 s0, 0x411
	s_lshr_b32 s0, s0, 16
	s_sub_i32 s1, s78, s0
	s_bfe_u32 s1, s1, 0xf0001
	s_add_i32 s1, s1, s0
	s_bfe_u32 s0, s1, 0xb0005
	s_lshl_b32 s1, s0, 12
	v_lshlrev_b32_e32 v2, 2, v32
	s_add_i32 s4, s1, 0x30000
	v_ashrrev_i32_e32 v3, 31, v2
	s_add_u32 s2, s60, s4
	s_addc_u32 s3, s61, 0
	v_lshlrev_b64 v[6:7], 2, v[2:3]
	v_lshl_add_u64 v[2:3], s[2:3], 0, v[6:7]
	global_load_dwordx4 v[2:5], v[2:3], off
	s_add_u32 s2, s62, s4
	v_lshlrev_b32_e32 v1, 4, v32
	s_addc_u32 s3, s63, 0
	s_add_i32 s1, s1, 0x48000
	v_and_b32_e32 v192, 63, v32
	s_waitcnt vmcnt(0)
	ds_write_b128 v1, v[2:5] offset:17408
	v_lshl_add_u64 v[2:3], s[2:3], 0, v[6:7]
	global_load_dwordx4 v[2:5], v[2:3], off
	s_add_u32 s2, s60, s1
	s_addc_u32 s3, s61, 0
	s_waitcnt vmcnt(0)
	ds_write_b128 v1, v[2:5] offset:21504
	v_lshl_add_u64 v[2:3], s[2:3], 0, v[6:7]
	global_load_dwordx4 v[2:5], v[2:3], off
	s_add_u32 s2, s62, s1
	s_addc_u32 s3, s63, 0
	s_movk_i32 s1, 0x7f
	v_cmp_lt_i32_e32 vcc, s1, v32
	s_waitcnt vmcnt(0)
	ds_write_b128 v1, v[2:5] offset:25600
	v_lshl_add_u64 v[2:3], s[2:3], 0, v[6:7]
	global_load_dwordx4 v[2:5], v[2:3], off
	s_waitcnt vmcnt(0)
	ds_write_b128 v1, v[2:5] offset:29696
	v_lshlrev_b32_e32 v3, 3, v32
	s_and_saveexec_b64 s[2:3], vcc
	s_xor_b64 s[2:3], exec, s[2:3]
	s_add_i32 s1, s0, 48
	v_and_b32_e32 v192, 63, v32
	v_lshlrev_b32_e32 v3, 3, v32
	v_mov_b32_e32 v4, s1
	s_or_saveexec_b64 s[2:3], s[2:3]
	s_mul_i32 s1, s0, 63
	s_sub_i32 s1, s78, s1
	s_and_b32 s5, s1, 0xffff
	s_sub_i32 s4, s5, 31
	s_xor_b64 exec, exec, s[2:3]
	s_cbranch_execz .LBB0_85
	s_sub_i32 s1, 31, s5
	v_ashrrev_i32_e32 v0, 6, v32
	s_cmp_lt_u32 s5, 31
	v_mul_lo_u32 v6, v0, 24
	s_cselect_b32 s7, s1, s4
	s_add_i32 s6, s0, 48
	v_ashrrev_i32_e32 v7, 31, v6
	s_mov_b32 s1, s79
	v_add_u32_e32 v0, s6, v6
	v_lshl_add_u64 v[6:7], s[0:1], 0, v[6:7]
	v_lshl_add_u64 v[6:7], v[6:7], 2, s[58:59]
	v_lshl_or_b32 v4, v0, 6, v192
	global_load_dword v0, v[6:7], off offset:192
	v_ashrrev_i32_e32 v5, 31, v4
	v_lshlrev_b64 v[8:9], 2, v[4:5]
	v_lshl_add_u64 v[4:5], s[54:55], 0, v[8:9]
	global_load_dword v4, v[4:5], off
	v_lshl_add_u64 v[8:9], s[56:57], 0, v[8:9]
	global_load_dword v5, v[8:9], off
	s_mov_b32 s1, 0x3fb8aa3b
	s_mov_b32 s9, 0xc2ce8ed0
	s_mov_b32 s12, 0x42b17218
	s_mov_b32 s10, 0x6dc9c883
	s_mov_b32 s11, 0x3fc45f30
	s_waitcnt vmcnt(2)
	v_mul_f32_e32 v2, 0x3fb8aa3b, v0
	v_fma_f32 v6, v0, s1, -v2
	v_rndne_f32_e32 v7, v2
	v_fmac_f32_e32 v6, 0x32a5705f, v0
	v_sub_f32_e32 v2, v2, v7
	v_add_f32_e32 v2, v2, v6
	v_exp_f32_e32 v2, v2
	v_cvt_i32_f32_e32 v6, v7
	v_cmp_ngt_f32_e32 vcc, s9, v0
	s_waitcnt vmcnt(0)
	v_cvt_f64_f32_e32 v[8:9], v5
	v_ldexp_f32 v2, v2, v6
	v_cndmask_b32_e32 v2, 0, v2, vcc
	v_cmp_nlt_f32_e32 vcc, s12, v0
	v_cvt_f32_i32_e32 v0, s7
	v_mul_f32_e32 v0, v4, v0
	v_cndmask_b32_e32 v14, v228, v2, vcc
	v_mul_f32_e32 v0, v0, v14
	v_mul_f32_e32 v2, 0x3fb8aa3b, v0
	v_fma_f32 v6, v0, s1, -v2
	v_rndne_f32_e32 v7, v2
	v_fmac_f32_e32 v6, 0x32a5705f, v0
	v_sub_f32_e32 v2, v2, v7
	v_add_f32_e32 v2, v2, v6
	v_exp_f32_e32 v2, v2
	v_cvt_i32_f32_e32 v6, v7
	v_cvt_f64_f32_e32 v[10:11], v14
	v_cmp_ngt_f32_e32 vcc, s9, v0
	v_ldexp_f32 v2, v2, v6
	v_cvt_f64_i32_e32 v[6:7], s7
	v_mul_f64 v[6:7], v[6:7], v[8:9]
	v_mul_f64 v[6:7], v[6:7], v[10:11]
	v_mul_f64 v[12:13], v[6:7], s[10:11]
	v_rndne_f64_e32 v[12:13], v[12:13]
	v_fma_f64 v[6:7], v[6:7], s[10:11], -v[12:13]
	v_cvt_f32_f64_e32 v6, v[6:7]
	v_cndmask_b32_e32 v2, 0, v2, vcc
	v_cmp_nlt_f32_e32 vcc, s12, v0
	v_cos_f32_e32 v0, v6
	v_sin_f32_e32 v6, v6
	v_cndmask_b32_e32 v2, v228, v2, vcc
	v_mul_f32_e32 v0, v2, v0
	v_mul_f32_e32 v2, v2, v6
	v_mul_f32_e32 v6, v4, v14
	v_mul_f32_e32 v7, 0x3fb8aa3b, v6
	v_fma_f32 v12, v6, s1, -v7
	v_rndne_f32_e32 v13, v7
	v_fmac_f32_e32 v12, 0x32a5705f, v6
	v_sub_f32_e32 v7, v7, v13
	v_add_f32_e32 v7, v7, v12
	v_exp_f32_e32 v7, v7
	v_cvt_i32_f32_e32 v12, v13
	v_cmp_ngt_f32_e32 vcc, s9, v6
	v_sub_u32_e32 v14, v1, v3
	v_ldexp_f32 v7, v7, v12
	v_cndmask_b32_e32 v7, 0, v7, vcc
	v_cmp_nlt_f32_e32 vcc, s12, v6
	s_nop 1
	v_cndmask_b32_e32 v12, v228, v7, vcc
	v_mul_f64 v[6:7], v[8:9], v[10:11]
	v_mul_f64 v[8:9], v[6:7], s[10:11]
	v_rndne_f64_e32 v[8:9], v[8:9]
	v_fma_f64 v[6:7], v[6:7], s[10:11], -v[8:9]
	v_cvt_f32_f64_e32 v6, v[6:7]
	v_cos_f32_e32 v7, v6
	v_sin_f32_e32 v6, v6
	v_mov_b32_e32 v10, v5
	v_fma_f32 v8, v12, v7, -1.0
	v_mul_f32_e32 v9, v12, v6
	v_pk_mul_f32 v[6:7], v[4:5], v[4:5]
	v_pk_mul_f32 v[12:13], v[10:11], v[8:9] op_sel:[0,1] op_sel_hi:[0,0]
	v_pk_fma_f32 v[10:11], v[4:5], v[8:9], v[12:13]
	v_pk_fma_f32 v[8:9], v[4:5], v[8:9], v[12:13] op_sel_hi:[0,1,1] neg_lo:[0,0,1] neg_hi:[0,0,1]
	v_pk_add_f32 v[4:5], v[6:7], v[6:7] op_sel:[0,1] op_sel_hi:[0,1]
	v_rcp_f32_e32 v6, v5
	s_nop 0
	v_mul_f32_e32 v5, v9, v6
	v_div_scale_f32 v1, s[10:11], v4, v4, v10
	v_rcp_f32_e32 v6, v1
	s_nop 0
	v_fma_f32 v7, -v1, v6, 1.0
	v_fmac_f32_e32 v6, v7, v6
	v_div_scale_f32 v7, vcc, v10, v4, v10
	v_mul_f32_e32 v8, v7, v6
	v_fma_f32 v9, -v1, v8, v7
	v_fmac_f32_e32 v8, v9, v6
	v_fma_f32 v1, -v1, v8, v7
	v_div_fmas_f32 v1, v1, v6, v8
	v_div_fixup_f32 v4, v1, v4, v10
	v_pk_mul_f32 v[6:7], v[2:3], v[4:5] op_sel:[0,1] op_sel_hi:[0,0]
	v_pk_fma_f32 v[8:9], v[0:1], v[4:5], v[6:7] neg_lo:[0,0,1] neg_hi:[0,0,1]
	v_pk_fma_f32 v[0:1], v[0:1], v[4:5], v[6:7] op_sel_hi:[0,1,1]
	v_mov_b32_e32 v9, v1
	v_mov_b32_e32 v4, s6
	ds_write_b64 v14, v[8:9]

.LBB0_122:
	v_mov_b32_e32 v36, 0
	v_mov_b32_e32 v37, 0
	v_mov_b32_e32 v38, 0
	v_mov_b32_e32 v39, 0
	v_mov_b32_e32 v40, 0
	v_mov_b32_e32 v41, 0
	v_mov_b32_e32 v42, 0
	v_mov_b32_e32 v43, 0
	v_mov_b32_e32 v128, 0
	v_mov_b32_e32 v129, 0
	v_mov_b32_e32 v130, 0
	v_mov_b32_e32 v131, 0
	v_mov_b32_e32 v194, 0
	v_mov_b32_e32 v195, 0
	v_mov_b32_e32 v196, 0
	v_mov_b32_e32 v197, 0
	v_mov_b32_e32 v198, 0
	v_mov_b32_e32 v199, 0
	v_mov_b32_e32 v200, 0
	v_mov_b32_e32 v201, 0
	s_nop 1
.Lrs1_top:
	s_add_i32 s7, s6, 64
	s_min_u32 s8, s7, 0xae0
	s_lshl_b32 s78, s8, 1
	ds_read_b128 v[52:55], v116 offset:0
	ds_read_b128 v[48:51], v116 offset:0x800
	ds_read_b128 v[44:47], v116 offset:0x1000
	ds_read_b128 v[96:99], v114 offset:0
	v_mfma_f32_32x32x16_bf16 a[144:159], v[128:131], v[40:43], a[144:159]
	ds_read_b128 v[92:95], v114 offset:0x800
	v_mfma_f32_32x32x16_bf16 a[160:175], v[128:131], v[36:39], a[160:175]
	ds_read_b128 v[88:91], v114 offset:0x1000
	v_lshl_add_u64 v[60:61], v[100:101], 0, s[78:79]
	global_load_dwordx4 v[64:67], v[60:61], off
	v_mfma_f32_32x32x16_bf16 a[176:191], v[128:131], v[194:197], a[176:191]
	ds_read_b128 v[56:59], v114 offset:0x1800
	v_lshl_add_u64 v[62:63], v[104:105], 0, s[78:79]
	global_load_dwordx4 v[60:63], v[62:63], off
	v_mfma_f32_32x32x16_bf16 a[32:47], v[198:201], v[40:43], a[32:47]
	v_lshl_add_u64 v[68:69], v[106:107], 0, s[78:79]
	global_load_dwordx4 v[72:75], v[68:69], off
	v_mfma_f32_32x32x16_bf16 a[16:31], v[198:201], v[36:39], a[16:31]
	v_lshl_add_u64 v[70:71], v[108:109], 0, s[78:79]
	global_load_dwordx4 v[68:71], v[70:71], off
	v_mfma_f32_32x32x16_bf16 a[0:15], v[198:201], v[194:197], a[0:15]
	v_lshl_add_u64 v[76:77], v[102:103], 0, s[78:79]
	global_load_dwordx4 v[84:87], v[76:77], off
	s_waitcnt lgkmcnt(3)
	v_mfma_f32_32x32x16_bf16 a[48:63], v[96:99], v[52:55], a[48:63]
	ds_read_b128 v[36:39], v117 offset:0
	v_mfma_f32_32x32x16_bf16 a[64:79], v[96:99], v[48:51], a[64:79]
	v_lshl_add_u64 v[78:79], v[110:111], 0, s[78:79]
	global_load_dwordx4 v[76:79], v[78:79], off
	v_mfma_f32_32x32x16_bf16 a[80:95], v[96:99], v[44:47], a[80:95]
	ds_read_b128 v[40:43], v117 offset:0x800
	s_waitcnt lgkmcnt(4)
	v_mfma_f32_32x32x16_bf16 a[96:111], v[92:95], v[52:55], a[96:111]
	v_lshl_add_u64 v[80:81], v[112:113], 0, s[78:79]
	global_load_dwordx4 v[80:83], v[80:81], off
	v_mfma_f32_32x32x16_bf16 a[112:127], v[92:95], v[48:51], a[112:127]
	ds_read_b128 v[120:123], v117 offset:0x1000
	s_min_u32 s6, s6, 0xa80
	s_lshl_b32 s78, s6, 1
	v_mfma_f32_32x32x16_bf16 a[128:143], v[92:95], v[44:47], a[128:143]
	ds_read_b128 v[124:127], v115 offset:0
	s_add_i32 s8, s78, 0xc0
	s_mov_b32 s9, s79
	s_waitcnt lgkmcnt(5)
	v_mfma_f32_32x32x16_bf16 a[144:159], v[88:91], v[52:55], a[144:159]
	ds_read_b128 v[128:131], v115 offset:0x800
	s_add_i32 s5, s5, 2
	s_cmpk_lt_u32 s5, 0x56
	v_mfma_f32_32x32x16_bf16 a[160:175], v[88:91], v[48:51], a[160:175]
	ds_read_b128 v[132:135], v115 offset:0x1000
	s_waitcnt vmcnt(13)
	ds_write_b128 v118, v[4:7] offset:0x8000
	v_mfma_f32_32x32x16_bf16 a[176:191], v[88:91], v[44:47], a[176:191]
	ds_read_b128 v[136:139], v115 offset:0x1800
	s_waitcnt vmcnt(12)
	ds_write_b128 v118, v[8:11] offset:0x9000
	s_waitcnt lgkmcnt(9)
	v_mfma_f32_32x32x16_bf16 a[32:47], v[56:59], v[52:55], a[32:47]
	s_waitcnt vmcnt(11)
	ds_write_b128 v118, v[12:15] offset:0xa000
	v_mfma_f32_32x32x16_bf16 a[16:31], v[56:59], v[48:51], a[16:31]
	s_waitcnt vmcnt(10)
	ds_write_b128 v118, v[16:19] offset:0xb000
	v_mfma_f32_32x32x16_bf16 a[0:15], v[56:59], v[44:47], a[0:15]
	s_waitcnt vmcnt(9)
	ds_write_b128 v118, v[20:23] offset:0xc000
	s_waitcnt lgkmcnt(8)
	v_mfma_f32_32x32x16_bf16 a[48:63], v[124:127], v[36:39], a[48:63]
	s_waitcnt vmcnt(8)
	ds_write_b128 v118, v[24:27] offset:0xd000
	v_mfma_f32_32x32x16_bf16 a[64:79], v[124:127], v[40:43], a[64:79]
	s_waitcnt vmcnt(7)
	ds_write_b128 v118, v[28:31] offset:0xe000
	v_mfma_f32_32x32x16_bf16 a[80:95], v[124:127], v[120:123], a[80:95]
	v_lshl_add_u64 v[4:5], v[100:101], 0, s[78:79]
	v_lshl_add_u64 v[8:9], v[104:105], 0, s[8:9]
	s_waitcnt lgkmcnt(9)
	v_mfma_f32_32x32x16_bf16 a[96:111], v[128:131], v[36:39], a[96:111]
	v_lshl_add_u64 v[12:13], v[106:107], 0, s[8:9]
	v_lshl_add_u64 v[16:17], v[108:109], 0, s[8:9]
	v_mfma_f32_32x32x16_bf16 a[112:127], v[128:131], v[40:43], a[112:127]
	v_lshl_add_u64 v[20:21], v[102:103], 0, s[78:79]
	v_lshl_add_u64 v[24:25], v[110:111], 0, s[8:9]
	v_mfma_f32_32x32x16_bf16 a[128:143], v[128:131], v[120:123], a[128:143]
	v_lshl_add_u64 v[28:29], v[112:113], 0, s[8:9]
	s_waitcnt lgkmcnt(0)
	s_barrier
	ds_read_b128 v[44:47], v116 offset:0x8000
	ds_read_b128 v[48:51], v116 offset:0x8800
	ds_read_b128 v[52:55], v116 offset:0x9000
	ds_read_b128 v[56:59], v114 offset:0x8000
	v_mfma_f32_32x32x16_bf16 a[144:159], v[132:135], v[36:39], a[144:159]
	ds_read_b128 v[88:91], v114 offset:0x8800
	v_mfma_f32_32x32x16_bf16 a[160:175], v[132:135], v[40:43], a[160:175]
	ds_read_b128 v[92:95], v114 offset:0x9000
	global_load_dwordx4 v[4:7], v[4:5], off offset:192
	v_mfma_f32_32x32x16_bf16 a[176:191], v[132:135], v[120:123], a[176:191]
	ds_read_b128 v[96:99], v114 offset:0x9800
	global_load_dwordx4 v[8:11], v[8:9], off
	v_mfma_f32_32x32x16_bf16 a[32:47], v[136:139], v[36:39], a[32:47]
	global_load_dwordx4 v[12:15], v[12:13], off
	v_mfma_f32_32x32x16_bf16 a[16:31], v[136:139], v[40:43], a[16:31]
	global_load_dwordx4 v[16:19], v[16:17], off
	v_mfma_f32_32x32x16_bf16 a[0:15], v[136:139], v[120:123], a[0:15]
	global_load_dwordx4 v[20:23], v[20:21], off offset:192
	s_waitcnt lgkmcnt(3)
	v_mfma_f32_32x32x16_bf16 a[48:63], v[56:59], v[44:47], a[48:63]
	ds_read_b128 v[40:43], v117 offset:0x8000
	v_mfma_f32_32x32x16_bf16 a[64:79], v[56:59], v[48:51], a[64:79]
	global_load_dwordx4 v[24:27], v[24:25], off
	v_mfma_f32_32x32x16_bf16 a[80:95], v[56:59], v[52:55], a[80:95]
	ds_read_b128 v[36:39], v117 offset:0x8800
	s_waitcnt lgkmcnt(4)
	v_mfma_f32_32x32x16_bf16 a[96:111], v[88:91], v[44:47], a[96:111]
	global_load_dwordx4 v[28:31], v[28:29], off
	v_mfma_f32_32x32x16_bf16 a[112:127], v[88:91], v[48:51], a[112:127]
	ds_read_b128 v[194:197], v117 offset:0x9000
	v_mfma_f32_32x32x16_bf16 a[128:143], v[88:91], v[52:55], a[128:143]
	ds_read_b128 v[120:123], v115 offset:0x8000
	s_waitcnt lgkmcnt(5)
	v_mfma_f32_32x32x16_bf16 a[144:159], v[92:95], v[44:47], a[144:159]
	ds_read_b128 v[124:127], v115 offset:0x8800
	v_mfma_f32_32x32x16_bf16 a[160:175], v[92:95], v[48:51], a[160:175]
	ds_read_b128 v[128:131], v115 offset:0x9000
	v_mfma_f32_32x32x16_bf16 a[176:191], v[92:95], v[52:55], a[176:191]
	ds_read_b128 v[198:201], v115 offset:0x9800
	s_waitcnt lgkmcnt(7)
	v_mfma_f32_32x32x16_bf16 a[32:47], v[96:99], v[44:47], a[32:47]
	s_waitcnt vmcnt(13)
	ds_write_b128 v118, v[64:67] offset:0
	v_mfma_f32_32x32x16_bf16 a[16:31], v[96:99], v[48:51], a[16:31]
	s_waitcnt vmcnt(12)
	ds_write_b128 v118, v[60:63] offset:0x1000
	v_mfma_f32_32x32x16_bf16 a[0:15], v[96:99], v[52:55], a[0:15]
	s_waitcnt vmcnt(11)
	ds_write_b128 v118, v[72:75] offset:0x2000
	s_waitcnt lgkmcnt(6)
	v_mfma_f32_32x32x16_bf16 a[48:63], v[120:123], v[40:43], a[48:63]
	s_waitcnt vmcnt(10)
	ds_write_b128 v118, v[68:71] offset:0x3000
	v_mfma_f32_32x32x16_bf16 a[64:79], v[120:123], v[36:39], a[64:79]
	s_waitcnt vmcnt(9)
	ds_write_b128 v118, v[84:87] offset:0x4000
	v_mfma_f32_32x32x16_bf16 a[80:95], v[120:123], v[194:197], a[80:95]
	s_waitcnt vmcnt(8)
	ds_write_b128 v118, v[76:79] offset:0x5000
	s_waitcnt lgkmcnt(8)
	v_mfma_f32_32x32x16_bf16 a[96:111], v[124:127], v[40:43], a[96:111]
	s_waitcnt vmcnt(7)
	ds_write_b128 v118, v[80:83] offset:0x6000
	v_mfma_f32_32x32x16_bf16 a[112:127], v[124:127], v[36:39], a[112:127]
	v_mfma_f32_32x32x16_bf16 a[128:143], v[124:127], v[194:197], a[128:143]
	s_waitcnt lgkmcnt(0)
	s_barrier
	s_cbranch_scc0 .Lrs1_exit
	s_mov_b32 s6, s7
	s_branch .Lrs1_top
.Lrs1_exit:
	v_mfma_f32_32x32x16_bf16 a[144:159], v[128:131], v[40:43], a[144:159]
	v_mfma_f32_32x32x16_bf16 a[160:175], v[128:131], v[36:39], a[160:175]
	v_mfma_f32_32x32x16_bf16 a[176:191], v[128:131], v[194:197], a[176:191]
	s_nop 7
	s_nop 3
	s_branch .LBB0_120

.LBB0_141:
	v_mov_b32_e32 v40, 0
	v_mov_b32_e32 v41, 0
	v_mov_b32_e32 v42, 0
	v_mov_b32_e32 v43, 0
	v_mov_b32_e32 v94, 0
	v_mov_b32_e32 v95, 0
	v_mov_b32_e32 v96, 0
	v_mov_b32_e32 v97, 0
	v_mov_b32_e32 v128, 0
	v_mov_b32_e32 v129, 0
	v_mov_b32_e32 v130, 0
	v_mov_b32_e32 v131, 0
	v_mov_b32_e32 v132, 0
	v_mov_b32_e32 v133, 0
	v_mov_b32_e32 v134, 0
	v_mov_b32_e32 v135, 0
	s_nop 1
.Lrs2_top:
	s_add_i32 s5, s4, 64
	s_min_u32 s6, s5, 0xae0
	s_lshl_b32 s78, s6, 1
	ds_read_b128 v[48:51], v82 offset:0
	ds_read_b128 v[44:47], v82 offset:0x800
	ds_read_b128 v[64:67], v80 offset:0
	v_mfma_f32_32x32x16_bf16 a[96:111], v[94:97], v[40:43], a[96:111]
	ds_read_b128 v[60:63], v80 offset:0x800
	v_mfma_f32_32x32x16_bf16 a[112:127], v[94:97], v[128:131], a[112:127]
	ds_read_b128 v[56:59], v80 offset:0x1000
	v_lshl_add_u64 v[106:107], v[68:69], 0, s[78:79]
	global_load_dwordx4 v[106:109], v[106:107], off
	v_mfma_f32_32x32x16_bf16 a[16:31], v[132:135], v[40:43], a[16:31]
	ds_read_b128 v[52:55], v80 offset:0x1800
	v_lshl_add_u64 v[110:111], v[72:73], 0, s[78:79]
	global_load_dwordx4 v[110:113], v[110:111], off
	v_mfma_f32_32x32x16_bf16 a[0:15], v[132:135], v[128:131], a[0:15]
	v_lshl_add_u64 v[114:115], v[74:75], 0, s[78:79]
	global_load_dwordx4 v[114:117], v[114:115], off
	s_waitcnt lgkmcnt(3)
	v_mfma_f32_32x32x16_bf16 a[32:47], v[64:67], v[48:51], a[32:47]
	ds_read_b128 v[40:43], v83 offset:0
	v_mfma_f32_32x32x16_bf16 a[48:63], v[64:67], v[44:47], a[48:63]
	v_lshl_add_u64 v[118:119], v[76:77], 0, s[78:79]
	global_load_dwordx4 v[118:121], v[118:119], off
	s_waitcnt lgkmcnt(3)
	v_mfma_f32_32x32x16_bf16 a[64:79], v[60:63], v[48:51], a[64:79]
	ds_read_b128 v[86:89], v83 offset:0x800
	v_mfma_f32_32x32x16_bf16 a[80:95], v[60:63], v[44:47], a[80:95]
	v_lshl_add_u64 v[122:123], v[70:71], 0, s[78:79]
	global_load_dwordx4 v[122:125], v[122:123], off
	s_waitcnt lgkmcnt(3)
	v_mfma_f32_32x32x16_bf16 a[96:111], v[56:59], v[48:51], a[96:111]
	ds_read_b128 v[90:93], v81 offset:0
	v_mfma_f32_32x32x16_bf16 a[112:127], v[56:59], v[44:47], a[112:127]
	v_lshl_add_u64 v[126:127], v[78:79], 0, s[78:79]
	global_load_dwordx4 v[140:143], v[126:127], off
	s_waitcnt vmcnt(11)
	ds_write_b128 v84, v[4:7] offset:0x8000
	s_waitcnt lgkmcnt(4)
	v_mfma_f32_32x32x16_bf16 a[16:31], v[52:55], v[48:51], a[16:31]
	ds_read_b128 v[94:97], v81 offset:0x800
	s_min_u32 s4, s4, 0xa80
	s_lshl_b32 s78, s4, 1
	s_waitcnt vmcnt(10)
	ds_write_b128 v84, v[8:11] offset:0x9000
	v_mfma_f32_32x32x16_bf16 a[0:15], v[52:55], v[44:47], a[0:15]
	ds_read_b128 v[98:101], v81 offset:0x1000
	s_add_i32 s6, s78, 0xc0
	s_mov_b32 s7, s79
	s_waitcnt vmcnt(9)
	ds_write_b128 v84, v[12:15] offset:0xa000
	s_waitcnt lgkmcnt(5)
	v_mfma_f32_32x32x16_bf16 a[32:47], v[90:93], v[40:43], a[32:47]
	ds_read_b128 v[102:105], v81 offset:0x1800
	s_add_i32 s3, s3, 2
	s_cmpk_lt_u32 s3, 0x56
	s_waitcnt vmcnt(8)
	ds_write_b128 v84, v[16:19] offset:0xb000
	v_mfma_f32_32x32x16_bf16 a[48:63], v[90:93], v[86:89], a[48:63]
	s_waitcnt vmcnt(7)
	ds_write_b128 v84, v[20:23] offset:0xc000
	s_waitcnt lgkmcnt(6)
	v_mfma_f32_32x32x16_bf16 a[64:79], v[94:97], v[40:43], a[64:79]
	s_waitcnt vmcnt(6)
	ds_write_b128 v84, v[24:27] offset:0xd000
	v_mfma_f32_32x32x16_bf16 a[80:95], v[94:97], v[86:89], a[80:95]
	v_lshl_add_u64 v[4:5], v[68:69], 0, s[78:79]
	v_lshl_add_u64 v[8:9], v[72:73], 0, s[6:7]
	v_lshl_add_u64 v[12:13], v[74:75], 0, s[6:7]
	v_lshl_add_u64 v[16:17], v[76:77], 0, s[6:7]
	v_lshl_add_u64 v[20:21], v[70:71], 0, s[78:79]
	v_lshl_add_u64 v[24:25], v[78:79], 0, s[6:7]
	s_waitcnt lgkmcnt(0)
	s_barrier
	ds_read_b128 v[44:47], v82 offset:0x8000
	ds_read_b128 v[48:51], v82 offset:0x8800
	ds_read_b128 v[52:55], v80 offset:0x8000
	v_mfma_f32_32x32x16_bf16 a[96:111], v[98:101], v[40:43], a[96:111]
	ds_read_b128 v[56:59], v80 offset:0x8800
	v_mfma_f32_32x32x16_bf16 a[112:127], v[98:101], v[86:89], a[112:127]
	ds_read_b128 v[60:63], v80 offset:0x9000
	global_load_dwordx4 v[4:7], v[4:5], off offset:192
	v_mfma_f32_32x32x16_bf16 a[16:31], v[102:105], v[40:43], a[16:31]
	ds_read_b128 v[64:67], v80 offset:0x9800
	global_load_dwordx4 v[8:11], v[8:9], off
	v_mfma_f32_32x32x16_bf16 a[0:15], v[102:105], v[86:89], a[0:15]
	global_load_dwordx4 v[12:15], v[12:13], off
	s_waitcnt lgkmcnt(3)
	v_mfma_f32_32x32x16_bf16 a[32:47], v[52:55], v[44:47], a[32:47]
	ds_read_b128 v[40:43], v83 offset:0x8000
	v_mfma_f32_32x32x16_bf16 a[48:63], v[52:55], v[48:51], a[48:63]
	global_load_dwordx4 v[16:19], v[16:17], off
	s_waitcnt lgkmcnt(3)
	v_mfma_f32_32x32x16_bf16 a[64:79], v[56:59], v[44:47], a[64:79]
	ds_read_b128 v[128:131], v83 offset:0x8800
	v_mfma_f32_32x32x16_bf16 a[80:95], v[56:59], v[48:51], a[80:95]
	global_load_dwordx4 v[20:23], v[20:21], off offset:192
	s_waitcnt lgkmcnt(3)
	v_mfma_f32_32x32x16_bf16 a[96:111], v[60:63], v[44:47], a[96:111]
	ds_read_b128 v[86:89], v81 offset:0x8000
	v_mfma_f32_32x32x16_bf16 a[112:127], v[60:63], v[48:51], a[112:127]
	global_load_dwordx4 v[24:27], v[24:25], off
	s_waitcnt vmcnt(11)
	ds_write_b128 v84, v[106:109] offset:0
	s_waitcnt lgkmcnt(4)
	v_mfma_f32_32x32x16_bf16 a[16:31], v[64:67], v[44:47], a[16:31]
	ds_read_b128 v[90:93], v81 offset:0x8800
	s_waitcnt vmcnt(10)
	ds_write_b128 v84, v[110:113] offset:0x1000
	v_mfma_f32_32x32x16_bf16 a[0:15], v[64:67], v[48:51], a[0:15]
	ds_read_b128 v[94:97], v81 offset:0x9000
	s_waitcnt vmcnt(9)
	ds_write_b128 v84, v[114:117] offset:0x2000
	s_waitcnt lgkmcnt(5)
	v_mfma_f32_32x32x16_bf16 a[32:47], v[86:89], v[40:43], a[32:47]
	ds_read_b128 v[132:135], v81 offset:0x9800
	s_waitcnt vmcnt(8)
	ds_write_b128 v84, v[118:121] offset:0x3000
	v_mfma_f32_32x32x16_bf16 a[48:63], v[86:89], v[128:131], a[48:63]
	s_waitcnt vmcnt(7)
	ds_write_b128 v84, v[122:125] offset:0x4000
	s_waitcnt lgkmcnt(6)
	v_mfma_f32_32x32x16_bf16 a[64:79], v[90:93], v[40:43], a[64:79]
	s_waitcnt vmcnt(6)
	ds_write_b128 v84, v[140:143] offset:0x5000
	v_mfma_f32_32x32x16_bf16 a[80:95], v[90:93], v[128:131], a[80:95]
	s_waitcnt lgkmcnt(0)
	s_barrier
	s_cbranch_scc0 .Lrs2_exit
	s_mov_b32 s4, s5
	s_branch .Lrs2_top
.Lrs2_exit:
	v_mfma_f32_32x32x16_bf16 a[96:111], v[94:97], v[40:43], a[96:111]
	v_mfma_f32_32x32x16_bf16 a[112:127], v[94:97], v[128:131], a[112:127]
	s_nop 7
	s_nop 3
	s_branch .LBB0_139

.LBB0_150:
	s_nop 1
	v_accvgpr_read_b32 v142, a80
	v_accvgpr_read_b32 v139, a83
	v_accvgpr_read_b32 v141, a81
	v_accvgpr_read_b32 v137, a84
	v_mul_f32_e32 v116, 0xbfb8aa3b, v142
	v_mfma_f32_32x32x16_bf16 a[16:31], v[132:135], v[112:115], a[16:31]
	v_mul_f32_e32 v112, 0xbfb8aa3b, v139
	v_accvgpr_read_b32 v140, a82
	v_accvgpr_read_b32 v136, a85
	v_exp_f32_e32 v142, v116
	v_mul_f32_e32 v116, 0xbfb8aa3b, v141
	v_exp_f32_e32 v215, v112
	v_mul_f32_e32 v112, 0xbfb8aa3b, v137
	v_accvgpr_read_b32 v127, a86
	v_exp_f32_e32 v214, v116
	v_mul_f32_e32 v116, 0xbfb8aa3b, v140
	v_exp_f32_e32 v220, v112
	v_mul_f32_e32 v112, 0xbfb8aa3b, v136
	v_accvgpr_read_b32 v126, a87
	v_exp_f32_e32 v143, v116
	v_exp_f32_e32 v116, v112
	v_mul_f32_e32 v112, 0xbfb8aa3b, v127
	v_accvgpr_read_b32 v125, a88
	v_exp_f32_e32 v221, v112
	v_mul_f32_e32 v112, 0xbfb8aa3b, v126
	v_accvgpr_read_b32 v124, a89
	v_exp_f32_e32 v117, v112
	v_mul_f32_e32 v112, 0xbfb8aa3b, v125
	v_accvgpr_read_b32 v123, a90
	v_exp_f32_e32 v126, v112
	v_mul_f32_e32 v112, 0xbfb8aa3b, v124
	v_accvgpr_read_b32 v122, a91
	v_exp_f32_e32 v124, v112
	v_mul_f32_e32 v112, 0xbfb8aa3b, v123
	v_accvgpr_read_b32 v121, a92
	v_accvgpr_read_b32 v119, a94
	v_mfma_f32_32x32x16_bf16 a[32:47], v[132:135], v[80:83], a[32:47]
	v_accvgpr_read_b32 v80, a80
	v_exp_f32_e32 v127, v112
	v_mul_f32_e32 v112, 0xbfb8aa3b, v122
	v_accvgpr_read_b32 v120, a93
	v_accvgpr_read_b32 v82, a82
	v_exp_f32_e32 v125, v112
	v_mul_f32_e32 v112, 0xbfb8aa3b, v121
	v_mul_f32_e32 v113, 0xbfb8aa3b, v119
	v_pk_add_f32 v[118:119], v[142:143], 1.0 op_sel_hi:[1,0]
	v_exp_f32_e32 v114, v112
	v_mul_f32_e32 v112, 0xbfb8aa3b, v120
	v_rcp_f32_e32 v121, v119
	v_accvgpr_read_b32 v83, a83
	v_accvgpr_read_b32 v81, a81
	v_accvgpr_read_b32 v90, a90
	v_rcp_f32_e32 v136, v118
	v_mul_f32_e32 v137, v82, v121
	v_accvgpr_read_b32 v138, a95
	v_pk_add_f32 v[120:121], v[214:215], 1.0 op_sel_hi:[1,0]
	v_rcp_f32_e32 v123, v121
	v_mul_f32_e32 v136, v80, v136
	v_exp_f32_e32 v115, v113
	v_rcp_f32_e32 v119, v120
	v_mul_f32_e32 v139, v83, v123
	v_pk_add_f32 v[82:83], v[126:127], 1.0 op_sel_hi:[1,0]
	v_rcp_f32_e32 v122, v83
	v_mul_f32_e32 v113, 0xbfb8aa3b, v138
	v_mul_f32_e32 v138, v81, v119
	v_accvgpr_read_b32 v88, a88
	v_rcp_f32_e32 v119, v82
	v_mul_f32_e32 v141, v90, v122
	v_accvgpr_read_b32 v91, a91
	v_pk_add_f32 v[80:81], v[124:125], 1.0 op_sel_hi:[1,0]
	v_rcp_f32_e32 v120, v81
	v_mul_f32_e32 v140, v88, v119
	v_accvgpr_read_b32 v89, a89
	v_accvgpr_read_b32 v86, a86
	v_rcp_f32_e32 v90, v80
	v_mul_f32_e32 v143, v91, v120
	v_pk_add_f32 v[82:83], v[220:221], 1.0 op_sel_hi:[1,0]
	v_rcp_f32_e32 v118, v83
	v_mul_f32_e32 v142, v89, v90
	v_accvgpr_read_b32 v84, a84
	v_rcp_f32_e32 v89, v82
	v_mul_f32_e32 v215, v86, v118
	v_accvgpr_read_b32 v87, a87
	v_pk_add_f32 v[80:81], v[116:117], 1.0 op_sel_hi:[1,0]
	v_rcp_f32_e32 v90, v81
	v_mul_f32_e32 v214, v84, v89
	v_accvgpr_read_b32 v85, a85
	v_accvgpr_read_b32 v94, a94
	v_rcp_f32_e32 v86, v80
	v_mul_f32_e32 v221, v87, v90
	v_pk_add_f32 v[82:83], v[114:115], 1.0 op_sel_hi:[1,0]
	v_rcp_f32_e32 v88, v83
	v_mul_f32_e32 v220, v85, v86
	v_accvgpr_read_b32 v92, a92
	v_rcp_f32_e32 v85, v82
	v_mul_f32_e32 v223, v94, v88
	v_exp_f32_e32 v112, v112
	v_exp_f32_e32 v113, v113
	v_accvgpr_read_b32 v95, a95
	v_pk_add_f32 v[80:81], v[112:113], 1.0 op_sel_hi:[1,0]
	v_accvgpr_read_b32 v96, a96
	v_rcp_f32_e32 v87, v81
	v_accvgpr_read_b32 v98, a98
	v_mfma_f32_32x32x16_bf16 a[0:15], v[132:135], v[128:131], a[0:15]
	v_or_b32_e32 v129, s2, v161
	v_accvgpr_read_b32 v97, a97
	v_or_b32_e32 v128, s1, v162
	v_add_u32_e32 v133, v163, v129
	v_mov_b32_e32 v162, v96
	v_mov_b32_e32 v163, v98
	v_accvgpr_read_b32 v99, a99
	v_mul_f32_e32 v222, v92, v85
	v_pk_mul_f32 v[136:137], v[162:163], v[136:137]
	v_mov_b32_e32 v98, v97
	v_pk_mul_f32 v[96:97], v[98:99], v[138:139]
	v_and_b32_sdwa v98, v137, v218 dst_sel:DWORD dst_unused:UNUSED_PAD src0_sel:WORD_1 src1_sel:DWORD
	v_and_b32_sdwa v99, v136, v218 dst_sel:DWORD dst_unused:UNUSED_PAD src0_sel:WORD_1 src1_sel:DWORD
	v_add3_u32 v99, v136, v99, s80
	v_add3_u32 v98, v137, v98, s80
	v_and_b32_sdwa v136, v97, v218 dst_sel:DWORD dst_unused:UNUSED_PAD src0_sel:WORD_1 src1_sel:DWORD
	v_and_b32_sdwa v137, v96, v218 dst_sel:DWORD dst_unused:UNUSED_PAD src0_sel:WORD_1 src1_sel:DWORD
	v_accvgpr_read_b32 v93, a93
	v_add3_u32 v97, v97, v136, s80
	v_add3_u32 v96, v96, v137, s80
	v_accvgpr_read_b32 v104, a104
	v_accvgpr_read_b32 v106, a106
	v_and_b32_e32 v97, 0xffff0000, v97
	v_and_b32_e32 v96, 0xffff0000, v96
	v_accvgpr_read_b32 v105, a105
	v_rcp_f32_e32 v85, v80
	v_or_b32_sdwa v136, v97, v98 dst_sel:DWORD dst_unused:UNUSED_PAD src0_sel:DWORD src1_sel:WORD_1
	v_or_b32_sdwa v137, v96, v99 dst_sel:DWORD dst_unused:UNUSED_PAD src0_sel:DWORD src1_sel:WORD_1
	v_mov_b32_e32 v96, v104
	v_mov_b32_e32 v97, v106
	v_accvgpr_read_b32 v107, a107
	v_pk_mul_f32 v[96:97], v[96:97], v[140:141]
	v_mov_b32_e32 v106, v105
	v_pk_mul_f32 v[98:99], v[106:107], v[142:143]
	v_and_b32_sdwa v104, v97, v218 dst_sel:DWORD dst_unused:UNUSED_PAD src0_sel:WORD_1 src1_sel:DWORD
	v_and_b32_sdwa v105, v96, v218 dst_sel:DWORD dst_unused:UNUSED_PAD src0_sel:WORD_1 src1_sel:DWORD
	v_accvgpr_read_b32 v100, a100
	v_accvgpr_read_b32 v102, a102
	v_add3_u32 v96, v96, v105, s80
	v_add3_u32 v97, v97, v104, s80
	v_and_b32_sdwa v104, v99, v218 dst_sel:DWORD dst_unused:UNUSED_PAD src0_sel:WORD_1 src1_sel:DWORD
	v_and_b32_sdwa v105, v98, v218 dst_sel:DWORD dst_unused:UNUSED_PAD src0_sel:WORD_1 src1_sel:DWORD
	v_accvgpr_read_b32 v101, a101
	v_mul_f32_e32 v227, v95, v87
	v_add3_u32 v99, v99, v104, s80
	v_add3_u32 v98, v98, v105, s80
	v_mov_b32_e32 v104, v100
	v_mov_b32_e32 v105, v102
	v_accvgpr_read_b32 v103, a103
	v_pk_mul_f32 v[104:105], v[104:105], v[214:215]
	v_mov_b32_e32 v102, v101
	v_pk_mul_f32 v[100:101], v[102:103], v[220:221]
	v_and_b32_sdwa v102, v105, v218 dst_sel:DWORD dst_unused:UNUSED_PAD src0_sel:WORD_1 src1_sel:DWORD
	v_and_b32_sdwa v103, v104, v218 dst_sel:DWORD dst_unused:UNUSED_PAD src0_sel:WORD_1 src1_sel:DWORD
	v_add3_u32 v103, v104, v103, s80
	v_add3_u32 v102, v105, v102, s80
	v_and_b32_sdwa v104, v101, v218 dst_sel:DWORD dst_unused:UNUSED_PAD src0_sel:WORD_1 src1_sel:DWORD
	v_and_b32_sdwa v105, v100, v218 dst_sel:DWORD dst_unused:UNUSED_PAD src0_sel:WORD_1 src1_sel:DWORD
	v_add3_u32 v101, v101, v104, s80
	v_add3_u32 v100, v100, v105, s80
	v_accvgpr_read_b32 v108, a108
	v_accvgpr_read_b32 v110, a110
	v_and_b32_e32 v101, 0xffff0000, v101
	v_and_b32_e32 v100, 0xffff0000, v100
	v_accvgpr_read_b32 v109, a109
	v_or_b32_sdwa v104, v101, v102 dst_sel:DWORD dst_unused:UNUSED_PAD src0_sel:DWORD src1_sel:WORD_1
	v_or_b32_sdwa v105, v100, v103 dst_sel:DWORD dst_unused:UNUSED_PAD src0_sel:DWORD src1_sel:WORD_1
	v_mov_b32_e32 v100, v108
	v_mov_b32_e32 v101, v110
	v_accvgpr_read_b32 v111, a111
	v_mul_f32_e32 v226, v93, v85
	v_cmp_lt_i32_e32 vcc, v211, v210
	v_readlane_b32 s2, v253, 61
	v_pk_mul_f32 v[100:101], v[100:101], v[222:223]
	v_mov_b32_e32 v110, v109
	v_cndmask_b32_e32 v129, v209, v211, vcc
	v_readlane_b32 s3, v253, 62
	v_pk_mul_f32 v[102:103], v[110:111], v[226:227]
	v_and_b32_sdwa v108, v101, v218 dst_sel:DWORD dst_unused:UNUSED_PAD src0_sel:WORD_1 src1_sel:DWORD
	v_and_b32_sdwa v109, v100, v218 dst_sel:DWORD dst_unused:UNUSED_PAD src0_sel:WORD_1 src1_sel:DWORD
	v_lshlrev_b32_e32 v132, 2, v129
	v_ashrrev_i32_e32 v130, 1, v128
	v_mov_b64_e32 v[128:129], s[2:3]
	s_movk_i32 s1, 0x1600
	v_and_b32_e32 v98, 0xffff0000, v98
	v_add3_u32 v100, v100, v109, s80
	v_add3_u32 v101, v101, v108, s80
	v_and_b32_sdwa v108, v103, v218 dst_sel:DWORD dst_unused:UNUSED_PAD src0_sel:WORD_1 src1_sel:DWORD
	v_and_b32_sdwa v109, v102, v218 dst_sel:DWORD dst_unused:UNUSED_PAD src0_sel:WORD_1 src1_sel:DWORD
	v_mad_i64_i32 v[134:135], s[2:3], v133, s1, v[128:129]
	v_and_b32_e32 v99, 0xffff0000, v99
	v_or_b32_sdwa v107, v98, v96 dst_sel:DWORD dst_unused:UNUSED_PAD src0_sel:DWORD src1_sel:WORD_1
	v_and_b32_e32 v96, 63, v160
	v_add3_u32 v103, v103, v108, s80
	v_add3_u32 v102, v102, v109, s80
	v_or_b32_sdwa v106, v99, v97 dst_sel:DWORD dst_unused:UNUSED_PAD src0_sel:DWORD src1_sel:WORD_1
	v_cmp_gt_u32_e64 s[2:3], 32, v96
	v_and_b32_e32 v103, 0xffff0000, v103
	v_and_b32_e32 v102, 0xffff0000, v102
	v_cndmask_b32_e64 v96, v137, v107, s[2:3]
	v_cndmask_b32_e64 v97, v136, v106, s[2:3]
	v_or_b32_sdwa v103, v103, v101 dst_sel:DWORD dst_unused:UNUSED_PAD src0_sel:DWORD src1_sel:WORD_1
	v_or_b32_sdwa v102, v102, v100 dst_sel:DWORD dst_unused:UNUSED_PAD src0_sel:DWORD src1_sel:WORD_1
	ds_bpermute_b32 v138, v132, v97
	ds_bpermute_b32 v139, v132, v96
	v_cndmask_b32_e64 v100, v105, v102, s[2:3]
	v_cndmask_b32_e64 v101, v104, v103, s[2:3]
	ds_bpermute_b32 v108, v132, v101
	ds_bpermute_b32 v109, v132, v100
	v_ashrrev_i32_e32 v131, 31, v130
	v_lshlrev_b64 v[130:131], 1, v[130:131]
	v_lshl_add_u64 v[96:97], v[134:135], 0, v[130:131]
	v_and_b32_e32 v192, 32, v160
	v_lshl_add_u64 v[96:97], v[96:97], 0, v[192:193]
	s_waitcnt lgkmcnt(3)
	v_cndmask_b32_e64 v99, v138, v136, s[2:3]
	s_waitcnt lgkmcnt(2)
	v_cndmask_b32_e64 v98, v139, v137, s[2:3]
	v_cndmask_b32_e64 v101, v106, v138, s[2:3]
	v_cndmask_b32_e64 v100, v107, v139, s[2:3]
	v_accvgpr_read_b32 v225, a48
	global_store_dwordx4 v[96:97], v[98:101], off
	v_accvgpr_read_b32 v224, a49
	v_accvgpr_read_b32 v252, a50
	s_waitcnt lgkmcnt(1)
	v_cndmask_b32_e64 v99, v108, v104, s[2:3]
	s_waitcnt lgkmcnt(0)
	v_cndmask_b32_e64 v98, v109, v105, s[2:3]
	v_cndmask_b32_e64 v101, v103, v108, s[2:3]
	v_cndmask_b32_e64 v100, v102, v109, s[2:3]
	global_store_dwordx4 v[96:97], v[98:101], off offset:16
	v_accvgpr_read_b32 v127, a63
	v_accvgpr_read_b32 v114, a50
	v_mul_f32_e32 v98, 0xbfb8aa3b, v225
	v_exp_f32_e32 v104, v98
	v_mul_f32_e32 v98, 0xbfb8aa3b, v224
	v_exp_f32_e32 v106, v98
	v_mul_f32_e32 v98, 0xbfb8aa3b, v252
	v_exp_f32_e32 v105, v98
	v_accvgpr_read_b32 v112, a48
	v_accvgpr_read_b32 v251, a51
	v_mul_f32_e32 v98, 0xbfb8aa3b, v251
	v_pk_add_f32 v[104:105], v[104:105], 1.0 op_sel_hi:[1,0]
	v_exp_f32_e32 v107, v98
	v_rcp_f32_e32 v139, v105
	v_accvgpr_read_b32 v115, a51
	v_pk_add_f32 v[106:107], v[106:107], 1.0 op_sel_hi:[1,0]
	v_accvgpr_read_b32 v64, a112
	v_rcp_f32_e32 v142, v104
	v_mul_f32_e32 v105, v114, v139
	v_accvgpr_read_b32 v66, a114
	v_mul_f32_e32 v104, v112, v142
	v_rcp_f32_e32 v114, v107
	v_mov_b32_e32 v138, v64
	v_mov_b32_e32 v139, v66
	v_pk_mul_f32 v[104:105], v[138:139], v[104:105]
	v_accvgpr_read_b32 v113, a49
	v_rcp_f32_e32 v138, v106
	v_accvgpr_read_b32 v250, a52
	v_accvgpr_read_b32 v249, a53
	v_mul_f32_e32 v98, 0xbfb8aa3b, v250
	v_mul_f32_e32 v107, v115, v114
	v_accvgpr_read_b32 v248, a54
	v_exp_f32_e32 v108, v98
	v_mul_f32_e32 v98, 0xbfb8aa3b, v249
	v_accvgpr_read_b32 v247, a55
	v_exp_f32_e32 v102, v98
	v_mul_f32_e32 v98, 0xbfb8aa3b, v248
	v_accvgpr_read_b32 v246, a56
	v_exp_f32_e32 v109, v98
	v_mul_f32_e32 v98, 0xbfb8aa3b, v247
	v_accvgpr_read_b32 v245, a57
	v_exp_f32_e32 v103, v98
	v_mul_f32_e32 v98, 0xbfb8aa3b, v246
	v_accvgpr_read_b32 v244, a58
	v_exp_f32_e32 v110, v98
	v_mul_f32_e32 v98, 0xbfb8aa3b, v245
	v_accvgpr_read_b32 v65, a113
	v_exp_f32_e32 v134, v98
	v_mul_f32_e32 v98, 0xbfb8aa3b, v244
	v_accvgpr_read_b32 v67, a115
	v_exp_f32_e32 v111, v98
	v_mul_f32_e32 v106, v113, v138
	v_mov_b32_e32 v66, v65
	v_pk_mul_f32 v[64:65], v[66:67], v[106:107]
	v_and_b32_sdwa v67, v104, v218 dst_sel:DWORD dst_unused:UNUSED_PAD src0_sel:WORD_1 src1_sel:DWORD
	v_and_b32_sdwa v66, v105, v218 dst_sel:DWORD dst_unused:UNUSED_PAD src0_sel:WORD_1 src1_sel:DWORD
	v_add3_u32 v67, v104, v67, s80
	v_and_b32_sdwa v104, v65, v218 dst_sel:DWORD dst_unused:UNUSED_PAD src0_sel:WORD_1 src1_sel:DWORD
	v_add3_u32 v66, v105, v66, s80
	v_and_b32_sdwa v105, v64, v218 dst_sel:DWORD dst_unused:UNUSED_PAD src0_sel:WORD_1 src1_sel:DWORD
	v_add3_u32 v65, v65, v104, s80
	v_accvgpr_read_b32 v122, a58
	v_add3_u32 v104, v64, v105, s80
	v_and_b32_e32 v105, 0xffff0000, v65
	v_pk_add_f32 v[64:65], v[110:111], 1.0 op_sel_hi:[1,0]
	v_or_b32_sdwa v110, v105, v66 dst_sel:DWORD dst_unused:UNUSED_PAD src0_sel:DWORD src1_sel:WORD_1
	v_rcp_f32_e32 v107, v65
	v_and_b32_e32 v104, 0xffff0000, v104
	v_or_b32_sdwa v111, v104, v67 dst_sel:DWORD dst_unused:UNUSED_PAD src0_sel:DWORD src1_sel:WORD_1
	v_accvgpr_read_b32 v120, a56
	v_rcp_f32_e32 v105, v64
	v_mul_f32_e32 v65, v122, v107
	v_accvgpr_read_b32 v243, a59
	v_mul_f32_e32 v98, 0xbfb8aa3b, v243
	v_exp_f32_e32 v135, v98
	v_accvgpr_read_b32 v123, a59
	v_mul_f32_e32 v64, v120, v105
	v_pk_add_f32 v[66:67], v[134:135], 1.0 op_sel_hi:[1,0]
	v_accvgpr_read_b32 v72, a120
	v_rcp_f32_e32 v107, v67
	v_mov_b32_e32 v104, v72
	v_accvgpr_read_b32 v74, a122
	v_mov_b32_e32 v105, v74
	v_accvgpr_read_b32 v121, a57
	v_pk_mul_f32 v[64:65], v[104:105], v[64:65]
	v_rcp_f32_e32 v105, v66
	v_mul_f32_e32 v67, v123, v107
	v_accvgpr_read_b32 v73, a121
	v_accvgpr_read_b32 v75, a123
	v_mul_f32_e32 v66, v121, v105
	v_mov_b32_e32 v74, v73
	v_pk_mul_f32 v[66:67], v[74:75], v[66:67]
	v_and_b32_sdwa v72, v65, v218 dst_sel:DWORD dst_unused:UNUSED_PAD src0_sel:WORD_1 src1_sel:DWORD
	v_and_b32_sdwa v73, v64, v218 dst_sel:DWORD dst_unused:UNUSED_PAD src0_sel:WORD_1 src1_sel:DWORD
	v_add3_u32 v64, v64, v73, s80
	v_add3_u32 v65, v65, v72, s80
	v_and_b32_sdwa v72, v67, v218 dst_sel:DWORD dst_unused:UNUSED_PAD src0_sel:WORD_1 src1_sel:DWORD
	v_and_b32_sdwa v73, v66, v218 dst_sel:DWORD dst_unused:UNUSED_PAD src0_sel:WORD_1 src1_sel:DWORD
	v_accvgpr_read_b32 v118, a54
	v_add3_u32 v67, v67, v72, s80
	v_add3_u32 v66, v66, v73, s80
	v_pk_add_f32 v[72:73], v[108:109], 1.0 op_sel_hi:[1,0]
	v_and_b32_e32 v67, 0xffff0000, v67
	v_or_b32_sdwa v104, v67, v65 dst_sel:DWORD dst_unused:UNUSED_PAD src0_sel:DWORD src1_sel:WORD_1
	v_rcp_f32_e32 v75, v73
	v_cndmask_b32_e64 v65, v110, v104, s[2:3]
	ds_bpermute_b32 v107, v132, v65
	v_accvgpr_read_b32 v116, a52
	s_waitcnt lgkmcnt(0)
	v_cndmask_b32_e64 v67, v107, v110, s[2:3]
	v_rcp_f32_e32 v110, v72
	v_mul_f32_e32 v73, v118, v75
	v_accvgpr_read_b32 v119, a55
	v_mul_f32_e32 v72, v116, v110
	v_pk_add_f32 v[74:75], v[102:103], 1.0 op_sel_hi:[1,0]
	v_accvgpr_read_b32 v68, a116
	v_rcp_f32_e32 v109, v75
	v_mov_b32_e32 v102, v68
	v_accvgpr_read_b32 v70, a118
	v_mov_b32_e32 v103, v70
	v_accvgpr_read_b32 v117, a53
	v_pk_mul_f32 v[72:73], v[102:103], v[72:73]
	v_rcp_f32_e32 v103, v74
	v_mul_f32_e32 v75, v119, v109
	v_accvgpr_read_b32 v242, a60
	v_accvgpr_read_b32 v240, a62
	v_accvgpr_read_b32 v69, a117
	v_mul_f32_e32 v98, 0xbfb8aa3b, v242
	v_mul_f32_e32 v99, 0xbfb8aa3b, v240
	v_accvgpr_read_b32 v71, a119
	v_exp_f32_e32 v100, v98
	v_exp_f32_e32 v101, v99
	v_mul_f32_e32 v74, v117, v103
	v_mov_b32_e32 v70, v69
	v_pk_mul_f32 v[68:69], v[70:71], v[74:75]
	v_and_b32_sdwa v71, v72, v218 dst_sel:DWORD dst_unused:UNUSED_PAD src0_sel:WORD_1 src1_sel:DWORD
	v_and_b32_sdwa v70, v73, v218 dst_sel:DWORD dst_unused:UNUSED_PAD src0_sel:WORD_1 src1_sel:DWORD
	v_add3_u32 v71, v72, v71, s80
	v_and_b32_sdwa v72, v69, v218 dst_sel:DWORD dst_unused:UNUSED_PAD src0_sel:WORD_1 src1_sel:DWORD
	v_add3_u32 v70, v73, v70, s80
	v_and_b32_sdwa v73, v68, v218 dst_sel:DWORD dst_unused:UNUSED_PAD src0_sel:WORD_1 src1_sel:DWORD
	v_add3_u32 v69, v69, v72, s80
	v_accvgpr_read_b32 v126, a62
	v_add3_u32 v72, v68, v73, s80
	v_and_b32_e32 v73, 0xffff0000, v69
	v_pk_add_f32 v[68:69], v[100:101], 1.0 op_sel_hi:[1,0]
	v_or_b32_sdwa v100, v73, v70 dst_sel:DWORD dst_unused:UNUSED_PAD src0_sel:DWORD src1_sel:WORD_1
	v_rcp_f32_e32 v75, v69
	v_and_b32_e32 v72, 0xffff0000, v72
	v_or_b32_sdwa v101, v72, v71 dst_sel:DWORD dst_unused:UNUSED_PAD src0_sel:DWORD src1_sel:WORD_1
	v_accvgpr_read_b32 v124, a60
	v_rcp_f32_e32 v73, v68
	v_mul_f32_e32 v69, v126, v75
	v_accvgpr_read_b32 v241, a61
	v_accvgpr_read_b32 v239, a63
	v_mul_f32_e32 v98, 0xbfb8aa3b, v241
	v_mul_f32_e32 v99, 0xbfb8aa3b, v239
	v_exp_f32_e32 v98, v98
	v_exp_f32_e32 v99, v99
	v_mul_f32_e32 v68, v124, v73
	v_pk_add_f32 v[70:71], v[98:99], 1.0 op_sel_hi:[1,0]
	v_accvgpr_read_b32 v76, a124
	v_rcp_f32_e32 v75, v71
	v_accvgpr_read_b32 v78, a126
	v_mov_b32_e32 v72, v76
	v_mov_b32_e32 v73, v78
	v_pk_mul_f32 v[68:69], v[72:73], v[68:69]
	v_accvgpr_read_b32 v125, a61
	v_rcp_f32_e32 v76, v70
	v_mul_f32_e32 v71, v127, v75
	v_accvgpr_read_b32 v77, a125
	v_accvgpr_read_b32 v79, a127
	v_mul_f32_e32 v70, v125, v76
	v_mov_b32_e32 v78, v77
	v_pk_mul_f32 v[70:71], v[78:79], v[70:71]
	v_and_b32_sdwa v72, v69, v218 dst_sel:DWORD dst_unused:UNUSED_PAD src0_sel:WORD_1 src1_sel:DWORD
	v_and_b32_sdwa v73, v68, v218 dst_sel:DWORD dst_unused:UNUSED_PAD src0_sel:WORD_1 src1_sel:DWORD
	v_add3_u32 v68, v68, v73, s80
	v_add3_u32 v69, v69, v72, s80
	v_and_b32_sdwa v72, v71, v218 dst_sel:DWORD dst_unused:UNUSED_PAD src0_sel:WORD_1 src1_sel:DWORD
	v_and_b32_sdwa v73, v70, v218 dst_sel:DWORD dst_unused:UNUSED_PAD src0_sel:WORD_1 src1_sel:DWORD
	v_and_b32_e32 v66, 0xffff0000, v66
	v_add3_u32 v71, v71, v72, s80
	v_add3_u32 v70, v70, v73, s80
	v_or_b32_sdwa v105, v66, v64 dst_sel:DWORD dst_unused:UNUSED_PAD src0_sel:DWORD src1_sel:WORD_1
	v_and_b32_e32 v71, 0xffff0000, v71
	v_and_b32_e32 v70, 0xffff0000, v70
	v_cndmask_b32_e64 v64, v111, v105, s[2:3]
	v_or_b32_sdwa v71, v71, v69 dst_sel:DWORD dst_unused:UNUSED_PAD src0_sel:DWORD src1_sel:WORD_1
	v_or_b32_sdwa v70, v70, v68 dst_sel:DWORD dst_unused:UNUSED_PAD src0_sel:DWORD src1_sel:WORD_1
	ds_bpermute_b32 v106, v132, v64
	v_cndmask_b32_e64 v68, v101, v70, s[2:3]
	v_cndmask_b32_e64 v69, v100, v71, s[2:3]
	ds_bpermute_b32 v72, v132, v69
	ds_bpermute_b32 v73, v132, v68
	v_add_u32_e32 v136, 32, v133
	v_mad_i64_i32 v[136:137], s[4:5], v136, s1, v[128:129]
	v_lshl_add_u64 v[136:137], v[136:137], 0, v[130:131]
	v_lshl_add_u64 v[64:65], v[136:137], 0, v[192:193]
	s_waitcnt lgkmcnt(2)
	v_cndmask_b32_e64 v66, v106, v111, s[2:3]
	v_cndmask_b32_e64 v69, v104, v107, s[2:3]
	v_cndmask_b32_e64 v68, v105, v106, s[2:3]
	v_accvgpr_read_b32 v237, a65
	global_store_dwordx4 v[64:65], v[66:69], off
	v_accvgpr_read_b32 v238, a64
	v_accvgpr_read_b32 v236, a66
	s_waitcnt lgkmcnt(1)
	v_cndmask_b32_e64 v67, v72, v100, s[2:3]
	s_waitcnt lgkmcnt(0)
	v_cndmask_b32_e64 v66, v73, v101, s[2:3]
	v_cndmask_b32_e64 v69, v71, v72, s[2:3]
	v_cndmask_b32_e64 v68, v70, v73, s[2:3]
	global_store_dwordx4 v[64:65], v[66:69], off offset:16
	v_accvgpr_read_b32 v95, a79
	v_accvgpr_read_b32 v82, a66
	v_mul_f32_e32 v67, 0xbfb8aa3b, v237
	v_mul_f32_e32 v66, 0xbfb8aa3b, v238
	v_exp_f32_e32 v74, v67
	v_mul_f32_e32 v67, 0xbfb8aa3b, v236
	v_exp_f32_e32 v66, v66
	v_exp_f32_e32 v67, v67
	v_accvgpr_read_b32 v80, a64
	v_accvgpr_read_b32 v235, a67
	v_mul_f32_e32 v68, 0xbfb8aa3b, v235
	v_pk_add_f32 v[66:67], v[66:67], 1.0 op_sel_hi:[1,0]
	v_exp_f32_e32 v75, v68
	v_rcp_f32_e32 v103, v67
	v_accvgpr_read_b32 v83, a67
	v_pk_add_f32 v[74:75], v[74:75], 1.0 op_sel_hi:[1,0]
	v_accvgpr_read_b32 v48, a128
	v_rcp_f32_e32 v106, v66
	v_mul_f32_e32 v67, v82, v103
	v_accvgpr_read_b32 v50, a130
	v_mul_f32_e32 v66, v80, v106
	v_rcp_f32_e32 v82, v75
	v_mov_b32_e32 v102, v48
	v_mov_b32_e32 v103, v50
	v_pk_mul_f32 v[66:67], v[102:103], v[66:67]
	v_accvgpr_read_b32 v81, a65
	v_rcp_f32_e32 v102, v74
	v_accvgpr_read_b32 v234, a68
	v_accvgpr_read_b32 v233, a69
	v_mul_f32_e32 v68, 0xbfb8aa3b, v234
	v_mul_f32_e32 v75, v83, v82
	v_accvgpr_read_b32 v232, a70
	v_exp_f32_e32 v76, v68
	v_mul_f32_e32 v68, 0xbfb8aa3b, v233
	v_accvgpr_read_b32 v231, a71
	v_exp_f32_e32 v72, v68
	v_mul_f32_e32 v68, 0xbfb8aa3b, v232
	v_accvgpr_read_b32 v207, a72
	v_exp_f32_e32 v77, v68
	v_mul_f32_e32 v68, 0xbfb8aa3b, v231
	v_accvgpr_read_b32 v205, a73
	v_exp_f32_e32 v73, v68
	v_mul_f32_e32 v68, 0xbfb8aa3b, v207
	v_accvgpr_read_b32 v204, a74
	v_exp_f32_e32 v78, v68
	v_mul_f32_e32 v68, 0xbfb8aa3b, v205
	v_accvgpr_read_b32 v49, a129
	v_exp_f32_e32 v98, v68
	v_mul_f32_e32 v68, 0xbfb8aa3b, v204
	v_accvgpr_read_b32 v51, a131
	v_exp_f32_e32 v79, v68
	v_mul_f32_e32 v74, v81, v102
	v_mov_b32_e32 v50, v49
	v_pk_mul_f32 v[48:49], v[50:51], v[74:75]
	v_and_b32_sdwa v51, v66, v218 dst_sel:DWORD dst_unused:UNUSED_PAD src0_sel:WORD_1 src1_sel:DWORD
	v_and_b32_sdwa v50, v67, v218 dst_sel:DWORD dst_unused:UNUSED_PAD src0_sel:WORD_1 src1_sel:DWORD
	v_add3_u32 v51, v66, v51, s80
	v_and_b32_sdwa v66, v49, v218 dst_sel:DWORD dst_unused:UNUSED_PAD src0_sel:WORD_1 src1_sel:DWORD
	v_add3_u32 v50, v67, v50, s80
	v_and_b32_sdwa v67, v48, v218 dst_sel:DWORD dst_unused:UNUSED_PAD src0_sel:WORD_1 src1_sel:DWORD
	v_add3_u32 v49, v49, v66, s80
	v_accvgpr_read_b32 v90, a74
	v_add3_u32 v66, v48, v67, s80
	v_and_b32_e32 v67, 0xffff0000, v49
	v_pk_add_f32 v[48:49], v[78:79], 1.0 op_sel_hi:[1,0]
	v_or_b32_sdwa v78, v67, v50 dst_sel:DWORD dst_unused:UNUSED_PAD src0_sel:DWORD src1_sel:WORD_1
	v_rcp_f32_e32 v75, v49
	v_and_b32_e32 v66, 0xffff0000, v66
	v_or_b32_sdwa v79, v66, v51 dst_sel:DWORD dst_unused:UNUSED_PAD src0_sel:DWORD src1_sel:WORD_1
	v_accvgpr_read_b32 v88, a72
	v_rcp_f32_e32 v67, v48
	v_mul_f32_e32 v49, v90, v75
	v_accvgpr_read_b32 v203, a75
	v_mul_f32_e32 v68, 0xbfb8aa3b, v203
	v_exp_f32_e32 v99, v68
	v_accvgpr_read_b32 v91, a75
	v_mul_f32_e32 v48, v88, v67
	v_pk_add_f32 v[50:51], v[98:99], 1.0 op_sel_hi:[1,0]
	v_accvgpr_read_b32 v56, a136
	v_rcp_f32_e32 v75, v51
	v_mov_b32_e32 v66, v56
	v_accvgpr_read_b32 v58, a138
	v_mov_b32_e32 v67, v58
	v_accvgpr_read_b32 v89, a73
	v_pk_mul_f32 v[48:49], v[66:67], v[48:49]
	v_rcp_f32_e32 v67, v50
	v_mul_f32_e32 v51, v91, v75
	v_accvgpr_read_b32 v57, a137
	v_accvgpr_read_b32 v59, a139
	v_mul_f32_e32 v50, v89, v67
	v_mov_b32_e32 v58, v57
	v_pk_mul_f32 v[50:51], v[58:59], v[50:51]
	v_and_b32_sdwa v56, v49, v218 dst_sel:DWORD dst_unused:UNUSED_PAD src0_sel:WORD_1 src1_sel:DWORD
	v_and_b32_sdwa v57, v48, v218 dst_sel:DWORD dst_unused:UNUSED_PAD src0_sel:WORD_1 src1_sel:DWORD
	v_add3_u32 v48, v48, v57, s80
	v_add3_u32 v49, v49, v56, s80
	v_and_b32_sdwa v56, v51, v218 dst_sel:DWORD dst_unused:UNUSED_PAD src0_sel:WORD_1 src1_sel:DWORD
	v_and_b32_sdwa v57, v50, v218 dst_sel:DWORD dst_unused:UNUSED_PAD src0_sel:WORD_1 src1_sel:DWORD
	v_add3_u32 v51, v51, v56, s80
	v_add3_u32 v50, v50, v57, s80
	v_and_b32_e32 v51, 0xffff0000, v51
	v_and_b32_e32 v50, 0xffff0000, v50
	v_accvgpr_read_b32 v86, a70
	v_or_b32_sdwa v74, v51, v49 dst_sel:DWORD dst_unused:UNUSED_PAD src0_sel:DWORD src1_sel:WORD_1
	v_or_b32_sdwa v75, v50, v48 dst_sel:DWORD dst_unused:UNUSED_PAD src0_sel:DWORD src1_sel:WORD_1
	v_pk_add_f32 v[50:51], v[76:77], 1.0 op_sel_hi:[1,0]
	v_accvgpr_read_b32 v84, a68
	v_rcp_f32_e32 v57, v51
	v_accvgpr_read_b32 v87, a71
	v_accvgpr_read_b32 v52, a132
	v_accvgpr_read_b32 v54, a134
	v_rcp_f32_e32 v76, v50
	v_mul_f32_e32 v51, v86, v57
	v_accvgpr_read_b32 v85, a69
	v_mul_f32_e32 v50, v84, v76
	v_pk_add_f32 v[56:57], v[72:73], 1.0 op_sel_hi:[1,0]
	v_mov_b32_e32 v58, v52
	v_rcp_f32_e32 v73, v57
	v_mov_b32_e32 v59, v54
	v_pk_mul_f32 v[50:51], v[58:59], v[50:51]
	v_accvgpr_read_b32 v201, a76
	v_rcp_f32_e32 v59, v56
	v_mul_f32_e32 v57, v87, v73
	v_accvgpr_read_b32 v199, a78
	v_accvgpr_read_b32 v53, a133
	v_mul_f32_e32 v68, 0xbfb8aa3b, v201
	v_mul_f32_e32 v69, 0xbfb8aa3b, v199
	v_accvgpr_read_b32 v55, a135
	v_exp_f32_e32 v70, v68
	v_exp_f32_e32 v71, v69
	v_mul_f32_e32 v56, v85, v59
	v_mov_b32_e32 v54, v53
	v_pk_mul_f32 v[52:53], v[54:55], v[56:57]
	v_and_b32_sdwa v55, v50, v218 dst_sel:DWORD dst_unused:UNUSED_PAD src0_sel:WORD_1 src1_sel:DWORD
	v_and_b32_sdwa v54, v51, v218 dst_sel:DWORD dst_unused:UNUSED_PAD src0_sel:WORD_1 src1_sel:DWORD
	v_add3_u32 v55, v50, v55, s80
	v_and_b32_sdwa v50, v53, v218 dst_sel:DWORD dst_unused:UNUSED_PAD src0_sel:WORD_1 src1_sel:DWORD
	v_add3_u32 v54, v51, v54, s80
	v_and_b32_sdwa v51, v52, v218 dst_sel:DWORD dst_unused:UNUSED_PAD src0_sel:WORD_1 src1_sel:DWORD
	v_add3_u32 v50, v53, v50, s80
	v_accvgpr_read_b32 v94, a78
	v_add3_u32 v52, v52, v51, s80
	v_and_b32_e32 v53, 0xffff0000, v50
	v_pk_add_f32 v[50:51], v[70:71], 1.0 op_sel_hi:[1,0]
	v_and_b32_e32 v52, 0xffff0000, v52
	v_rcp_f32_e32 v57, v51
	v_or_b32_sdwa v59, v52, v55 dst_sel:DWORD dst_unused:UNUSED_PAD src0_sel:DWORD src1_sel:WORD_1
	v_or_b32_sdwa v58, v53, v54 dst_sel:DWORD dst_unused:UNUSED_PAD src0_sel:DWORD src1_sel:WORD_1
	v_accvgpr_read_b32 v92, a76
	v_rcp_f32_e32 v55, v50
	v_mul_f32_e32 v51, v94, v57
	v_accvgpr_read_b32 v200, a77
	v_accvgpr_read_b32 v198, a79
	v_mul_f32_e32 v68, 0xbfb8aa3b, v200
	v_mul_f32_e32 v69, 0xbfb8aa3b, v198
	v_exp_f32_e32 v68, v68
	v_exp_f32_e32 v69, v69
	v_mul_f32_e32 v50, v92, v55
	v_pk_add_f32 v[52:53], v[68:69], 1.0 op_sel_hi:[1,0]
	v_accvgpr_read_b32 v60, a140
	v_rcp_f32_e32 v57, v53
	v_accvgpr_read_b32 v62, a142
	v_mov_b32_e32 v54, v60
	v_mov_b32_e32 v55, v62
	v_pk_mul_f32 v[50:51], v[54:55], v[50:51]
	v_accvgpr_read_b32 v93, a77
	v_rcp_f32_e32 v60, v52
	v_mul_f32_e32 v53, v95, v57
	v_accvgpr_read_b32 v61, a141
	v_accvgpr_read_b32 v63, a143
	v_mul_f32_e32 v52, v93, v60
	v_mov_b32_e32 v62, v61
	v_cndmask_b32_e64 v49, v78, v74, s[2:3]
	v_pk_mul_f32 v[52:53], v[62:63], v[52:53]
	v_and_b32_sdwa v54, v51, v218 dst_sel:DWORD dst_unused:UNUSED_PAD src0_sel:WORD_1 src1_sel:DWORD
	ds_bpermute_b32 v81, v132, v49
	v_add3_u32 v51, v51, v54, s80
	v_and_b32_sdwa v54, v53, v218 dst_sel:DWORD dst_unused:UNUSED_PAD src0_sel:WORD_1 src1_sel:DWORD
	v_cndmask_b32_e64 v48, v79, v75, s[2:3]
	v_and_b32_sdwa v55, v50, v218 dst_sel:DWORD dst_unused:UNUSED_PAD src0_sel:WORD_1 src1_sel:DWORD
	v_add3_u32 v53, v53, v54, s80
	ds_bpermute_b32 v80, v132, v48
	v_add3_u32 v50, v50, v55, s80
	v_and_b32_sdwa v55, v52, v218 dst_sel:DWORD dst_unused:UNUSED_PAD src0_sel:WORD_1 src1_sel:DWORD
	v_and_b32_e32 v53, 0xffff0000, v53
	v_accvgpr_read_b32 v197, a144
	v_add3_u32 v52, v52, v55, s80
	v_or_b32_sdwa v53, v53, v51 dst_sel:DWORD dst_unused:UNUSED_PAD src0_sel:DWORD src1_sel:WORD_1
	v_accvgpr_read_b32 v196, a145
	v_and_b32_e32 v52, 0xffff0000, v52
	v_cndmask_b32_e64 v51, v58, v53, s[2:3]
	v_mul_f32_e32 v68, 0xbfb8aa3b, v197
	v_accvgpr_read_b32 v195, a146
	v_or_b32_sdwa v52, v52, v50 dst_sel:DWORD dst_unused:UNUSED_PAD src0_sel:DWORD src1_sel:WORD_1
	ds_bpermute_b32 v54, v132, v51
	s_waitcnt lgkmcnt(2)
	v_cndmask_b32_e64 v51, v74, v81, s[2:3]
	v_exp_f32_e32 v74, v68
	v_mul_f32_e32 v68, 0xbfb8aa3b, v196
	v_cndmask_b32_e64 v50, v59, v52, s[2:3]
	v_exp_f32_e32 v76, v68
	v_mul_f32_e32 v68, 0xbfb8aa3b, v195
	ds_bpermute_b32 v55, v132, v50
	s_waitcnt lgkmcnt(2)
	v_cndmask_b32_e64 v50, v75, v80, s[2:3]
	v_exp_f32_e32 v75, v68
	v_accvgpr_read_b32 v32, a144
	v_accvgpr_read_b32 v34, a146
	v_accvgpr_read_b32 v194, a147
	v_pk_add_f32 v[74:75], v[74:75], 1.0 op_sel_hi:[1,0]
	v_mul_f32_e32 v68, 0xbfb8aa3b, v194
	v_rcp_f32_e32 v84, v75
	v_exp_f32_e32 v77, v68
	v_add_u32_e32 v100, 64, v133
	v_accvgpr_read_b32 v35, a147
	v_rcp_f32_e32 v88, v74
	v_mul_f32_e32 v75, v34, v84
	v_mad_i64_i32 v[100:101], s[4:5], v100, s1, v[128:129]
	v_pk_add_f32 v[76:77], v[76:77], 1.0 op_sel_hi:[1,0]
	v_lshl_add_u64 v[100:101], v[100:101], 0, v[130:131]
	v_mul_f32_e32 v74, v32, v88
	v_lshl_add_u64 v[66:67], v[100:101], 0, v[192:193]
	v_cndmask_b32_e64 v49, v81, v78, s[2:3]
	v_cndmask_b32_e64 v48, v80, v79, s[2:3]
	v_rcp_f32_e32 v34, v77
	global_store_dwordx4 v[66:67], v[48:51], off
	v_accvgpr_read_b32 v33, a145
	v_accvgpr_read_b32 v191, a148
	s_waitcnt lgkmcnt(1)
	v_cndmask_b32_e64 v49, v54, v58, s[2:3]
	s_waitcnt lgkmcnt(0)
	v_cndmask_b32_e64 v48, v55, v59, s[2:3]
	v_cndmask_b32_e64 v51, v53, v54, s[2:3]
	v_cndmask_b32_e64 v50, v52, v55, s[2:3]
	global_store_dwordx4 v[66:67], v[48:51], off offset:16
	v_accvgpr_read_b32 v63, a47
	v_accvgpr_read_b32 v190, a149
	v_accvgpr_read_b32 v48, a32
	v_mov_b32_e32 v84, v48
	v_accvgpr_read_b32 v50, a34
	v_mov_b32_e32 v85, v50
	v_rcp_f32_e32 v69, v76
	v_mul_f32_e32 v68, 0xbfb8aa3b, v191
	v_mul_f32_e32 v35, v35, v34
	v_accvgpr_read_b32 v189, a150
	v_exp_f32_e32 v78, v68
	v_mul_f32_e32 v68, 0xbfb8aa3b, v190
	v_accvgpr_read_b32 v188, a151
	v_exp_f32_e32 v72, v68
	v_mul_f32_e32 v68, 0xbfb8aa3b, v189
	v_accvgpr_read_b32 v187, a152
	v_exp_f32_e32 v79, v68
	v_mul_f32_e32 v68, 0xbfb8aa3b, v188
	v_accvgpr_read_b32 v186, a153
	v_exp_f32_e32 v73, v68
	v_mul_f32_e32 v68, 0xbfb8aa3b, v187
	v_accvgpr_read_b32 v185, a154
	v_exp_f32_e32 v80, v68
	v_mul_f32_e32 v68, 0xbfb8aa3b, v186
	v_accvgpr_read_b32 v49, a33
	v_exp_f32_e32 v82, v68
	v_mul_f32_e32 v68, 0xbfb8aa3b, v185
	v_accvgpr_read_b32 v51, a35
	v_exp_f32_e32 v81, v68
	v_mul_f32_e32 v34, v33, v69
	v_mov_b32_e32 v50, v49
	v_pk_mul_f32 v[32:33], v[34:35], v[50:51]
	v_accvgpr_read_b32 v42, a154
	v_and_b32_sdwa v48, v33, v218 dst_sel:DWORD dst_unused:UNUSED_PAD src0_sel:WORD_1 src1_sel:DWORD
	v_and_b32_sdwa v49, v32, v218 dst_sel:DWORD dst_unused:UNUSED_PAD src0_sel:WORD_1 src1_sel:DWORD
	v_add3_u32 v33, v33, v48, s80
	v_add3_u32 v48, v32, v49, s80
	v_and_b32_e32 v49, 0xffff0000, v33
	v_pk_add_f32 v[32:33], v[80:81], 1.0 op_sel_hi:[1,0]
	v_pk_mul_f32 v[74:75], v[74:75], v[84:85]
	v_rcp_f32_e32 v51, v33
	v_and_b32_sdwa v34, v75, v218 dst_sel:DWORD dst_unused:UNUSED_PAD src0_sel:WORD_1 src1_sel:DWORD
	v_and_b32_sdwa v35, v74, v218 dst_sel:DWORD dst_unused:UNUSED_PAD src0_sel:WORD_1 src1_sel:DWORD
	v_add3_u32 v34, v75, v34, s80
	v_add3_u32 v35, v74, v35, s80
	v_or_b32_sdwa v74, v49, v34 dst_sel:DWORD dst_unused:UNUSED_PAD src0_sel:DWORD src1_sel:WORD_1
	v_and_b32_e32 v48, 0xffff0000, v48
	v_or_b32_sdwa v75, v48, v35 dst_sel:DWORD dst_unused:UNUSED_PAD src0_sel:DWORD src1_sel:WORD_1
	v_accvgpr_read_b32 v40, a152
	v_rcp_f32_e32 v49, v32
	v_mul_f32_e32 v33, v42, v51
	v_accvgpr_read_b32 v184, a155
	v_mul_f32_e32 v68, 0xbfb8aa3b, v184
	v_exp_f32_e32 v83, v68
	v_accvgpr_read_b32 v43, a155
	v_mul_f32_e32 v32, v40, v49
	v_pk_add_f32 v[34:35], v[82:83], 1.0 op_sel_hi:[1,0]
	v_accvgpr_read_b32 v58, a42
	v_rcp_f32_e32 v42, v35
	v_accvgpr_read_b32 v56, a40
	v_mov_b32_e32 v48, v56
	v_mov_b32_e32 v49, v58
	v_pk_mul_f32 v[32:33], v[32:33], v[48:49]
	v_accvgpr_read_b32 v41, a153
	v_rcp_f32_e32 v50, v34
	v_mul_f32_e32 v35, v43, v42
	v_accvgpr_read_b32 v57, a41
	v_accvgpr_read_b32 v59, a43
	v_mul_f32_e32 v34, v41, v50
	v_mov_b32_e32 v58, v57
	v_pk_mul_f32 v[34:35], v[34:35], v[58:59]
	v_and_b32_sdwa v40, v33, v218 dst_sel:DWORD dst_unused:UNUSED_PAD src0_sel:WORD_1 src1_sel:DWORD
	v_and_b32_sdwa v41, v32, v218 dst_sel:DWORD dst_unused:UNUSED_PAD src0_sel:WORD_1 src1_sel:DWORD
	v_add3_u32 v32, v32, v41, s80
	v_add3_u32 v33, v33, v40, s80
	v_and_b32_sdwa v40, v35, v218 dst_sel:DWORD dst_unused:UNUSED_PAD src0_sel:WORD_1 src1_sel:DWORD
	v_and_b32_sdwa v41, v34, v218 dst_sel:DWORD dst_unused:UNUSED_PAD src0_sel:WORD_1 src1_sel:DWORD
	v_add3_u32 v35, v35, v40, s80
	v_add3_u32 v34, v34, v41, s80
	v_and_b32_e32 v35, 0xffff0000, v35
	v_and_b32_e32 v34, 0xffff0000, v34
	v_accvgpr_read_b32 v38, a150
	v_or_b32_sdwa v48, v35, v33 dst_sel:DWORD dst_unused:UNUSED_PAD src0_sel:DWORD src1_sel:WORD_1
	v_or_b32_sdwa v49, v34, v32 dst_sel:DWORD dst_unused:UNUSED_PAD src0_sel:DWORD src1_sel:WORD_1
	v_pk_add_f32 v[34:35], v[78:79], 1.0 op_sel_hi:[1,0]
	v_accvgpr_read_b32 v36, a148
	v_rcp_f32_e32 v41, v35
	v_accvgpr_read_b32 v39, a151
	v_accvgpr_read_b32 v54, a38
	v_accvgpr_read_b32 v52, a36
	v_rcp_f32_e32 v56, v34
	v_mul_f32_e32 v35, v38, v41
	v_mov_b32_e32 v43, v54
	v_pk_add_f32 v[40:41], v[72:73], 1.0 op_sel_hi:[1,0]
	v_mul_f32_e32 v34, v36, v56
	v_rcp_f32_e32 v38, v41
	v_mov_b32_e32 v42, v52
	v_pk_mul_f32 v[34:35], v[34:35], v[42:43]
	v_accvgpr_read_b32 v37, a149
	v_rcp_f32_e32 v52, v40
	v_mul_f32_e32 v39, v39, v38
	v_accvgpr_read_b32 v183, a156
	v_accvgpr_read_b32 v181, a158
	v_accvgpr_read_b32 v53, a37
	v_mul_f32_e32 v68, 0xbfb8aa3b, v183
	v_mul_f32_e32 v71, 0xbfb8aa3b, v181
	v_accvgpr_read_b32 v55, a39
	v_exp_f32_e32 v70, v68
	v_exp_f32_e32 v71, v71
	v_mul_f32_e32 v38, v37, v52
	v_mov_b32_e32 v54, v53
	v_pk_mul_f32 v[36:37], v[38:39], v[54:55]
	v_and_b32_sdwa v39, v34, v218 dst_sel:DWORD dst_unused:UNUSED_PAD src0_sel:WORD_1 src1_sel:DWORD
	v_and_b32_sdwa v38, v35, v218 dst_sel:DWORD dst_unused:UNUSED_PAD src0_sel:WORD_1 src1_sel:DWORD
	v_add3_u32 v39, v34, v39, s80
	v_and_b32_sdwa v34, v37, v218 dst_sel:DWORD dst_unused:UNUSED_PAD src0_sel:WORD_1 src1_sel:DWORD
	v_add3_u32 v38, v35, v38, s80
	v_and_b32_sdwa v35, v36, v218 dst_sel:DWORD dst_unused:UNUSED_PAD src0_sel:WORD_1 src1_sel:DWORD
	v_add3_u32 v34, v37, v34, s80
	v_accvgpr_read_b32 v46, a158
	v_add3_u32 v36, v36, v35, s80
	v_and_b32_e32 v37, 0xffff0000, v34
	v_pk_add_f32 v[34:35], v[70:71], 1.0 op_sel_hi:[1,0]
	v_and_b32_e32 v36, 0xffff0000, v36
	v_rcp_f32_e32 v41, v35
	v_or_b32_sdwa v43, v36, v39 dst_sel:DWORD dst_unused:UNUSED_PAD src0_sel:DWORD src1_sel:WORD_1
	v_or_b32_sdwa v42, v37, v38 dst_sel:DWORD dst_unused:UNUSED_PAD src0_sel:DWORD src1_sel:WORD_1
	v_accvgpr_read_b32 v44, a156
	v_rcp_f32_e32 v39, v34
	v_mul_f32_e32 v35, v46, v41
	v_accvgpr_read_b32 v182, a157
	v_accvgpr_read_b32 v180, a159
	v_mul_f32_e32 v68, 0xbfb8aa3b, v182
	v_mul_f32_e32 v86, 0xbfb8aa3b, v180
	v_exp_f32_e32 v68, v68
	v_exp_f32_e32 v69, v86
	v_accvgpr_read_b32 v47, a159
	v_mul_f32_e32 v34, v44, v39
	v_pk_add_f32 v[36:37], v[68:69], 1.0 op_sel_hi:[1,0]
	v_accvgpr_read_b32 v62, a46
	v_rcp_f32_e32 v41, v37
	v_accvgpr_read_b32 v60, a44
	v_mov_b32_e32 v38, v60
	v_mov_b32_e32 v39, v62
	v_pk_mul_f32 v[34:35], v[34:35], v[38:39]
	v_accvgpr_read_b32 v45, a157
	v_rcp_f32_e32 v44, v36
	v_mul_f32_e32 v37, v47, v41
	v_accvgpr_read_b32 v61, a45
	v_mul_f32_e32 v36, v45, v44
	v_mov_b32_e32 v62, v61
	v_cndmask_b32_e64 v33, v74, v48, s[2:3]
	v_pk_mul_f32 v[36:37], v[36:37], v[62:63]
	v_and_b32_sdwa v38, v35, v218 dst_sel:DWORD dst_unused:UNUSED_PAD src0_sel:WORD_1 src1_sel:DWORD
	ds_bpermute_b32 v51, v132, v33
	v_add3_u32 v35, v35, v38, s80
	v_and_b32_sdwa v38, v37, v218 dst_sel:DWORD dst_unused:UNUSED_PAD src0_sel:WORD_1 src1_sel:DWORD
	v_add3_u32 v37, v37, v38, s80
	v_and_b32_e32 v37, 0xffff0000, v37
	v_or_b32_sdwa v37, v37, v35 dst_sel:DWORD dst_unused:UNUSED_PAD src0_sel:DWORD src1_sel:WORD_1
	v_accvgpr_read_b32 v179, a160
	v_cndmask_b32_e64 v35, v42, v37, s[2:3]
	v_accvgpr_read_b32 v178, a161
	ds_bpermute_b32 v38, v132, v35
	s_waitcnt lgkmcnt(1)
	v_cndmask_b32_e64 v35, v48, v51, s[2:3]
	v_mul_f32_e32 v48, 0xbfb8aa3b, v179
	v_accvgpr_read_b32 v177, a162
	v_exp_f32_e32 v54, v48
	v_mul_f32_e32 v48, 0xbfb8aa3b, v178
	v_cndmask_b32_e64 v32, v75, v49, s[2:3]
	v_and_b32_sdwa v39, v34, v218 dst_sel:DWORD dst_unused:UNUSED_PAD src0_sel:WORD_1 src1_sel:DWORD
	v_exp_f32_e32 v56, v48
	v_mul_f32_e32 v48, 0xbfb8aa3b, v177
	ds_bpermute_b32 v50, v132, v32
	v_add3_u32 v34, v34, v39, s80
	v_and_b32_sdwa v39, v36, v218 dst_sel:DWORD dst_unused:UNUSED_PAD src0_sel:WORD_1 src1_sel:DWORD
	v_exp_f32_e32 v55, v48
	v_add3_u32 v36, v36, v39, s80
	v_and_b32_e32 v36, 0xffff0000, v36
	s_waitcnt vmcnt(9)
	v_accvgpr_read_b32 v16, a160
	v_or_b32_sdwa v36, v36, v34 dst_sel:DWORD dst_unused:UNUSED_PAD src0_sel:DWORD src1_sel:WORD_1
	v_accvgpr_read_b32 v18, a162
	v_cndmask_b32_e64 v34, v43, v36, s[2:3]
	v_pk_add_f32 v[54:55], v[54:55], 1.0 op_sel_hi:[1,0]
	ds_bpermute_b32 v39, v132, v34
	s_waitcnt lgkmcnt(1)
	v_cndmask_b32_e64 v34, v49, v50, s[2:3]
	v_rcp_f32_e32 v68, v55
	v_accvgpr_read_b32 v176, a163
	v_mul_f32_e32 v48, 0xbfb8aa3b, v176
	v_exp_f32_e32 v57, v48
	v_rcp_f32_e32 v72, v54
	v_mul_f32_e32 v55, v18, v68
	v_accvgpr_read_b32 v19, a163
	v_pk_add_f32 v[56:57], v[56:57], 1.0 op_sel_hi:[1,0]
	v_mul_f32_e32 v54, v16, v72
	v_cndmask_b32_e64 v33, v51, v74, s[2:3]
	v_cndmask_b32_e64 v32, v50, v75, s[2:3]
	v_rcp_f32_e32 v18, v57
	global_store_dwordx4 v[96:97], v[32:35], off offset:64
	v_accvgpr_read_b32 v17, a161
	v_accvgpr_read_b32 v175, a164
	v_cndmask_b32_e64 v33, v38, v42, s[2:3]
	s_waitcnt lgkmcnt(0)
	v_cndmask_b32_e64 v32, v39, v43, s[2:3]
	v_cndmask_b32_e64 v35, v37, v38, s[2:3]
	v_cndmask_b32_e64 v34, v36, v39, s[2:3]
	global_store_dwordx4 v[96:97], v[32:35], off offset:80
	v_accvgpr_read_b32 v47, a31
	v_accvgpr_read_b32 v174, a165
	v_accvgpr_read_b32 v32, a16
	v_mov_b32_e32 v68, v32
	v_accvgpr_read_b32 v34, a18
	v_mov_b32_e32 v69, v34
	v_rcp_f32_e32 v49, v56
	v_mul_f32_e32 v48, 0xbfb8aa3b, v175
	v_mul_f32_e32 v19, v19, v18
	v_accvgpr_read_b32 v173, a166
	v_exp_f32_e32 v58, v48
	v_mul_f32_e32 v48, 0xbfb8aa3b, v174
	v_accvgpr_read_b32 v172, a167
	v_exp_f32_e32 v52, v48
	v_mul_f32_e32 v48, 0xbfb8aa3b, v173
	v_accvgpr_read_b32 v171, a168
	v_exp_f32_e32 v59, v48
	v_mul_f32_e32 v48, 0xbfb8aa3b, v172
	v_accvgpr_read_b32 v170, a169
	v_exp_f32_e32 v53, v48
	v_mul_f32_e32 v48, 0xbfb8aa3b, v171
	v_accvgpr_read_b32 v169, a170
	v_exp_f32_e32 v60, v48
	v_mul_f32_e32 v48, 0xbfb8aa3b, v170
	v_accvgpr_read_b32 v33, a17
	v_exp_f32_e32 v62, v48
	v_mul_f32_e32 v48, 0xbfb8aa3b, v169
	v_accvgpr_read_b32 v35, a19
	v_exp_f32_e32 v61, v48
	v_mul_f32_e32 v18, v17, v49
	v_mov_b32_e32 v34, v33
	v_pk_mul_f32 v[16:17], v[18:19], v[34:35]
	v_accvgpr_read_b32 v26, a170
	v_and_b32_sdwa v32, v17, v218 dst_sel:DWORD dst_unused:UNUSED_PAD src0_sel:WORD_1 src1_sel:DWORD
	v_and_b32_sdwa v33, v16, v218 dst_sel:DWORD dst_unused:UNUSED_PAD src0_sel:WORD_1 src1_sel:DWORD
	v_add3_u32 v17, v17, v32, s80
	v_add3_u32 v32, v16, v33, s80
	v_and_b32_e32 v33, 0xffff0000, v17
	v_pk_add_f32 v[16:17], v[60:61], 1.0 op_sel_hi:[1,0]
	v_pk_mul_f32 v[54:55], v[54:55], v[68:69]
	v_rcp_f32_e32 v35, v17
	v_and_b32_sdwa v18, v55, v218 dst_sel:DWORD dst_unused:UNUSED_PAD src0_sel:WORD_1 src1_sel:DWORD
	v_and_b32_sdwa v19, v54, v218 dst_sel:DWORD dst_unused:UNUSED_PAD src0_sel:WORD_1 src1_sel:DWORD
	v_add3_u32 v18, v55, v18, s80
	v_add3_u32 v19, v54, v19, s80
	v_or_b32_sdwa v54, v33, v18 dst_sel:DWORD dst_unused:UNUSED_PAD src0_sel:DWORD src1_sel:WORD_1
	v_and_b32_e32 v32, 0xffff0000, v32
	v_or_b32_sdwa v55, v32, v19 dst_sel:DWORD dst_unused:UNUSED_PAD src0_sel:DWORD src1_sel:WORD_1
	v_accvgpr_read_b32 v24, a168
	v_rcp_f32_e32 v33, v16
	v_mul_f32_e32 v17, v26, v35
	v_accvgpr_read_b32 v168, a171
	v_mul_f32_e32 v48, 0xbfb8aa3b, v168
	v_exp_f32_e32 v63, v48
	v_accvgpr_read_b32 v27, a171
	v_mul_f32_e32 v16, v24, v33
	v_pk_add_f32 v[18:19], v[62:63], 1.0 op_sel_hi:[1,0]
	v_accvgpr_read_b32 v42, a26
	v_rcp_f32_e32 v26, v19
	v_accvgpr_read_b32 v40, a24
	v_mov_b32_e32 v32, v40
	v_mov_b32_e32 v33, v42
	v_pk_mul_f32 v[16:17], v[16:17], v[32:33]
	v_accvgpr_read_b32 v25, a169
	v_rcp_f32_e32 v34, v18
	v_mul_f32_e32 v19, v27, v26
	v_accvgpr_read_b32 v41, a25
	v_accvgpr_read_b32 v43, a27
	v_mul_f32_e32 v18, v25, v34
	v_mov_b32_e32 v42, v41
	v_pk_mul_f32 v[18:19], v[18:19], v[42:43]
	v_and_b32_sdwa v24, v17, v218 dst_sel:DWORD dst_unused:UNUSED_PAD src0_sel:WORD_1 src1_sel:DWORD
	v_and_b32_sdwa v25, v16, v218 dst_sel:DWORD dst_unused:UNUSED_PAD src0_sel:WORD_1 src1_sel:DWORD
	v_add3_u32 v16, v16, v25, s80
	v_add3_u32 v17, v17, v24, s80
	v_and_b32_sdwa v24, v19, v218 dst_sel:DWORD dst_unused:UNUSED_PAD src0_sel:WORD_1 src1_sel:DWORD
	v_and_b32_sdwa v25, v18, v218 dst_sel:DWORD dst_unused:UNUSED_PAD src0_sel:WORD_1 src1_sel:DWORD
	v_add3_u32 v19, v19, v24, s80
	v_add3_u32 v18, v18, v25, s80
	v_and_b32_e32 v19, 0xffff0000, v19
	v_and_b32_e32 v18, 0xffff0000, v18
	v_accvgpr_read_b32 v22, a166
	v_or_b32_sdwa v32, v19, v17 dst_sel:DWORD dst_unused:UNUSED_PAD src0_sel:DWORD src1_sel:WORD_1
	v_or_b32_sdwa v33, v18, v16 dst_sel:DWORD dst_unused:UNUSED_PAD src0_sel:DWORD src1_sel:WORD_1
	v_pk_add_f32 v[18:19], v[58:59], 1.0 op_sel_hi:[1,0]
	v_accvgpr_read_b32 v20, a164
	v_rcp_f32_e32 v25, v19
	v_accvgpr_read_b32 v23, a167
	v_accvgpr_read_b32 v38, a22
	v_accvgpr_read_b32 v36, a20
	v_rcp_f32_e32 v40, v18
	v_mul_f32_e32 v19, v22, v25
	v_mov_b32_e32 v27, v38
	v_pk_add_f32 v[24:25], v[52:53], 1.0 op_sel_hi:[1,0]
	v_mul_f32_e32 v18, v20, v40
	v_rcp_f32_e32 v22, v25
	v_mov_b32_e32 v26, v36
	v_pk_mul_f32 v[18:19], v[18:19], v[26:27]
	v_accvgpr_read_b32 v21, a165
	v_rcp_f32_e32 v36, v24
	v_mul_f32_e32 v23, v23, v22
	v_accvgpr_read_b32 v167, a172
	v_accvgpr_read_b32 v165, a174
	v_accvgpr_read_b32 v37, a21
	v_mul_f32_e32 v48, 0xbfb8aa3b, v167
	v_mul_f32_e32 v51, 0xbfb8aa3b, v165
	v_accvgpr_read_b32 v39, a23
	v_exp_f32_e32 v50, v48
	v_exp_f32_e32 v51, v51
	v_mul_f32_e32 v22, v21, v36
	v_mov_b32_e32 v38, v37
	v_pk_mul_f32 v[20:21], v[22:23], v[38:39]
	v_and_b32_sdwa v23, v18, v218 dst_sel:DWORD dst_unused:UNUSED_PAD src0_sel:WORD_1 src1_sel:DWORD
	v_and_b32_sdwa v22, v19, v218 dst_sel:DWORD dst_unused:UNUSED_PAD src0_sel:WORD_1 src1_sel:DWORD
	v_add3_u32 v23, v18, v23, s80
	v_and_b32_sdwa v18, v21, v218 dst_sel:DWORD dst_unused:UNUSED_PAD src0_sel:WORD_1 src1_sel:DWORD
	v_add3_u32 v22, v19, v22, s80
	v_and_b32_sdwa v19, v20, v218 dst_sel:DWORD dst_unused:UNUSED_PAD src0_sel:WORD_1 src1_sel:DWORD
	v_add3_u32 v18, v21, v18, s80
	v_accvgpr_read_b32 v30, a174
	v_add3_u32 v20, v20, v19, s80
	v_and_b32_e32 v21, 0xffff0000, v18
	v_pk_add_f32 v[18:19], v[50:51], 1.0 op_sel_hi:[1,0]
	v_and_b32_e32 v20, 0xffff0000, v20
	v_rcp_f32_e32 v25, v19
	v_or_b32_sdwa v27, v20, v23 dst_sel:DWORD dst_unused:UNUSED_PAD src0_sel:DWORD src1_sel:WORD_1
	v_or_b32_sdwa v26, v21, v22 dst_sel:DWORD dst_unused:UNUSED_PAD src0_sel:DWORD src1_sel:WORD_1
	v_accvgpr_read_b32 v28, a172
	v_rcp_f32_e32 v23, v18
	v_mul_f32_e32 v19, v30, v25
	v_accvgpr_read_b32 v166, a173
	v_accvgpr_read_b32 v164, a175
	v_mul_f32_e32 v48, 0xbfb8aa3b, v166
	v_mul_f32_e32 v70, 0xbfb8aa3b, v164
	v_exp_f32_e32 v48, v48
	v_exp_f32_e32 v49, v70
	v_accvgpr_read_b32 v31, a175
	v_mul_f32_e32 v18, v28, v23
	v_pk_add_f32 v[20:21], v[48:49], 1.0 op_sel_hi:[1,0]
	v_accvgpr_read_b32 v46, a30
	v_rcp_f32_e32 v25, v21
	v_accvgpr_read_b32 v44, a28
	v_mov_b32_e32 v22, v44
	v_mov_b32_e32 v23, v46
	v_pk_mul_f32 v[18:19], v[18:19], v[22:23]
	v_accvgpr_read_b32 v29, a173
	v_rcp_f32_e32 v28, v20
	v_mul_f32_e32 v21, v31, v25
	v_accvgpr_read_b32 v45, a29
	v_mul_f32_e32 v20, v29, v28
	v_mov_b32_e32 v46, v45
	v_cndmask_b32_e64 v17, v54, v32, s[2:3]
	v_pk_mul_f32 v[20:21], v[20:21], v[46:47]
	v_and_b32_sdwa v22, v19, v218 dst_sel:DWORD dst_unused:UNUSED_PAD src0_sel:WORD_1 src1_sel:DWORD
	ds_bpermute_b32 v35, v132, v17
	v_add3_u32 v19, v19, v22, s80
	v_and_b32_sdwa v22, v21, v218 dst_sel:DWORD dst_unused:UNUSED_PAD src0_sel:WORD_1 src1_sel:DWORD
	v_add3_u32 v21, v21, v22, s80
	v_and_b32_e32 v21, 0xffff0000, v21
	v_or_b32_sdwa v21, v21, v19 dst_sel:DWORD dst_unused:UNUSED_PAD src0_sel:DWORD src1_sel:WORD_1
	v_accvgpr_read_b32 v159, a176
	v_cndmask_b32_e64 v19, v26, v21, s[2:3]
	v_accvgpr_read_b32 v158, a177
	ds_bpermute_b32 v22, v132, v19
	s_waitcnt lgkmcnt(1)
	v_cndmask_b32_e64 v19, v32, v35, s[2:3]
	v_mul_f32_e32 v32, 0xbfb8aa3b, v159
	v_accvgpr_read_b32 v157, a178
	v_exp_f32_e32 v38, v32
	v_mul_f32_e32 v32, 0xbfb8aa3b, v158
	v_cndmask_b32_e64 v16, v55, v33, s[2:3]
	v_and_b32_sdwa v23, v18, v218 dst_sel:DWORD dst_unused:UNUSED_PAD src0_sel:WORD_1 src1_sel:DWORD
	v_exp_f32_e32 v40, v32
	v_mul_f32_e32 v32, 0xbfb8aa3b, v157
	ds_bpermute_b32 v34, v132, v16
	v_add3_u32 v18, v18, v23, s80
	v_and_b32_sdwa v23, v20, v218 dst_sel:DWORD dst_unused:UNUSED_PAD src0_sel:WORD_1 src1_sel:DWORD
	v_exp_f32_e32 v39, v32
	v_add3_u32 v20, v20, v23, s80
	v_and_b32_e32 v20, 0xffff0000, v20
	s_waitcnt vmcnt(8)
	v_accvgpr_read_b32 v0, a176
	v_or_b32_sdwa v20, v20, v18 dst_sel:DWORD dst_unused:UNUSED_PAD src0_sel:DWORD src1_sel:WORD_1
	v_accvgpr_read_b32 v2, a178
	v_cndmask_b32_e64 v18, v27, v20, s[2:3]
	v_pk_add_f32 v[38:39], v[38:39], 1.0 op_sel_hi:[1,0]
	ds_bpermute_b32 v23, v132, v18
	s_waitcnt lgkmcnt(1)
	v_cndmask_b32_e64 v18, v33, v34, s[2:3]
	v_rcp_f32_e32 v48, v39
	v_accvgpr_read_b32 v156, a179
	v_mul_f32_e32 v32, 0xbfb8aa3b, v156
	v_exp_f32_e32 v41, v32
	v_rcp_f32_e32 v52, v38
	v_mul_f32_e32 v39, v2, v48
	v_accvgpr_read_b32 v3, a179
	v_pk_add_f32 v[40:41], v[40:41], 1.0 op_sel_hi:[1,0]
	v_mul_f32_e32 v38, v0, v52
	v_cndmask_b32_e64 v17, v35, v54, s[2:3]
	v_cndmask_b32_e64 v16, v34, v55, s[2:3]
	v_rcp_f32_e32 v2, v41
	global_store_dwordx4 v[64:65], v[16:19], off offset:64
	v_accvgpr_read_b32 v1, a177
	v_accvgpr_read_b32 v155, a180
	v_cndmask_b32_e64 v17, v22, v26, s[2:3]
	s_waitcnt lgkmcnt(0)
	v_cndmask_b32_e64 v16, v23, v27, s[2:3]
	v_cndmask_b32_e64 v19, v21, v22, s[2:3]
	v_cndmask_b32_e64 v18, v20, v23, s[2:3]
	global_store_dwordx4 v[64:65], v[16:19], off offset:80
	v_accvgpr_read_b32 v31, a15
	v_accvgpr_read_b32 v154, a181
	v_accvgpr_read_b32 v16, a0
	v_mov_b32_e32 v48, v16
	v_accvgpr_read_b32 v18, a2
	v_mov_b32_e32 v49, v18
	v_rcp_f32_e32 v33, v40
	v_mul_f32_e32 v32, 0xbfb8aa3b, v155
	v_mul_f32_e32 v3, v3, v2
	v_accvgpr_read_b32 v153, a182
	v_exp_f32_e32 v42, v32
	v_mul_f32_e32 v32, 0xbfb8aa3b, v154
	v_accvgpr_read_b32 v152, a183
	v_exp_f32_e32 v36, v32
	v_mul_f32_e32 v32, 0xbfb8aa3b, v153
	v_accvgpr_read_b32 v151, a184
	v_exp_f32_e32 v43, v32
	v_mul_f32_e32 v32, 0xbfb8aa3b, v152
	v_accvgpr_read_b32 v150, a185
	v_exp_f32_e32 v37, v32
	v_mul_f32_e32 v32, 0xbfb8aa3b, v151
	v_accvgpr_read_b32 v149, a186
	v_exp_f32_e32 v44, v32
	v_mul_f32_e32 v32, 0xbfb8aa3b, v150
	v_accvgpr_read_b32 v17, a1
	v_exp_f32_e32 v46, v32
	v_mul_f32_e32 v32, 0xbfb8aa3b, v149
	v_accvgpr_read_b32 v19, a3
	v_exp_f32_e32 v45, v32
	v_mul_f32_e32 v2, v1, v33
	v_mov_b32_e32 v18, v17
	v_pk_mul_f32 v[0:1], v[2:3], v[18:19]
	v_accvgpr_read_b32 v10, a186
	v_and_b32_sdwa v16, v1, v218 dst_sel:DWORD dst_unused:UNUSED_PAD src0_sel:WORD_1 src1_sel:DWORD
	v_and_b32_sdwa v17, v0, v218 dst_sel:DWORD dst_unused:UNUSED_PAD src0_sel:WORD_1 src1_sel:DWORD
	v_add3_u32 v1, v1, v16, s80
	v_add3_u32 v16, v0, v17, s80
	v_and_b32_e32 v17, 0xffff0000, v1
	v_pk_add_f32 v[0:1], v[44:45], 1.0 op_sel_hi:[1,0]
	v_pk_mul_f32 v[38:39], v[38:39], v[48:49]
	v_rcp_f32_e32 v19, v1
	v_and_b32_sdwa v2, v39, v218 dst_sel:DWORD dst_unused:UNUSED_PAD src0_sel:WORD_1 src1_sel:DWORD
	v_and_b32_sdwa v3, v38, v218 dst_sel:DWORD dst_unused:UNUSED_PAD src0_sel:WORD_1 src1_sel:DWORD
	v_add3_u32 v2, v39, v2, s80
	v_add3_u32 v3, v38, v3, s80
	v_or_b32_sdwa v38, v17, v2 dst_sel:DWORD dst_unused:UNUSED_PAD src0_sel:DWORD src1_sel:WORD_1
	v_and_b32_e32 v16, 0xffff0000, v16
	v_or_b32_sdwa v39, v16, v3 dst_sel:DWORD dst_unused:UNUSED_PAD src0_sel:DWORD src1_sel:WORD_1
	v_accvgpr_read_b32 v8, a184
	v_rcp_f32_e32 v17, v0
	v_mul_f32_e32 v1, v10, v19
	v_accvgpr_read_b32 v148, a187
	v_mul_f32_e32 v32, 0xbfb8aa3b, v148
	v_exp_f32_e32 v47, v32
	v_accvgpr_read_b32 v11, a187
	v_mul_f32_e32 v0, v8, v17
	v_pk_add_f32 v[2:3], v[46:47], 1.0 op_sel_hi:[1,0]
	v_accvgpr_read_b32 v26, a10
	v_rcp_f32_e32 v10, v3
	v_accvgpr_read_b32 v24, a8
	v_mov_b32_e32 v16, v24
	v_mov_b32_e32 v17, v26
	v_pk_mul_f32 v[0:1], v[0:1], v[16:17]
	v_accvgpr_read_b32 v9, a185
	v_rcp_f32_e32 v18, v2
	v_mul_f32_e32 v3, v11, v10
	v_accvgpr_read_b32 v25, a9
	v_accvgpr_read_b32 v27, a11
	v_mul_f32_e32 v2, v9, v18
	v_mov_b32_e32 v26, v25
	v_pk_mul_f32 v[2:3], v[2:3], v[26:27]
	v_and_b32_sdwa v8, v1, v218 dst_sel:DWORD dst_unused:UNUSED_PAD src0_sel:WORD_1 src1_sel:DWORD
	v_and_b32_sdwa v9, v0, v218 dst_sel:DWORD dst_unused:UNUSED_PAD src0_sel:WORD_1 src1_sel:DWORD
	v_add3_u32 v0, v0, v9, s80
	v_add3_u32 v1, v1, v8, s80
	v_and_b32_sdwa v8, v3, v218 dst_sel:DWORD dst_unused:UNUSED_PAD src0_sel:WORD_1 src1_sel:DWORD
	v_and_b32_sdwa v9, v2, v218 dst_sel:DWORD dst_unused:UNUSED_PAD src0_sel:WORD_1 src1_sel:DWORD
	v_add3_u32 v3, v3, v8, s80
	v_add3_u32 v2, v2, v9, s80
	v_and_b32_e32 v3, 0xffff0000, v3
	v_and_b32_e32 v2, 0xffff0000, v2
	v_accvgpr_read_b32 v6, a182
	v_or_b32_sdwa v16, v3, v1 dst_sel:DWORD dst_unused:UNUSED_PAD src0_sel:DWORD src1_sel:WORD_1
	v_or_b32_sdwa v17, v2, v0 dst_sel:DWORD dst_unused:UNUSED_PAD src0_sel:DWORD src1_sel:WORD_1
	v_pk_add_f32 v[2:3], v[42:43], 1.0 op_sel_hi:[1,0]
	v_accvgpr_read_b32 v4, a180
	v_rcp_f32_e32 v9, v3
	v_accvgpr_read_b32 v7, a183
	v_accvgpr_read_b32 v22, a6
	v_accvgpr_read_b32 v20, a4
	v_rcp_f32_e32 v24, v2
	v_mul_f32_e32 v3, v6, v9
	v_mov_b32_e32 v11, v22
	v_pk_add_f32 v[8:9], v[36:37], 1.0 op_sel_hi:[1,0]
	v_mul_f32_e32 v2, v4, v24
	v_rcp_f32_e32 v6, v9
	v_mov_b32_e32 v10, v20
	v_pk_mul_f32 v[2:3], v[2:3], v[10:11]
	v_accvgpr_read_b32 v5, a181
	v_rcp_f32_e32 v20, v8
	v_mul_f32_e32 v7, v7, v6
	v_accvgpr_read_b32 v147, a188
	v_accvgpr_read_b32 v145, a190
	v_accvgpr_read_b32 v21, a5
	v_mul_f32_e32 v32, 0xbfb8aa3b, v147
	v_mul_f32_e32 v35, 0xbfb8aa3b, v145
	v_accvgpr_read_b32 v23, a7
	v_exp_f32_e32 v34, v32
	v_exp_f32_e32 v35, v35
	v_mul_f32_e32 v6, v5, v20
	v_mov_b32_e32 v22, v21
	v_pk_mul_f32 v[4:5], v[6:7], v[22:23]
	v_and_b32_sdwa v7, v2, v218 dst_sel:DWORD dst_unused:UNUSED_PAD src0_sel:WORD_1 src1_sel:DWORD
	v_and_b32_sdwa v6, v3, v218 dst_sel:DWORD dst_unused:UNUSED_PAD src0_sel:WORD_1 src1_sel:DWORD
	v_add3_u32 v7, v2, v7, s80
	v_and_b32_sdwa v2, v5, v218 dst_sel:DWORD dst_unused:UNUSED_PAD src0_sel:WORD_1 src1_sel:DWORD
	v_add3_u32 v6, v3, v6, s80
	v_and_b32_sdwa v3, v4, v218 dst_sel:DWORD dst_unused:UNUSED_PAD src0_sel:WORD_1 src1_sel:DWORD
	v_add3_u32 v2, v5, v2, s80
	v_accvgpr_read_b32 v14, a190
	v_add3_u32 v4, v4, v3, s80
	v_and_b32_e32 v5, 0xffff0000, v2
	v_pk_add_f32 v[2:3], v[34:35], 1.0 op_sel_hi:[1,0]
	v_and_b32_e32 v4, 0xffff0000, v4
	v_rcp_f32_e32 v9, v3
	v_or_b32_sdwa v11, v4, v7 dst_sel:DWORD dst_unused:UNUSED_PAD src0_sel:DWORD src1_sel:WORD_1
	v_or_b32_sdwa v10, v5, v6 dst_sel:DWORD dst_unused:UNUSED_PAD src0_sel:DWORD src1_sel:WORD_1
	v_accvgpr_read_b32 v12, a188
	v_rcp_f32_e32 v7, v2
	v_mul_f32_e32 v3, v14, v9
	v_accvgpr_read_b32 v146, a189
	v_accvgpr_read_b32 v144, a191
	v_mul_f32_e32 v32, 0xbfb8aa3b, v146
	v_mul_f32_e32 v50, 0xbfb8aa3b, v144
	v_exp_f32_e32 v32, v32
	v_exp_f32_e32 v33, v50
	v_accvgpr_read_b32 v15, a191
	v_mul_f32_e32 v2, v12, v7
	v_pk_add_f32 v[4:5], v[32:33], 1.0 op_sel_hi:[1,0]
	v_accvgpr_read_b32 v30, a14
	v_rcp_f32_e32 v9, v5
	v_accvgpr_read_b32 v28, a12
	v_mov_b32_e32 v6, v28
	v_mov_b32_e32 v7, v30
	v_pk_mul_f32 v[2:3], v[2:3], v[6:7]
	v_accvgpr_read_b32 v13, a189
	v_rcp_f32_e32 v12, v4
	v_mul_f32_e32 v5, v15, v9
	v_accvgpr_read_b32 v29, a13
	v_mul_f32_e32 v4, v13, v12
	v_mov_b32_e32 v30, v29
	v_pk_mul_f32 v[4:5], v[4:5], v[30:31]
	v_and_b32_sdwa v6, v3, v218 dst_sel:DWORD dst_unused:UNUSED_PAD src0_sel:WORD_1 src1_sel:DWORD
	v_and_b32_sdwa v7, v2, v218 dst_sel:DWORD dst_unused:UNUSED_PAD src0_sel:WORD_1 src1_sel:DWORD
	v_add3_u32 v2, v2, v7, s80
	v_add3_u32 v3, v3, v6, s80
	v_and_b32_sdwa v6, v5, v218 dst_sel:DWORD dst_unused:UNUSED_PAD src0_sel:WORD_1 src1_sel:DWORD
	v_and_b32_sdwa v7, v4, v218 dst_sel:DWORD dst_unused:UNUSED_PAD src0_sel:WORD_1 src1_sel:DWORD
	v_add3_u32 v5, v5, v6, s80
	v_add3_u32 v4, v4, v7, s80
	v_and_b32_e32 v5, 0xffff0000, v5
	v_and_b32_e32 v4, 0xffff0000, v4
	v_cndmask_b32_e64 v0, v39, v17, s[2:3]
	v_cndmask_b32_e64 v1, v38, v16, s[2:3]
	v_or_b32_sdwa v5, v5, v3 dst_sel:DWORD dst_unused:UNUSED_PAD src0_sel:DWORD src1_sel:WORD_1
	v_or_b32_sdwa v4, v4, v2 dst_sel:DWORD dst_unused:UNUSED_PAD src0_sel:DWORD src1_sel:WORD_1
	ds_bpermute_b32 v18, v132, v0
	ds_bpermute_b32 v19, v132, v1
	v_cndmask_b32_e64 v2, v11, v4, s[2:3]
	v_cndmask_b32_e64 v3, v10, v5, s[2:3]
	ds_bpermute_b32 v6, v132, v3
	ds_bpermute_b32 v7, v132, v2
	v_mov_b32_e32 v229, 0x4000
	s_waitcnt lgkmcnt(2)
	v_cndmask_b32_e64 v1, v19, v38, s[2:3]
	v_cndmask_b32_e64 v0, v18, v39, s[2:3]
	v_cndmask_b32_e64 v3, v16, v19, s[2:3]
	v_cndmask_b32_e64 v2, v17, v18, s[2:3]
	s_add_i32 s0, s0, s93
	global_store_dwordx4 v[66:67], v[0:3], off offset:64
	s_cmpk_gt_i32 s0, 0x78f
	v_mov_b32_e32 v214, v229
	s_waitcnt lgkmcnt(1)
	v_cndmask_b32_e64 v1, v6, v10, s[2:3]
	s_waitcnt lgkmcnt(0)
	v_cndmask_b32_e64 v0, v7, v11, s[2:3]
	v_cndmask_b32_e64 v3, v5, v6, s[2:3]
	v_cndmask_b32_e64 v2, v4, v7, s[2:3]
	global_store_dwordx4 v[66:67], v[0:3], off offset:80
	s_cbranch_scc1 .LBB0_156

.LBB0_160:
	s_nop 1
	v_accvgpr_read_b32 v142, a80
	v_accvgpr_read_b32 v139, a83
	v_accvgpr_read_b32 v141, a81
	v_accvgpr_read_b32 v137, a84
	v_mul_f32_e32 v116, 0xbfb8aa3b, v142
	v_mfma_f32_32x32x16_bf16 a[16:31], v[132:135], v[112:115], a[16:31]
	v_mul_f32_e32 v112, 0xbfb8aa3b, v139
	v_accvgpr_read_b32 v140, a82
	v_accvgpr_read_b32 v136, a85
	v_exp_f32_e32 v142, v116
	v_mul_f32_e32 v116, 0xbfb8aa3b, v141
	v_exp_f32_e32 v221, v112
	v_mul_f32_e32 v112, 0xbfb8aa3b, v137
	v_accvgpr_read_b32 v127, a86
	v_exp_f32_e32 v220, v116
	v_mul_f32_e32 v116, 0xbfb8aa3b, v140
	v_exp_f32_e32 v226, v112
	v_mul_f32_e32 v112, 0xbfb8aa3b, v136
	v_accvgpr_read_b32 v126, a87
	v_exp_f32_e32 v143, v116
	v_exp_f32_e32 v116, v112
	v_mul_f32_e32 v112, 0xbfb8aa3b, v127
	v_accvgpr_read_b32 v125, a88
	v_exp_f32_e32 v227, v112
	v_mul_f32_e32 v112, 0xbfb8aa3b, v126
	v_accvgpr_read_b32 v124, a89
	v_exp_f32_e32 v117, v112
	v_mul_f32_e32 v112, 0xbfb8aa3b, v125
	v_accvgpr_read_b32 v123, a90
	v_exp_f32_e32 v126, v112
	v_mul_f32_e32 v112, 0xbfb8aa3b, v124
	v_accvgpr_read_b32 v122, a91
	v_exp_f32_e32 v124, v112
	v_mul_f32_e32 v112, 0xbfb8aa3b, v123
	v_accvgpr_read_b32 v121, a92
	v_accvgpr_read_b32 v119, a94
	v_mfma_f32_32x32x16_bf16 a[32:47], v[132:135], v[80:83], a[32:47]
	v_accvgpr_read_b32 v80, a80
	v_exp_f32_e32 v127, v112
	v_mul_f32_e32 v112, 0xbfb8aa3b, v122
	v_accvgpr_read_b32 v120, a93
	v_accvgpr_read_b32 v82, a82
	v_exp_f32_e32 v125, v112
	v_mul_f32_e32 v112, 0xbfb8aa3b, v121
	v_mul_f32_e32 v113, 0xbfb8aa3b, v119
	v_pk_add_f32 v[118:119], v[142:143], 1.0 op_sel_hi:[1,0]
	v_exp_f32_e32 v114, v112
	v_mul_f32_e32 v112, 0xbfb8aa3b, v120
	v_rcp_f32_e32 v121, v119
	v_accvgpr_read_b32 v83, a83
	v_accvgpr_read_b32 v81, a81
	v_accvgpr_read_b32 v90, a90
	v_rcp_f32_e32 v136, v118
	v_mul_f32_e32 v137, v82, v121
	v_accvgpr_read_b32 v138, a95
	v_pk_add_f32 v[120:121], v[220:221], 1.0 op_sel_hi:[1,0]
	v_rcp_f32_e32 v123, v121
	v_mul_f32_e32 v136, v80, v136
	v_exp_f32_e32 v115, v113
	v_rcp_f32_e32 v119, v120
	v_mul_f32_e32 v139, v83, v123
	v_pk_add_f32 v[82:83], v[126:127], 1.0 op_sel_hi:[1,0]
	v_rcp_f32_e32 v122, v83
	v_mul_f32_e32 v113, 0xbfb8aa3b, v138
	v_mul_f32_e32 v138, v81, v119
	v_accvgpr_read_b32 v88, a88
	v_rcp_f32_e32 v119, v82
	v_mul_f32_e32 v141, v90, v122
	v_accvgpr_read_b32 v91, a91
	v_pk_add_f32 v[80:81], v[124:125], 1.0 op_sel_hi:[1,0]
	v_rcp_f32_e32 v120, v81
	v_mul_f32_e32 v140, v88, v119
	v_accvgpr_read_b32 v89, a89
	v_accvgpr_read_b32 v86, a86
	v_rcp_f32_e32 v90, v80
	v_mul_f32_e32 v143, v91, v120
	v_pk_add_f32 v[82:83], v[226:227], 1.0 op_sel_hi:[1,0]
	v_rcp_f32_e32 v118, v83
	v_mul_f32_e32 v142, v89, v90
	v_accvgpr_read_b32 v84, a84
	v_rcp_f32_e32 v89, v82
	v_mul_f32_e32 v221, v86, v118
	v_accvgpr_read_b32 v87, a87
	v_pk_add_f32 v[80:81], v[116:117], 1.0 op_sel_hi:[1,0]
	v_rcp_f32_e32 v90, v81
	v_mul_f32_e32 v220, v84, v89
	v_accvgpr_read_b32 v85, a85
	v_accvgpr_read_b32 v94, a94
	v_rcp_f32_e32 v86, v80
	v_mul_f32_e32 v227, v87, v90
	v_pk_add_f32 v[82:83], v[114:115], 1.0 op_sel_hi:[1,0]
	v_rcp_f32_e32 v88, v83
	v_mul_f32_e32 v226, v85, v86
	v_accvgpr_read_b32 v92, a92
	v_rcp_f32_e32 v85, v82
	v_mul_f32_e32 v215, v94, v88
	v_exp_f32_e32 v112, v112
	v_exp_f32_e32 v113, v113
	v_accvgpr_read_b32 v95, a95
	v_pk_add_f32 v[80:81], v[112:113], 1.0 op_sel_hi:[1,0]
	v_accvgpr_read_b32 v96, a96
	v_rcp_f32_e32 v87, v81
	v_accvgpr_read_b32 v98, a98
	v_mfma_f32_32x32x16_bf16 a[0:15], v[132:135], v[128:131], a[0:15]
	v_or_b32_e32 v129, s2, v161
	v_accvgpr_read_b32 v97, a97
	v_or_b32_e32 v128, s1, v162
	v_add_u32_e32 v133, v163, v129
	v_mov_b32_e32 v162, v96
	v_mov_b32_e32 v163, v98
	v_accvgpr_read_b32 v99, a99
	v_mul_f32_e32 v214, v92, v85
	v_pk_mul_f32 v[136:137], v[162:163], v[136:137]
	v_mov_b32_e32 v98, v97
	v_pk_mul_f32 v[96:97], v[98:99], v[138:139]
	v_and_b32_sdwa v98, v137, v218 dst_sel:DWORD dst_unused:UNUSED_PAD src0_sel:WORD_1 src1_sel:DWORD
	v_and_b32_sdwa v99, v136, v218 dst_sel:DWORD dst_unused:UNUSED_PAD src0_sel:WORD_1 src1_sel:DWORD
	v_add3_u32 v99, v136, v99, s80
	v_add3_u32 v98, v137, v98, s80
	v_and_b32_sdwa v136, v97, v218 dst_sel:DWORD dst_unused:UNUSED_PAD src0_sel:WORD_1 src1_sel:DWORD
	v_and_b32_sdwa v137, v96, v218 dst_sel:DWORD dst_unused:UNUSED_PAD src0_sel:WORD_1 src1_sel:DWORD
	v_accvgpr_read_b32 v93, a93
	v_add3_u32 v97, v97, v136, s80
	v_add3_u32 v96, v96, v137, s80
	v_accvgpr_read_b32 v104, a104
	v_accvgpr_read_b32 v106, a106
	v_and_b32_e32 v97, 0xffff0000, v97
	v_and_b32_e32 v96, 0xffff0000, v96
	v_accvgpr_read_b32 v105, a105
	v_rcp_f32_e32 v85, v80
	v_or_b32_sdwa v136, v97, v98 dst_sel:DWORD dst_unused:UNUSED_PAD src0_sel:DWORD src1_sel:WORD_1
	v_or_b32_sdwa v137, v96, v99 dst_sel:DWORD dst_unused:UNUSED_PAD src0_sel:DWORD src1_sel:WORD_1
	v_mov_b32_e32 v96, v104
	v_mov_b32_e32 v97, v106
	v_accvgpr_read_b32 v107, a107
	v_pk_mul_f32 v[96:97], v[96:97], v[140:141]
	v_mov_b32_e32 v106, v105
	v_pk_mul_f32 v[98:99], v[106:107], v[142:143]
	v_and_b32_sdwa v104, v97, v218 dst_sel:DWORD dst_unused:UNUSED_PAD src0_sel:WORD_1 src1_sel:DWORD
	v_and_b32_sdwa v105, v96, v218 dst_sel:DWORD dst_unused:UNUSED_PAD src0_sel:WORD_1 src1_sel:DWORD
	v_accvgpr_read_b32 v100, a100
	v_accvgpr_read_b32 v102, a102
	v_add3_u32 v96, v96, v105, s80
	v_add3_u32 v97, v97, v104, s80
	v_and_b32_sdwa v104, v99, v218 dst_sel:DWORD dst_unused:UNUSED_PAD src0_sel:WORD_1 src1_sel:DWORD
	v_and_b32_sdwa v105, v98, v218 dst_sel:DWORD dst_unused:UNUSED_PAD src0_sel:WORD_1 src1_sel:DWORD
	v_accvgpr_read_b32 v101, a101
	v_mul_f32_e32 v223, v95, v87
	v_add3_u32 v99, v99, v104, s80
	v_add3_u32 v98, v98, v105, s80
	v_mov_b32_e32 v104, v100
	v_mov_b32_e32 v105, v102
	v_accvgpr_read_b32 v103, a103
	v_pk_mul_f32 v[104:105], v[104:105], v[220:221]
	v_mov_b32_e32 v102, v101
	v_pk_mul_f32 v[100:101], v[102:103], v[226:227]
	v_and_b32_sdwa v102, v105, v218 dst_sel:DWORD dst_unused:UNUSED_PAD src0_sel:WORD_1 src1_sel:DWORD
	v_and_b32_sdwa v103, v104, v218 dst_sel:DWORD dst_unused:UNUSED_PAD src0_sel:WORD_1 src1_sel:DWORD
	v_add3_u32 v103, v104, v103, s80
	v_add3_u32 v102, v105, v102, s80
	v_and_b32_sdwa v104, v101, v218 dst_sel:DWORD dst_unused:UNUSED_PAD src0_sel:WORD_1 src1_sel:DWORD
	v_and_b32_sdwa v105, v100, v218 dst_sel:DWORD dst_unused:UNUSED_PAD src0_sel:WORD_1 src1_sel:DWORD
	v_add3_u32 v101, v101, v104, s80
	v_add3_u32 v100, v100, v105, s80
	v_accvgpr_read_b32 v108, a108
	v_accvgpr_read_b32 v110, a110
	v_and_b32_e32 v101, 0xffff0000, v101
	v_and_b32_e32 v100, 0xffff0000, v100
	v_accvgpr_read_b32 v109, a109
	v_or_b32_sdwa v104, v101, v102 dst_sel:DWORD dst_unused:UNUSED_PAD src0_sel:DWORD src1_sel:WORD_1
	v_or_b32_sdwa v105, v100, v103 dst_sel:DWORD dst_unused:UNUSED_PAD src0_sel:DWORD src1_sel:WORD_1
	v_mov_b32_e32 v100, v108
	v_mov_b32_e32 v101, v110
	v_accvgpr_read_b32 v111, a111
	v_mul_f32_e32 v222, v93, v85
	v_cmp_lt_i32_e32 vcc, v211, v210
	v_readlane_b32 s2, v253, 61
	v_pk_mul_f32 v[100:101], v[100:101], v[214:215]
	v_mov_b32_e32 v110, v109
	v_cndmask_b32_e32 v129, v209, v211, vcc
	v_readlane_b32 s3, v253, 62
	v_pk_mul_f32 v[102:103], v[110:111], v[222:223]
	v_and_b32_sdwa v108, v101, v218 dst_sel:DWORD dst_unused:UNUSED_PAD src0_sel:WORD_1 src1_sel:DWORD
	v_and_b32_sdwa v109, v100, v218 dst_sel:DWORD dst_unused:UNUSED_PAD src0_sel:WORD_1 src1_sel:DWORD
	v_lshlrev_b32_e32 v132, 2, v129
	v_ashrrev_i32_e32 v130, 1, v128
	v_mov_b64_e32 v[128:129], s[2:3]
	s_movk_i32 s1, 0x1600
	v_and_b32_e32 v98, 0xffff0000, v98
	v_add3_u32 v100, v100, v109, s80
	v_add3_u32 v101, v101, v108, s80
	v_and_b32_sdwa v108, v103, v218 dst_sel:DWORD dst_unused:UNUSED_PAD src0_sel:WORD_1 src1_sel:DWORD
	v_and_b32_sdwa v109, v102, v218 dst_sel:DWORD dst_unused:UNUSED_PAD src0_sel:WORD_1 src1_sel:DWORD
	v_mad_i64_i32 v[134:135], s[2:3], v133, s1, v[128:129]
	v_and_b32_e32 v99, 0xffff0000, v99
	v_or_b32_sdwa v107, v98, v96 dst_sel:DWORD dst_unused:UNUSED_PAD src0_sel:DWORD src1_sel:WORD_1
	v_and_b32_e32 v96, 63, v160
	v_add3_u32 v103, v103, v108, s80
	v_add3_u32 v102, v102, v109, s80
	v_or_b32_sdwa v106, v99, v97 dst_sel:DWORD dst_unused:UNUSED_PAD src0_sel:DWORD src1_sel:WORD_1
	v_cmp_gt_u32_e64 s[2:3], 32, v96
	v_and_b32_e32 v103, 0xffff0000, v103
	v_and_b32_e32 v102, 0xffff0000, v102
	v_cndmask_b32_e64 v96, v137, v107, s[2:3]
	v_cndmask_b32_e64 v97, v136, v106, s[2:3]
	v_or_b32_sdwa v103, v103, v101 dst_sel:DWORD dst_unused:UNUSED_PAD src0_sel:DWORD src1_sel:WORD_1
	v_or_b32_sdwa v102, v102, v100 dst_sel:DWORD dst_unused:UNUSED_PAD src0_sel:DWORD src1_sel:WORD_1
	ds_bpermute_b32 v138, v132, v97
	ds_bpermute_b32 v139, v132, v96
	v_cndmask_b32_e64 v100, v105, v102, s[2:3]
	v_cndmask_b32_e64 v101, v104, v103, s[2:3]
	ds_bpermute_b32 v108, v132, v101
	ds_bpermute_b32 v109, v132, v100
	v_ashrrev_i32_e32 v131, 31, v130
	v_lshlrev_b64 v[130:131], 1, v[130:131]
	v_lshl_add_u64 v[96:97], v[134:135], 0, v[130:131]
	v_and_b32_e32 v192, 32, v160
	v_lshl_add_u64 v[96:97], v[96:97], 0, v[192:193]
	s_waitcnt lgkmcnt(3)
	v_cndmask_b32_e64 v99, v138, v136, s[2:3]
	s_waitcnt lgkmcnt(2)
	v_cndmask_b32_e64 v98, v139, v137, s[2:3]
	v_cndmask_b32_e64 v101, v106, v138, s[2:3]
	v_cndmask_b32_e64 v100, v107, v139, s[2:3]
	v_accvgpr_read_b32 v225, a48
	global_store_dwordx4 v[96:97], v[98:101], off
	v_accvgpr_read_b32 v224, a49
	v_accvgpr_read_b32 v252, a50
	s_waitcnt lgkmcnt(1)
	v_cndmask_b32_e64 v99, v108, v104, s[2:3]
	s_waitcnt lgkmcnt(0)
	v_cndmask_b32_e64 v98, v109, v105, s[2:3]
	v_cndmask_b32_e64 v101, v103, v108, s[2:3]
	v_cndmask_b32_e64 v100, v102, v109, s[2:3]
	global_store_dwordx4 v[96:97], v[98:101], off offset:16
	v_accvgpr_read_b32 v127, a63
	v_accvgpr_read_b32 v114, a50
	v_mul_f32_e32 v98, 0xbfb8aa3b, v225
	v_exp_f32_e32 v104, v98
	v_mul_f32_e32 v98, 0xbfb8aa3b, v224
	v_exp_f32_e32 v106, v98
	v_mul_f32_e32 v98, 0xbfb8aa3b, v252
	v_exp_f32_e32 v105, v98
	v_accvgpr_read_b32 v112, a48
	v_accvgpr_read_b32 v251, a51
	v_mul_f32_e32 v98, 0xbfb8aa3b, v251
	v_pk_add_f32 v[104:105], v[104:105], 1.0 op_sel_hi:[1,0]
	v_exp_f32_e32 v107, v98
	v_rcp_f32_e32 v139, v105
	v_accvgpr_read_b32 v115, a51
	v_pk_add_f32 v[106:107], v[106:107], 1.0 op_sel_hi:[1,0]
	v_accvgpr_read_b32 v64, a112
	v_rcp_f32_e32 v142, v104
	v_mul_f32_e32 v105, v114, v139
	v_accvgpr_read_b32 v66, a114
	v_mul_f32_e32 v104, v112, v142
	v_rcp_f32_e32 v114, v107
	v_mov_b32_e32 v138, v64
	v_mov_b32_e32 v139, v66
	v_pk_mul_f32 v[104:105], v[138:139], v[104:105]
	v_accvgpr_read_b32 v113, a49
	v_rcp_f32_e32 v138, v106
	v_accvgpr_read_b32 v250, a52
	v_accvgpr_read_b32 v249, a53
	v_mul_f32_e32 v98, 0xbfb8aa3b, v250
	v_mul_f32_e32 v107, v115, v114
	v_accvgpr_read_b32 v248, a54
	v_exp_f32_e32 v108, v98
	v_mul_f32_e32 v98, 0xbfb8aa3b, v249
	v_accvgpr_read_b32 v247, a55
	v_exp_f32_e32 v102, v98
	v_mul_f32_e32 v98, 0xbfb8aa3b, v248
	v_accvgpr_read_b32 v246, a56
	v_exp_f32_e32 v109, v98
	v_mul_f32_e32 v98, 0xbfb8aa3b, v247
	v_accvgpr_read_b32 v245, a57
	v_exp_f32_e32 v103, v98
	v_mul_f32_e32 v98, 0xbfb8aa3b, v246
	v_accvgpr_read_b32 v244, a58
	v_exp_f32_e32 v110, v98
	v_mul_f32_e32 v98, 0xbfb8aa3b, v245
	v_accvgpr_read_b32 v65, a113
	v_exp_f32_e32 v134, v98
	v_mul_f32_e32 v98, 0xbfb8aa3b, v244
	v_accvgpr_read_b32 v67, a115
	v_exp_f32_e32 v111, v98
	v_mul_f32_e32 v106, v113, v138
	v_mov_b32_e32 v66, v65
	v_pk_mul_f32 v[64:65], v[66:67], v[106:107]
	v_and_b32_sdwa v67, v104, v218 dst_sel:DWORD dst_unused:UNUSED_PAD src0_sel:WORD_1 src1_sel:DWORD
	v_and_b32_sdwa v66, v105, v218 dst_sel:DWORD dst_unused:UNUSED_PAD src0_sel:WORD_1 src1_sel:DWORD
	v_add3_u32 v67, v104, v67, s80
	v_and_b32_sdwa v104, v65, v218 dst_sel:DWORD dst_unused:UNUSED_PAD src0_sel:WORD_1 src1_sel:DWORD
	v_add3_u32 v66, v105, v66, s80
	v_and_b32_sdwa v105, v64, v218 dst_sel:DWORD dst_unused:UNUSED_PAD src0_sel:WORD_1 src1_sel:DWORD
	v_add3_u32 v65, v65, v104, s80
	v_accvgpr_read_b32 v122, a58
	v_add3_u32 v104, v64, v105, s80
	v_and_b32_e32 v105, 0xffff0000, v65
	v_pk_add_f32 v[64:65], v[110:111], 1.0 op_sel_hi:[1,0]
	v_or_b32_sdwa v110, v105, v66 dst_sel:DWORD dst_unused:UNUSED_PAD src0_sel:DWORD src1_sel:WORD_1
	v_rcp_f32_e32 v107, v65
	v_and_b32_e32 v104, 0xffff0000, v104
	v_or_b32_sdwa v111, v104, v67 dst_sel:DWORD dst_unused:UNUSED_PAD src0_sel:DWORD src1_sel:WORD_1
	v_accvgpr_read_b32 v120, a56
	v_rcp_f32_e32 v105, v64
	v_mul_f32_e32 v65, v122, v107
	v_accvgpr_read_b32 v243, a59
	v_mul_f32_e32 v98, 0xbfb8aa3b, v243
	v_exp_f32_e32 v135, v98
	v_accvgpr_read_b32 v123, a59
	v_mul_f32_e32 v64, v120, v105
	v_pk_add_f32 v[66:67], v[134:135], 1.0 op_sel_hi:[1,0]
	v_accvgpr_read_b32 v72, a120
	v_rcp_f32_e32 v107, v67
	v_mov_b32_e32 v104, v72
	v_accvgpr_read_b32 v74, a122
	v_mov_b32_e32 v105, v74
	v_accvgpr_read_b32 v121, a57
	v_pk_mul_f32 v[64:65], v[104:105], v[64:65]
	v_rcp_f32_e32 v105, v66
	v_mul_f32_e32 v67, v123, v107
	v_accvgpr_read_b32 v73, a121
	v_accvgpr_read_b32 v75, a123
	v_mul_f32_e32 v66, v121, v105
	v_mov_b32_e32 v74, v73
	v_pk_mul_f32 v[66:67], v[74:75], v[66:67]
	v_and_b32_sdwa v72, v65, v218 dst_sel:DWORD dst_unused:UNUSED_PAD src0_sel:WORD_1 src1_sel:DWORD
	v_and_b32_sdwa v73, v64, v218 dst_sel:DWORD dst_unused:UNUSED_PAD src0_sel:WORD_1 src1_sel:DWORD
	v_add3_u32 v64, v64, v73, s80
	v_add3_u32 v65, v65, v72, s80
	v_and_b32_sdwa v72, v67, v218 dst_sel:DWORD dst_unused:UNUSED_PAD src0_sel:WORD_1 src1_sel:DWORD
	v_and_b32_sdwa v73, v66, v218 dst_sel:DWORD dst_unused:UNUSED_PAD src0_sel:WORD_1 src1_sel:DWORD
	v_add3_u32 v67, v67, v72, s80
	v_add3_u32 v66, v66, v73, s80
	v_and_b32_e32 v67, 0xffff0000, v67
	v_and_b32_e32 v66, 0xffff0000, v66
	v_or_b32_sdwa v104, v67, v65 dst_sel:DWORD dst_unused:UNUSED_PAD src0_sel:DWORD src1_sel:WORD_1
	v_or_b32_sdwa v105, v66, v64 dst_sel:DWORD dst_unused:UNUSED_PAD src0_sel:DWORD src1_sel:WORD_1
	v_cndmask_b32_e64 v64, v111, v105, s[2:3]
	v_cndmask_b32_e64 v65, v110, v104, s[2:3]
	v_accvgpr_read_b32 v118, a54
	ds_bpermute_b32 v106, v132, v64
	ds_bpermute_b32 v107, v132, v65
	v_pk_add_f32 v[64:65], v[108:109], 1.0 op_sel_hi:[1,0]
	v_accvgpr_read_b32 v116, a52
	v_rcp_f32_e32 v75, v65
	s_waitcnt lgkmcnt(0)
	v_cndmask_b32_e64 v73, v107, v110, s[2:3]
	v_accvgpr_read_b32 v119, a55
	v_accvgpr_read_b32 v68, a116
	v_rcp_f32_e32 v110, v64
	v_mul_f32_e32 v65, v118, v75
	v_accvgpr_read_b32 v70, a118
	v_mul_f32_e32 v64, v116, v110
	v_pk_add_f32 v[74:75], v[102:103], 1.0 op_sel_hi:[1,0]
	v_mov_b32_e32 v102, v68
	v_rcp_f32_e32 v109, v75
	v_mov_b32_e32 v103, v70
	v_accvgpr_read_b32 v117, a53
	v_pk_mul_f32 v[64:65], v[102:103], v[64:65]
	v_rcp_f32_e32 v103, v74
	v_mul_f32_e32 v75, v119, v109
	v_accvgpr_read_b32 v242, a60
	v_accvgpr_read_b32 v240, a62
	v_accvgpr_read_b32 v69, a117
	v_mul_f32_e32 v98, 0xbfb8aa3b, v242
	v_mul_f32_e32 v99, 0xbfb8aa3b, v240
	v_accvgpr_read_b32 v71, a119
	v_exp_f32_e32 v100, v98
	v_exp_f32_e32 v101, v99
	v_mul_f32_e32 v74, v117, v103
	v_mov_b32_e32 v70, v69
	v_pk_mul_f32 v[68:69], v[70:71], v[74:75]
	v_and_b32_sdwa v71, v64, v218 dst_sel:DWORD dst_unused:UNUSED_PAD src0_sel:WORD_1 src1_sel:DWORD
	v_and_b32_sdwa v70, v65, v218 dst_sel:DWORD dst_unused:UNUSED_PAD src0_sel:WORD_1 src1_sel:DWORD
	v_add3_u32 v71, v64, v71, s80
	v_and_b32_sdwa v64, v69, v218 dst_sel:DWORD dst_unused:UNUSED_PAD src0_sel:WORD_1 src1_sel:DWORD
	v_add3_u32 v70, v65, v70, s80
	v_and_b32_sdwa v65, v68, v218 dst_sel:DWORD dst_unused:UNUSED_PAD src0_sel:WORD_1 src1_sel:DWORD
	v_add3_u32 v64, v69, v64, s80
	v_accvgpr_read_b32 v126, a62
	v_add3_u32 v68, v68, v65, s80
	v_and_b32_e32 v69, 0xffff0000, v64
	v_pk_add_f32 v[64:65], v[100:101], 1.0 op_sel_hi:[1,0]
	v_and_b32_e32 v68, 0xffff0000, v68
	v_rcp_f32_e32 v75, v65
	v_or_b32_sdwa v101, v68, v71 dst_sel:DWORD dst_unused:UNUSED_PAD src0_sel:DWORD src1_sel:WORD_1
	v_or_b32_sdwa v100, v69, v70 dst_sel:DWORD dst_unused:UNUSED_PAD src0_sel:DWORD src1_sel:WORD_1
	v_accvgpr_read_b32 v124, a60
	v_rcp_f32_e32 v71, v64
	v_mul_f32_e32 v65, v126, v75
	v_accvgpr_read_b32 v241, a61
	v_accvgpr_read_b32 v239, a63
	v_mul_f32_e32 v98, 0xbfb8aa3b, v241
	v_mul_f32_e32 v99, 0xbfb8aa3b, v239
	v_exp_f32_e32 v98, v98
	v_exp_f32_e32 v99, v99
	v_mul_f32_e32 v64, v124, v71
	v_pk_add_f32 v[68:69], v[98:99], 1.0 op_sel_hi:[1,0]
	v_accvgpr_read_b32 v76, a124
	v_rcp_f32_e32 v75, v69
	v_accvgpr_read_b32 v78, a126
	v_mov_b32_e32 v70, v76
	v_mov_b32_e32 v71, v78
	v_pk_mul_f32 v[64:65], v[70:71], v[64:65]
	v_accvgpr_read_b32 v125, a61
	v_rcp_f32_e32 v76, v68
	v_mul_f32_e32 v69, v127, v75
	v_accvgpr_read_b32 v77, a125
	v_accvgpr_read_b32 v79, a127
	v_mul_f32_e32 v68, v125, v76
	v_mov_b32_e32 v78, v77
	v_pk_mul_f32 v[68:69], v[78:79], v[68:69]
	v_and_b32_sdwa v70, v65, v218 dst_sel:DWORD dst_unused:UNUSED_PAD src0_sel:WORD_1 src1_sel:DWORD
	v_and_b32_sdwa v71, v64, v218 dst_sel:DWORD dst_unused:UNUSED_PAD src0_sel:WORD_1 src1_sel:DWORD
	v_add3_u32 v65, v65, v70, s80
	v_and_b32_sdwa v70, v69, v218 dst_sel:DWORD dst_unused:UNUSED_PAD src0_sel:WORD_1 src1_sel:DWORD
	v_add3_u32 v64, v64, v71, s80
	v_and_b32_sdwa v71, v68, v218 dst_sel:DWORD dst_unused:UNUSED_PAD src0_sel:WORD_1 src1_sel:DWORD
	v_add3_u32 v69, v69, v70, s80
	v_add3_u32 v68, v68, v71, s80
	v_and_b32_e32 v69, 0xffff0000, v69
	v_and_b32_e32 v68, 0xffff0000, v68
	v_or_b32_sdwa v65, v69, v65 dst_sel:DWORD dst_unused:UNUSED_PAD src0_sel:DWORD src1_sel:WORD_1
	v_or_b32_sdwa v64, v68, v64 dst_sel:DWORD dst_unused:UNUSED_PAD src0_sel:DWORD src1_sel:WORD_1
	v_cndmask_b32_e64 v69, v100, v65, s[2:3]
	v_cndmask_b32_e64 v68, v101, v64, s[2:3]
	ds_bpermute_b32 v70, v132, v69
	ds_bpermute_b32 v76, v132, v68
	v_add_u32_e32 v136, 32, v133
	v_mad_i64_i32 v[136:137], s[4:5], v136, s1, v[128:129]
	v_accvgpr_read_b32 v237, a65
	v_lshl_add_u64 v[136:137], v[136:137], 0, v[130:131]
	v_accvgpr_read_b32 v238, a64
	v_accvgpr_read_b32 v236, a66
	v_lshl_add_u64 v[66:67], v[136:137], 0, v[192:193]
	v_cndmask_b32_e64 v72, v106, v111, s[2:3]
	v_cndmask_b32_e64 v75, v104, v107, s[2:3]
	v_cndmask_b32_e64 v74, v105, v106, s[2:3]
	s_waitcnt lgkmcnt(1)
	v_cndmask_b32_e64 v71, v65, v70, s[2:3]
	v_mul_f32_e32 v65, 0xbfb8aa3b, v237
	global_store_dwordx4 v[66:67], v[72:75], off
	v_cndmask_b32_e64 v69, v70, v100, s[2:3]
	s_waitcnt lgkmcnt(0)
	v_cndmask_b32_e64 v70, v64, v76, s[2:3]
	v_mul_f32_e32 v64, 0xbfb8aa3b, v238
	v_exp_f32_e32 v74, v65
	v_mul_f32_e32 v65, 0xbfb8aa3b, v236
	v_exp_f32_e32 v64, v64
	v_exp_f32_e32 v65, v65
	v_accvgpr_read_b32 v95, a79
	v_accvgpr_read_b32 v82, a66
	v_accvgpr_read_b32 v80, a64
	v_pk_add_f32 v[64:65], v[64:65], 1.0 op_sel_hi:[1,0]
	v_accvgpr_read_b32 v235, a67
	v_rcp_f32_e32 v103, v65
	v_cndmask_b32_e64 v68, v76, v101, s[2:3]
	global_store_dwordx4 v[66:67], v[68:71], off offset:16
	v_accvgpr_read_b32 v83, a67
	v_rcp_f32_e32 v106, v64
	v_mul_f32_e32 v65, v82, v103
	v_mul_f32_e32 v68, 0xbfb8aa3b, v235
	v_exp_f32_e32 v75, v68
	s_nop 0
	v_pk_add_f32 v[74:75], v[74:75], 1.0 op_sel_hi:[1,0]
	v_mul_f32_e32 v64, v80, v106
	v_rcp_f32_e32 v82, v75
	v_accvgpr_read_b32 v48, a128
	v_mov_b32_e32 v102, v48
	v_accvgpr_read_b32 v50, a130
	v_mov_b32_e32 v103, v50
	v_pk_mul_f32 v[64:65], v[102:103], v[64:65]
	v_accvgpr_read_b32 v81, a65
	v_rcp_f32_e32 v102, v74
	v_accvgpr_read_b32 v234, a68
	v_accvgpr_read_b32 v233, a69
	v_mul_f32_e32 v68, 0xbfb8aa3b, v234
	v_mul_f32_e32 v75, v83, v82
	v_accvgpr_read_b32 v232, a70
	v_exp_f32_e32 v76, v68
	v_mul_f32_e32 v68, 0xbfb8aa3b, v233
	v_accvgpr_read_b32 v231, a71
	v_exp_f32_e32 v72, v68
	v_mul_f32_e32 v68, 0xbfb8aa3b, v232
	v_accvgpr_read_b32 v207, a72
	v_exp_f32_e32 v77, v68
	v_mul_f32_e32 v68, 0xbfb8aa3b, v231
	v_accvgpr_read_b32 v205, a73
	v_exp_f32_e32 v73, v68
	v_mul_f32_e32 v68, 0xbfb8aa3b, v207
	v_accvgpr_read_b32 v204, a74
	v_exp_f32_e32 v78, v68
	v_mul_f32_e32 v68, 0xbfb8aa3b, v205
	v_accvgpr_read_b32 v49, a129
	v_exp_f32_e32 v98, v68
	v_mul_f32_e32 v68, 0xbfb8aa3b, v204
	v_accvgpr_read_b32 v51, a131
	v_exp_f32_e32 v79, v68
	v_mul_f32_e32 v74, v81, v102
	v_mov_b32_e32 v50, v49
	v_pk_mul_f32 v[48:49], v[50:51], v[74:75]
	v_and_b32_sdwa v51, v64, v218 dst_sel:DWORD dst_unused:UNUSED_PAD src0_sel:WORD_1 src1_sel:DWORD
	v_and_b32_sdwa v50, v65, v218 dst_sel:DWORD dst_unused:UNUSED_PAD src0_sel:WORD_1 src1_sel:DWORD
	v_add3_u32 v51, v64, v51, s80
	v_and_b32_sdwa v64, v49, v218 dst_sel:DWORD dst_unused:UNUSED_PAD src0_sel:WORD_1 src1_sel:DWORD
	v_add3_u32 v50, v65, v50, s80
	v_and_b32_sdwa v65, v48, v218 dst_sel:DWORD dst_unused:UNUSED_PAD src0_sel:WORD_1 src1_sel:DWORD
	v_add3_u32 v49, v49, v64, s80
	v_accvgpr_read_b32 v90, a74
	v_add3_u32 v64, v48, v65, s80
	v_and_b32_e32 v65, 0xffff0000, v49
	v_pk_add_f32 v[48:49], v[78:79], 1.0 op_sel_hi:[1,0]
	v_or_b32_sdwa v78, v65, v50 dst_sel:DWORD dst_unused:UNUSED_PAD src0_sel:DWORD src1_sel:WORD_1
	v_rcp_f32_e32 v75, v49
	v_and_b32_e32 v64, 0xffff0000, v64
	v_or_b32_sdwa v79, v64, v51 dst_sel:DWORD dst_unused:UNUSED_PAD src0_sel:DWORD src1_sel:WORD_1
	v_accvgpr_read_b32 v88, a72
	v_rcp_f32_e32 v65, v48
	v_mul_f32_e32 v49, v90, v75
	v_accvgpr_read_b32 v203, a75
	v_mul_f32_e32 v68, 0xbfb8aa3b, v203
	v_exp_f32_e32 v99, v68
	v_accvgpr_read_b32 v91, a75
	v_mul_f32_e32 v48, v88, v65
	v_pk_add_f32 v[50:51], v[98:99], 1.0 op_sel_hi:[1,0]
	v_accvgpr_read_b32 v56, a136
	v_rcp_f32_e32 v75, v51
	v_mov_b32_e32 v64, v56
	v_accvgpr_read_b32 v58, a138
	v_mov_b32_e32 v65, v58
	v_accvgpr_read_b32 v89, a73
	v_pk_mul_f32 v[48:49], v[64:65], v[48:49]
	v_rcp_f32_e32 v65, v50
	v_mul_f32_e32 v51, v91, v75
	v_accvgpr_read_b32 v57, a137
	v_accvgpr_read_b32 v59, a139
	v_mul_f32_e32 v50, v89, v65
	v_mov_b32_e32 v58, v57
	v_pk_mul_f32 v[50:51], v[58:59], v[50:51]
	v_and_b32_sdwa v56, v49, v218 dst_sel:DWORD dst_unused:UNUSED_PAD src0_sel:WORD_1 src1_sel:DWORD
	v_and_b32_sdwa v57, v48, v218 dst_sel:DWORD dst_unused:UNUSED_PAD src0_sel:WORD_1 src1_sel:DWORD
	v_add3_u32 v48, v48, v57, s80
	v_add3_u32 v49, v49, v56, s80
	v_and_b32_sdwa v56, v51, v218 dst_sel:DWORD dst_unused:UNUSED_PAD src0_sel:WORD_1 src1_sel:DWORD
	v_and_b32_sdwa v57, v50, v218 dst_sel:DWORD dst_unused:UNUSED_PAD src0_sel:WORD_1 src1_sel:DWORD
	v_add3_u32 v51, v51, v56, s80
	v_add3_u32 v50, v50, v57, s80
	v_and_b32_e32 v51, 0xffff0000, v51
	v_and_b32_e32 v50, 0xffff0000, v50
	v_accvgpr_read_b32 v86, a70
	v_or_b32_sdwa v74, v51, v49 dst_sel:DWORD dst_unused:UNUSED_PAD src0_sel:DWORD src1_sel:WORD_1
	v_or_b32_sdwa v75, v50, v48 dst_sel:DWORD dst_unused:UNUSED_PAD src0_sel:DWORD src1_sel:WORD_1
	v_pk_add_f32 v[50:51], v[76:77], 1.0 op_sel_hi:[1,0]
	v_accvgpr_read_b32 v84, a68
	v_rcp_f32_e32 v57, v51
	v_accvgpr_read_b32 v87, a71
	v_accvgpr_read_b32 v52, a132
	v_accvgpr_read_b32 v54, a134
	v_rcp_f32_e32 v76, v50
	v_mul_f32_e32 v51, v86, v57
	v_accvgpr_read_b32 v85, a69
	v_mul_f32_e32 v50, v84, v76
	v_pk_add_f32 v[56:57], v[72:73], 1.0 op_sel_hi:[1,0]
	v_mov_b32_e32 v58, v52
	v_rcp_f32_e32 v73, v57
	v_mov_b32_e32 v59, v54
	v_pk_mul_f32 v[50:51], v[58:59], v[50:51]
	v_accvgpr_read_b32 v201, a76
	v_rcp_f32_e32 v59, v56
	v_mul_f32_e32 v57, v87, v73
	v_accvgpr_read_b32 v199, a78
	v_accvgpr_read_b32 v53, a133
	v_mul_f32_e32 v68, 0xbfb8aa3b, v201
	v_mul_f32_e32 v69, 0xbfb8aa3b, v199
	v_accvgpr_read_b32 v55, a135
	v_exp_f32_e32 v70, v68
	v_exp_f32_e32 v71, v69
	v_mul_f32_e32 v56, v85, v59
	v_mov_b32_e32 v54, v53
	v_pk_mul_f32 v[52:53], v[54:55], v[56:57]
	v_and_b32_sdwa v55, v50, v218 dst_sel:DWORD dst_unused:UNUSED_PAD src0_sel:WORD_1 src1_sel:DWORD
	v_and_b32_sdwa v54, v51, v218 dst_sel:DWORD dst_unused:UNUSED_PAD src0_sel:WORD_1 src1_sel:DWORD
	v_add3_u32 v55, v50, v55, s80
	v_and_b32_sdwa v50, v53, v218 dst_sel:DWORD dst_unused:UNUSED_PAD src0_sel:WORD_1 src1_sel:DWORD
	v_add3_u32 v54, v51, v54, s80
	v_and_b32_sdwa v51, v52, v218 dst_sel:DWORD dst_unused:UNUSED_PAD src0_sel:WORD_1 src1_sel:DWORD
	v_add3_u32 v50, v53, v50, s80
	v_accvgpr_read_b32 v94, a78
	v_add3_u32 v52, v52, v51, s80
	v_and_b32_e32 v53, 0xffff0000, v50
	v_pk_add_f32 v[50:51], v[70:71], 1.0 op_sel_hi:[1,0]
	v_and_b32_e32 v52, 0xffff0000, v52
	v_rcp_f32_e32 v57, v51
	v_or_b32_sdwa v59, v52, v55 dst_sel:DWORD dst_unused:UNUSED_PAD src0_sel:DWORD src1_sel:WORD_1
	v_or_b32_sdwa v58, v53, v54 dst_sel:DWORD dst_unused:UNUSED_PAD src0_sel:DWORD src1_sel:WORD_1
	v_accvgpr_read_b32 v92, a76
	v_rcp_f32_e32 v55, v50
	v_mul_f32_e32 v51, v94, v57
	v_accvgpr_read_b32 v200, a77
	v_accvgpr_read_b32 v198, a79
	v_mul_f32_e32 v68, 0xbfb8aa3b, v200
	v_mul_f32_e32 v69, 0xbfb8aa3b, v198
	v_exp_f32_e32 v68, v68
	v_exp_f32_e32 v69, v69
	v_mul_f32_e32 v50, v92, v55
	v_pk_add_f32 v[52:53], v[68:69], 1.0 op_sel_hi:[1,0]
	v_accvgpr_read_b32 v60, a140
	v_rcp_f32_e32 v57, v53
	v_accvgpr_read_b32 v62, a142
	v_mov_b32_e32 v54, v60
	v_mov_b32_e32 v55, v62
	v_pk_mul_f32 v[50:51], v[54:55], v[50:51]
	v_accvgpr_read_b32 v93, a77
	v_rcp_f32_e32 v60, v52
	v_mul_f32_e32 v53, v95, v57
	v_accvgpr_read_b32 v61, a141
	v_accvgpr_read_b32 v63, a143
	v_mul_f32_e32 v52, v93, v60
	v_mov_b32_e32 v62, v61
	v_cndmask_b32_e64 v49, v78, v74, s[2:3]
	v_pk_mul_f32 v[52:53], v[62:63], v[52:53]
	v_and_b32_sdwa v54, v51, v218 dst_sel:DWORD dst_unused:UNUSED_PAD src0_sel:WORD_1 src1_sel:DWORD
	ds_bpermute_b32 v81, v132, v49
	v_add3_u32 v51, v51, v54, s80
	v_and_b32_sdwa v54, v53, v218 dst_sel:DWORD dst_unused:UNUSED_PAD src0_sel:WORD_1 src1_sel:DWORD
	v_cndmask_b32_e64 v48, v79, v75, s[2:3]
	v_and_b32_sdwa v55, v50, v218 dst_sel:DWORD dst_unused:UNUSED_PAD src0_sel:WORD_1 src1_sel:DWORD
	v_add3_u32 v53, v53, v54, s80
	ds_bpermute_b32 v80, v132, v48
	v_add3_u32 v50, v50, v55, s80
	v_and_b32_sdwa v55, v52, v218 dst_sel:DWORD dst_unused:UNUSED_PAD src0_sel:WORD_1 src1_sel:DWORD
	v_and_b32_e32 v53, 0xffff0000, v53
	v_accvgpr_read_b32 v197, a144
	v_add3_u32 v52, v52, v55, s80
	v_or_b32_sdwa v53, v53, v51 dst_sel:DWORD dst_unused:UNUSED_PAD src0_sel:DWORD src1_sel:WORD_1
	v_accvgpr_read_b32 v196, a145
	v_and_b32_e32 v52, 0xffff0000, v52
	v_cndmask_b32_e64 v51, v58, v53, s[2:3]
	v_mul_f32_e32 v68, 0xbfb8aa3b, v197
	v_accvgpr_read_b32 v195, a146
	v_or_b32_sdwa v52, v52, v50 dst_sel:DWORD dst_unused:UNUSED_PAD src0_sel:DWORD src1_sel:WORD_1
	ds_bpermute_b32 v54, v132, v51
	s_waitcnt lgkmcnt(2)
	v_cndmask_b32_e64 v51, v74, v81, s[2:3]
	v_exp_f32_e32 v74, v68
	v_mul_f32_e32 v68, 0xbfb8aa3b, v196
	v_cndmask_b32_e64 v50, v59, v52, s[2:3]
	v_exp_f32_e32 v76, v68
	v_mul_f32_e32 v68, 0xbfb8aa3b, v195
	ds_bpermute_b32 v55, v132, v50
	s_waitcnt lgkmcnt(2)
	v_cndmask_b32_e64 v50, v75, v80, s[2:3]
	v_exp_f32_e32 v75, v68
	v_accvgpr_read_b32 v32, a144
	v_accvgpr_read_b32 v34, a146
	v_accvgpr_read_b32 v194, a147
	v_pk_add_f32 v[74:75], v[74:75], 1.0 op_sel_hi:[1,0]
	v_mul_f32_e32 v68, 0xbfb8aa3b, v194
	v_rcp_f32_e32 v84, v75
	v_exp_f32_e32 v77, v68
	v_add_u32_e32 v100, 64, v133
	v_accvgpr_read_b32 v35, a147
	v_rcp_f32_e32 v88, v74
	v_mul_f32_e32 v75, v34, v84
	v_mad_i64_i32 v[100:101], s[4:5], v100, s1, v[128:129]
	v_pk_add_f32 v[76:77], v[76:77], 1.0 op_sel_hi:[1,0]
	v_lshl_add_u64 v[100:101], v[100:101], 0, v[130:131]
	v_mul_f32_e32 v74, v32, v88
	v_lshl_add_u64 v[64:65], v[100:101], 0, v[192:193]
	v_cndmask_b32_e64 v49, v81, v78, s[2:3]
	v_cndmask_b32_e64 v48, v80, v79, s[2:3]
	v_rcp_f32_e32 v34, v77
	global_store_dwordx4 v[64:65], v[48:51], off
	v_accvgpr_read_b32 v33, a145
	v_accvgpr_read_b32 v191, a148
	s_waitcnt lgkmcnt(1)
	v_cndmask_b32_e64 v49, v54, v58, s[2:3]
	s_waitcnt lgkmcnt(0)
	v_cndmask_b32_e64 v48, v55, v59, s[2:3]
	v_cndmask_b32_e64 v51, v53, v54, s[2:3]
	v_cndmask_b32_e64 v50, v52, v55, s[2:3]
	global_store_dwordx4 v[64:65], v[48:51], off offset:16
	v_accvgpr_read_b32 v63, a47
	v_accvgpr_read_b32 v190, a149
	v_accvgpr_read_b32 v48, a32
	v_mov_b32_e32 v84, v48
	v_accvgpr_read_b32 v50, a34
	v_mov_b32_e32 v85, v50
	v_rcp_f32_e32 v69, v76
	v_mul_f32_e32 v68, 0xbfb8aa3b, v191
	v_mul_f32_e32 v35, v35, v34
	v_accvgpr_read_b32 v189, a150
	v_exp_f32_e32 v78, v68
	v_mul_f32_e32 v68, 0xbfb8aa3b, v190
	v_accvgpr_read_b32 v188, a151
	v_exp_f32_e32 v72, v68
	v_mul_f32_e32 v68, 0xbfb8aa3b, v189
	v_accvgpr_read_b32 v187, a152
	v_exp_f32_e32 v79, v68
	v_mul_f32_e32 v68, 0xbfb8aa3b, v188
	v_accvgpr_read_b32 v186, a153
	v_exp_f32_e32 v73, v68
	v_mul_f32_e32 v68, 0xbfb8aa3b, v187
	v_accvgpr_read_b32 v185, a154
	v_exp_f32_e32 v80, v68
	v_mul_f32_e32 v68, 0xbfb8aa3b, v186
	v_accvgpr_read_b32 v49, a33
	v_exp_f32_e32 v82, v68
	v_mul_f32_e32 v68, 0xbfb8aa3b, v185
	v_accvgpr_read_b32 v51, a35
	v_exp_f32_e32 v81, v68
	v_mul_f32_e32 v34, v33, v69
	v_mov_b32_e32 v50, v49
	v_pk_mul_f32 v[32:33], v[34:35], v[50:51]
	v_accvgpr_read_b32 v42, a154
	v_and_b32_sdwa v48, v33, v218 dst_sel:DWORD dst_unused:UNUSED_PAD src0_sel:WORD_1 src1_sel:DWORD
	v_and_b32_sdwa v49, v32, v218 dst_sel:DWORD dst_unused:UNUSED_PAD src0_sel:WORD_1 src1_sel:DWORD
	v_add3_u32 v33, v33, v48, s80
	v_add3_u32 v48, v32, v49, s80
	v_and_b32_e32 v49, 0xffff0000, v33
	v_pk_add_f32 v[32:33], v[80:81], 1.0 op_sel_hi:[1,0]
	v_pk_mul_f32 v[74:75], v[74:75], v[84:85]
	v_rcp_f32_e32 v51, v33
	v_and_b32_sdwa v34, v75, v218 dst_sel:DWORD dst_unused:UNUSED_PAD src0_sel:WORD_1 src1_sel:DWORD
	v_and_b32_sdwa v35, v74, v218 dst_sel:DWORD dst_unused:UNUSED_PAD src0_sel:WORD_1 src1_sel:DWORD
	v_add3_u32 v34, v75, v34, s80
	v_add3_u32 v35, v74, v35, s80
	v_or_b32_sdwa v74, v49, v34 dst_sel:DWORD dst_unused:UNUSED_PAD src0_sel:DWORD src1_sel:WORD_1
	v_and_b32_e32 v48, 0xffff0000, v48
	v_or_b32_sdwa v75, v48, v35 dst_sel:DWORD dst_unused:UNUSED_PAD src0_sel:DWORD src1_sel:WORD_1
	v_accvgpr_read_b32 v40, a152
	v_rcp_f32_e32 v49, v32
	v_mul_f32_e32 v33, v42, v51
	v_accvgpr_read_b32 v184, a155
	v_mul_f32_e32 v68, 0xbfb8aa3b, v184
	v_exp_f32_e32 v83, v68
	v_accvgpr_read_b32 v43, a155
	v_mul_f32_e32 v32, v40, v49
	v_pk_add_f32 v[34:35], v[82:83], 1.0 op_sel_hi:[1,0]
	v_accvgpr_read_b32 v58, a42
	v_rcp_f32_e32 v42, v35
	v_accvgpr_read_b32 v56, a40
	v_mov_b32_e32 v48, v56
	v_mov_b32_e32 v49, v58
	v_pk_mul_f32 v[32:33], v[32:33], v[48:49]
	v_accvgpr_read_b32 v41, a153
	v_rcp_f32_e32 v50, v34
	v_mul_f32_e32 v35, v43, v42
	v_accvgpr_read_b32 v57, a41
	v_accvgpr_read_b32 v59, a43
	v_mul_f32_e32 v34, v41, v50
	v_mov_b32_e32 v58, v57
	v_pk_mul_f32 v[34:35], v[34:35], v[58:59]
	v_and_b32_sdwa v40, v33, v218 dst_sel:DWORD dst_unused:UNUSED_PAD src0_sel:WORD_1 src1_sel:DWORD
	v_and_b32_sdwa v41, v32, v218 dst_sel:DWORD dst_unused:UNUSED_PAD src0_sel:WORD_1 src1_sel:DWORD
	v_add3_u32 v32, v32, v41, s80
	v_add3_u32 v33, v33, v40, s80
	v_and_b32_sdwa v40, v35, v218 dst_sel:DWORD dst_unused:UNUSED_PAD src0_sel:WORD_1 src1_sel:DWORD
	v_and_b32_sdwa v41, v34, v218 dst_sel:DWORD dst_unused:UNUSED_PAD src0_sel:WORD_1 src1_sel:DWORD
	v_add3_u32 v35, v35, v40, s80
	v_add3_u32 v34, v34, v41, s80
	v_and_b32_e32 v35, 0xffff0000, v35
	v_and_b32_e32 v34, 0xffff0000, v34
	v_accvgpr_read_b32 v38, a150
	v_or_b32_sdwa v48, v35, v33 dst_sel:DWORD dst_unused:UNUSED_PAD src0_sel:DWORD src1_sel:WORD_1
	v_or_b32_sdwa v49, v34, v32 dst_sel:DWORD dst_unused:UNUSED_PAD src0_sel:DWORD src1_sel:WORD_1
	v_pk_add_f32 v[34:35], v[78:79], 1.0 op_sel_hi:[1,0]
	v_accvgpr_read_b32 v36, a148
	v_rcp_f32_e32 v41, v35
	v_accvgpr_read_b32 v39, a151
	v_accvgpr_read_b32 v54, a38
	v_accvgpr_read_b32 v52, a36
	v_rcp_f32_e32 v56, v34
	v_mul_f32_e32 v35, v38, v41
	v_mov_b32_e32 v43, v54
	v_pk_add_f32 v[40:41], v[72:73], 1.0 op_sel_hi:[1,0]
	v_mul_f32_e32 v34, v36, v56
	v_rcp_f32_e32 v38, v41
	v_mov_b32_e32 v42, v52
	v_pk_mul_f32 v[34:35], v[34:35], v[42:43]
	v_accvgpr_read_b32 v37, a149
	v_rcp_f32_e32 v52, v40
	v_mul_f32_e32 v39, v39, v38
	v_accvgpr_read_b32 v183, a156
	v_accvgpr_read_b32 v181, a158
	v_accvgpr_read_b32 v53, a37
	v_mul_f32_e32 v68, 0xbfb8aa3b, v183
	v_mul_f32_e32 v71, 0xbfb8aa3b, v181
	v_accvgpr_read_b32 v55, a39
	v_exp_f32_e32 v70, v68
	v_exp_f32_e32 v71, v71
	v_mul_f32_e32 v38, v37, v52
	v_mov_b32_e32 v54, v53
	v_pk_mul_f32 v[36:37], v[38:39], v[54:55]
	v_and_b32_sdwa v39, v34, v218 dst_sel:DWORD dst_unused:UNUSED_PAD src0_sel:WORD_1 src1_sel:DWORD
	v_and_b32_sdwa v38, v35, v218 dst_sel:DWORD dst_unused:UNUSED_PAD src0_sel:WORD_1 src1_sel:DWORD
	v_add3_u32 v39, v34, v39, s80
	v_and_b32_sdwa v34, v37, v218 dst_sel:DWORD dst_unused:UNUSED_PAD src0_sel:WORD_1 src1_sel:DWORD
	v_add3_u32 v38, v35, v38, s80
	v_and_b32_sdwa v35, v36, v218 dst_sel:DWORD dst_unused:UNUSED_PAD src0_sel:WORD_1 src1_sel:DWORD
	v_add3_u32 v34, v37, v34, s80
	v_accvgpr_read_b32 v46, a158
	v_add3_u32 v36, v36, v35, s80
	v_and_b32_e32 v37, 0xffff0000, v34
	v_pk_add_f32 v[34:35], v[70:71], 1.0 op_sel_hi:[1,0]
	v_and_b32_e32 v36, 0xffff0000, v36
	v_rcp_f32_e32 v41, v35
	v_or_b32_sdwa v43, v36, v39 dst_sel:DWORD dst_unused:UNUSED_PAD src0_sel:DWORD src1_sel:WORD_1
	v_or_b32_sdwa v42, v37, v38 dst_sel:DWORD dst_unused:UNUSED_PAD src0_sel:DWORD src1_sel:WORD_1
	v_accvgpr_read_b32 v44, a156
	v_rcp_f32_e32 v39, v34
	v_mul_f32_e32 v35, v46, v41
	v_accvgpr_read_b32 v182, a157
	v_accvgpr_read_b32 v180, a159
	v_mul_f32_e32 v68, 0xbfb8aa3b, v182
	v_mul_f32_e32 v86, 0xbfb8aa3b, v180
	v_exp_f32_e32 v68, v68
	v_exp_f32_e32 v69, v86
	v_accvgpr_read_b32 v47, a159
	v_mul_f32_e32 v34, v44, v39
	v_pk_add_f32 v[36:37], v[68:69], 1.0 op_sel_hi:[1,0]
	v_accvgpr_read_b32 v62, a46
	v_rcp_f32_e32 v41, v37
	v_accvgpr_read_b32 v60, a44
	v_mov_b32_e32 v38, v60
	v_mov_b32_e32 v39, v62
	v_pk_mul_f32 v[34:35], v[34:35], v[38:39]
	v_accvgpr_read_b32 v45, a157
	v_rcp_f32_e32 v44, v36
	v_mul_f32_e32 v37, v47, v41
	v_accvgpr_read_b32 v61, a45
	v_mul_f32_e32 v36, v45, v44
	v_mov_b32_e32 v62, v61
	v_cndmask_b32_e64 v33, v74, v48, s[2:3]
	v_pk_mul_f32 v[36:37], v[36:37], v[62:63]
	v_and_b32_sdwa v38, v35, v218 dst_sel:DWORD dst_unused:UNUSED_PAD src0_sel:WORD_1 src1_sel:DWORD
	ds_bpermute_b32 v51, v132, v33
	v_add3_u32 v35, v35, v38, s80
	v_and_b32_sdwa v38, v37, v218 dst_sel:DWORD dst_unused:UNUSED_PAD src0_sel:WORD_1 src1_sel:DWORD
	v_add3_u32 v37, v37, v38, s80
	v_and_b32_e32 v37, 0xffff0000, v37
	v_or_b32_sdwa v37, v37, v35 dst_sel:DWORD dst_unused:UNUSED_PAD src0_sel:DWORD src1_sel:WORD_1
	v_accvgpr_read_b32 v179, a160
	v_cndmask_b32_e64 v35, v42, v37, s[2:3]
	v_accvgpr_read_b32 v178, a161
	ds_bpermute_b32 v38, v132, v35
	s_waitcnt lgkmcnt(1)
	v_cndmask_b32_e64 v35, v48, v51, s[2:3]
	v_mul_f32_e32 v48, 0xbfb8aa3b, v179
	v_accvgpr_read_b32 v177, a162
	v_exp_f32_e32 v54, v48
	v_mul_f32_e32 v48, 0xbfb8aa3b, v178
	v_cndmask_b32_e64 v32, v75, v49, s[2:3]
	v_and_b32_sdwa v39, v34, v218 dst_sel:DWORD dst_unused:UNUSED_PAD src0_sel:WORD_1 src1_sel:DWORD
	v_exp_f32_e32 v56, v48
	v_mul_f32_e32 v48, 0xbfb8aa3b, v177
	ds_bpermute_b32 v50, v132, v32
	v_add3_u32 v34, v34, v39, s80
	v_and_b32_sdwa v39, v36, v218 dst_sel:DWORD dst_unused:UNUSED_PAD src0_sel:WORD_1 src1_sel:DWORD
	v_exp_f32_e32 v55, v48
	v_add3_u32 v36, v36, v39, s80
	v_and_b32_e32 v36, 0xffff0000, v36
	s_waitcnt vmcnt(6)
	v_accvgpr_read_b32 v16, a160
	v_or_b32_sdwa v36, v36, v34 dst_sel:DWORD dst_unused:UNUSED_PAD src0_sel:DWORD src1_sel:WORD_1
	v_accvgpr_read_b32 v18, a162
	v_cndmask_b32_e64 v34, v43, v36, s[2:3]
	v_pk_add_f32 v[54:55], v[54:55], 1.0 op_sel_hi:[1,0]
	ds_bpermute_b32 v39, v132, v34
	s_waitcnt lgkmcnt(1)
	v_cndmask_b32_e64 v34, v49, v50, s[2:3]
	v_rcp_f32_e32 v68, v55
	v_accvgpr_read_b32 v176, a163
	v_mul_f32_e32 v48, 0xbfb8aa3b, v176
	v_exp_f32_e32 v57, v48
	v_rcp_f32_e32 v72, v54
	v_mul_f32_e32 v55, v18, v68
	v_accvgpr_read_b32 v19, a163
	v_pk_add_f32 v[56:57], v[56:57], 1.0 op_sel_hi:[1,0]
	v_mul_f32_e32 v54, v16, v72
	v_cndmask_b32_e64 v33, v51, v74, s[2:3]
	v_cndmask_b32_e64 v32, v50, v75, s[2:3]
	v_rcp_f32_e32 v18, v57
	global_store_dwordx4 v[96:97], v[32:35], off offset:64
	v_accvgpr_read_b32 v17, a161
	v_accvgpr_read_b32 v175, a164
	v_cndmask_b32_e64 v33, v38, v42, s[2:3]
	s_waitcnt lgkmcnt(0)
	v_cndmask_b32_e64 v32, v39, v43, s[2:3]
	v_cndmask_b32_e64 v35, v37, v38, s[2:3]
	v_cndmask_b32_e64 v34, v36, v39, s[2:3]
	global_store_dwordx4 v[96:97], v[32:35], off offset:80
	v_accvgpr_read_b32 v47, a31
	v_accvgpr_read_b32 v174, a165
	v_accvgpr_read_b32 v32, a16
	v_mov_b32_e32 v68, v32
	v_accvgpr_read_b32 v34, a18
	v_mov_b32_e32 v69, v34
	v_rcp_f32_e32 v49, v56
	v_mul_f32_e32 v48, 0xbfb8aa3b, v175
	v_mul_f32_e32 v19, v19, v18
	v_accvgpr_read_b32 v173, a166
	v_exp_f32_e32 v58, v48
	v_mul_f32_e32 v48, 0xbfb8aa3b, v174
	v_accvgpr_read_b32 v172, a167
	v_exp_f32_e32 v52, v48
	v_mul_f32_e32 v48, 0xbfb8aa3b, v173
	v_accvgpr_read_b32 v171, a168
	v_exp_f32_e32 v59, v48
	v_mul_f32_e32 v48, 0xbfb8aa3b, v172
	v_accvgpr_read_b32 v170, a169
	v_exp_f32_e32 v53, v48
	v_mul_f32_e32 v48, 0xbfb8aa3b, v171
	v_accvgpr_read_b32 v169, a170
	v_exp_f32_e32 v60, v48
	v_mul_f32_e32 v48, 0xbfb8aa3b, v170
	v_accvgpr_read_b32 v33, a17
	v_exp_f32_e32 v62, v48
	v_mul_f32_e32 v48, 0xbfb8aa3b, v169
	v_accvgpr_read_b32 v35, a19
	v_exp_f32_e32 v61, v48
	v_mul_f32_e32 v18, v17, v49
	v_mov_b32_e32 v34, v33
	v_pk_mul_f32 v[16:17], v[18:19], v[34:35]
	v_accvgpr_read_b32 v26, a170
	v_and_b32_sdwa v32, v17, v218 dst_sel:DWORD dst_unused:UNUSED_PAD src0_sel:WORD_1 src1_sel:DWORD
	v_and_b32_sdwa v33, v16, v218 dst_sel:DWORD dst_unused:UNUSED_PAD src0_sel:WORD_1 src1_sel:DWORD
	v_add3_u32 v17, v17, v32, s80
	v_add3_u32 v32, v16, v33, s80
	v_and_b32_e32 v33, 0xffff0000, v17
	v_pk_add_f32 v[16:17], v[60:61], 1.0 op_sel_hi:[1,0]
	v_pk_mul_f32 v[54:55], v[54:55], v[68:69]
	v_rcp_f32_e32 v35, v17
	v_and_b32_sdwa v18, v55, v218 dst_sel:DWORD dst_unused:UNUSED_PAD src0_sel:WORD_1 src1_sel:DWORD
	v_and_b32_sdwa v19, v54, v218 dst_sel:DWORD dst_unused:UNUSED_PAD src0_sel:WORD_1 src1_sel:DWORD
	v_add3_u32 v18, v55, v18, s80
	v_add3_u32 v19, v54, v19, s80
	v_or_b32_sdwa v54, v33, v18 dst_sel:DWORD dst_unused:UNUSED_PAD src0_sel:DWORD src1_sel:WORD_1
	v_and_b32_e32 v32, 0xffff0000, v32
	v_or_b32_sdwa v55, v32, v19 dst_sel:DWORD dst_unused:UNUSED_PAD src0_sel:DWORD src1_sel:WORD_1
	v_accvgpr_read_b32 v24, a168
	v_rcp_f32_e32 v33, v16
	v_mul_f32_e32 v17, v26, v35
	v_accvgpr_read_b32 v168, a171
	v_mul_f32_e32 v48, 0xbfb8aa3b, v168
	v_exp_f32_e32 v63, v48
	v_accvgpr_read_b32 v27, a171
	v_mul_f32_e32 v16, v24, v33
	v_pk_add_f32 v[18:19], v[62:63], 1.0 op_sel_hi:[1,0]
	v_accvgpr_read_b32 v42, a26
	v_rcp_f32_e32 v26, v19
	v_accvgpr_read_b32 v40, a24
	v_mov_b32_e32 v32, v40
	v_mov_b32_e32 v33, v42
	v_pk_mul_f32 v[16:17], v[16:17], v[32:33]
	v_accvgpr_read_b32 v25, a169
	v_rcp_f32_e32 v34, v18
	v_mul_f32_e32 v19, v27, v26
	v_accvgpr_read_b32 v41, a25
	v_accvgpr_read_b32 v43, a27
	v_mul_f32_e32 v18, v25, v34
	v_mov_b32_e32 v42, v41
	v_pk_mul_f32 v[18:19], v[18:19], v[42:43]
	v_and_b32_sdwa v24, v17, v218 dst_sel:DWORD dst_unused:UNUSED_PAD src0_sel:WORD_1 src1_sel:DWORD
	v_and_b32_sdwa v25, v16, v218 dst_sel:DWORD dst_unused:UNUSED_PAD src0_sel:WORD_1 src1_sel:DWORD
	v_add3_u32 v16, v16, v25, s80
	v_add3_u32 v17, v17, v24, s80
	v_and_b32_sdwa v24, v19, v218 dst_sel:DWORD dst_unused:UNUSED_PAD src0_sel:WORD_1 src1_sel:DWORD
	v_and_b32_sdwa v25, v18, v218 dst_sel:DWORD dst_unused:UNUSED_PAD src0_sel:WORD_1 src1_sel:DWORD
	v_add3_u32 v19, v19, v24, s80
	v_add3_u32 v18, v18, v25, s80
	v_and_b32_e32 v19, 0xffff0000, v19
	v_and_b32_e32 v18, 0xffff0000, v18
	v_accvgpr_read_b32 v22, a166
	v_or_b32_sdwa v32, v19, v17 dst_sel:DWORD dst_unused:UNUSED_PAD src0_sel:DWORD src1_sel:WORD_1
	v_or_b32_sdwa v33, v18, v16 dst_sel:DWORD dst_unused:UNUSED_PAD src0_sel:DWORD src1_sel:WORD_1
	v_pk_add_f32 v[18:19], v[58:59], 1.0 op_sel_hi:[1,0]
	v_accvgpr_read_b32 v20, a164
	v_rcp_f32_e32 v25, v19
	v_accvgpr_read_b32 v23, a167
	v_accvgpr_read_b32 v38, a22
	v_accvgpr_read_b32 v36, a20
	v_rcp_f32_e32 v40, v18
	v_mul_f32_e32 v19, v22, v25
	v_mov_b32_e32 v27, v38
	v_pk_add_f32 v[24:25], v[52:53], 1.0 op_sel_hi:[1,0]
	v_mul_f32_e32 v18, v20, v40
	v_rcp_f32_e32 v22, v25
	v_mov_b32_e32 v26, v36
	v_pk_mul_f32 v[18:19], v[18:19], v[26:27]
	v_accvgpr_read_b32 v21, a165
	v_rcp_f32_e32 v36, v24
	v_mul_f32_e32 v23, v23, v22
	v_accvgpr_read_b32 v167, a172
	v_accvgpr_read_b32 v165, a174
	v_accvgpr_read_b32 v37, a21
	v_mul_f32_e32 v48, 0xbfb8aa3b, v167
	v_mul_f32_e32 v51, 0xbfb8aa3b, v165
	v_accvgpr_read_b32 v39, a23
	v_exp_f32_e32 v50, v48
	v_exp_f32_e32 v51, v51
	v_mul_f32_e32 v22, v21, v36
	v_mov_b32_e32 v38, v37
	v_pk_mul_f32 v[20:21], v[22:23], v[38:39]
	v_and_b32_sdwa v23, v18, v218 dst_sel:DWORD dst_unused:UNUSED_PAD src0_sel:WORD_1 src1_sel:DWORD
	v_and_b32_sdwa v22, v19, v218 dst_sel:DWORD dst_unused:UNUSED_PAD src0_sel:WORD_1 src1_sel:DWORD
	v_add3_u32 v23, v18, v23, s80
	v_and_b32_sdwa v18, v21, v218 dst_sel:DWORD dst_unused:UNUSED_PAD src0_sel:WORD_1 src1_sel:DWORD
	v_add3_u32 v22, v19, v22, s80
	v_and_b32_sdwa v19, v20, v218 dst_sel:DWORD dst_unused:UNUSED_PAD src0_sel:WORD_1 src1_sel:DWORD
	v_add3_u32 v18, v21, v18, s80
	v_accvgpr_read_b32 v30, a174
	v_add3_u32 v20, v20, v19, s80
	v_and_b32_e32 v21, 0xffff0000, v18
	v_pk_add_f32 v[18:19], v[50:51], 1.0 op_sel_hi:[1,0]
	v_and_b32_e32 v20, 0xffff0000, v20
	v_rcp_f32_e32 v25, v19
	v_or_b32_sdwa v27, v20, v23 dst_sel:DWORD dst_unused:UNUSED_PAD src0_sel:DWORD src1_sel:WORD_1
	v_or_b32_sdwa v26, v21, v22 dst_sel:DWORD dst_unused:UNUSED_PAD src0_sel:DWORD src1_sel:WORD_1
	v_accvgpr_read_b32 v28, a172
	v_rcp_f32_e32 v23, v18
	v_mul_f32_e32 v19, v30, v25
	v_accvgpr_read_b32 v166, a173
	v_accvgpr_read_b32 v164, a175
	v_mul_f32_e32 v48, 0xbfb8aa3b, v166
	v_mul_f32_e32 v70, 0xbfb8aa3b, v164
	v_exp_f32_e32 v48, v48
	v_exp_f32_e32 v49, v70
	v_accvgpr_read_b32 v31, a175
	v_mul_f32_e32 v18, v28, v23
	v_pk_add_f32 v[20:21], v[48:49], 1.0 op_sel_hi:[1,0]
	v_accvgpr_read_b32 v46, a30
	v_rcp_f32_e32 v25, v21
	v_accvgpr_read_b32 v44, a28
	v_mov_b32_e32 v22, v44
	v_mov_b32_e32 v23, v46
	v_pk_mul_f32 v[18:19], v[18:19], v[22:23]
	v_accvgpr_read_b32 v29, a173
	v_rcp_f32_e32 v28, v20
	v_mul_f32_e32 v21, v31, v25
	v_accvgpr_read_b32 v45, a29
	v_mul_f32_e32 v20, v29, v28
	v_mov_b32_e32 v46, v45
	v_cndmask_b32_e64 v17, v54, v32, s[2:3]
	v_pk_mul_f32 v[20:21], v[20:21], v[46:47]
	v_and_b32_sdwa v22, v19, v218 dst_sel:DWORD dst_unused:UNUSED_PAD src0_sel:WORD_1 src1_sel:DWORD
	ds_bpermute_b32 v35, v132, v17
	v_add3_u32 v19, v19, v22, s80
	v_and_b32_sdwa v22, v21, v218 dst_sel:DWORD dst_unused:UNUSED_PAD src0_sel:WORD_1 src1_sel:DWORD
	v_add3_u32 v21, v21, v22, s80
	v_and_b32_e32 v21, 0xffff0000, v21
	v_or_b32_sdwa v21, v21, v19 dst_sel:DWORD dst_unused:UNUSED_PAD src0_sel:DWORD src1_sel:WORD_1
	v_accvgpr_read_b32 v159, a176
	v_cndmask_b32_e64 v19, v26, v21, s[2:3]
	v_accvgpr_read_b32 v158, a177
	ds_bpermute_b32 v22, v132, v19
	s_waitcnt lgkmcnt(1)
	v_cndmask_b32_e64 v19, v32, v35, s[2:3]
	v_mul_f32_e32 v32, 0xbfb8aa3b, v159
	v_accvgpr_read_b32 v157, a178
	v_exp_f32_e32 v38, v32
	v_mul_f32_e32 v32, 0xbfb8aa3b, v158
	v_cndmask_b32_e64 v16, v55, v33, s[2:3]
	v_and_b32_sdwa v23, v18, v218 dst_sel:DWORD dst_unused:UNUSED_PAD src0_sel:WORD_1 src1_sel:DWORD
	v_exp_f32_e32 v40, v32
	v_mul_f32_e32 v32, 0xbfb8aa3b, v157
	ds_bpermute_b32 v34, v132, v16
	v_add3_u32 v18, v18, v23, s80
	v_and_b32_sdwa v23, v20, v218 dst_sel:DWORD dst_unused:UNUSED_PAD src0_sel:WORD_1 src1_sel:DWORD
	v_exp_f32_e32 v39, v32
	v_add3_u32 v20, v20, v23, s80
	v_and_b32_e32 v20, 0xffff0000, v20
	v_accvgpr_read_b32 v0, a176
	v_or_b32_sdwa v20, v20, v18 dst_sel:DWORD dst_unused:UNUSED_PAD src0_sel:DWORD src1_sel:WORD_1
	v_accvgpr_read_b32 v2, a178
	v_cndmask_b32_e64 v18, v27, v20, s[2:3]
	v_pk_add_f32 v[38:39], v[38:39], 1.0 op_sel_hi:[1,0]
	ds_bpermute_b32 v23, v132, v18
	s_waitcnt lgkmcnt(1)
	v_cndmask_b32_e64 v18, v33, v34, s[2:3]
	v_rcp_f32_e32 v48, v39
	v_accvgpr_read_b32 v156, a179
	v_mul_f32_e32 v32, 0xbfb8aa3b, v156
	v_exp_f32_e32 v41, v32
	v_rcp_f32_e32 v52, v38
	v_mul_f32_e32 v39, v2, v48
	v_accvgpr_read_b32 v3, a179
	v_pk_add_f32 v[40:41], v[40:41], 1.0 op_sel_hi:[1,0]
	v_mul_f32_e32 v38, v0, v52
	v_cndmask_b32_e64 v17, v35, v54, s[2:3]
	v_cndmask_b32_e64 v16, v34, v55, s[2:3]
	v_rcp_f32_e32 v2, v41
	global_store_dwordx4 v[66:67], v[16:19], off offset:64
	v_accvgpr_read_b32 v1, a177
	v_accvgpr_read_b32 v155, a180
	v_cndmask_b32_e64 v17, v22, v26, s[2:3]
	s_waitcnt lgkmcnt(0)
	v_cndmask_b32_e64 v16, v23, v27, s[2:3]
	v_cndmask_b32_e64 v19, v21, v22, s[2:3]
	v_cndmask_b32_e64 v18, v20, v23, s[2:3]
	global_store_dwordx4 v[66:67], v[16:19], off offset:80
	v_accvgpr_read_b32 v31, a15
	v_accvgpr_read_b32 v154, a181
	v_accvgpr_read_b32 v16, a0
	v_mov_b32_e32 v48, v16
	v_accvgpr_read_b32 v18, a2
	v_mov_b32_e32 v49, v18
	v_rcp_f32_e32 v33, v40
	v_mul_f32_e32 v32, 0xbfb8aa3b, v155
	v_mul_f32_e32 v3, v3, v2
	v_accvgpr_read_b32 v153, a182
	v_exp_f32_e32 v42, v32
	v_mul_f32_e32 v32, 0xbfb8aa3b, v154
	v_accvgpr_read_b32 v152, a183
	v_exp_f32_e32 v36, v32
	v_mul_f32_e32 v32, 0xbfb8aa3b, v153
	v_accvgpr_read_b32 v151, a184
	v_exp_f32_e32 v43, v32
	v_mul_f32_e32 v32, 0xbfb8aa3b, v152
	v_accvgpr_read_b32 v150, a185
	v_exp_f32_e32 v37, v32
	v_mul_f32_e32 v32, 0xbfb8aa3b, v151
	v_accvgpr_read_b32 v149, a186
	v_exp_f32_e32 v44, v32
	v_mul_f32_e32 v32, 0xbfb8aa3b, v150
	v_accvgpr_read_b32 v17, a1
	v_exp_f32_e32 v46, v32
	v_mul_f32_e32 v32, 0xbfb8aa3b, v149
	v_accvgpr_read_b32 v19, a3
	v_exp_f32_e32 v45, v32
	v_mul_f32_e32 v2, v1, v33
	v_mov_b32_e32 v18, v17
	v_pk_mul_f32 v[0:1], v[2:3], v[18:19]
	v_accvgpr_read_b32 v10, a186
	v_and_b32_sdwa v16, v1, v218 dst_sel:DWORD dst_unused:UNUSED_PAD src0_sel:WORD_1 src1_sel:DWORD
	v_and_b32_sdwa v17, v0, v218 dst_sel:DWORD dst_unused:UNUSED_PAD src0_sel:WORD_1 src1_sel:DWORD
	v_add3_u32 v1, v1, v16, s80
	v_add3_u32 v16, v0, v17, s80
	v_and_b32_e32 v17, 0xffff0000, v1
	v_pk_add_f32 v[0:1], v[44:45], 1.0 op_sel_hi:[1,0]
	v_pk_mul_f32 v[38:39], v[38:39], v[48:49]
	v_rcp_f32_e32 v19, v1
	v_and_b32_sdwa v2, v39, v218 dst_sel:DWORD dst_unused:UNUSED_PAD src0_sel:WORD_1 src1_sel:DWORD
	v_and_b32_sdwa v3, v38, v218 dst_sel:DWORD dst_unused:UNUSED_PAD src0_sel:WORD_1 src1_sel:DWORD
	v_add3_u32 v2, v39, v2, s80
	v_add3_u32 v3, v38, v3, s80
	v_or_b32_sdwa v38, v17, v2 dst_sel:DWORD dst_unused:UNUSED_PAD src0_sel:DWORD src1_sel:WORD_1
	v_and_b32_e32 v16, 0xffff0000, v16
	v_or_b32_sdwa v39, v16, v3 dst_sel:DWORD dst_unused:UNUSED_PAD src0_sel:DWORD src1_sel:WORD_1
	v_accvgpr_read_b32 v8, a184
	v_rcp_f32_e32 v17, v0
	v_mul_f32_e32 v1, v10, v19
	v_accvgpr_read_b32 v148, a187
	v_mul_f32_e32 v32, 0xbfb8aa3b, v148
	v_exp_f32_e32 v47, v32
	v_accvgpr_read_b32 v11, a187
	v_mul_f32_e32 v0, v8, v17
	v_pk_add_f32 v[2:3], v[46:47], 1.0 op_sel_hi:[1,0]
	v_accvgpr_read_b32 v26, a10
	v_rcp_f32_e32 v10, v3
	v_accvgpr_read_b32 v24, a8
	v_mov_b32_e32 v16, v24
	v_mov_b32_e32 v17, v26
	v_pk_mul_f32 v[0:1], v[0:1], v[16:17]
	v_accvgpr_read_b32 v9, a185
	v_rcp_f32_e32 v18, v2
	v_mul_f32_e32 v3, v11, v10
	v_accvgpr_read_b32 v25, a9
	v_accvgpr_read_b32 v27, a11
	v_mul_f32_e32 v2, v9, v18
	v_mov_b32_e32 v26, v25
	v_pk_mul_f32 v[2:3], v[2:3], v[26:27]
	v_and_b32_sdwa v8, v1, v218 dst_sel:DWORD dst_unused:UNUSED_PAD src0_sel:WORD_1 src1_sel:DWORD
	v_and_b32_sdwa v9, v0, v218 dst_sel:DWORD dst_unused:UNUSED_PAD src0_sel:WORD_1 src1_sel:DWORD
	v_add3_u32 v0, v0, v9, s80
	v_add3_u32 v1, v1, v8, s80
	v_and_b32_sdwa v8, v3, v218 dst_sel:DWORD dst_unused:UNUSED_PAD src0_sel:WORD_1 src1_sel:DWORD
	v_and_b32_sdwa v9, v2, v218 dst_sel:DWORD dst_unused:UNUSED_PAD src0_sel:WORD_1 src1_sel:DWORD
	v_add3_u32 v3, v3, v8, s80
	v_add3_u32 v2, v2, v9, s80
	v_and_b32_e32 v3, 0xffff0000, v3
	v_and_b32_e32 v2, 0xffff0000, v2
	v_accvgpr_read_b32 v6, a182
	v_or_b32_sdwa v16, v3, v1 dst_sel:DWORD dst_unused:UNUSED_PAD src0_sel:DWORD src1_sel:WORD_1
	v_or_b32_sdwa v17, v2, v0 dst_sel:DWORD dst_unused:UNUSED_PAD src0_sel:DWORD src1_sel:WORD_1
	v_pk_add_f32 v[2:3], v[42:43], 1.0 op_sel_hi:[1,0]
	v_accvgpr_read_b32 v4, a180
	v_rcp_f32_e32 v9, v3
	v_accvgpr_read_b32 v7, a183
	v_accvgpr_read_b32 v22, a6
	v_accvgpr_read_b32 v20, a4
	v_rcp_f32_e32 v24, v2
	v_mul_f32_e32 v3, v6, v9
	v_mov_b32_e32 v11, v22
	v_pk_add_f32 v[8:9], v[36:37], 1.0 op_sel_hi:[1,0]
	v_mul_f32_e32 v2, v4, v24
	v_rcp_f32_e32 v6, v9
	v_mov_b32_e32 v10, v20
	v_pk_mul_f32 v[2:3], v[2:3], v[10:11]
	v_accvgpr_read_b32 v5, a181
	v_rcp_f32_e32 v20, v8
	v_mul_f32_e32 v7, v7, v6
	v_accvgpr_read_b32 v147, a188
	v_accvgpr_read_b32 v145, a190
	v_accvgpr_read_b32 v21, a5
	v_mul_f32_e32 v32, 0xbfb8aa3b, v147
	v_mul_f32_e32 v35, 0xbfb8aa3b, v145
	v_accvgpr_read_b32 v23, a7
	v_exp_f32_e32 v34, v32
	v_exp_f32_e32 v35, v35
	v_mul_f32_e32 v6, v5, v20
	v_mov_b32_e32 v22, v21
	v_pk_mul_f32 v[4:5], v[6:7], v[22:23]
	v_and_b32_sdwa v7, v2, v218 dst_sel:DWORD dst_unused:UNUSED_PAD src0_sel:WORD_1 src1_sel:DWORD
	v_and_b32_sdwa v6, v3, v218 dst_sel:DWORD dst_unused:UNUSED_PAD src0_sel:WORD_1 src1_sel:DWORD
	v_add3_u32 v7, v2, v7, s80
	v_and_b32_sdwa v2, v5, v218 dst_sel:DWORD dst_unused:UNUSED_PAD src0_sel:WORD_1 src1_sel:DWORD
	v_add3_u32 v6, v3, v6, s80
	v_and_b32_sdwa v3, v4, v218 dst_sel:DWORD dst_unused:UNUSED_PAD src0_sel:WORD_1 src1_sel:DWORD
	v_add3_u32 v2, v5, v2, s80
	v_accvgpr_read_b32 v14, a190
	v_add3_u32 v4, v4, v3, s80
	v_and_b32_e32 v5, 0xffff0000, v2
	v_pk_add_f32 v[2:3], v[34:35], 1.0 op_sel_hi:[1,0]
	v_and_b32_e32 v4, 0xffff0000, v4
	v_rcp_f32_e32 v9, v3
	v_or_b32_sdwa v11, v4, v7 dst_sel:DWORD dst_unused:UNUSED_PAD src0_sel:DWORD src1_sel:WORD_1
	v_or_b32_sdwa v10, v5, v6 dst_sel:DWORD dst_unused:UNUSED_PAD src0_sel:DWORD src1_sel:WORD_1
	v_accvgpr_read_b32 v12, a188
	v_rcp_f32_e32 v7, v2
	v_mul_f32_e32 v3, v14, v9
	v_accvgpr_read_b32 v146, a189
	v_accvgpr_read_b32 v144, a191
	v_mul_f32_e32 v32, 0xbfb8aa3b, v146
	v_mul_f32_e32 v50, 0xbfb8aa3b, v144
	v_exp_f32_e32 v32, v32
	v_exp_f32_e32 v33, v50
	v_accvgpr_read_b32 v15, a191
	v_mul_f32_e32 v2, v12, v7
	v_pk_add_f32 v[4:5], v[32:33], 1.0 op_sel_hi:[1,0]
	v_accvgpr_read_b32 v30, a14
	v_rcp_f32_e32 v9, v5
	v_accvgpr_read_b32 v28, a12
	v_mov_b32_e32 v6, v28
	v_mov_b32_e32 v7, v30
	v_pk_mul_f32 v[2:3], v[2:3], v[6:7]
	v_accvgpr_read_b32 v13, a189
	v_rcp_f32_e32 v12, v4
	v_mul_f32_e32 v5, v15, v9
	v_accvgpr_read_b32 v29, a13
	v_mul_f32_e32 v4, v13, v12
	v_mov_b32_e32 v30, v29
	v_pk_mul_f32 v[4:5], v[4:5], v[30:31]
	v_and_b32_sdwa v6, v3, v218 dst_sel:DWORD dst_unused:UNUSED_PAD src0_sel:WORD_1 src1_sel:DWORD
	v_and_b32_sdwa v7, v2, v218 dst_sel:DWORD dst_unused:UNUSED_PAD src0_sel:WORD_1 src1_sel:DWORD
	v_add3_u32 v2, v2, v7, s80
	v_add3_u32 v3, v3, v6, s80
	v_and_b32_sdwa v6, v5, v218 dst_sel:DWORD dst_unused:UNUSED_PAD src0_sel:WORD_1 src1_sel:DWORD
	v_and_b32_sdwa v7, v4, v218 dst_sel:DWORD dst_unused:UNUSED_PAD src0_sel:WORD_1 src1_sel:DWORD
	v_add3_u32 v5, v5, v6, s80
	v_add3_u32 v4, v4, v7, s80
	v_and_b32_e32 v5, 0xffff0000, v5
	v_and_b32_e32 v4, 0xffff0000, v4
	v_cndmask_b32_e64 v0, v39, v17, s[2:3]
	v_cndmask_b32_e64 v1, v38, v16, s[2:3]
	v_or_b32_sdwa v5, v5, v3 dst_sel:DWORD dst_unused:UNUSED_PAD src0_sel:DWORD src1_sel:WORD_1
	v_or_b32_sdwa v4, v4, v2 dst_sel:DWORD dst_unused:UNUSED_PAD src0_sel:DWORD src1_sel:WORD_1
	ds_bpermute_b32 v18, v132, v0
	ds_bpermute_b32 v19, v132, v1
	v_cndmask_b32_e64 v2, v11, v4, s[2:3]
	v_cndmask_b32_e64 v3, v10, v5, s[2:3]
	ds_bpermute_b32 v6, v132, v3
	ds_bpermute_b32 v7, v132, v2
	v_readlane_b32 s1, v255, 6
	v_mov_b32_e32 v229, 0x4000
	s_waitcnt lgkmcnt(2)
	v_cndmask_b32_e64 v1, v19, v38, s[2:3]
	v_cndmask_b32_e64 v0, v18, v39, s[2:3]
	v_cndmask_b32_e64 v3, v16, v19, s[2:3]
	v_cndmask_b32_e64 v2, v17, v18, s[2:3]
	s_add_i32 s0, s0, s1
	v_readlane_b32 s1, v254, 40
	global_store_dwordx4 v[64:65], v[0:3], off offset:64
	s_cmp_ge_i32 s0, s1
	v_mov_b32_e32 v214, v229
	s_waitcnt lgkmcnt(1)
	v_cndmask_b32_e64 v1, v6, v10, s[2:3]
	s_waitcnt lgkmcnt(0)
	v_cndmask_b32_e64 v0, v7, v11, s[2:3]
	v_cndmask_b32_e64 v3, v5, v6, s[2:3]
	v_cndmask_b32_e64 v2, v4, v7, s[2:3]
	global_store_dwordx4 v[64:65], v[0:3], off offset:80
	s_cbranch_scc1 .LBB0_166

.LBB0_162:
	v_mov_b32_e32 v80, 0
	v_mov_b32_e32 v81, 0
	v_mov_b32_e32 v82, 0
	v_mov_b32_e32 v83, 0
	v_mov_b32_e32 v112, 0
	v_mov_b32_e32 v113, 0
	v_mov_b32_e32 v114, 0
	v_mov_b32_e32 v115, 0
	v_mov_b32_e32 v128, 0
	v_mov_b32_e32 v129, 0
	v_mov_b32_e32 v130, 0
	v_mov_b32_e32 v131, 0
	v_mov_b32_e32 v132, 0
	v_mov_b32_e32 v133, 0
	v_mov_b32_e32 v134, 0
	v_mov_b32_e32 v135, 0
	v_mov_b32_e32 v136, 0
	v_mov_b32_e32 v137, 0
	v_mov_b32_e32 v138, 0
	v_mov_b32_e32 v139, 0
	s_nop 1
.Lrs0_top:
	s_add_i32 s5, s4, 64
	s_min_u32 s6, s5, 0x3e0
	s_lshl_b32 s78, s6, 1
	ds_read_b128 v[44:47], v116 offset:0
	ds_read_b128 v[40:43], v116 offset:0x800
	ds_read_b128 v[36:39], v116 offset:0x1000
	ds_read_b128 v[92:95], v110 offset:0
	v_mfma_f32_32x32x16_bf16 a[144:159], v[136:139], v[80:83], a[144:159]
	ds_read_b128 v[88:91], v110 offset:0x800
	v_mfma_f32_32x32x16_bf16 a[160:175], v[136:139], v[112:115], a[160:175]
	ds_read_b128 v[84:87], v110 offset:0x1000
	v_lshl_add_u64 v[52:53], v[96:97], 0, s[78:79]
	global_load_dwordx4 v[56:59], v[52:53], off
	v_mfma_f32_32x32x16_bf16 a[176:191], v[136:139], v[128:131], a[176:191]
	ds_read_b128 v[48:51], v110 offset:0x1800
	v_lshl_add_u64 v[54:55], v[100:101], 0, s[78:79]
	global_load_dwordx4 v[52:55], v[54:55], off
	v_mfma_f32_32x32x16_bf16 a[32:47], v[132:135], v[80:83], a[32:47]
	v_lshl_add_u64 v[60:61], v[102:103], 0, s[78:79]
	global_load_dwordx4 v[64:67], v[60:61], off
	v_mfma_f32_32x32x16_bf16 a[16:31], v[132:135], v[112:115], a[16:31]
	v_lshl_add_u64 v[62:63], v[104:105], 0, s[78:79]
	global_load_dwordx4 v[60:63], v[62:63], off
	v_mfma_f32_32x32x16_bf16 a[0:15], v[132:135], v[128:131], a[0:15]
	v_lshl_add_u64 v[68:69], v[98:99], 0, s[78:79]
	global_load_dwordx4 v[76:79], v[68:69], off
	s_waitcnt lgkmcnt(3)
	v_mfma_f32_32x32x16_bf16 a[80:95], v[92:95], v[44:47], a[80:95]
	ds_read_b128 v[80:83], v117 offset:0
	v_mfma_f32_32x32x16_bf16 a[48:63], v[92:95], v[40:43], a[48:63]
	v_lshl_add_u64 v[70:71], v[106:107], 0, s[78:79]
	global_load_dwordx4 v[68:71], v[70:71], off
	v_mfma_f32_32x32x16_bf16 a[64:79], v[92:95], v[36:39], a[64:79]
	ds_read_b128 v[112:115], v117 offset:0x800
	s_waitcnt lgkmcnt(4)
	v_mfma_f32_32x32x16_bf16 a[96:111], v[88:91], v[44:47], a[96:111]
	v_lshl_add_u64 v[72:73], v[108:109], 0, s[78:79]
	global_load_dwordx4 v[72:75], v[72:73], off
	v_mfma_f32_32x32x16_bf16 a[112:127], v[88:91], v[40:43], a[112:127]
	ds_read_b128 v[120:123], v117 offset:0x1000
	s_min_u32 s4, s4, 0x380
	s_lshl_b32 s78, s4, 1
	v_mfma_f32_32x32x16_bf16 a[128:143], v[88:91], v[36:39], a[128:143]
	ds_read_b128 v[124:127], v111 offset:0
	s_add_i32 s6, s78, 0xc0
	s_mov_b32 s7, s79
	s_waitcnt lgkmcnt(5)
	v_mfma_f32_32x32x16_bf16 a[144:159], v[84:87], v[44:47], a[144:159]
	ds_read_b128 v[128:131], v111 offset:0x800
	s_add_i32 s3, s3, 2
	s_cmp_lt_u32 s3, 30
	v_mfma_f32_32x32x16_bf16 a[160:175], v[84:87], v[40:43], a[160:175]
	ds_read_b128 v[132:135], v111 offset:0x1000
	s_waitcnt vmcnt(13)
	ds_write_b128 v118, v[4:7] offset:0x8000
	v_mfma_f32_32x32x16_bf16 a[176:191], v[84:87], v[36:39], a[176:191]
	ds_read_b128 v[136:139], v111 offset:0x1800
	s_waitcnt vmcnt(12)
	ds_write_b128 v118, v[8:11] offset:0x9000
	s_waitcnt lgkmcnt(9)
	v_mfma_f32_32x32x16_bf16 a[32:47], v[48:51], v[44:47], a[32:47]
	s_waitcnt vmcnt(11)
	ds_write_b128 v118, v[12:15] offset:0xa000
	v_mfma_f32_32x32x16_bf16 a[16:31], v[48:51], v[40:43], a[16:31]
	s_waitcnt vmcnt(10)
	ds_write_b128 v118, v[16:19] offset:0xb000
	v_mfma_f32_32x32x16_bf16 a[0:15], v[48:51], v[36:39], a[0:15]
	s_waitcnt vmcnt(9)
	ds_write_b128 v118, v[20:23] offset:0xc000
	s_waitcnt lgkmcnt(8)
	v_mfma_f32_32x32x16_bf16 a[80:95], v[124:127], v[80:83], a[80:95]
	s_waitcnt vmcnt(8)
	ds_write_b128 v118, v[24:27] offset:0xd000
	v_mfma_f32_32x32x16_bf16 a[48:63], v[124:127], v[112:115], a[48:63]
	s_waitcnt vmcnt(7)
	ds_write_b128 v118, v[28:31] offset:0xe000
	v_mfma_f32_32x32x16_bf16 a[64:79], v[124:127], v[120:123], a[64:79]
	v_lshl_add_u64 v[4:5], v[96:97], 0, s[78:79]
	v_lshl_add_u64 v[8:9], v[100:101], 0, s[6:7]
	s_waitcnt lgkmcnt(9)
	v_mfma_f32_32x32x16_bf16 a[96:111], v[128:131], v[80:83], a[96:111]
	v_lshl_add_u64 v[12:13], v[102:103], 0, s[6:7]
	v_lshl_add_u64 v[16:17], v[104:105], 0, s[6:7]
	v_mfma_f32_32x32x16_bf16 a[112:127], v[128:131], v[112:115], a[112:127]
	v_lshl_add_u64 v[20:21], v[98:99], 0, s[78:79]
	v_lshl_add_u64 v[24:25], v[106:107], 0, s[6:7]
	v_mfma_f32_32x32x16_bf16 a[128:143], v[128:131], v[120:123], a[128:143]
	v_lshl_add_u64 v[28:29], v[108:109], 0, s[6:7]
	s_waitcnt lgkmcnt(0)
	s_barrier
	ds_read_b128 v[36:39], v116 offset:0x8000
	ds_read_b128 v[40:43], v116 offset:0x8800
	ds_read_b128 v[44:47], v116 offset:0x9000
	ds_read_b128 v[48:51], v110 offset:0x8000
	v_mfma_f32_32x32x16_bf16 a[144:159], v[132:135], v[80:83], a[144:159]
	ds_read_b128 v[84:87], v110 offset:0x8800
	v_mfma_f32_32x32x16_bf16 a[160:175], v[132:135], v[112:115], a[160:175]
	ds_read_b128 v[88:91], v110 offset:0x9000
	global_load_dwordx4 v[4:7], v[4:5], off offset:192
	v_mfma_f32_32x32x16_bf16 a[176:191], v[132:135], v[120:123], a[176:191]
	ds_read_b128 v[92:95], v110 offset:0x9800
	global_load_dwordx4 v[8:11], v[8:9], off
	v_mfma_f32_32x32x16_bf16 a[32:47], v[136:139], v[80:83], a[32:47]
	global_load_dwordx4 v[12:15], v[12:13], off
	v_mfma_f32_32x32x16_bf16 a[16:31], v[136:139], v[112:115], a[16:31]
	global_load_dwordx4 v[16:19], v[16:17], off
	v_mfma_f32_32x32x16_bf16 a[0:15], v[136:139], v[120:123], a[0:15]
	global_load_dwordx4 v[20:23], v[20:21], off offset:192
	s_waitcnt lgkmcnt(3)
	v_mfma_f32_32x32x16_bf16 a[80:95], v[48:51], v[36:39], a[80:95]
	ds_read_b128 v[80:83], v117 offset:0x8000
	v_mfma_f32_32x32x16_bf16 a[48:63], v[48:51], v[40:43], a[48:63]
	global_load_dwordx4 v[24:27], v[24:25], off
	v_mfma_f32_32x32x16_bf16 a[64:79], v[48:51], v[44:47], a[64:79]
	ds_read_b128 v[112:115], v117 offset:0x8800
	s_waitcnt lgkmcnt(4)
	v_mfma_f32_32x32x16_bf16 a[96:111], v[84:87], v[36:39], a[96:111]
	global_load_dwordx4 v[28:31], v[28:29], off
	v_mfma_f32_32x32x16_bf16 a[112:127], v[84:87], v[40:43], a[112:127]
	ds_read_b128 v[128:131], v117 offset:0x9000
	v_mfma_f32_32x32x16_bf16 a[128:143], v[84:87], v[44:47], a[128:143]
	ds_read_b128 v[120:123], v111 offset:0x8000
	s_waitcnt lgkmcnt(5)
	v_mfma_f32_32x32x16_bf16 a[144:159], v[88:91], v[36:39], a[144:159]
	ds_read_b128 v[124:127], v111 offset:0x8800
	v_mfma_f32_32x32x16_bf16 a[160:175], v[88:91], v[40:43], a[160:175]
	ds_read_b128 v[136:139], v111 offset:0x9000
	v_mfma_f32_32x32x16_bf16 a[176:191], v[88:91], v[44:47], a[176:191]
	ds_read_b128 v[132:135], v111 offset:0x9800
	s_waitcnt lgkmcnt(7)
	v_mfma_f32_32x32x16_bf16 a[32:47], v[92:95], v[36:39], a[32:47]
	s_waitcnt vmcnt(13)
	ds_write_b128 v118, v[56:59] offset:0
	v_mfma_f32_32x32x16_bf16 a[16:31], v[92:95], v[40:43], a[16:31]
	s_waitcnt vmcnt(12)
	ds_write_b128 v118, v[52:55] offset:0x1000
	v_mfma_f32_32x32x16_bf16 a[0:15], v[92:95], v[44:47], a[0:15]
	s_waitcnt vmcnt(11)
	ds_write_b128 v118, v[64:67] offset:0x2000
	s_waitcnt lgkmcnt(6)
	v_mfma_f32_32x32x16_bf16 a[80:95], v[120:123], v[80:83], a[80:95]
	s_waitcnt vmcnt(10)
	ds_write_b128 v118, v[60:63] offset:0x3000
	v_mfma_f32_32x32x16_bf16 a[48:63], v[120:123], v[112:115], a[48:63]
	s_waitcnt vmcnt(9)
	ds_write_b128 v118, v[76:79] offset:0x4000
	v_mfma_f32_32x32x16_bf16 a[64:79], v[120:123], v[128:131], a[64:79]
	s_waitcnt vmcnt(8)
	ds_write_b128 v118, v[68:71] offset:0x5000
	s_waitcnt lgkmcnt(8)
	v_mfma_f32_32x32x16_bf16 a[96:111], v[124:127], v[80:83], a[96:111]
	s_waitcnt vmcnt(7)
	ds_write_b128 v118, v[72:75] offset:0x6000
	v_mfma_f32_32x32x16_bf16 a[112:127], v[124:127], v[112:115], a[112:127]
	v_mfma_f32_32x32x16_bf16 a[128:143], v[124:127], v[128:131], a[128:143]
	s_waitcnt lgkmcnt(0)
	s_barrier
	s_cbranch_scc0 .Lrs0_exit
	s_mov_b32 s4, s5
	s_branch .Lrs0_top
.Lrs0_exit:
	v_mfma_f32_32x32x16_bf16 a[144:159], v[136:139], v[80:83], a[144:159]
	v_mfma_f32_32x32x16_bf16 a[160:175], v[136:139], v[112:115], a[160:175]
	v_mfma_f32_32x32x16_bf16 a[176:191], v[136:139], v[128:131], a[176:191]
	s_nop 7
	s_nop 3
	s_branch .LBB0_160

.Lrs3_top:
	s_add_i32 s7, s6, 64
	s_min_u32 s8, s7, 0x3e0
	s_lshl_b32 s78, s8, 1
	ds_read_b128 v[52:55], v116 offset:0
	ds_read_b128 v[48:51], v116 offset:0x800
	ds_read_b128 v[44:47], v116 offset:0x1000
	ds_read_b128 v[96:99], v114 offset:0
	v_mfma_f32_32x32x16_bf16 a[144:159], v[128:131], v[40:43], a[144:159]
	ds_read_b128 v[92:95], v114 offset:0x800
	v_mfma_f32_32x32x16_bf16 a[160:175], v[128:131], v[36:39], a[160:175]
	ds_read_b128 v[88:91], v114 offset:0x1000
	v_lshl_add_u64 v[60:61], v[100:101], 0, s[78:79]
	global_load_dwordx4 v[64:67], v[60:61], off
	v_mfma_f32_32x32x16_bf16 a[176:191], v[128:131], v[194:197], a[176:191]
	ds_read_b128 v[56:59], v114 offset:0x1800
	v_lshl_add_u64 v[62:63], v[104:105], 0, s[78:79]
	global_load_dwordx4 v[60:63], v[62:63], off
	v_mfma_f32_32x32x16_bf16 a[32:47], v[198:201], v[40:43], a[32:47]
	v_lshl_add_u64 v[68:69], v[106:107], 0, s[78:79]
	global_load_dwordx4 v[72:75], v[68:69], off
	v_mfma_f32_32x32x16_bf16 a[16:31], v[198:201], v[36:39], a[16:31]
	v_lshl_add_u64 v[70:71], v[108:109], 0, s[78:79]
	global_load_dwordx4 v[68:71], v[70:71], off
	v_mfma_f32_32x32x16_bf16 a[0:15], v[198:201], v[194:197], a[0:15]
	v_lshl_add_u64 v[76:77], v[102:103], 0, s[78:79]
	global_load_dwordx4 v[84:87], v[76:77], off
	s_waitcnt lgkmcnt(3)
	v_mfma_f32_32x32x16_bf16 a[48:63], v[96:99], v[52:55], a[48:63]
	ds_read_b128 v[36:39], v117 offset:0
	v_mfma_f32_32x32x16_bf16 a[64:79], v[96:99], v[48:51], a[64:79]
	v_lshl_add_u64 v[78:79], v[110:111], 0, s[78:79]
	global_load_dwordx4 v[76:79], v[78:79], off
	v_mfma_f32_32x32x16_bf16 a[80:95], v[96:99], v[44:47], a[80:95]
	ds_read_b128 v[40:43], v117 offset:0x800
	s_waitcnt lgkmcnt(4)
	v_mfma_f32_32x32x16_bf16 a[96:111], v[92:95], v[52:55], a[96:111]
	v_lshl_add_u64 v[80:81], v[112:113], 0, s[78:79]
	global_load_dwordx4 v[80:83], v[80:81], off
	v_mfma_f32_32x32x16_bf16 a[112:127], v[92:95], v[48:51], a[112:127]
	ds_read_b128 v[120:123], v117 offset:0x1000
	s_min_u32 s6, s6, 0x380
	s_lshl_b32 s78, s6, 1
	v_mfma_f32_32x32x16_bf16 a[128:143], v[92:95], v[44:47], a[128:143]
	ds_read_b128 v[124:127], v115 offset:0
	s_add_i32 s8, s78, 0xc0
	s_mov_b32 s9, s79
	s_waitcnt lgkmcnt(5)
	v_mfma_f32_32x32x16_bf16 a[144:159], v[88:91], v[52:55], a[144:159]
	ds_read_b128 v[128:131], v115 offset:0x800
	s_add_i32 s5, s5, 2
	s_cmp_lt_u32 s5, 30
	v_mfma_f32_32x32x16_bf16 a[160:175], v[88:91], v[48:51], a[160:175]
	ds_read_b128 v[132:135], v115 offset:0x1000
	s_waitcnt vmcnt(13)
	ds_write_b128 v118, v[4:7] offset:0x8000
	v_mfma_f32_32x32x16_bf16 a[176:191], v[88:91], v[44:47], a[176:191]
	ds_read_b128 v[136:139], v115 offset:0x1800
	s_waitcnt vmcnt(12)
	ds_write_b128 v118, v[8:11] offset:0x9000
	s_waitcnt lgkmcnt(9)
	v_mfma_f32_32x32x16_bf16 a[32:47], v[56:59], v[52:55], a[32:47]
	s_waitcnt vmcnt(11)
	ds_write_b128 v118, v[12:15] offset:0xa000
	v_mfma_f32_32x32x16_bf16 a[16:31], v[56:59], v[48:51], a[16:31]
	s_waitcnt vmcnt(10)
	ds_write_b128 v118, v[16:19] offset:0xb000
	v_mfma_f32_32x32x16_bf16 a[0:15], v[56:59], v[44:47], a[0:15]
	s_waitcnt vmcnt(9)
	ds_write_b128 v118, v[20:23] offset:0xc000
	s_waitcnt lgkmcnt(8)
	v_mfma_f32_32x32x16_bf16 a[48:63], v[124:127], v[36:39], a[48:63]
	s_waitcnt vmcnt(8)
	ds_write_b128 v118, v[24:27] offset:0xd000
	v_mfma_f32_32x32x16_bf16 a[64:79], v[124:127], v[40:43], a[64:79]
	s_waitcnt vmcnt(7)
	ds_write_b128 v118, v[28:31] offset:0xe000
	v_mfma_f32_32x32x16_bf16 a[80:95], v[124:127], v[120:123], a[80:95]
	v_lshl_add_u64 v[4:5], v[100:101], 0, s[78:79]
	v_lshl_add_u64 v[8:9], v[104:105], 0, s[8:9]
	s_waitcnt lgkmcnt(9)
	v_mfma_f32_32x32x16_bf16 a[96:111], v[128:131], v[36:39], a[96:111]
	v_lshl_add_u64 v[12:13], v[106:107], 0, s[8:9]
	v_lshl_add_u64 v[16:17], v[108:109], 0, s[8:9]
	v_mfma_f32_32x32x16_bf16 a[112:127], v[128:131], v[40:43], a[112:127]
	v_lshl_add_u64 v[20:21], v[102:103], 0, s[78:79]
	v_lshl_add_u64 v[24:25], v[110:111], 0, s[8:9]
	v_mfma_f32_32x32x16_bf16 a[128:143], v[128:131], v[120:123], a[128:143]
	v_lshl_add_u64 v[28:29], v[112:113], 0, s[8:9]
	s_waitcnt lgkmcnt(0)
	s_barrier
	ds_read_b128 v[44:47], v116 offset:0x8000
	ds_read_b128 v[48:51], v116 offset:0x8800
	ds_read_b128 v[52:55], v116 offset:0x9000
	ds_read_b128 v[56:59], v114 offset:0x8000
	v_mfma_f32_32x32x16_bf16 a[144:159], v[132:135], v[36:39], a[144:159]
	ds_read_b128 v[88:91], v114 offset:0x8800
	v_mfma_f32_32x32x16_bf16 a[160:175], v[132:135], v[40:43], a[160:175]
	ds_read_b128 v[92:95], v114 offset:0x9000
	global_load_dwordx4 v[4:7], v[4:5], off offset:192
	v_mfma_f32_32x32x16_bf16 a[176:191], v[132:135], v[120:123], a[176:191]
	ds_read_b128 v[96:99], v114 offset:0x9800
	global_load_dwordx4 v[8:11], v[8:9], off
	v_mfma_f32_32x32x16_bf16 a[32:47], v[136:139], v[36:39], a[32:47]
	global_load_dwordx4 v[12:15], v[12:13], off
	v_mfma_f32_32x32x16_bf16 a[16:31], v[136:139], v[40:43], a[16:31]
	global_load_dwordx4 v[16:19], v[16:17], off
	v_mfma_f32_32x32x16_bf16 a[0:15], v[136:139], v[120:123], a[0:15]
	global_load_dwordx4 v[20:23], v[20:21], off offset:192
	s_waitcnt lgkmcnt(3)
	v_mfma_f32_32x32x16_bf16 a[48:63], v[56:59], v[44:47], a[48:63]
	ds_read_b128 v[40:43], v117 offset:0x8000
	v_mfma_f32_32x32x16_bf16 a[64:79], v[56:59], v[48:51], a[64:79]
	global_load_dwordx4 v[24:27], v[24:25], off
	v_mfma_f32_32x32x16_bf16 a[80:95], v[56:59], v[52:55], a[80:95]
	ds_read_b128 v[36:39], v117 offset:0x8800
	s_waitcnt lgkmcnt(4)
	v_mfma_f32_32x32x16_bf16 a[96:111], v[88:91], v[44:47], a[96:111]
	global_load_dwordx4 v[28:31], v[28:29], off
	v_mfma_f32_32x32x16_bf16 a[112:127], v[88:91], v[48:51], a[112:127]
	ds_read_b128 v[194:197], v117 offset:0x9000
	v_mfma_f32_32x32x16_bf16 a[128:143], v[88:91], v[52:55], a[128:143]
	ds_read_b128 v[120:123], v115 offset:0x8000
	s_waitcnt lgkmcnt(5)
	v_mfma_f32_32x32x16_bf16 a[144:159], v[92:95], v[44:47], a[144:159]
	ds_read_b128 v[124:127], v115 offset:0x8800
	v_mfma_f32_32x32x16_bf16 a[160:175], v[92:95], v[48:51], a[160:175]
	ds_read_b128 v[128:131], v115 offset:0x9000
	v_mfma_f32_32x32x16_bf16 a[176:191], v[92:95], v[52:55], a[176:191]
	ds_read_b128 v[198:201], v115 offset:0x9800
	s_waitcnt lgkmcnt(7)
	v_mfma_f32_32x32x16_bf16 a[32:47], v[96:99], v[44:47], a[32:47]
	s_waitcnt vmcnt(13)
	ds_write_b128 v118, v[64:67] offset:0
	v_mfma_f32_32x32x16_bf16 a[16:31], v[96:99], v[48:51], a[16:31]
	s_waitcnt vmcnt(12)
	ds_write_b128 v118, v[60:63] offset:0x1000
	v_mfma_f32_32x32x16_bf16 a[0:15], v[96:99], v[52:55], a[0:15]
	s_waitcnt vmcnt(11)
	ds_write_b128 v118, v[72:75] offset:0x2000
	s_waitcnt lgkmcnt(6)
	v_mfma_f32_32x32x16_bf16 a[48:63], v[120:123], v[40:43], a[48:63]
	s_waitcnt vmcnt(10)
	ds_write_b128 v118, v[68:71] offset:0x3000
	v_mfma_f32_32x32x16_bf16 a[64:79], v[120:123], v[36:39], a[64:79]
	s_waitcnt vmcnt(9)
	ds_write_b128 v118, v[84:87] offset:0x4000
	v_mfma_f32_32x32x16_bf16 a[80:95], v[120:123], v[194:197], a[80:95]
	s_waitcnt vmcnt(8)
	ds_write_b128 v118, v[76:79] offset:0x5000
	s_waitcnt lgkmcnt(8)
	v_mfma_f32_32x32x16_bf16 a[96:111], v[124:127], v[40:43], a[96:111]
	s_waitcnt vmcnt(7)
	ds_write_b128 v118, v[80:83] offset:0x6000
	v_mfma_f32_32x32x16_bf16 a[112:127], v[124:127], v[36:39], a[112:127]
	v_mfma_f32_32x32x16_bf16 a[128:143], v[124:127], v[194:197], a[128:143]
	s_waitcnt lgkmcnt(0)
	s_barrier
	s_cbranch_scc0 .Lrs3_exit
	s_mov_b32 s6, s7
	s_branch .Lrs3_top

.Lrs4_top:
	s_add_i32 s5, s4, 64
	s_min_u32 s6, s5, 0x3e0
	s_lshl_b32 s78, s6, 1
	ds_read_b128 v[48:51], v82 offset:0
	ds_read_b128 v[44:47], v82 offset:0x800
	ds_read_b128 v[64:67], v80 offset:0
	v_mfma_f32_32x32x16_bf16 a[96:111], v[94:97], v[40:43], a[96:111]
	ds_read_b128 v[60:63], v80 offset:0x800
	v_mfma_f32_32x32x16_bf16 a[112:127], v[94:97], v[128:131], a[112:127]
	ds_read_b128 v[56:59], v80 offset:0x1000
	v_lshl_add_u64 v[106:107], v[68:69], 0, s[78:79]
	global_load_dwordx4 v[106:109], v[106:107], off
	v_mfma_f32_32x32x16_bf16 a[16:31], v[132:135], v[40:43], a[16:31]
	ds_read_b128 v[52:55], v80 offset:0x1800
	v_lshl_add_u64 v[110:111], v[72:73], 0, s[78:79]
	global_load_dwordx4 v[110:113], v[110:111], off
	v_mfma_f32_32x32x16_bf16 a[0:15], v[132:135], v[128:131], a[0:15]
	v_lshl_add_u64 v[114:115], v[74:75], 0, s[78:79]
	global_load_dwordx4 v[114:117], v[114:115], off
	s_waitcnt lgkmcnt(3)
	v_mfma_f32_32x32x16_bf16 a[32:47], v[64:67], v[48:51], a[32:47]
	ds_read_b128 v[40:43], v83 offset:0
	v_mfma_f32_32x32x16_bf16 a[48:63], v[64:67], v[44:47], a[48:63]
	v_lshl_add_u64 v[118:119], v[76:77], 0, s[78:79]
	global_load_dwordx4 v[118:121], v[118:119], off
	s_waitcnt lgkmcnt(3)
	v_mfma_f32_32x32x16_bf16 a[64:79], v[60:63], v[48:51], a[64:79]
	ds_read_b128 v[86:89], v83 offset:0x800
	v_mfma_f32_32x32x16_bf16 a[80:95], v[60:63], v[44:47], a[80:95]
	v_lshl_add_u64 v[122:123], v[70:71], 0, s[78:79]
	global_load_dwordx4 v[122:125], v[122:123], off
	s_waitcnt lgkmcnt(3)
	v_mfma_f32_32x32x16_bf16 a[96:111], v[56:59], v[48:51], a[96:111]
	ds_read_b128 v[90:93], v81 offset:0
	v_mfma_f32_32x32x16_bf16 a[112:127], v[56:59], v[44:47], a[112:127]
	v_lshl_add_u64 v[126:127], v[78:79], 0, s[78:79]
	global_load_dwordx4 v[140:143], v[126:127], off
	s_waitcnt vmcnt(11)
	ds_write_b128 v84, v[4:7] offset:0x8000
	s_waitcnt lgkmcnt(4)
	v_mfma_f32_32x32x16_bf16 a[16:31], v[52:55], v[48:51], a[16:31]
	ds_read_b128 v[94:97], v81 offset:0x800
	s_min_u32 s4, s4, 0x380
	s_lshl_b32 s78, s4, 1
	s_waitcnt vmcnt(10)
	ds_write_b128 v84, v[8:11] offset:0x9000
	v_mfma_f32_32x32x16_bf16 a[0:15], v[52:55], v[44:47], a[0:15]
	ds_read_b128 v[98:101], v81 offset:0x1000
	s_add_i32 s6, s78, 0xc0
	s_mov_b32 s7, s79
	s_waitcnt vmcnt(9)
	ds_write_b128 v84, v[12:15] offset:0xa000
	s_waitcnt lgkmcnt(5)
	v_mfma_f32_32x32x16_bf16 a[32:47], v[90:93], v[40:43], a[32:47]
	ds_read_b128 v[102:105], v81 offset:0x1800
	s_add_i32 s3, s3, 2
	s_cmp_lt_u32 s3, 30
	s_waitcnt vmcnt(8)
	ds_write_b128 v84, v[16:19] offset:0xb000
	v_mfma_f32_32x32x16_bf16 a[48:63], v[90:93], v[86:89], a[48:63]
	s_waitcnt vmcnt(7)
	ds_write_b128 v84, v[20:23] offset:0xc000
	s_waitcnt lgkmcnt(6)
	v_mfma_f32_32x32x16_bf16 a[64:79], v[94:97], v[40:43], a[64:79]
	s_waitcnt vmcnt(6)
	ds_write_b128 v84, v[24:27] offset:0xd000
	v_mfma_f32_32x32x16_bf16 a[80:95], v[94:97], v[86:89], a[80:95]
	v_lshl_add_u64 v[4:5], v[68:69], 0, s[78:79]
	v_lshl_add_u64 v[8:9], v[72:73], 0, s[6:7]
	v_lshl_add_u64 v[12:13], v[74:75], 0, s[6:7]
	v_lshl_add_u64 v[16:17], v[76:77], 0, s[6:7]
	v_lshl_add_u64 v[20:21], v[70:71], 0, s[78:79]
	v_lshl_add_u64 v[24:25], v[78:79], 0, s[6:7]
	s_waitcnt lgkmcnt(0)
	s_barrier
	ds_read_b128 v[44:47], v82 offset:0x8000
	ds_read_b128 v[48:51], v82 offset:0x8800
	ds_read_b128 v[52:55], v80 offset:0x8000
	v_mfma_f32_32x32x16_bf16 a[96:111], v[98:101], v[40:43], a[96:111]
	ds_read_b128 v[56:59], v80 offset:0x8800
	v_mfma_f32_32x32x16_bf16 a[112:127], v[98:101], v[86:89], a[112:127]
	ds_read_b128 v[60:63], v80 offset:0x9000
	global_load_dwordx4 v[4:7], v[4:5], off offset:192
	v_mfma_f32_32x32x16_bf16 a[16:31], v[102:105], v[40:43], a[16:31]
	ds_read_b128 v[64:67], v80 offset:0x9800
	global_load_dwordx4 v[8:11], v[8:9], off
	v_mfma_f32_32x32x16_bf16 a[0:15], v[102:105], v[86:89], a[0:15]
	global_load_dwordx4 v[12:15], v[12:13], off
	s_waitcnt lgkmcnt(3)
	v_mfma_f32_32x32x16_bf16 a[32:47], v[52:55], v[44:47], a[32:47]
	ds_read_b128 v[40:43], v83 offset:0x8000
	v_mfma_f32_32x32x16_bf16 a[48:63], v[52:55], v[48:51], a[48:63]
	global_load_dwordx4 v[16:19], v[16:17], off
	s_waitcnt lgkmcnt(3)
	v_mfma_f32_32x32x16_bf16 a[64:79], v[56:59], v[44:47], a[64:79]
	ds_read_b128 v[128:131], v83 offset:0x8800
	v_mfma_f32_32x32x16_bf16 a[80:95], v[56:59], v[48:51], a[80:95]
	global_load_dwordx4 v[20:23], v[20:21], off offset:192
	s_waitcnt lgkmcnt(3)
	v_mfma_f32_32x32x16_bf16 a[96:111], v[60:63], v[44:47], a[96:111]
	ds_read_b128 v[86:89], v81 offset:0x8000
	v_mfma_f32_32x32x16_bf16 a[112:127], v[60:63], v[48:51], a[112:127]
	global_load_dwordx4 v[24:27], v[24:25], off
	s_waitcnt vmcnt(11)
	ds_write_b128 v84, v[106:109] offset:0
	s_waitcnt lgkmcnt(4)
	v_mfma_f32_32x32x16_bf16 a[16:31], v[64:67], v[44:47], a[16:31]
	ds_read_b128 v[90:93], v81 offset:0x8800
	s_waitcnt vmcnt(10)
	ds_write_b128 v84, v[110:113] offset:0x1000
	v_mfma_f32_32x32x16_bf16 a[0:15], v[64:67], v[48:51], a[0:15]
	ds_read_b128 v[94:97], v81 offset:0x9000
	s_waitcnt vmcnt(9)
	ds_write_b128 v84, v[114:117] offset:0x2000
	s_waitcnt lgkmcnt(5)
	v_mfma_f32_32x32x16_bf16 a[32:47], v[86:89], v[40:43], a[32:47]
	ds_read_b128 v[132:135], v81 offset:0x9800
	s_waitcnt vmcnt(8)
	ds_write_b128 v84, v[118:121] offset:0x3000
	v_mfma_f32_32x32x16_bf16 a[48:63], v[86:89], v[128:131], a[48:63]
	s_waitcnt vmcnt(7)
	ds_write_b128 v84, v[122:125] offset:0x4000
	s_waitcnt lgkmcnt(6)
	v_mfma_f32_32x32x16_bf16 a[64:79], v[90:93], v[40:43], a[64:79]
	s_waitcnt vmcnt(6)
	ds_write_b128 v84, v[140:143] offset:0x5000
	v_mfma_f32_32x32x16_bf16 a[80:95], v[90:93], v[128:131], a[80:95]
	s_waitcnt lgkmcnt(0)
	s_barrier
	s_cbranch_scc0 .Lrs4_exit
	s_mov_b32 s4, s5
	s_branch .Lrs4_top

.LBB0_235:
	v_lshrrev_b32_e32 v0, 3, v108
	v_and_b32_e32 v9, 4, v0
	v_and_or_b32 v22, v107, 64, s1
	v_or_b32_e32 v0, s0, v106
	v_add_u32_e32 v6, v0, v109
	v_lshrrev_b32_e32 v0, 4, v22
	s_movk_i32 s3, 0x4200
	v_mul_lo_u32 v0, v0, s3
	v_ashrrev_i32_e32 v7, 31, v6
	v_ashrrev_i32_e32 v1, 31, v0
	v_lshl_add_u64 v[4:5], v[0:1], 0, v[6:7]
	v_readlane_b32 s6, v254, 3
	v_lshlrev_b64 v[4:5], 5, v[4:5]
	v_readlane_b32 s7, v254, 4
	v_lshlrev_b32_e32 v192, 1, v9
	v_or_b32_e32 v8, v9, v22
	v_lshl_add_u64 v[4:5], s[6:7], 0, v[4:5]
	v_lshl_add_u64 v[10:11], v[4:5], 0, v[192:193]
	global_load_dwordx2 v[10:11], v[10:11], off
	v_accvgpr_read_b32 v134, a32
	v_ashrrev_i32_e32 v9, 31, v8
	v_accvgpr_read_b32 v133, a33
	v_lshlrev_b64 v[14:15], 1, v[8:9]
	v_mul_f32_e32 v9, 0xbfb8aa3b, v134
	v_accvgpr_read_b32 v132, a34
	v_exp_f32_e32 v12, v9
	v_mul_f32_e32 v9, 0xbfb8aa3b, v133
	v_exp_f32_e32 v16, v9
	v_mul_f32_e32 v9, 0xbfb8aa3b, v132
	v_exp_f32_e32 v13, v9
	v_accvgpr_read_b32 v131, a35
	v_mul_f32_e32 v9, 0xbfb8aa3b, v131
	v_exp_f32_e32 v17, v9
	v_readlane_b32 s4, v253, 61
	v_lshlrev_b64 v[2:3], 11, v[6:7]
	v_readlane_b32 s5, v253, 62
	v_accvgpr_read_b32 v130, a36
	v_accvgpr_read_b32 v128, a38
	v_lshl_add_u64 v[2:3], s[4:5], 0, v[2:3]
	v_lshl_add_u64 v[2:3], v[2:3], 0, v[14:15]
	v_accvgpr_read_b32 v129, a37
	v_accvgpr_read_b32 v127, a39
	v_accvgpr_read_b32 v105, a40
	v_accvgpr_read_b32 v104, a41
	v_accvgpr_read_b32 v103, a42
	v_accvgpr_read_b32 v102, a43
	v_accvgpr_read_b32 v101, a44
	v_accvgpr_read_b32 v100, a45
	v_accvgpr_read_b32 v99, a46
	v_accvgpr_read_b32 v98, a47
	v_accvgpr_read_b32 v97, a48
	v_accvgpr_read_b32 v96, a49
	v_accvgpr_read_b32 v95, a50
	v_accvgpr_read_b32 v94, a51
	v_accvgpr_read_b32 v93, a52
	v_accvgpr_read_b32 v92, a53
	v_accvgpr_read_b32 v91, a54
	v_accvgpr_read_b32 v90, a55
	v_accvgpr_read_b32 v89, a56
	v_accvgpr_read_b32 v88, a57
	v_accvgpr_read_b32 v87, a58
	v_accvgpr_read_b32 v86, a59
	v_accvgpr_read_b32 v85, a60
	v_accvgpr_read_b32 v84, a61
	v_accvgpr_read_b32 v83, a62
	v_accvgpr_read_b32 v82, a63
	v_accvgpr_read_b32 v81, a0
	v_accvgpr_read_b32 v80, a1
	v_accvgpr_read_b32 v79, a2
	v_accvgpr_read_b32 v78, a3
	v_accvgpr_read_b32 v77, a4
	v_accvgpr_read_b32 v75, a6
	v_accvgpr_read_b32 v76, a5
	v_accvgpr_read_b32 v74, a7
	v_accvgpr_read_b32 v73, a8
	v_accvgpr_read_b32 v71, a10
	v_accvgpr_read_b32 v72, a9
	v_accvgpr_read_b32 v70, a11
	v_accvgpr_read_b32 v68, a13
	v_accvgpr_read_b32 v69, a12
	v_accvgpr_read_b32 v67, a14
	v_accvgpr_read_b32 v66, a15
	v_accvgpr_read_b32 v65, a16
	v_accvgpr_read_b32 v63, a18
	v_accvgpr_read_b32 v64, a17
	v_accvgpr_read_b32 v62, a19
	v_accvgpr_read_b32 v61, a20
	v_accvgpr_read_b32 v59, a22
	v_accvgpr_read_b32 v60, a21
	v_accvgpr_read_b32 v58, a23
	v_accvgpr_read_b32 v57, a24
	v_accvgpr_read_b32 v55, a26
	v_accvgpr_read_b32 v56, a25
	v_accvgpr_read_b32 v54, a27
	v_accvgpr_read_b32 v52, a29
	v_accvgpr_read_b32 v53, a28
	v_accvgpr_read_b32 v51, a30
	v_accvgpr_read_b32 v50, a31
	s_waitcnt vmcnt(0)
	v_lshlrev_b32_e32 v9, 16, v11
	v_lshlrev_b32_e32 v18, 16, v10
	v_and_b32_e32 v19, 0xffff0000, v11
	v_and_b32_e32 v20, 0xffff0000, v10
	v_pk_add_f32 v[10:11], v[12:13], 1.0 op_sel_hi:[1,0]
	s_nop 0
	v_rcp_f32_e32 v13, v10
	s_nop 0
	v_mul_f32_e32 v12, v18, v13
	v_rcp_f32_e32 v13, v11
	s_nop 0
	v_mul_f32_e32 v9, v9, v13
	v_pk_add_f32 v[10:11], v[16:17], 1.0 op_sel_hi:[1,0]
	s_nop 0
	v_rcp_f32_e32 v16, v10
	s_nop 0
	v_mul_f32_e32 v10, v20, v16
	v_rcp_f32_e32 v16, v11
	s_nop 0
	v_mul_f32_e32 v11, v19, v16
	v_and_b32_sdwa v13, v9, v218 dst_sel:DWORD dst_unused:UNUSED_PAD src0_sel:WORD_1 src1_sel:DWORD
	v_and_b32_sdwa v16, v12, v218 dst_sel:DWORD dst_unused:UNUSED_PAD src0_sel:WORD_1 src1_sel:DWORD
	v_add3_u32 v12, v12, v16, s80
	v_add3_u32 v9, v9, v13, s80
	v_and_b32_sdwa v13, v11, v218 dst_sel:DWORD dst_unused:UNUSED_PAD src0_sel:WORD_1 src1_sel:DWORD
	v_and_b32_sdwa v16, v10, v218 dst_sel:DWORD dst_unused:UNUSED_PAD src0_sel:WORD_1 src1_sel:DWORD
	v_add3_u32 v11, v11, v13, s80
	v_add3_u32 v10, v10, v16, s80
	v_and_b32_e32 v11, 0xffff0000, v11
	v_and_b32_e32 v10, 0xffff0000, v10
	v_or_b32_sdwa v11, v11, v9 dst_sel:DWORD dst_unused:UNUSED_PAD src0_sel:DWORD src1_sel:WORD_1
	v_or_b32_sdwa v10, v10, v12 dst_sel:DWORD dst_unused:UNUSED_PAD src0_sel:DWORD src1_sel:WORD_1
	v_bitop3_b32 v9, v8, 12, 8 bitop3:0xc8
	global_store_dwordx2 v[2:3], v[10:11], off
	v_lshlrev_b32_e32 v10, 1, v9
	v_mov_b32_e32 v11, v193
	v_lshl_add_u64 v[16:17], v[4:5], 0, v[10:11]
	global_load_dwordx2 v[16:17], v[16:17], off
	v_mul_f32_e32 v4, 0xbfb8aa3b, v130
	v_mul_f32_e32 v5, 0xbfb8aa3b, v128
	v_exp_f32_e32 v12, v4
	v_exp_f32_e32 v13, v5
	v_mul_f32_e32 v4, 0xbfb8aa3b, v129
	v_mul_f32_e32 v5, 0xbfb8aa3b, v127
	v_exp_f32_e32 v4, v4
	v_pk_add_f32 v[12:13], v[12:13], 1.0 op_sel_hi:[1,0]
	v_exp_f32_e32 v5, v5
	s_waitcnt vmcnt(0)
	v_lshlrev_b32_e32 v18, 16, v16
	v_rcp_f32_e32 v20, v12
	v_lshlrev_b32_e32 v9, 16, v17
	v_and_b32_e32 v16, 0xffff0000, v16
	v_pk_add_f32 v[4:5], v[4:5], 1.0 op_sel_hi:[1,0]
	v_mul_f32_e32 v12, v18, v20
	v_rcp_f32_e32 v19, v13
	v_and_b32_e32 v17, 0xffff0000, v17
	v_mul_f32_e32 v9, v9, v19
	v_rcp_f32_e32 v18, v4
	s_nop 0
	v_mul_f32_e32 v4, v16, v18
	v_rcp_f32_e32 v16, v5
	s_nop 0
	v_mul_f32_e32 v5, v17, v16
	v_and_b32_sdwa v13, v9, v218 dst_sel:DWORD dst_unused:UNUSED_PAD src0_sel:WORD_1 src1_sel:DWORD
	v_and_b32_sdwa v16, v12, v218 dst_sel:DWORD dst_unused:UNUSED_PAD src0_sel:WORD_1 src1_sel:DWORD
	v_add3_u32 v12, v12, v16, s80
	v_add3_u32 v9, v9, v13, s80
	v_and_b32_sdwa v13, v5, v218 dst_sel:DWORD dst_unused:UNUSED_PAD src0_sel:WORD_1 src1_sel:DWORD
	v_and_b32_sdwa v16, v4, v218 dst_sel:DWORD dst_unused:UNUSED_PAD src0_sel:WORD_1 src1_sel:DWORD
	v_add3_u32 v5, v5, v13, s80
	v_add3_u32 v4, v4, v16, s80
	v_and_b32_e32 v5, 0xffff0000, v5
	v_and_b32_e32 v4, 0xffff0000, v4
	v_or_b32_sdwa v5, v5, v9 dst_sel:DWORD dst_unused:UNUSED_PAD src0_sel:DWORD src1_sel:WORD_1
	v_or_b32_sdwa v4, v4, v12 dst_sel:DWORD dst_unused:UNUSED_PAD src0_sel:DWORD src1_sel:WORD_1
	global_store_dwordx2 v[2:3], v[4:5], off offset:16
	v_or_b32_e32 v4, 16, v22
	v_lshrrev_b32_e32 v4, 4, v4
	v_mul_lo_u32 v12, v4, s3
	v_ashrrev_i32_e32 v13, 31, v12
	v_lshl_add_u64 v[4:5], v[12:13], 0, v[6:7]
	v_lshlrev_b64 v[4:5], 5, v[4:5]
	v_lshl_add_u64 v[4:5], s[6:7], 0, v[4:5]
	v_lshl_add_u64 v[4:5], v[4:5], 0, v[192:193]
	global_load_dwordx2 v[20:21], v[4:5], off
	v_mul_f32_e32 v9, 0xbfb8aa3b, v105
	v_exp_f32_e32 v18, v9
	v_mul_f32_e32 v9, 0xbfb8aa3b, v104
	v_exp_f32_e32 v16, v9
	v_mul_f32_e32 v9, 0xbfb8aa3b, v103
	v_exp_f32_e32 v19, v9
	v_mul_f32_e32 v9, 0xbfb8aa3b, v102
	v_exp_f32_e32 v17, v9
	v_pk_add_f32 v[18:19], v[18:19], 1.0 op_sel_hi:[1,0]
	v_pk_add_f32 v[16:17], v[16:17], 1.0 op_sel_hi:[1,0]
	s_waitcnt vmcnt(0)
	v_lshlrev_b32_e32 v23, 16, v20
	v_rcp_f32_e32 v25, v18
	v_lshlrev_b32_e32 v9, 16, v21
	v_and_b32_e32 v20, 0xffff0000, v20
	v_and_b32_e32 v21, 0xffff0000, v21
	v_mul_f32_e32 v18, v23, v25
	v_rcp_f32_e32 v24, v19
	s_nop 0
	v_mul_f32_e32 v9, v9, v24
	v_rcp_f32_e32 v23, v16
	s_nop 0
	v_mul_f32_e32 v16, v20, v23
	v_rcp_f32_e32 v20, v17
	s_nop 0
	v_mul_f32_e32 v17, v21, v20
	v_and_b32_sdwa v19, v9, v218 dst_sel:DWORD dst_unused:UNUSED_PAD src0_sel:WORD_1 src1_sel:DWORD
	v_and_b32_sdwa v20, v18, v218 dst_sel:DWORD dst_unused:UNUSED_PAD src0_sel:WORD_1 src1_sel:DWORD
	v_add3_u32 v18, v18, v20, s80
	v_add3_u32 v9, v9, v19, s80
	v_and_b32_sdwa v19, v17, v218 dst_sel:DWORD dst_unused:UNUSED_PAD src0_sel:WORD_1 src1_sel:DWORD
	v_and_b32_sdwa v20, v16, v218 dst_sel:DWORD dst_unused:UNUSED_PAD src0_sel:WORD_1 src1_sel:DWORD
	v_add3_u32 v17, v17, v19, s80
	v_add3_u32 v16, v16, v20, s80
	v_and_b32_e32 v17, 0xffff0000, v17
	v_and_b32_e32 v16, 0xffff0000, v16
	v_or_b32_sdwa v17, v17, v9 dst_sel:DWORD dst_unused:UNUSED_PAD src0_sel:DWORD src1_sel:WORD_1
	v_or_b32_sdwa v16, v16, v18 dst_sel:DWORD dst_unused:UNUSED_PAD src0_sel:DWORD src1_sel:WORD_1
	global_store_dwordx2 v[2:3], v[16:17], off offset:32
	global_load_dwordx2 v[4:5], v[4:5], off offset:16
	v_mul_f32_e32 v9, 0xbfb8aa3b, v101
	v_exp_f32_e32 v16, v9
	v_mul_f32_e32 v9, 0xbfb8aa3b, v100
	v_exp_f32_e32 v18, v9
	v_mul_f32_e32 v9, 0xbfb8aa3b, v99
	v_exp_f32_e32 v17, v9
	v_mul_f32_e32 v9, 0xbfb8aa3b, v98
	v_exp_f32_e32 v19, v9
	s_waitcnt vmcnt(0)
	v_lshlrev_b32_e32 v9, 16, v5
	v_lshlrev_b32_e32 v20, 16, v4
	v_and_b32_e32 v21, 0xffff0000, v5
	v_and_b32_e32 v23, 0xffff0000, v4
	v_pk_add_f32 v[4:5], v[16:17], 1.0 op_sel_hi:[1,0]
	s_nop 0
	v_rcp_f32_e32 v17, v4
	s_nop 0
	v_mul_f32_e32 v16, v20, v17
	v_rcp_f32_e32 v17, v5
	s_nop 0
	v_mul_f32_e32 v9, v9, v17
	v_pk_add_f32 v[4:5], v[18:19], 1.0 op_sel_hi:[1,0]
	s_nop 0
	v_rcp_f32_e32 v18, v4
	s_nop 0
	v_mul_f32_e32 v4, v23, v18
	v_rcp_f32_e32 v18, v5
	s_nop 0
	v_mul_f32_e32 v5, v21, v18
	v_and_b32_sdwa v17, v9, v218 dst_sel:DWORD dst_unused:UNUSED_PAD src0_sel:WORD_1 src1_sel:DWORD
	v_and_b32_sdwa v18, v16, v218 dst_sel:DWORD dst_unused:UNUSED_PAD src0_sel:WORD_1 src1_sel:DWORD
	v_add3_u32 v16, v16, v18, s80
	v_add3_u32 v9, v9, v17, s80
	v_and_b32_sdwa v17, v5, v218 dst_sel:DWORD dst_unused:UNUSED_PAD src0_sel:WORD_1 src1_sel:DWORD
	v_and_b32_sdwa v18, v4, v218 dst_sel:DWORD dst_unused:UNUSED_PAD src0_sel:WORD_1 src1_sel:DWORD
	v_add3_u32 v5, v5, v17, s80
	v_add3_u32 v4, v4, v18, s80
	v_and_b32_e32 v5, 0xffff0000, v5
	v_and_b32_e32 v4, 0xffff0000, v4
	v_or_b32_sdwa v5, v5, v9 dst_sel:DWORD dst_unused:UNUSED_PAD src0_sel:DWORD src1_sel:WORD_1
	v_or_b32_sdwa v4, v4, v16 dst_sel:DWORD dst_unused:UNUSED_PAD src0_sel:DWORD src1_sel:WORD_1
	global_store_dwordx2 v[2:3], v[4:5], off offset:48
	v_or_b32_e32 v4, 32, v6
	v_ashrrev_i32_e32 v5, 31, v4
	v_lshl_add_u64 v[0:1], v[0:1], 0, v[4:5]
	v_lshlrev_b64 v[0:1], 5, v[0:1]
	v_lshl_add_u64 v[16:17], s[6:7], 0, v[0:1]
	v_lshl_add_u64 v[20:21], v[16:17], 0, v[192:193]
	global_load_dwordx2 v[20:21], v[20:21], off
	v_lshlrev_b64 v[18:19], 11, v[4:5]
	v_mul_f32_e32 v9, 0xbfb8aa3b, v97
	v_lshl_add_u64 v[0:1], s[4:5], 0, v[18:19]
	v_exp_f32_e32 v18, v9
	v_mul_f32_e32 v9, 0xbfb8aa3b, v96
	v_lshl_add_u64 v[0:1], v[0:1], 0, v[14:15]
	v_exp_f32_e32 v14, v9
	v_mul_f32_e32 v9, 0xbfb8aa3b, v95
	v_exp_f32_e32 v19, v9
	v_mul_f32_e32 v9, 0xbfb8aa3b, v94
	v_exp_f32_e32 v15, v9
	v_lshl_add_u64 v[16:17], v[16:17], 0, v[10:11]
	v_pk_add_f32 v[18:19], v[18:19], 1.0 op_sel_hi:[1,0]
	v_pk_add_f32 v[14:15], v[14:15], 1.0 op_sel_hi:[1,0]
	s_waitcnt vmcnt(0)
	v_lshlrev_b32_e32 v23, 16, v20
	v_rcp_f32_e32 v25, v18
	v_lshlrev_b32_e32 v9, 16, v21
	v_and_b32_e32 v20, 0xffff0000, v20
	v_and_b32_e32 v21, 0xffff0000, v21
	v_mul_f32_e32 v18, v23, v25
	v_rcp_f32_e32 v24, v19
	s_nop 0
	v_mul_f32_e32 v9, v9, v24
	v_rcp_f32_e32 v23, v14
	s_nop 0
	v_mul_f32_e32 v14, v20, v23
	v_rcp_f32_e32 v20, v15
	s_nop 0
	v_mul_f32_e32 v15, v21, v20
	v_and_b32_sdwa v19, v9, v218 dst_sel:DWORD dst_unused:UNUSED_PAD src0_sel:WORD_1 src1_sel:DWORD
	v_and_b32_sdwa v20, v18, v218 dst_sel:DWORD dst_unused:UNUSED_PAD src0_sel:WORD_1 src1_sel:DWORD
	v_add3_u32 v18, v18, v20, s80
	v_add3_u32 v9, v9, v19, s80
	v_and_b32_sdwa v19, v15, v218 dst_sel:DWORD dst_unused:UNUSED_PAD src0_sel:WORD_1 src1_sel:DWORD
	v_and_b32_sdwa v20, v14, v218 dst_sel:DWORD dst_unused:UNUSED_PAD src0_sel:WORD_1 src1_sel:DWORD
	v_add3_u32 v15, v15, v19, s80
	v_add3_u32 v14, v14, v20, s80
	v_and_b32_e32 v15, 0xffff0000, v15
	v_and_b32_e32 v14, 0xffff0000, v14
	v_or_b32_sdwa v15, v15, v9 dst_sel:DWORD dst_unused:UNUSED_PAD src0_sel:DWORD src1_sel:WORD_1
	v_or_b32_sdwa v14, v14, v18 dst_sel:DWORD dst_unused:UNUSED_PAD src0_sel:DWORD src1_sel:WORD_1
	global_store_dwordx2 v[0:1], v[14:15], off
	global_load_dwordx2 v[16:17], v[16:17], off
	v_mul_f32_e32 v9, 0xbfb8aa3b, v93
	v_exp_f32_e32 v14, v9
	v_mul_f32_e32 v9, 0xbfb8aa3b, v92
	v_exp_f32_e32 v10, v9
	v_mul_f32_e32 v9, 0xbfb8aa3b, v91
	v_exp_f32_e32 v15, v9
	v_mul_f32_e32 v9, 0xbfb8aa3b, v90
	v_exp_f32_e32 v11, v9
	v_pk_add_f32 v[14:15], v[14:15], 1.0 op_sel_hi:[1,0]
	v_pk_add_f32 v[10:11], v[10:11], 1.0 op_sel_hi:[1,0]
	s_waitcnt vmcnt(0)
	v_lshlrev_b32_e32 v18, 16, v16
	v_rcp_f32_e32 v20, v14
	v_lshlrev_b32_e32 v9, 16, v17
	v_and_b32_e32 v16, 0xffff0000, v16
	v_and_b32_e32 v17, 0xffff0000, v17
	v_mul_f32_e32 v14, v18, v20
	v_rcp_f32_e32 v19, v15
	s_nop 0
	v_mul_f32_e32 v9, v9, v19
	v_rcp_f32_e32 v18, v10
	s_nop 0
	v_mul_f32_e32 v10, v16, v18
	v_rcp_f32_e32 v16, v11
	s_nop 0
	v_mul_f32_e32 v11, v17, v16
	v_and_b32_sdwa v15, v9, v218 dst_sel:DWORD dst_unused:UNUSED_PAD src0_sel:WORD_1 src1_sel:DWORD
	v_and_b32_sdwa v16, v14, v218 dst_sel:DWORD dst_unused:UNUSED_PAD src0_sel:WORD_1 src1_sel:DWORD
	v_add3_u32 v14, v14, v16, s80
	v_add3_u32 v9, v9, v15, s80
	v_and_b32_sdwa v15, v11, v218 dst_sel:DWORD dst_unused:UNUSED_PAD src0_sel:WORD_1 src1_sel:DWORD
	v_and_b32_sdwa v16, v10, v218 dst_sel:DWORD dst_unused:UNUSED_PAD src0_sel:WORD_1 src1_sel:DWORD
	v_add3_u32 v11, v11, v15, s80
	v_add3_u32 v10, v10, v16, s80
	v_and_b32_e32 v11, 0xffff0000, v11
	v_and_b32_e32 v10, 0xffff0000, v10
	v_or_b32_sdwa v11, v11, v9 dst_sel:DWORD dst_unused:UNUSED_PAD src0_sel:DWORD src1_sel:WORD_1
	v_or_b32_sdwa v10, v10, v14 dst_sel:DWORD dst_unused:UNUSED_PAD src0_sel:DWORD src1_sel:WORD_1
	global_store_dwordx2 v[0:1], v[10:11], off offset:16
	v_lshl_add_u64 v[10:11], v[12:13], 0, v[4:5]
	v_lshlrev_b64 v[10:11], 5, v[10:11]
	v_lshl_add_u64 v[10:11], s[6:7], 0, v[10:11]
	v_lshl_add_u64 v[10:11], v[10:11], 0, v[192:193]
	global_load_dwordx2 v[16:17], v[10:11], off
	v_mul_f32_e32 v9, 0xbfb8aa3b, v89
	v_exp_f32_e32 v14, v9
	v_mul_f32_e32 v9, 0xbfb8aa3b, v88
	v_exp_f32_e32 v12, v9
	v_mul_f32_e32 v9, 0xbfb8aa3b, v87
	v_exp_f32_e32 v15, v9
	v_mul_f32_e32 v9, 0xbfb8aa3b, v86
	v_exp_f32_e32 v13, v9
	v_pk_add_f32 v[14:15], v[14:15], 1.0 op_sel_hi:[1,0]
	v_pk_add_f32 v[12:13], v[12:13], 1.0 op_sel_hi:[1,0]
	s_waitcnt vmcnt(0)
	v_lshlrev_b32_e32 v18, 16, v16
	v_rcp_f32_e32 v20, v14
	v_lshlrev_b32_e32 v9, 16, v17
	v_and_b32_e32 v16, 0xffff0000, v16
	v_and_b32_e32 v17, 0xffff0000, v17
	v_mul_f32_e32 v14, v18, v20
	v_rcp_f32_e32 v19, v15
	s_nop 0
	v_mul_f32_e32 v9, v9, v19
	v_rcp_f32_e32 v18, v12
	s_nop 0
	v_mul_f32_e32 v12, v16, v18
	v_rcp_f32_e32 v16, v13
	s_nop 0
	v_mul_f32_e32 v13, v17, v16
	v_and_b32_sdwa v15, v9, v218 dst_sel:DWORD dst_unused:UNUSED_PAD src0_sel:WORD_1 src1_sel:DWORD
	v_and_b32_sdwa v16, v14, v218 dst_sel:DWORD dst_unused:UNUSED_PAD src0_sel:WORD_1 src1_sel:DWORD
	v_add3_u32 v14, v14, v16, s80
	v_add3_u32 v9, v9, v15, s80
	v_and_b32_sdwa v15, v13, v218 dst_sel:DWORD dst_unused:UNUSED_PAD src0_sel:WORD_1 src1_sel:DWORD
	v_and_b32_sdwa v16, v12, v218 dst_sel:DWORD dst_unused:UNUSED_PAD src0_sel:WORD_1 src1_sel:DWORD
	v_add3_u32 v13, v13, v15, s80
	v_add3_u32 v12, v12, v16, s80
	v_and_b32_e32 v13, 0xffff0000, v13
	v_and_b32_e32 v12, 0xffff0000, v12
	v_or_b32_sdwa v13, v13, v9 dst_sel:DWORD dst_unused:UNUSED_PAD src0_sel:DWORD src1_sel:WORD_1
	v_or_b32_sdwa v12, v12, v14 dst_sel:DWORD dst_unused:UNUSED_PAD src0_sel:DWORD src1_sel:WORD_1
	global_store_dwordx2 v[0:1], v[12:13], off offset:32
	global_load_dwordx2 v[10:11], v[10:11], off offset:16
	v_mul_f32_e32 v9, 0xbfb8aa3b, v85
	v_exp_f32_e32 v12, v9
	v_mul_f32_e32 v9, 0xbfb8aa3b, v84
	v_exp_f32_e32 v14, v9
	v_mul_f32_e32 v9, 0xbfb8aa3b, v83
	v_exp_f32_e32 v13, v9
	v_mul_f32_e32 v9, 0xbfb8aa3b, v82
	v_exp_f32_e32 v15, v9
	s_waitcnt vmcnt(0)
	v_lshlrev_b32_e32 v9, 16, v11
	v_lshlrev_b32_e32 v16, 16, v10
	v_and_b32_e32 v17, 0xffff0000, v11
	v_and_b32_e32 v18, 0xffff0000, v10
	v_pk_add_f32 v[10:11], v[12:13], 1.0 op_sel_hi:[1,0]
	s_nop 0
	v_rcp_f32_e32 v13, v10
	s_nop 0
	v_mul_f32_e32 v12, v16, v13
	v_rcp_f32_e32 v13, v11
	s_nop 0
	v_mul_f32_e32 v9, v9, v13
	v_pk_add_f32 v[10:11], v[14:15], 1.0 op_sel_hi:[1,0]
	s_nop 0
	v_rcp_f32_e32 v14, v10
	s_nop 0
	v_mul_f32_e32 v10, v18, v14
	v_rcp_f32_e32 v14, v11
	s_nop 0
	v_mul_f32_e32 v11, v17, v14
	v_and_b32_sdwa v13, v9, v218 dst_sel:DWORD dst_unused:UNUSED_PAD src0_sel:WORD_1 src1_sel:DWORD
	v_add3_u32 v9, v9, v13, s80
	v_and_b32_sdwa v13, v11, v218 dst_sel:DWORD dst_unused:UNUSED_PAD src0_sel:WORD_1 src1_sel:DWORD
	v_and_b32_sdwa v14, v12, v218 dst_sel:DWORD dst_unused:UNUSED_PAD src0_sel:WORD_1 src1_sel:DWORD
	v_add3_u32 v11, v11, v13, s80
	v_add3_u32 v12, v12, v14, s80
	v_and_b32_sdwa v14, v10, v218 dst_sel:DWORD dst_unused:UNUSED_PAD src0_sel:WORD_1 src1_sel:DWORD
	v_and_b32_e32 v11, 0xffff0000, v11
	v_add3_u32 v10, v10, v14, s80
	v_or_b32_sdwa v11, v11, v9 dst_sel:DWORD dst_unused:UNUSED_PAD src0_sel:DWORD src1_sel:WORD_1
	v_or_b32_e32 v9, 32, v22
	v_and_b32_e32 v10, 0xffff0000, v10
	v_lshrrev_b32_e32 v9, 4, v9
	v_or_b32_sdwa v10, v10, v12 dst_sel:DWORD dst_unused:UNUSED_PAD src0_sel:DWORD src1_sel:WORD_1
	v_mul_lo_u32 v12, v9, s3
	v_ashrrev_i32_e32 v13, 31, v12
	global_store_dwordx2 v[0:1], v[10:11], off offset:48
	v_lshl_add_u64 v[10:11], v[12:13], 0, v[6:7]
	v_lshlrev_b64 v[10:11], 5, v[10:11]
	v_lshl_add_u64 v[10:11], s[6:7], 0, v[10:11]
	v_lshl_add_u64 v[16:17], v[10:11], 0, v[192:193]
	global_load_dwordx2 v[16:17], v[16:17], off
	v_mul_f32_e32 v9, 0xbfb8aa3b, v81
	v_exp_f32_e32 v14, v9
	v_mul_f32_e32 v9, 0xbfb8aa3b, v80
	v_exp_f32_e32 v10, v9
	v_mul_f32_e32 v9, 0xbfb8aa3b, v79
	v_exp_f32_e32 v15, v9
	v_mul_f32_e32 v9, 0xbfb8aa3b, v78
	v_exp_f32_e32 v11, v9
	v_pk_add_f32 v[14:15], v[14:15], 1.0 op_sel_hi:[1,0]
	v_pk_add_f32 v[10:11], v[10:11], 1.0 op_sel_hi:[1,0]
	s_waitcnt vmcnt(0)
	v_lshlrev_b32_e32 v18, 16, v16
	v_rcp_f32_e32 v20, v14
	v_lshlrev_b32_e32 v9, 16, v17
	v_and_b32_e32 v16, 0xffff0000, v16
	v_and_b32_e32 v17, 0xffff0000, v17
	v_mul_f32_e32 v14, v18, v20
	v_rcp_f32_e32 v19, v15
	s_nop 0
	v_mul_f32_e32 v9, v9, v19
	v_rcp_f32_e32 v18, v10
	s_nop 0
	v_mul_f32_e32 v10, v16, v18
	v_rcp_f32_e32 v16, v11
	s_nop 0
	v_mul_f32_e32 v11, v17, v16
	v_and_b32_sdwa v15, v9, v218 dst_sel:DWORD dst_unused:UNUSED_PAD src0_sel:WORD_1 src1_sel:DWORD
	v_and_b32_sdwa v16, v14, v218 dst_sel:DWORD dst_unused:UNUSED_PAD src0_sel:WORD_1 src1_sel:DWORD
	v_add3_u32 v9, v9, v15, s80
	v_and_b32_sdwa v15, v11, v218 dst_sel:DWORD dst_unused:UNUSED_PAD src0_sel:WORD_1 src1_sel:DWORD
	v_add3_u32 v14, v14, v16, s80
	v_and_b32_sdwa v16, v10, v218 dst_sel:DWORD dst_unused:UNUSED_PAD src0_sel:WORD_1 src1_sel:DWORD
	v_add3_u32 v11, v11, v15, s80
	v_add3_u32 v10, v10, v16, s80
	v_and_b32_e32 v11, 0xffff0000, v11
	v_and_b32_e32 v10, 0xffff0000, v10
	v_or_b32_sdwa v11, v11, v9 dst_sel:DWORD dst_unused:UNUSED_PAD src0_sel:DWORD src1_sel:WORD_1
	v_or_b32_e32 v9, 40, v8
	v_or_b32_sdwa v10, v10, v14 dst_sel:DWORD dst_unused:UNUSED_PAD src0_sel:DWORD src1_sel:WORD_1
	v_lshrrev_b32_e32 v9, 4, v9
	global_store_dwordx2 v[2:3], v[10:11], off offset:64
	v_mul_lo_u32 v10, v9, s3
	v_ashrrev_i32_e32 v11, 31, v10
	v_lshl_add_u64 v[14:15], v[10:11], 0, v[6:7]
	v_lshlrev_b64 v[14:15], 5, v[14:15]
	v_bitop3_b32 v8, v8, 12, 40 bitop3:0xc8
	v_lshl_add_u64 v[14:15], s[6:7], 0, v[14:15]
	v_lshlrev_b32_e32 v8, 1, v8
	v_mov_b32_e32 v9, v193
	v_lshl_add_u64 v[18:19], v[14:15], 0, v[8:9]
	global_load_dwordx2 v[18:19], v[18:19], off
	v_mul_f32_e32 v14, 0xbfb8aa3b, v77
	v_mul_f32_e32 v15, 0xbfb8aa3b, v75
	v_exp_f32_e32 v16, v14
	v_exp_f32_e32 v17, v15
	v_mul_f32_e32 v14, 0xbfb8aa3b, v76
	v_mul_f32_e32 v15, 0xbfb8aa3b, v74
	v_exp_f32_e32 v14, v14
	v_pk_add_f32 v[16:17], v[16:17], 1.0 op_sel_hi:[1,0]
	v_exp_f32_e32 v15, v15
	s_waitcnt vmcnt(0)
	v_lshlrev_b32_e32 v21, 16, v18
	v_rcp_f32_e32 v24, v16
	v_lshlrev_b32_e32 v20, 16, v19
	v_and_b32_e32 v18, 0xffff0000, v18
	v_pk_add_f32 v[14:15], v[14:15], 1.0 op_sel_hi:[1,0]
	v_mul_f32_e32 v16, v21, v24
	v_rcp_f32_e32 v23, v17
	v_and_b32_e32 v19, 0xffff0000, v19
	v_mul_f32_e32 v17, v20, v23
	v_rcp_f32_e32 v21, v14
	s_nop 0
	v_mul_f32_e32 v14, v18, v21
	v_rcp_f32_e32 v20, v15
	s_nop 0
	v_mul_f32_e32 v15, v19, v20
	v_and_b32_sdwa v18, v17, v218 dst_sel:DWORD dst_unused:UNUSED_PAD src0_sel:WORD_1 src1_sel:DWORD
	v_and_b32_sdwa v19, v16, v218 dst_sel:DWORD dst_unused:UNUSED_PAD src0_sel:WORD_1 src1_sel:DWORD
	v_add3_u32 v16, v16, v19, s80
	v_add3_u32 v17, v17, v18, s80
	v_and_b32_sdwa v18, v15, v218 dst_sel:DWORD dst_unused:UNUSED_PAD src0_sel:WORD_1 src1_sel:DWORD
	v_and_b32_sdwa v19, v14, v218 dst_sel:DWORD dst_unused:UNUSED_PAD src0_sel:WORD_1 src1_sel:DWORD
	v_add3_u32 v15, v15, v18, s80
	v_add3_u32 v14, v14, v19, s80
	v_and_b32_e32 v15, 0xffff0000, v15
	v_and_b32_e32 v14, 0xffff0000, v14
	v_or_b32_sdwa v15, v15, v17 dst_sel:DWORD dst_unused:UNUSED_PAD src0_sel:DWORD src1_sel:WORD_1
	v_or_b32_sdwa v14, v14, v16 dst_sel:DWORD dst_unused:UNUSED_PAD src0_sel:DWORD src1_sel:WORD_1
	global_store_dwordx2 v[2:3], v[14:15], off offset:80
	v_or_b32_e32 v14, 48, v22
	v_lshrrev_b32_e32 v14, 4, v14
	v_mul_lo_u32 v14, v14, s3
	v_ashrrev_i32_e32 v15, 31, v14
	v_lshl_add_u64 v[6:7], v[14:15], 0, v[6:7]
	v_lshlrev_b64 v[6:7], 5, v[6:7]
	v_lshl_add_u64 v[6:7], s[6:7], 0, v[6:7]
	v_lshl_add_u64 v[6:7], v[6:7], 0, v[192:193]
	global_load_dwordx2 v[20:21], v[6:7], off
	v_mul_f32_e32 v16, 0xbfb8aa3b, v73
	v_mul_f32_e32 v17, 0xbfb8aa3b, v71
	v_exp_f32_e32 v18, v16
	v_exp_f32_e32 v19, v17
	v_mul_f32_e32 v16, 0xbfb8aa3b, v72
	v_mul_f32_e32 v17, 0xbfb8aa3b, v70
	v_exp_f32_e32 v16, v16
	v_pk_add_f32 v[18:19], v[18:19], 1.0 op_sel_hi:[1,0]
	v_exp_f32_e32 v17, v17
	s_waitcnt vmcnt(0)
	v_lshlrev_b32_e32 v23, 16, v20
	v_rcp_f32_e32 v25, v18
	v_lshlrev_b32_e32 v22, 16, v21
	v_and_b32_e32 v20, 0xffff0000, v20
	v_pk_add_f32 v[16:17], v[16:17], 1.0 op_sel_hi:[1,0]
	v_mul_f32_e32 v18, v23, v25
	v_rcp_f32_e32 v24, v19
	v_and_b32_e32 v21, 0xffff0000, v21
	v_mul_f32_e32 v19, v22, v24
	v_rcp_f32_e32 v23, v16
	s_nop 0
	v_mul_f32_e32 v16, v20, v23
	v_rcp_f32_e32 v22, v17
	s_nop 0
	v_mul_f32_e32 v17, v21, v22
	v_and_b32_sdwa v20, v19, v218 dst_sel:DWORD dst_unused:UNUSED_PAD src0_sel:WORD_1 src1_sel:DWORD
	v_and_b32_sdwa v21, v18, v218 dst_sel:DWORD dst_unused:UNUSED_PAD src0_sel:WORD_1 src1_sel:DWORD
	v_add3_u32 v18, v18, v21, s80
	v_add3_u32 v19, v19, v20, s80
	v_and_b32_sdwa v20, v17, v218 dst_sel:DWORD dst_unused:UNUSED_PAD src0_sel:WORD_1 src1_sel:DWORD
	v_and_b32_sdwa v21, v16, v218 dst_sel:DWORD dst_unused:UNUSED_PAD src0_sel:WORD_1 src1_sel:DWORD
	v_add3_u32 v17, v17, v20, s80
	v_add3_u32 v16, v16, v21, s80
	v_and_b32_e32 v17, 0xffff0000, v17
	v_and_b32_e32 v16, 0xffff0000, v16
	v_or_b32_sdwa v17, v17, v19 dst_sel:DWORD dst_unused:UNUSED_PAD src0_sel:DWORD src1_sel:WORD_1
	v_or_b32_sdwa v16, v16, v18 dst_sel:DWORD dst_unused:UNUSED_PAD src0_sel:DWORD src1_sel:WORD_1
	global_store_dwordx2 v[2:3], v[16:17], off offset:96
	global_load_dwordx2 v[6:7], v[6:7], off offset:16
	v_mul_f32_e32 v17, 0xbfb8aa3b, v68
	v_mul_f32_e32 v16, 0xbfb8aa3b, v69
	v_exp_f32_e32 v18, v17
	v_mul_f32_e32 v17, 0xbfb8aa3b, v67
	v_exp_f32_e32 v16, v16
	v_exp_f32_e32 v17, v17
	v_mul_f32_e32 v19, 0xbfb8aa3b, v66
	v_exp_f32_e32 v19, v19
	s_waitcnt vmcnt(0)
	v_lshlrev_b32_e32 v20, 16, v7
	v_lshlrev_b32_e32 v21, 16, v6
	v_and_b32_e32 v22, 0xffff0000, v7
	v_and_b32_e32 v23, 0xffff0000, v6
	v_pk_add_f32 v[6:7], v[16:17], 1.0 op_sel_hi:[1,0]
	s_nop 0
	v_rcp_f32_e32 v17, v6
	s_nop 0
	v_mul_f32_e32 v16, v21, v17
	v_rcp_f32_e32 v17, v7
	s_nop 0
	v_mul_f32_e32 v17, v20, v17
	v_pk_add_f32 v[6:7], v[18:19], 1.0 op_sel_hi:[1,0]
	s_nop 0
	v_rcp_f32_e32 v19, v6
	s_nop 0
	v_mul_f32_e32 v6, v23, v19
	v_rcp_f32_e32 v19, v7
	s_nop 0
	v_mul_f32_e32 v7, v22, v19
	v_and_b32_sdwa v18, v17, v218 dst_sel:DWORD dst_unused:UNUSED_PAD src0_sel:WORD_1 src1_sel:DWORD
	v_and_b32_sdwa v19, v16, v218 dst_sel:DWORD dst_unused:UNUSED_PAD src0_sel:WORD_1 src1_sel:DWORD
	v_add3_u32 v16, v16, v19, s80
	v_add3_u32 v17, v17, v18, s80
	v_and_b32_sdwa v18, v7, v218 dst_sel:DWORD dst_unused:UNUSED_PAD src0_sel:WORD_1 src1_sel:DWORD
	v_and_b32_sdwa v19, v6, v218 dst_sel:DWORD dst_unused:UNUSED_PAD src0_sel:WORD_1 src1_sel:DWORD
	v_add3_u32 v7, v7, v18, s80
	v_add3_u32 v6, v6, v19, s80
	v_and_b32_e32 v7, 0xffff0000, v7
	v_and_b32_e32 v6, 0xffff0000, v6
	v_or_b32_sdwa v7, v7, v17 dst_sel:DWORD dst_unused:UNUSED_PAD src0_sel:DWORD src1_sel:WORD_1
	v_or_b32_sdwa v6, v6, v16 dst_sel:DWORD dst_unused:UNUSED_PAD src0_sel:DWORD src1_sel:WORD_1
	global_store_dwordx2 v[2:3], v[6:7], off offset:112
	v_lshl_add_u64 v[2:3], v[12:13], 0, v[4:5]
	v_lshlrev_b64 v[2:3], 5, v[2:3]
	v_lshl_add_u64 v[2:3], s[6:7], 0, v[2:3]
	v_lshl_add_u64 v[12:13], v[2:3], 0, v[192:193]
	global_load_dwordx2 v[12:13], v[12:13], off
	v_mul_f32_e32 v2, 0xbfb8aa3b, v65
	v_mul_f32_e32 v3, 0xbfb8aa3b, v63
	v_exp_f32_e32 v6, v2
	v_exp_f32_e32 v7, v3
	v_mul_f32_e32 v2, 0xbfb8aa3b, v64
	v_mul_f32_e32 v3, 0xbfb8aa3b, v62
	v_exp_f32_e32 v2, v2
	v_pk_add_f32 v[6:7], v[6:7], 1.0 op_sel_hi:[1,0]
	v_exp_f32_e32 v3, v3
	s_waitcnt vmcnt(0)
	v_lshlrev_b32_e32 v17, 16, v12
	v_rcp_f32_e32 v19, v6
	v_lshlrev_b32_e32 v16, 16, v13
	v_and_b32_e32 v12, 0xffff0000, v12
	v_pk_add_f32 v[2:3], v[2:3], 1.0 op_sel_hi:[1,0]
	v_mul_f32_e32 v6, v17, v19
	v_rcp_f32_e32 v18, v7
	v_and_b32_e32 v13, 0xffff0000, v13
	v_mul_f32_e32 v7, v16, v18
	v_rcp_f32_e32 v17, v2
	s_nop 0
	v_mul_f32_e32 v2, v12, v17
	v_rcp_f32_e32 v16, v3
	s_nop 0
	v_mul_f32_e32 v3, v13, v16
	v_and_b32_sdwa v12, v7, v218 dst_sel:DWORD dst_unused:UNUSED_PAD src0_sel:WORD_1 src1_sel:DWORD
	v_and_b32_sdwa v13, v6, v218 dst_sel:DWORD dst_unused:UNUSED_PAD src0_sel:WORD_1 src1_sel:DWORD
	v_add3_u32 v6, v6, v13, s80
	v_add3_u32 v7, v7, v12, s80
	v_and_b32_sdwa v12, v3, v218 dst_sel:DWORD dst_unused:UNUSED_PAD src0_sel:WORD_1 src1_sel:DWORD
	v_and_b32_sdwa v13, v2, v218 dst_sel:DWORD dst_unused:UNUSED_PAD src0_sel:WORD_1 src1_sel:DWORD
	v_add3_u32 v3, v3, v12, s80
	v_add3_u32 v2, v2, v13, s80
	v_and_b32_e32 v3, 0xffff0000, v3
	v_and_b32_e32 v2, 0xffff0000, v2
	v_or_b32_sdwa v3, v3, v7 dst_sel:DWORD dst_unused:UNUSED_PAD src0_sel:DWORD src1_sel:WORD_1
	v_or_b32_sdwa v2, v2, v6 dst_sel:DWORD dst_unused:UNUSED_PAD src0_sel:DWORD src1_sel:WORD_1
	global_store_dwordx2 v[0:1], v[2:3], off offset:64
	v_lshl_add_u64 v[2:3], v[10:11], 0, v[4:5]
	v_lshlrev_b64 v[2:3], 5, v[2:3]
	v_lshl_add_u64 v[2:3], s[6:7], 0, v[2:3]
	v_lshl_add_u64 v[8:9], v[2:3], 0, v[8:9]
	global_load_dwordx2 v[8:9], v[8:9], off
	v_mul_f32_e32 v2, 0xbfb8aa3b, v61
	v_mul_f32_e32 v3, 0xbfb8aa3b, v59
	v_exp_f32_e32 v6, v2
	v_exp_f32_e32 v7, v3
	v_mul_f32_e32 v2, 0xbfb8aa3b, v60
	v_mul_f32_e32 v3, 0xbfb8aa3b, v58
	v_exp_f32_e32 v2, v2
	v_pk_add_f32 v[6:7], v[6:7], 1.0 op_sel_hi:[1,0]
	v_exp_f32_e32 v3, v3
	s_waitcnt vmcnt(0)
	v_lshlrev_b32_e32 v11, 16, v8
	v_rcp_f32_e32 v13, v6
	v_lshlrev_b32_e32 v10, 16, v9
	v_and_b32_e32 v8, 0xffff0000, v8
	v_pk_add_f32 v[2:3], v[2:3], 1.0 op_sel_hi:[1,0]
	v_mul_f32_e32 v6, v11, v13
	v_rcp_f32_e32 v12, v7
	v_and_b32_e32 v9, 0xffff0000, v9
	v_mul_f32_e32 v7, v10, v12
	v_rcp_f32_e32 v11, v2
	s_nop 0
	v_mul_f32_e32 v2, v8, v11
	v_rcp_f32_e32 v10, v3
	s_nop 0
	v_mul_f32_e32 v3, v9, v10
	v_and_b32_sdwa v8, v7, v218 dst_sel:DWORD dst_unused:UNUSED_PAD src0_sel:WORD_1 src1_sel:DWORD
	v_and_b32_sdwa v9, v6, v218 dst_sel:DWORD dst_unused:UNUSED_PAD src0_sel:WORD_1 src1_sel:DWORD
	v_add3_u32 v6, v6, v9, s80
	v_add3_u32 v7, v7, v8, s80
	v_and_b32_sdwa v8, v3, v218 dst_sel:DWORD dst_unused:UNUSED_PAD src0_sel:WORD_1 src1_sel:DWORD
	v_and_b32_sdwa v9, v2, v218 dst_sel:DWORD dst_unused:UNUSED_PAD src0_sel:WORD_1 src1_sel:DWORD
	v_add3_u32 v3, v3, v8, s80
	v_add3_u32 v2, v2, v9, s80
	v_and_b32_e32 v3, 0xffff0000, v3
	v_and_b32_e32 v2, 0xffff0000, v2
	v_or_b32_sdwa v3, v3, v7 dst_sel:DWORD dst_unused:UNUSED_PAD src0_sel:DWORD src1_sel:WORD_1
	v_or_b32_sdwa v2, v2, v6 dst_sel:DWORD dst_unused:UNUSED_PAD src0_sel:DWORD src1_sel:WORD_1
	global_store_dwordx2 v[0:1], v[2:3], off offset:80
	v_lshl_add_u64 v[2:3], v[14:15], 0, v[4:5]
	v_lshlrev_b64 v[2:3], 5, v[2:3]
	v_lshl_add_u64 v[2:3], s[6:7], 0, v[2:3]
	v_lshl_add_u64 v[2:3], v[2:3], 0, v[192:193]
	global_load_dwordx2 v[8:9], v[2:3], off
	v_mul_f32_e32 v4, 0xbfb8aa3b, v57
	v_mul_f32_e32 v5, 0xbfb8aa3b, v55
	v_exp_f32_e32 v6, v4
	v_exp_f32_e32 v7, v5
	v_mul_f32_e32 v4, 0xbfb8aa3b, v56
	v_mul_f32_e32 v5, 0xbfb8aa3b, v54
	v_exp_f32_e32 v4, v4
	v_pk_add_f32 v[6:7], v[6:7], 1.0 op_sel_hi:[1,0]
	v_exp_f32_e32 v5, v5
	s_waitcnt vmcnt(0)
	v_lshlrev_b32_e32 v11, 16, v8
	v_rcp_f32_e32 v13, v6
	v_lshlrev_b32_e32 v10, 16, v9
	v_and_b32_e32 v8, 0xffff0000, v8
	v_pk_add_f32 v[4:5], v[4:5], 1.0 op_sel_hi:[1,0]
	v_mul_f32_e32 v6, v11, v13
	v_rcp_f32_e32 v12, v7
	v_and_b32_e32 v9, 0xffff0000, v9
	v_mul_f32_e32 v7, v10, v12
	v_rcp_f32_e32 v11, v4
	s_nop 0
	v_mul_f32_e32 v4, v8, v11
	v_rcp_f32_e32 v10, v5
	s_nop 0
	v_mul_f32_e32 v5, v9, v10
	v_and_b32_sdwa v8, v7, v218 dst_sel:DWORD dst_unused:UNUSED_PAD src0_sel:WORD_1 src1_sel:DWORD
	v_and_b32_sdwa v9, v6, v218 dst_sel:DWORD dst_unused:UNUSED_PAD src0_sel:WORD_1 src1_sel:DWORD
	v_add3_u32 v6, v6, v9, s80
	v_add3_u32 v7, v7, v8, s80
	v_and_b32_sdwa v8, v5, v218 dst_sel:DWORD dst_unused:UNUSED_PAD src0_sel:WORD_1 src1_sel:DWORD
	v_and_b32_sdwa v9, v4, v218 dst_sel:DWORD dst_unused:UNUSED_PAD src0_sel:WORD_1 src1_sel:DWORD
	v_add3_u32 v5, v5, v8, s80
	v_add3_u32 v4, v4, v9, s80
	v_and_b32_e32 v5, 0xffff0000, v5
	v_and_b32_e32 v4, 0xffff0000, v4
	v_or_b32_sdwa v5, v5, v7 dst_sel:DWORD dst_unused:UNUSED_PAD src0_sel:DWORD src1_sel:WORD_1
	v_or_b32_sdwa v4, v4, v6 dst_sel:DWORD dst_unused:UNUSED_PAD src0_sel:DWORD src1_sel:WORD_1
	global_store_dwordx2 v[0:1], v[4:5], off offset:96
	global_load_dwordx2 v[2:3], v[2:3], off offset:16
	v_mul_f32_e32 v5, 0xbfb8aa3b, v52
	v_mul_f32_e32 v4, 0xbfb8aa3b, v53
	v_exp_f32_e32 v6, v5
	v_mul_f32_e32 v5, 0xbfb8aa3b, v51
	v_exp_f32_e32 v4, v4
	v_exp_f32_e32 v5, v5
	v_mul_f32_e32 v7, 0xbfb8aa3b, v50
	v_exp_f32_e32 v7, v7
	s_waitcnt vmcnt(0)
	v_lshlrev_b32_e32 v8, 16, v3
	v_lshlrev_b32_e32 v9, 16, v2
	v_and_b32_e32 v10, 0xffff0000, v3
	v_and_b32_e32 v11, 0xffff0000, v2
	v_pk_add_f32 v[2:3], v[4:5], 1.0 op_sel_hi:[1,0]
	s_nop 0
	v_rcp_f32_e32 v5, v2
	s_nop 0
	v_mul_f32_e32 v4, v9, v5
	v_rcp_f32_e32 v5, v3
	s_nop 0
	v_mul_f32_e32 v5, v8, v5
	v_pk_add_f32 v[2:3], v[6:7], 1.0 op_sel_hi:[1,0]
	s_nop 0
	v_rcp_f32_e32 v7, v2
	s_nop 0
	v_mul_f32_e32 v2, v11, v7
	v_rcp_f32_e32 v7, v3
	s_nop 0
	v_mul_f32_e32 v3, v10, v7
	v_and_b32_sdwa v6, v5, v218 dst_sel:DWORD dst_unused:UNUSED_PAD src0_sel:WORD_1 src1_sel:DWORD
	v_and_b32_sdwa v7, v4, v218 dst_sel:DWORD dst_unused:UNUSED_PAD src0_sel:WORD_1 src1_sel:DWORD
	v_add3_u32 v4, v4, v7, s80
	v_add3_u32 v5, v5, v6, s80
	v_and_b32_sdwa v6, v3, v218 dst_sel:DWORD dst_unused:UNUSED_PAD src0_sel:WORD_1 src1_sel:DWORD
	v_and_b32_sdwa v7, v2, v218 dst_sel:DWORD dst_unused:UNUSED_PAD src0_sel:WORD_1 src1_sel:DWORD
	v_add3_u32 v3, v3, v6, s80
	v_add3_u32 v2, v2, v7, s80
	v_and_b32_e32 v3, 0xffff0000, v3
	v_and_b32_e32 v2, 0xffff0000, v2
	v_or_b32_sdwa v3, v3, v5 dst_sel:DWORD dst_unused:UNUSED_PAD src0_sel:DWORD src1_sel:WORD_1
	v_or_b32_sdwa v2, v2, v4 dst_sel:DWORD dst_unused:UNUSED_PAD src0_sel:DWORD src1_sel:WORD_1
	global_store_dwordx2 v[0:1], v[2:3], off offset:112

.LBB0_254:
	s_add_i32 s2, s1, 0x80
	s_min_u32 s3, s2, 0x2c0
	s_lshl_b32 s78, s3, 1
	v_lshl_add_u64 v[0:1], v[32:33], 0, s[78:79]
	v_lshl_add_u64 v[4:5], v[34:35], 0, s[78:79]
	v_lshl_add_u64 v[8:9], v[36:37], 0, s[78:79]
	v_lshl_add_u64 v[12:13], v[38:39], 0, s[78:79]
	v_lshl_add_u64 v[16:17], v[40:41], 0, s[78:79]
	v_lshl_add_u64 v[20:21], v[42:43], 0, s[78:79]
	v_lshl_add_u64 v[24:25], v[44:45], 0, s[78:79]
	v_lshl_add_u64 v[28:29], v[46:47], 0, s[78:79]
	global_load_dwordx4 v[0:3], v[0:1], off
	s_nop 0
	global_load_dwordx4 v[4:7], v[4:5], off
	s_nop 0
	global_load_dwordx4 v[8:11], v[8:9], off
	s_nop 0
	global_load_dwordx4 v[12:15], v[12:13], off
	s_nop 0
	global_load_dwordx4 v[16:19], v[16:17], off
	s_nop 0
	global_load_dwordx4 v[20:23], v[20:21], off
	s_nop 0
	global_load_dwordx4 v[24:27], v[24:25], off
	s_nop 0
	global_load_dwordx4 v[28:31], v[28:29], off
	ds_read_b128 v[68:71], v48 offset:0
	ds_read_b128 v[72:75], v48 offset:0x1000
	ds_read_b128 v[76:79], v52 offset:0
	ds_read_b128 v[80:83], v52 offset:0x1000
	s_min_u32 s1, s1, 0x200
	ds_read_b128 v[84:87], v49 offset:0
	ds_read_b128 v[88:91], v49 offset:0x1000
	ds_read_b128 v[92:95], v53 offset:0
	ds_read_b128 v[96:99], v53 offset:0x1000
	ds_read_b128 v[100:103], v50 offset:0
	ds_read_b128 v[104:107], v50 offset:0x1000
	ds_read_b128 v[108:111], v54 offset:0
	ds_read_b128 v[112:115], v54 offset:0x1000
	ds_read_b128 v[116:119], v51 offset:0
	ds_read_b128 v[120:123], v51 offset:0x1000
	ds_read_b128 v[124:127], v55 offset:0
	ds_read_b128 v[128:131], v55 offset:0x1000
	s_waitcnt lgkmcnt(12)
	s_lshl_b32 s78, s1, 1
	v_mfma_f32_32x32x16_bf16 a[32:47], v[68:71], v[76:79], a[32:47]
	v_add_u32_e32 v67, v56, v57
	s_waitcnt lgkmcnt(8)
	s_waitcnt lgkmcnt(4)
	v_add_u32_e32 v170, v58, v59
	v_add_u32_e32 v171, v60, v61
	v_add_u32_e32 v172, v62, v63
	s_waitcnt lgkmcnt(0)
	v_mfma_f32_32x32x16_bf16 a[48:63], v[68:71], v[80:83], a[48:63]
	v_lshl_add_u64 v[68:69], v[32:33], 0, s[78:79]
	v_lshl_add_u64 v[70:71], v[34:35], 0, s[78:79]
	s_waitcnt vmcnt(15)
	ds_write_b128 v67, v[138:141] offset:32768
	s_waitcnt vmcnt(14)
	ds_write_b128 v67, v[142:145] offset:49152
	s_waitcnt vmcnt(13)
	ds_write_b128 v170, v[146:149] offset:32768
	s_waitcnt vmcnt(12)
	ds_write_b128 v170, v[150:153] offset:49152
	s_waitcnt vmcnt(11)
	ds_write_b128 v171, v[154:157] offset:32768
	s_waitcnt vmcnt(10)
	ds_write_b128 v171, v[158:161] offset:49152
	s_waitcnt vmcnt(9)
	ds_write_b128 v172, v[162:165] offset:32768
	s_waitcnt vmcnt(8)
	ds_write_b128 v172, v[166:169] offset:49152
	s_waitcnt lgkmcnt(0)
	s_barrier
	v_mfma_f32_32x32x16_bf16 a[0:15], v[72:75], v[76:79], a[0:15]
	v_lshl_add_u64 v[76:77], v[40:41], 0, s[78:79]
	v_lshl_add_u64 v[78:79], v[42:43], 0, s[78:79]
	s_add_i32 s0, s0, 2
	s_mov_b32 s1, s2
	s_cmp_gt_u32 s0, 9
	v_mfma_f32_32x32x16_bf16 a[16:31], v[72:75], v[80:83], a[16:31]
	v_lshl_add_u64 v[72:73], v[36:37], 0, s[78:79]
	v_lshl_add_u64 v[74:75], v[38:39], 0, s[78:79]
	v_lshl_add_u64 v[80:81], v[44:45], 0, s[78:79]
	v_lshl_add_u64 v[82:83], v[46:47], 0, s[78:79]
	global_load_dwordx4 v[138:141], v[68:69], off offset:384
	global_load_dwordx4 v[142:145], v[70:71], off offset:384
	global_load_dwordx4 v[146:149], v[72:73], off offset:384
	global_load_dwordx4 v[150:153], v[74:75], off offset:384
	global_load_dwordx4 v[154:157], v[76:77], off offset:384
	global_load_dwordx4 v[158:161], v[78:79], off offset:384
	global_load_dwordx4 v[162:165], v[80:81], off offset:384
	global_load_dwordx4 v[166:169], v[82:83], off offset:384
	ds_read_b128 v[68:71], v48 offset:0x8000
	v_mfma_f32_32x32x16_bf16 a[32:47], v[84:87], v[92:95], a[32:47]
	ds_read_b128 v[72:75], v48 offset:0x9000
	ds_read_b128 v[76:79], v52 offset:0x8000
	ds_read_b128 v[80:83], v52 offset:0x9000
	v_mfma_f32_32x32x16_bf16 a[48:63], v[84:87], v[96:99], a[48:63]
	ds_read_b128 v[84:87], v49 offset:0x8000
	v_mfma_f32_32x32x16_bf16 a[0:15], v[88:91], v[92:95], a[0:15]
	v_mfma_f32_32x32x16_bf16 a[16:31], v[88:91], v[96:99], a[16:31]
	ds_read_b128 v[88:91], v49 offset:0x9000
	ds_read_b128 v[92:95], v53 offset:0x8000
	ds_read_b128 v[96:99], v53 offset:0x9000
	v_mfma_f32_32x32x16_bf16 a[32:47], v[100:103], v[108:111], a[32:47]
	v_mfma_f32_32x32x16_bf16 a[48:63], v[100:103], v[112:115], a[48:63]
	ds_read_b128 v[100:103], v50 offset:0x8000
	v_mfma_f32_32x32x16_bf16 a[0:15], v[104:107], v[108:111], a[0:15]
	v_mfma_f32_32x32x16_bf16 a[16:31], v[104:107], v[112:115], a[16:31]
	ds_read_b128 v[104:107], v50 offset:0x9000
	ds_read_b128 v[108:111], v54 offset:0x8000
	ds_read_b128 v[112:115], v54 offset:0x9000
	v_mfma_f32_32x32x16_bf16 a[32:47], v[116:119], v[124:127], a[32:47]
	v_mfma_f32_32x32x16_bf16 a[48:63], v[116:119], v[128:131], a[48:63]
	ds_read_b128 v[116:119], v51 offset:0x8000
	v_mfma_f32_32x32x16_bf16 a[0:15], v[120:123], v[124:127], a[0:15]
	v_mfma_f32_32x32x16_bf16 a[16:31], v[120:123], v[128:131], a[16:31]
	ds_read_b128 v[120:123], v51 offset:0x9000
	ds_read_b128 v[124:127], v55 offset:0x8000
	ds_read_b128 v[128:131], v55 offset:0x9000
	s_waitcnt lgkmcnt(12)
	s_waitcnt lgkmcnt(8)
	s_waitcnt lgkmcnt(4)
	s_nop 0
	v_mfma_f32_32x32x16_bf16 a[32:47], v[68:71], v[76:79], a[32:47]
	s_waitcnt lgkmcnt(0)
	s_waitcnt vmcnt(15)
	ds_write_b128 v67, v[0:3]
	s_waitcnt vmcnt(14)
	ds_write_b128 v67, v[4:7] offset:16384
	s_waitcnt vmcnt(13)
	ds_write_b128 v170, v[8:11]
	s_waitcnt vmcnt(12)
	ds_write_b128 v170, v[12:15] offset:16384
	s_waitcnt vmcnt(11)
	ds_write_b128 v171, v[16:19]
	s_waitcnt vmcnt(10)
	ds_write_b128 v171, v[20:23] offset:16384
	s_waitcnt vmcnt(9)
	ds_write_b128 v172, v[24:27]
	s_waitcnt vmcnt(8)
	ds_write_b128 v172, v[28:31] offset:16384
	s_waitcnt lgkmcnt(0)
	s_barrier
	v_mfma_f32_32x32x16_bf16 a[48:63], v[68:71], v[80:83], a[48:63]
	v_mfma_f32_32x32x16_bf16 a[0:15], v[72:75], v[76:79], a[0:15]
	v_mfma_f32_32x32x16_bf16 a[16:31], v[72:75], v[80:83], a[16:31]
	v_mfma_f32_32x32x16_bf16 a[32:47], v[84:87], v[92:95], a[32:47]
	v_mfma_f32_32x32x16_bf16 a[48:63], v[84:87], v[96:99], a[48:63]
	v_mfma_f32_32x32x16_bf16 a[0:15], v[88:91], v[92:95], a[0:15]
	v_mfma_f32_32x32x16_bf16 a[16:31], v[88:91], v[96:99], a[16:31]
	v_mfma_f32_32x32x16_bf16 a[32:47], v[100:103], v[108:111], a[32:47]
	v_mfma_f32_32x32x16_bf16 a[48:63], v[100:103], v[112:115], a[48:63]
	v_mfma_f32_32x32x16_bf16 a[0:15], v[104:107], v[108:111], a[0:15]
	v_mfma_f32_32x32x16_bf16 a[16:31], v[104:107], v[112:115], a[16:31]
	v_mfma_f32_32x32x16_bf16 a[32:47], v[116:119], v[124:127], a[32:47]
	v_mfma_f32_32x32x16_bf16 a[48:63], v[116:119], v[128:131], a[48:63]
	v_mfma_f32_32x32x16_bf16 a[0:15], v[120:123], v[124:127], a[0:15]
	v_mfma_f32_32x32x16_bf16 a[16:31], v[120:123], v[128:131], a[16:31]
	s_cbranch_scc0 .LBB0_254
	v_or_b32_e32 v65, s5, v65
	v_add_u32_e32 v121, v65, v66
	v_lshrrev_b32_e32 v65, 3, v64
	s_nop 7
	v_accvgpr_read_b32 v0, a16
	v_accvgpr_read_b32 v31, a15
	v_accvgpr_read_b32 v32, a48
	v_accvgpr_read_b32 v63, a47
	v_and_b32_e32 v103, 4, v65
	v_and_or_b32 v104, v64, 64, s4
	s_movk_i32 s0, 0x210
	v_lshlrev_b32_e32 v64, 5, v121
	v_accvgpr_read_b32 v86, a16
	v_accvgpr_read_b32 v85, a17
	v_accvgpr_read_b32 v84, a18
	v_accvgpr_read_b32 v83, a19
	v_accvgpr_read_b32 v81, a20
	v_accvgpr_read_b32 v80, a21
	v_accvgpr_read_b32 v79, a22
	v_accvgpr_read_b32 v78, a23
	v_accvgpr_read_b32 v77, a24
	v_accvgpr_read_b32 v76, a25
	v_accvgpr_read_b32 v75, a26
	v_accvgpr_read_b32 v74, a27
	v_accvgpr_read_b32 v73, a28
	v_accvgpr_read_b32 v72, a29
	v_accvgpr_read_b32 v71, a30
	v_accvgpr_read_b32 v70, a31
	v_accvgpr_read_b32 v102, a0
	v_accvgpr_read_b32 v101, a1
	v_accvgpr_read_b32 v100, a2
	v_accvgpr_read_b32 v99, a3
	v_accvgpr_read_b32 v98, a4
	v_accvgpr_read_b32 v97, a5
	v_accvgpr_read_b32 v96, a6
	v_accvgpr_read_b32 v95, a7
	v_accvgpr_read_b32 v94, a8
	v_accvgpr_read_b32 v93, a9
	v_accvgpr_read_b32 v92, a10
	v_accvgpr_read_b32 v91, a11
	v_accvgpr_read_b32 v90, a12
	v_accvgpr_read_b32 v89, a13
	v_accvgpr_read_b32 v88, a14
	v_accvgpr_read_b32 v87, a15
	v_accvgpr_read_b32 v120, a48
	v_accvgpr_read_b32 v119, a49
	v_accvgpr_read_b32 v118, a50
	v_accvgpr_read_b32 v117, a51
	v_accvgpr_read_b32 v116, a52
	v_accvgpr_read_b32 v115, a53
	v_accvgpr_read_b32 v114, a54
	v_accvgpr_read_b32 v113, a55
	v_accvgpr_read_b32 v112, a56
	v_accvgpr_read_b32 v111, a57
	v_accvgpr_read_b32 v110, a58
	v_accvgpr_read_b32 v109, a59
	v_accvgpr_read_b32 v108, a60
	v_accvgpr_read_b32 v107, a61
	v_accvgpr_read_b32 v106, a62
	v_accvgpr_read_b32 v105, a63
	v_accvgpr_read_b32 v137, a32
	v_accvgpr_read_b32 v136, a33
	v_accvgpr_read_b32 v135, a34
	v_accvgpr_read_b32 v134, a35
	v_accvgpr_read_b32 v133, a36
	v_accvgpr_read_b32 v132, a37
	v_accvgpr_read_b32 v131, a38
	v_accvgpr_read_b32 v130, a39
	v_accvgpr_read_b32 v129, a40
	v_accvgpr_read_b32 v128, a41
	v_accvgpr_read_b32 v127, a42
	v_accvgpr_read_b32 v126, a43
	v_accvgpr_read_b32 v125, a44
	v_accvgpr_read_b32 v124, a45
	v_accvgpr_read_b32 v123, a46
	v_accvgpr_read_b32 v122, a47
	v_accvgpr_read_b32 v1, a17
	v_accvgpr_read_b32 v2, a18
	v_accvgpr_read_b32 v3, a19
	v_accvgpr_read_b32 v4, a20
	v_accvgpr_read_b32 v5, a21
	v_accvgpr_read_b32 v6, a22
	v_accvgpr_read_b32 v7, a23
	v_accvgpr_read_b32 v8, a24
	v_accvgpr_read_b32 v9, a25
	v_accvgpr_read_b32 v10, a26
	v_accvgpr_read_b32 v11, a27
	v_accvgpr_read_b32 v12, a28
	v_accvgpr_read_b32 v13, a29
	v_accvgpr_read_b32 v14, a30
	v_accvgpr_read_b32 v15, a31
	v_accvgpr_read_b32 v30, a14
	v_accvgpr_read_b32 v29, a13
	v_accvgpr_read_b32 v28, a12
	v_accvgpr_read_b32 v27, a11
	v_accvgpr_read_b32 v26, a10
	v_accvgpr_read_b32 v25, a9
	v_accvgpr_read_b32 v24, a8
	v_accvgpr_read_b32 v23, a7
	v_accvgpr_read_b32 v22, a6
	v_accvgpr_read_b32 v21, a5
	v_accvgpr_read_b32 v20, a4
	v_accvgpr_read_b32 v19, a3
	v_accvgpr_read_b32 v18, a2
	v_accvgpr_read_b32 v17, a1
	v_accvgpr_read_b32 v16, a0
	v_accvgpr_read_b32 v33, a49
	v_accvgpr_read_b32 v34, a50
	v_accvgpr_read_b32 v35, a51
	v_accvgpr_read_b32 v36, a52
	v_accvgpr_read_b32 v37, a53
	v_accvgpr_read_b32 v38, a54
	v_accvgpr_read_b32 v39, a55
	v_accvgpr_read_b32 v40, a56
	v_accvgpr_read_b32 v41, a57
	v_accvgpr_read_b32 v42, a58
	v_accvgpr_read_b32 v43, a59
	v_accvgpr_read_b32 v44, a60
	v_accvgpr_read_b32 v45, a61
	v_accvgpr_read_b32 v46, a62
	v_accvgpr_read_b32 v47, a63
	v_accvgpr_read_b32 v62, a46
	v_accvgpr_read_b32 v61, a45
	v_accvgpr_read_b32 v60, a44
	v_accvgpr_read_b32 v59, a43
	v_accvgpr_read_b32 v58, a42
	v_accvgpr_read_b32 v57, a41
	v_accvgpr_read_b32 v56, a40
	v_accvgpr_read_b32 v55, a39
	v_accvgpr_read_b32 v54, a38
	v_accvgpr_read_b32 v53, a37
	v_accvgpr_read_b32 v52, a36
	v_accvgpr_read_b32 v51, a35
	v_accvgpr_read_b32 v50, a34
	v_accvgpr_read_b32 v49, a33
	v_accvgpr_read_b32 v48, a32
	v_cmp_gt_i32_e64 s[2:3], s0, v121
	v_ashrrev_i32_e32 v65, 31, v64
	v_lshrrev_b32_e32 v82, 4, v104
	v_lshlrev_b32_e32 v192, 1, v103
	s_and_saveexec_b64 s[0:1], s[2:3]
	s_cbranch_execz .LBB0_257
	s_waitcnt vmcnt(7)
	v_mul_f32_e32 v138, 0x3d372713, v137
	v_mul_f32_e32 v138, v137, v138
	v_fma_f32 v137, v137, v138, v137
	v_mul_f32_e32 v137, 0x3f4c422a, v137
	v_add_f32_e32 v137, v137, v137
	v_mul_f32_e32 v137, 0x3fb8aa3b, v137
	v_exp_f32_e32 v138, v137
	v_mul_f32_e32 v137, 0x3d372713, v136
	v_mul_f32_e32 v137, v136, v137
	v_fma_f32 v136, v136, v137, v136
	v_mul_f32_e32 v137, 0x3d372713, v135
	v_mul_f32_e32 v137, v135, v137
	v_fma_f32 v135, v135, v137, v135
	v_mul_f32_e32 v135, 0x3f4c422a, v135
	v_add_f32_e32 v135, v135, v135
	v_mul_f32_e32 v135, 0x3fb8aa3b, v135
	v_exp_f32_e32 v139, v135
	v_mul_f32_e32 v135, 0x3d372713, v134
	v_mul_f32_e32 v135, v134, v135
	v_fma_f32 v134, v134, v135, v134
	v_mul_f32_e32 v134, 0x3f4c422a, v134
	v_add_f32_e32 v134, v134, v134
	v_mul_f32_e32 v134, 0x3fb8aa3b, v134
	v_exp_f32_e32 v137, v134
	v_pk_add_f32 v[134:135], v[138:139], 1.0 op_sel_hi:[1,0]
	v_mul_f32_e32 v136, 0x3f4c422a, v136
	v_rcp_f32_e32 v139, v135
	v_add_f32_e32 v136, v136, v136
	v_mul_f32_e32 v136, 0x3fb8aa3b, v136
	v_exp_f32_e32 v136, v136
	s_waitcnt vmcnt(6)
	v_mul_f32_e32 v135, 2.0, v139
	v_rcp_f32_e32 v139, v134
	v_pk_add_f32 v[136:137], v[136:137], 1.0 op_sel_hi:[1,0]
	v_mad_i64_i32 v[66:67], s[4:5], s7, v215, v[64:65]
	v_mul_f32_e32 v134, 2.0, v139
	v_mov_b32_e32 v138, v48
	v_mov_b32_e32 v139, v50
	v_rcp_f32_e32 v50, v137
	v_pk_add_f32 v[134:135], v[134:135], 1.0 op_sel_hi:[1,0] neg_lo:[1,0] neg_hi:[1,0]
	v_pk_mul_f32 v[138:139], v[138:139], 0.5 op_sel_hi:[1,0]
	v_pk_add_f32 v[134:135], v[134:135], 1.0 op_sel_hi:[1,0]
	v_or_b32_e32 v66, v82, v66
	v_pk_mul_f32 v[134:135], v[138:139], v[134:135]
	v_mul_f32_e32 v137, 2.0, v50
	v_rcp_f32_e32 v50, v136
	v_readlane_b32 s8, v254, 3
	v_lshlrev_b64 v[68:69], 5, v[66:67]
	v_readlane_b32 s9, v254, 4
	v_mul_f32_e32 v136, 2.0, v50
	v_pk_add_f32 v[136:137], v[136:137], 1.0 op_sel_hi:[1,0] neg_lo:[1,0] neg_hi:[1,0]
	v_mov_b32_e32 v50, v49
	v_pk_mul_f32 v[48:49], v[50:51], 0.5 op_sel_hi:[1,0]
	v_pk_add_f32 v[50:51], v[136:137], 1.0 op_sel_hi:[1,0]
	v_lshl_add_u64 v[68:69], s[8:9], 0, v[68:69]
	v_pk_mul_f32 v[48:49], v[48:49], v[50:51]
	v_and_b32_sdwa v50, v135, v218 dst_sel:DWORD dst_unused:UNUSED_PAD src0_sel:WORD_1 src1_sel:DWORD
	v_and_b32_sdwa v51, v134, v218 dst_sel:DWORD dst_unused:UNUSED_PAD src0_sel:WORD_1 src1_sel:DWORD
	v_add3_u32 v51, v134, v51, s80
	v_add3_u32 v50, v135, v50, s80
	v_and_b32_sdwa v134, v49, v218 dst_sel:DWORD dst_unused:UNUSED_PAD src0_sel:WORD_1 src1_sel:DWORD
	v_and_b32_sdwa v135, v48, v218 dst_sel:DWORD dst_unused:UNUSED_PAD src0_sel:WORD_1 src1_sel:DWORD
	v_add3_u32 v49, v49, v134, s80
	v_add3_u32 v48, v48, v135, s80
	v_and_b32_e32 v49, 0xffff0000, v49
	v_and_b32_e32 v48, 0xffff0000, v48
	v_lshl_add_u64 v[68:69], v[68:69], 0, v[192:193]
	v_or_b32_sdwa v49, v49, v50 dst_sel:DWORD dst_unused:UNUSED_PAD src0_sel:DWORD src1_sel:WORD_1
	v_or_b32_sdwa v48, v48, v51 dst_sel:DWORD dst_unused:UNUSED_PAD src0_sel:DWORD src1_sel:WORD_1
	global_store_dwordx2 v[68:69], v[48:49], off
	v_mul_f32_e32 v49, 0x3d372713, v132
	v_mul_f32_e32 v49, v132, v49
	v_fma_f32 v49, v132, v49, v132
	v_mul_f32_e32 v49, 0x3f4c422a, v49
	v_add_f32_e32 v49, v49, v49
	v_mul_f32_e32 v49, 0x3fb8aa3b, v49
	v_mul_f32_e32 v48, 0x3d372713, v133
	v_exp_f32_e32 v50, v49
	v_mul_f32_e32 v49, 0x3d372713, v131
	v_mul_f32_e32 v48, v133, v48
	v_mul_f32_e32 v49, v131, v49
	v_fma_f32 v48, v133, v48, v133
	v_fma_f32 v49, v131, v49, v131
	v_mul_f32_e32 v48, 0x3f4c422a, v48
	v_mul_f32_e32 v49, 0x3f4c422a, v49
	v_add_f32_e32 v48, v48, v48
	v_add_f32_e32 v49, v49, v49
	v_mul_f32_e32 v48, 0x3fb8aa3b, v48
	v_mul_f32_e32 v49, 0x3fb8aa3b, v49
	v_exp_f32_e32 v48, v48
	v_exp_f32_e32 v49, v49
	v_mul_f32_e32 v51, 0x3d372713, v130
	v_mul_f32_e32 v51, v130, v51
	v_fma_f32 v51, v130, v51, v130
	v_pk_add_f32 v[48:49], v[48:49], 1.0 op_sel_hi:[1,0]
	v_mul_f32_e32 v51, 0x3f4c422a, v51
	v_rcp_f32_e32 v131, v49
	v_add_f32_e32 v51, v51, v51
	v_mul_f32_e32 v51, 0x3fb8aa3b, v51
	v_exp_f32_e32 v51, v51
	v_mul_f32_e32 v49, 2.0, v131
	v_rcp_f32_e32 v131, v48
	v_pk_add_f32 v[50:51], v[50:51], 1.0 op_sel_hi:[1,0]
	v_or_b32_e32 v66, 1, v66
	v_mul_f32_e32 v48, 2.0, v131
	v_mov_b32_e32 v130, v52
	v_mov_b32_e32 v131, v54
	v_rcp_f32_e32 v54, v51
	v_pk_add_f32 v[48:49], v[48:49], 1.0 op_sel_hi:[1,0] neg_lo:[1,0] neg_hi:[1,0]
	v_pk_mul_f32 v[130:131], v[130:131], 0.5 op_sel_hi:[1,0]
	v_pk_add_f32 v[48:49], v[48:49], 1.0 op_sel_hi:[1,0]
	s_nop 0
	v_pk_mul_f32 v[48:49], v[130:131], v[48:49]
	v_mul_f32_e32 v51, 2.0, v54
	v_rcp_f32_e32 v54, v50
	s_nop 0
	v_mul_f32_e32 v50, 2.0, v54
	v_pk_add_f32 v[50:51], v[50:51], 1.0 op_sel_hi:[1,0] neg_lo:[1,0] neg_hi:[1,0]
	v_mov_b32_e32 v54, v53
	v_pk_mul_f32 v[52:53], v[54:55], 0.5 op_sel_hi:[1,0]
	v_pk_add_f32 v[50:51], v[50:51], 1.0 op_sel_hi:[1,0]
	s_nop 0
	v_pk_mul_f32 v[50:51], v[52:53], v[50:51]
	v_and_b32_sdwa v52, v49, v218 dst_sel:DWORD dst_unused:UNUSED_PAD src0_sel:WORD_1 src1_sel:DWORD
	v_add3_u32 v49, v49, v52, s80
	v_and_b32_sdwa v52, v51, v218 dst_sel:DWORD dst_unused:UNUSED_PAD src0_sel:WORD_1 src1_sel:DWORD
	v_add3_u32 v51, v51, v52, s80
	v_and_b32_e32 v51, 0xffff0000, v51
	v_or_b32_sdwa v49, v51, v49 dst_sel:DWORD dst_unused:UNUSED_PAD src0_sel:DWORD src1_sel:WORD_1
	v_mul_f32_e32 v51, 0x3d372713, v128
	v_mul_f32_e32 v51, v128, v51
	v_and_b32_sdwa v53, v48, v218 dst_sel:DWORD dst_unused:UNUSED_PAD src0_sel:WORD_1 src1_sel:DWORD
	v_fma_f32 v51, v128, v51, v128
	v_add3_u32 v48, v48, v53, s80
	v_and_b32_sdwa v53, v50, v218 dst_sel:DWORD dst_unused:UNUSED_PAD src0_sel:WORD_1 src1_sel:DWORD
	v_mul_f32_e32 v51, 0x3f4c422a, v51
	v_add3_u32 v50, v50, v53, s80
	v_add_f32_e32 v51, v51, v51
	v_and_b32_e32 v50, 0xffff0000, v50
	v_mul_f32_e32 v51, 0x3fb8aa3b, v51
	v_or_b32_sdwa v48, v50, v48 dst_sel:DWORD dst_unused:UNUSED_PAD src0_sel:DWORD src1_sel:WORD_1
	v_mul_f32_e32 v50, 0x3d372713, v129
	v_exp_f32_e32 v52, v51
	v_mul_f32_e32 v51, 0x3d372713, v127
	v_mul_f32_e32 v50, v129, v50
	v_mul_f32_e32 v51, v127, v51
	v_fma_f32 v50, v129, v50, v129
	v_fma_f32 v51, v127, v51, v127
	v_mul_f32_e32 v50, 0x3f4c422a, v50
	v_mul_f32_e32 v51, 0x3f4c422a, v51
	v_add_f32_e32 v50, v50, v50
	v_add_f32_e32 v51, v51, v51
	v_mul_f32_e32 v50, 0x3fb8aa3b, v50
	v_mul_f32_e32 v51, 0x3fb8aa3b, v51
	v_exp_f32_e32 v50, v50
	v_exp_f32_e32 v51, v51
	global_store_dwordx2 v[68:69], v[48:49], off offset:16
	v_lshlrev_b64 v[48:49], 5, v[66:67]
	v_mul_f32_e32 v53, 0x3d372713, v126
	v_pk_add_f32 v[50:51], v[50:51], 1.0 op_sel_hi:[1,0]
	v_mul_f32_e32 v53, v126, v53
	v_rcp_f32_e32 v55, v51
	v_fma_f32 v53, v126, v53, v126
	v_mul_f32_e32 v53, 0x3f4c422a, v53
	v_add_f32_e32 v53, v53, v53
	v_mul_f32_e32 v51, 2.0, v55
	v_rcp_f32_e32 v55, v50
	v_mul_f32_e32 v53, 0x3fb8aa3b, v53
	v_exp_f32_e32 v53, v53
	v_lshl_add_u64 v[48:49], s[8:9], 0, v[48:49]
	v_mul_f32_e32 v50, 2.0, v55
	v_pk_add_f32 v[50:51], v[50:51], 1.0 op_sel_hi:[1,0] neg_lo:[1,0] neg_hi:[1,0]
	v_mov_b32_e32 v54, v56
	v_mov_b32_e32 v55, v58
	v_pk_mul_f32 v[54:55], v[54:55], 0.5 op_sel_hi:[1,0]
	v_pk_add_f32 v[50:51], v[50:51], 1.0 op_sel_hi:[1,0]
	v_pk_add_f32 v[52:53], v[52:53], 1.0 op_sel_hi:[1,0]
	v_pk_mul_f32 v[50:51], v[54:55], v[50:51]
	v_rcp_f32_e32 v55, v53
	v_lshl_add_u64 v[48:49], v[48:49], 0, v[192:193]
	v_mul_f32_e32 v53, 2.0, v55
	v_rcp_f32_e32 v55, v52
	s_nop 0
	v_mul_f32_e32 v52, 2.0, v55
	v_pk_add_f32 v[52:53], v[52:53], 1.0 op_sel_hi:[1,0] neg_lo:[1,0] neg_hi:[1,0]
	v_mov_b32_e32 v58, v57
	v_pk_mul_f32 v[54:55], v[58:59], 0.5 op_sel_hi:[1,0]
	v_pk_add_f32 v[52:53], v[52:53], 1.0 op_sel_hi:[1,0]
	s_nop 0
	v_pk_mul_f32 v[52:53], v[54:55], v[52:53]
	v_and_b32_sdwa v54, v51, v218 dst_sel:DWORD dst_unused:UNUSED_PAD src0_sel:WORD_1 src1_sel:DWORD
	v_and_b32_sdwa v55, v50, v218 dst_sel:DWORD dst_unused:UNUSED_PAD src0_sel:WORD_1 src1_sel:DWORD
	v_add3_u32 v50, v50, v55, s80
	v_add3_u32 v51, v51, v54, s80
	v_and_b32_sdwa v54, v53, v218 dst_sel:DWORD dst_unused:UNUSED_PAD src0_sel:WORD_1 src1_sel:DWORD
	v_and_b32_sdwa v55, v52, v218 dst_sel:DWORD dst_unused:UNUSED_PAD src0_sel:WORD_1 src1_sel:DWORD
	v_add3_u32 v53, v53, v54, s80
	v_add3_u32 v52, v52, v55, s80
	v_and_b32_e32 v53, 0xffff0000, v53
	v_and_b32_e32 v52, 0xffff0000, v52
	v_or_b32_sdwa v51, v53, v51 dst_sel:DWORD dst_unused:UNUSED_PAD src0_sel:DWORD src1_sel:WORD_1
	v_or_b32_sdwa v50, v52, v50 dst_sel:DWORD dst_unused:UNUSED_PAD src0_sel:DWORD src1_sel:WORD_1
	global_store_dwordx2 v[48:49], v[50:51], off
	v_mul_f32_e32 v51, 0x3d372713, v124
	v_mul_f32_e32 v51, v124, v51
	v_fma_f32 v51, v124, v51, v124
	v_mul_f32_e32 v51, 0x3f4c422a, v51
	v_add_f32_e32 v51, v51, v51
	v_mul_f32_e32 v51, 0x3fb8aa3b, v51
	v_mul_f32_e32 v50, 0x3d372713, v125
	v_exp_f32_e32 v52, v51
	v_mul_f32_e32 v51, 0x3d372713, v123
	v_mul_f32_e32 v50, v125, v50
	v_mul_f32_e32 v51, v123, v51
	v_fma_f32 v50, v125, v50, v125
	v_fma_f32 v51, v123, v51, v123
	v_mul_f32_e32 v50, 0x3f4c422a, v50
	v_mul_f32_e32 v51, 0x3f4c422a, v51
	v_add_f32_e32 v50, v50, v50
	v_add_f32_e32 v51, v51, v51
	v_mul_f32_e32 v50, 0x3fb8aa3b, v50
	v_mul_f32_e32 v51, 0x3fb8aa3b, v51
	v_exp_f32_e32 v50, v50
	v_exp_f32_e32 v51, v51
	v_mul_f32_e32 v53, 0x3d372713, v122
	v_mul_f32_e32 v53, v122, v53
	v_fma_f32 v53, v122, v53, v122
	v_pk_add_f32 v[50:51], v[50:51], 1.0 op_sel_hi:[1,0]
	v_mul_f32_e32 v53, 0x3f4c422a, v53
	v_rcp_f32_e32 v55, v51
	v_add_f32_e32 v53, v53, v53
	v_mul_f32_e32 v53, 0x3fb8aa3b, v53
	v_exp_f32_e32 v53, v53
	v_mul_f32_e32 v51, 2.0, v55
	v_rcp_f32_e32 v55, v50
	v_pk_add_f32 v[52:53], v[52:53], 1.0 op_sel_hi:[1,0]
	v_mul_f32_e32 v50, 2.0, v55
	v_pk_add_f32 v[50:51], v[50:51], 1.0 op_sel_hi:[1,0] neg_lo:[1,0] neg_hi:[1,0]
	v_mov_b32_e32 v54, v60
	v_mov_b32_e32 v55, v62
	v_pk_mul_f32 v[54:55], v[54:55], 0.5 op_sel_hi:[1,0]
	v_pk_add_f32 v[50:51], v[50:51], 1.0 op_sel_hi:[1,0]
	v_mov_b32_e32 v62, v61
	v_pk_mul_f32 v[50:51], v[54:55], v[50:51]
	v_rcp_f32_e32 v55, v53
	s_nop 0
	v_mul_f32_e32 v53, 2.0, v55
	v_rcp_f32_e32 v55, v52
	s_nop 0
	v_mul_f32_e32 v52, 2.0, v55
	v_pk_add_f32 v[52:53], v[52:53], 1.0 op_sel_hi:[1,0] neg_lo:[1,0] neg_hi:[1,0]
	v_pk_mul_f32 v[54:55], v[62:63], 0.5 op_sel_hi:[1,0]
	v_pk_add_f32 v[52:53], v[52:53], 1.0 op_sel_hi:[1,0]
	s_nop 0
	v_pk_mul_f32 v[52:53], v[54:55], v[52:53]
	v_and_b32_sdwa v54, v51, v218 dst_sel:DWORD dst_unused:UNUSED_PAD src0_sel:WORD_1 src1_sel:DWORD
	v_and_b32_sdwa v55, v50, v218 dst_sel:DWORD dst_unused:UNUSED_PAD src0_sel:WORD_1 src1_sel:DWORD
	v_add3_u32 v50, v50, v55, s80
	v_add3_u32 v51, v51, v54, s80
	v_and_b32_sdwa v54, v53, v218 dst_sel:DWORD dst_unused:UNUSED_PAD src0_sel:WORD_1 src1_sel:DWORD
	v_and_b32_sdwa v55, v52, v218 dst_sel:DWORD dst_unused:UNUSED_PAD src0_sel:WORD_1 src1_sel:DWORD
	v_add3_u32 v53, v53, v54, s80
	v_add3_u32 v52, v52, v55, s80
	v_and_b32_e32 v53, 0xffff0000, v53
	v_and_b32_e32 v52, 0xffff0000, v52
	v_or_b32_sdwa v51, v53, v51 dst_sel:DWORD dst_unused:UNUSED_PAD src0_sel:DWORD src1_sel:WORD_1
	v_or_b32_sdwa v50, v52, v50 dst_sel:DWORD dst_unused:UNUSED_PAD src0_sel:DWORD src1_sel:WORD_1
	global_store_dwordx2 v[48:49], v[50:51], off offset:16
.LBB0_257:
	s_or_b64 exec, exec, s[0:1]
	s_movk_i32 s0, 0x1f0
	v_or_b32_e32 v48, 0x400, v64
	v_cmp_gt_i32_e64 s[4:5], s0, v121
	v_ashrrev_i32_e32 v49, 31, v48
	s_and_saveexec_b64 s[0:1], s[4:5]
	s_cbranch_execz .LBB0_259
	v_mul_f32_e32 v53, 0x3d372713, v119
	v_mul_f32_e32 v53, v119, v53
	v_fma_f32 v53, v119, v53, v119
	v_mul_f32_e32 v53, 0x3f4c422a, v53
	v_add_f32_e32 v53, v53, v53
	v_mul_f32_e32 v53, 0x3fb8aa3b, v53
	v_mul_f32_e32 v52, 0x3d372713, v120
	v_exp_f32_e32 v54, v53
	v_mul_f32_e32 v53, 0x3d372713, v118
	v_mul_f32_e32 v52, v120, v52
	v_mul_f32_e32 v53, v118, v53
	v_fma_f32 v52, v120, v52, v120
	v_fma_f32 v53, v118, v53, v118
	v_mul_f32_e32 v52, 0x3f4c422a, v52
	v_mul_f32_e32 v53, 0x3f4c422a, v53
	v_add_f32_e32 v52, v52, v52
	v_add_f32_e32 v53, v53, v53
	v_mul_f32_e32 v52, 0x3fb8aa3b, v52
	v_mul_f32_e32 v53, 0x3fb8aa3b, v53
	v_exp_f32_e32 v52, v52
	v_exp_f32_e32 v53, v53
	s_mul_hi_i32 s8, s7, 0x4200
	s_mul_i32 s9, s7, 0x4200
	v_or_b32_e32 v50, s9, v82
	v_pk_add_f32 v[52:53], v[52:53], 1.0 op_sel_hi:[1,0]
	v_mov_b32_e32 v51, s8
	v_rcp_f32_e32 v57, v53
	v_mul_f32_e32 v55, 0x3d372713, v117
	v_mul_f32_e32 v55, v117, v55
	v_fma_f32 v55, v117, v55, v117
	v_mul_f32_e32 v53, 2.0, v57
	v_rcp_f32_e32 v57, v52
	v_mul_f32_e32 v55, 0x3f4c422a, v55
	v_add_f32_e32 v55, v55, v55
	v_mul_f32_e32 v55, 0x3fb8aa3b, v55
	v_exp_f32_e32 v55, v55
	s_nop 0
	v_pk_add_f32 v[54:55], v[54:55], 1.0 op_sel_hi:[1,0]
	v_mul_f32_e32 v52, 2.0, v57
	v_mov_b32_e32 v56, v32
	v_mov_b32_e32 v57, v34
	v_rcp_f32_e32 v34, v55
	v_pk_add_f32 v[52:53], v[52:53], 1.0 op_sel_hi:[1,0] neg_lo:[1,0] neg_hi:[1,0]
	v_pk_mul_f32 v[56:57], v[56:57], 0.5 op_sel_hi:[1,0]
	v_pk_add_f32 v[52:53], v[52:53], 1.0 op_sel_hi:[1,0]
	v_lshl_add_u64 v[50:51], v[50:51], 0, v[48:49]
	v_pk_mul_f32 v[52:53], v[56:57], v[52:53]
	v_mul_f32_e32 v55, 2.0, v34
	v_rcp_f32_e32 v34, v54
	v_readlane_b32 s10, v254, 3
	v_lshlrev_b64 v[50:51], 5, v[50:51]
	v_readlane_b32 s11, v254, 4
	v_mul_f32_e32 v54, 2.0, v34
	v_pk_add_f32 v[54:55], v[54:55], 1.0 op_sel_hi:[1,0] neg_lo:[1,0] neg_hi:[1,0]
	v_mov_b32_e32 v34, v33
	v_pk_mul_f32 v[32:33], v[34:35], 0.5 op_sel_hi:[1,0]
	v_pk_add_f32 v[34:35], v[54:55], 1.0 op_sel_hi:[1,0]
	v_lshl_add_u64 v[50:51], s[10:11], 0, v[50:51]
	v_pk_mul_f32 v[32:33], v[32:33], v[34:35]
	v_and_b32_sdwa v34, v53, v218 dst_sel:DWORD dst_unused:UNUSED_PAD src0_sel:WORD_1 src1_sel:DWORD
	v_and_b32_sdwa v35, v52, v218 dst_sel:DWORD dst_unused:UNUSED_PAD src0_sel:WORD_1 src1_sel:DWORD
	v_add3_u32 v35, v52, v35, s80
	v_add3_u32 v34, v53, v34, s80
	v_and_b32_sdwa v52, v33, v218 dst_sel:DWORD dst_unused:UNUSED_PAD src0_sel:WORD_1 src1_sel:DWORD
	v_and_b32_sdwa v53, v32, v218 dst_sel:DWORD dst_unused:UNUSED_PAD src0_sel:WORD_1 src1_sel:DWORD
	v_add3_u32 v33, v33, v52, s80
	v_add3_u32 v32, v32, v53, s80
	v_and_b32_e32 v33, 0xffff0000, v33
	v_and_b32_e32 v32, 0xffff0000, v32
	v_lshl_add_u64 v[50:51], v[50:51], 0, v[192:193]
	v_or_b32_sdwa v33, v33, v34 dst_sel:DWORD dst_unused:UNUSED_PAD src0_sel:DWORD src1_sel:WORD_1
	v_or_b32_sdwa v32, v32, v35 dst_sel:DWORD dst_unused:UNUSED_PAD src0_sel:DWORD src1_sel:WORD_1
	global_store_dwordx2 v[50:51], v[32:33], off
	v_mul_f32_e32 v33, 0x3d372713, v115
	v_mul_f32_e32 v33, v115, v33
	v_fma_f32 v33, v115, v33, v115
	v_mul_f32_e32 v33, 0x3f4c422a, v33
	v_add_f32_e32 v33, v33, v33
	v_mul_f32_e32 v33, 0x3fb8aa3b, v33
	v_mul_f32_e32 v32, 0x3d372713, v116
	v_exp_f32_e32 v34, v33
	v_mul_f32_e32 v33, 0x3d372713, v114
	v_mul_f32_e32 v32, v116, v32
	v_mul_f32_e32 v33, v114, v33
	v_fma_f32 v32, v116, v32, v116
	v_fma_f32 v33, v114, v33, v114
	v_mul_f32_e32 v32, 0x3f4c422a, v32
	v_mul_f32_e32 v33, 0x3f4c422a, v33
	v_add_f32_e32 v32, v32, v32
	v_add_f32_e32 v33, v33, v33
	v_mul_f32_e32 v32, 0x3fb8aa3b, v32
	v_mul_f32_e32 v33, 0x3fb8aa3b, v33
	v_exp_f32_e32 v32, v32
	v_exp_f32_e32 v33, v33
	v_mul_f32_e32 v35, 0x3d372713, v113
	v_mul_f32_e32 v35, v113, v35
	v_fma_f32 v35, v113, v35, v113
	v_pk_add_f32 v[32:33], v[32:33], 1.0 op_sel_hi:[1,0]
	v_mul_f32_e32 v35, 0x3f4c422a, v35
	v_rcp_f32_e32 v53, v33
	v_add_f32_e32 v35, v35, v35
	v_mul_f32_e32 v35, 0x3fb8aa3b, v35
	v_exp_f32_e32 v35, v35
	v_mul_f32_e32 v33, 2.0, v53
	v_rcp_f32_e32 v53, v32
	v_pk_add_f32 v[34:35], v[34:35], 1.0 op_sel_hi:[1,0]
	v_mul_f32_e32 v32, 2.0, v53
	v_mov_b32_e32 v52, v36
	v_mov_b32_e32 v53, v38
	v_rcp_f32_e32 v38, v35
	v_pk_add_f32 v[32:33], v[32:33], 1.0 op_sel_hi:[1,0] neg_lo:[1,0] neg_hi:[1,0]
	v_pk_mul_f32 v[52:53], v[52:53], 0.5 op_sel_hi:[1,0]
	v_pk_add_f32 v[32:33], v[32:33], 1.0 op_sel_hi:[1,0]
	s_nop 0
	v_pk_mul_f32 v[32:33], v[52:53], v[32:33]
	v_mul_f32_e32 v35, 2.0, v38
	v_rcp_f32_e32 v38, v34
	s_nop 0
	v_mul_f32_e32 v34, 2.0, v38
	v_pk_add_f32 v[34:35], v[34:35], 1.0 op_sel_hi:[1,0] neg_lo:[1,0] neg_hi:[1,0]
	v_mov_b32_e32 v38, v37
	v_pk_mul_f32 v[36:37], v[38:39], 0.5 op_sel_hi:[1,0]
	v_pk_add_f32 v[34:35], v[34:35], 1.0 op_sel_hi:[1,0]
	s_nop 0
	v_pk_mul_f32 v[34:35], v[36:37], v[34:35]
	v_and_b32_sdwa v36, v33, v218 dst_sel:DWORD dst_unused:UNUSED_PAD src0_sel:WORD_1 src1_sel:DWORD
	v_add3_u32 v33, v33, v36, s80
	v_and_b32_sdwa v36, v35, v218 dst_sel:DWORD dst_unused:UNUSED_PAD src0_sel:WORD_1 src1_sel:DWORD
	v_add3_u32 v35, v35, v36, s80
	v_and_b32_e32 v35, 0xffff0000, v35
	v_or_b32_sdwa v33, v35, v33 dst_sel:DWORD dst_unused:UNUSED_PAD src0_sel:DWORD src1_sel:WORD_1
	v_mul_f32_e32 v35, 0x3d372713, v111
	v_mul_f32_e32 v35, v111, v35
	v_and_b32_sdwa v37, v32, v218 dst_sel:DWORD dst_unused:UNUSED_PAD src0_sel:WORD_1 src1_sel:DWORD
	v_fma_f32 v35, v111, v35, v111
	v_add3_u32 v32, v32, v37, s80
	v_and_b32_sdwa v37, v34, v218 dst_sel:DWORD dst_unused:UNUSED_PAD src0_sel:WORD_1 src1_sel:DWORD
	v_mul_f32_e32 v35, 0x3f4c422a, v35
	v_add3_u32 v34, v34, v37, s80
	v_add_f32_e32 v35, v35, v35
	v_and_b32_e32 v34, 0xffff0000, v34
	v_mul_f32_e32 v35, 0x3fb8aa3b, v35
	v_or_b32_sdwa v32, v34, v32 dst_sel:DWORD dst_unused:UNUSED_PAD src0_sel:DWORD src1_sel:WORD_1
	v_mul_f32_e32 v34, 0x3d372713, v112
	v_exp_f32_e32 v36, v35
	v_mul_f32_e32 v35, 0x3d372713, v110
	v_mul_f32_e32 v34, v112, v34
	v_mul_f32_e32 v35, v110, v35
	v_fma_f32 v34, v112, v34, v112
	v_fma_f32 v35, v110, v35, v110
	v_mul_f32_e32 v34, 0x3f4c422a, v34
	v_mul_f32_e32 v35, 0x3f4c422a, v35
	v_add_f32_e32 v34, v34, v34
	v_add_f32_e32 v35, v35, v35
	v_mul_f32_e32 v34, 0x3fb8aa3b, v34
	v_mul_f32_e32 v35, 0x3fb8aa3b, v35
	v_exp_f32_e32 v34, v34
	v_exp_f32_e32 v35, v35
	global_store_dwordx2 v[50:51], v[32:33], off offset:16
	v_mul_f32_e32 v37, 0x3d372713, v109
	v_mul_f32_e32 v37, v109, v37
	v_pk_add_f32 v[34:35], v[34:35], 1.0 op_sel_hi:[1,0]
	v_fma_f32 v37, v109, v37, v109
	v_rcp_f32_e32 v39, v35
	v_mul_f32_e32 v37, 0x3f4c422a, v37
	v_add_f32_e32 v37, v37, v37
	v_mul_f32_e32 v37, 0x3fb8aa3b, v37
	v_mul_f32_e32 v35, 2.0, v39
	v_rcp_f32_e32 v39, v34
	v_exp_f32_e32 v37, v37
	v_mad_i64_i32 v[32:33], s[8:9], s7, v215, v[48:49]
	v_mul_f32_e32 v34, 2.0, v39
	v_pk_add_f32 v[34:35], v[34:35], 1.0 op_sel_hi:[1,0] neg_lo:[1,0] neg_hi:[1,0]
	v_mov_b32_e32 v38, v40
	v_mov_b32_e32 v39, v42
	v_pk_mul_f32 v[38:39], v[38:39], 0.5 op_sel_hi:[1,0]
	v_pk_add_f32 v[34:35], v[34:35], 1.0 op_sel_hi:[1,0]
	v_pk_add_f32 v[36:37], v[36:37], 1.0 op_sel_hi:[1,0]
	v_pk_mul_f32 v[34:35], v[38:39], v[34:35]
	v_rcp_f32_e32 v39, v37
	v_or3_b32 v32, v82, v32, 1
	v_lshlrev_b64 v[32:33], 5, v[32:33]
	v_lshl_add_u64 v[32:33], s[10:11], 0, v[32:33]
	v_mul_f32_e32 v37, 2.0, v39
	v_rcp_f32_e32 v39, v36
	v_lshl_add_u64 v[32:33], v[32:33], 0, v[192:193]
	v_mul_f32_e32 v36, 2.0, v39
	v_pk_add_f32 v[36:37], v[36:37], 1.0 op_sel_hi:[1,0] neg_lo:[1,0] neg_hi:[1,0]
	v_mov_b32_e32 v42, v41
	v_pk_mul_f32 v[38:39], v[42:43], 0.5 op_sel_hi:[1,0]
	v_pk_add_f32 v[36:37], v[36:37], 1.0 op_sel_hi:[1,0]
	s_nop 0
	v_pk_mul_f32 v[36:37], v[38:39], v[36:37]
	v_and_b32_sdwa v38, v35, v218 dst_sel:DWORD dst_unused:UNUSED_PAD src0_sel:WORD_1 src1_sel:DWORD
	v_and_b32_sdwa v39, v34, v218 dst_sel:DWORD dst_unused:UNUSED_PAD src0_sel:WORD_1 src1_sel:DWORD
	v_add3_u32 v34, v34, v39, s80
	v_add3_u32 v35, v35, v38, s80
	v_and_b32_sdwa v38, v37, v218 dst_sel:DWORD dst_unused:UNUSED_PAD src0_sel:WORD_1 src1_sel:DWORD
	v_and_b32_sdwa v39, v36, v218 dst_sel:DWORD dst_unused:UNUSED_PAD src0_sel:WORD_1 src1_sel:DWORD
	v_add3_u32 v37, v37, v38, s80
	v_add3_u32 v36, v36, v39, s80
	v_and_b32_e32 v37, 0xffff0000, v37
	v_and_b32_e32 v36, 0xffff0000, v36
	v_or_b32_sdwa v35, v37, v35 dst_sel:DWORD dst_unused:UNUSED_PAD src0_sel:DWORD src1_sel:WORD_1
	v_or_b32_sdwa v34, v36, v34 dst_sel:DWORD dst_unused:UNUSED_PAD src0_sel:DWORD src1_sel:WORD_1
	global_store_dwordx2 v[32:33], v[34:35], off
	v_mul_f32_e32 v35, 0x3d372713, v107
	v_mul_f32_e32 v35, v107, v35
	v_fma_f32 v35, v107, v35, v107
	v_mul_f32_e32 v35, 0x3f4c422a, v35
	v_add_f32_e32 v35, v35, v35
	v_mul_f32_e32 v35, 0x3fb8aa3b, v35
	v_mul_f32_e32 v34, 0x3d372713, v108
	v_exp_f32_e32 v36, v35
	v_mul_f32_e32 v35, 0x3d372713, v106
	v_mul_f32_e32 v34, v108, v34
	v_mul_f32_e32 v35, v106, v35
	v_fma_f32 v34, v108, v34, v108
	v_fma_f32 v35, v106, v35, v106
	v_mul_f32_e32 v34, 0x3f4c422a, v34
	v_mul_f32_e32 v35, 0x3f4c422a, v35
	v_add_f32_e32 v34, v34, v34
	v_add_f32_e32 v35, v35, v35
	v_mul_f32_e32 v34, 0x3fb8aa3b, v34
	v_mul_f32_e32 v35, 0x3fb8aa3b, v35
	v_exp_f32_e32 v34, v34
	v_exp_f32_e32 v35, v35
	v_mul_f32_e32 v37, 0x3d372713, v105
	v_mul_f32_e32 v37, v105, v37
	v_fma_f32 v37, v105, v37, v105
	v_pk_add_f32 v[34:35], v[34:35], 1.0 op_sel_hi:[1,0]
	v_mul_f32_e32 v37, 0x3f4c422a, v37
	v_rcp_f32_e32 v39, v35
	v_add_f32_e32 v37, v37, v37
	v_mul_f32_e32 v37, 0x3fb8aa3b, v37
	v_exp_f32_e32 v37, v37
	v_mul_f32_e32 v35, 2.0, v39
	v_rcp_f32_e32 v39, v34
	v_pk_add_f32 v[36:37], v[36:37], 1.0 op_sel_hi:[1,0]
	v_mul_f32_e32 v34, 2.0, v39
	v_pk_add_f32 v[34:35], v[34:35], 1.0 op_sel_hi:[1,0] neg_lo:[1,0] neg_hi:[1,0]
	v_mov_b32_e32 v38, v44
	v_mov_b32_e32 v39, v46
	v_pk_mul_f32 v[38:39], v[38:39], 0.5 op_sel_hi:[1,0]
	v_pk_add_f32 v[34:35], v[34:35], 1.0 op_sel_hi:[1,0]
	v_mov_b32_e32 v46, v45
	v_pk_mul_f32 v[34:35], v[38:39], v[34:35]
	v_rcp_f32_e32 v39, v37
	s_nop 0
	v_mul_f32_e32 v37, 2.0, v39
	v_rcp_f32_e32 v39, v36
	s_nop 0
	v_mul_f32_e32 v36, 2.0, v39
	v_pk_add_f32 v[36:37], v[36:37], 1.0 op_sel_hi:[1,0] neg_lo:[1,0] neg_hi:[1,0]
	v_pk_mul_f32 v[38:39], v[46:47], 0.5 op_sel_hi:[1,0]
	v_pk_add_f32 v[36:37], v[36:37], 1.0 op_sel_hi:[1,0]
	s_nop 0
	v_pk_mul_f32 v[36:37], v[38:39], v[36:37]
	v_and_b32_sdwa v38, v35, v218 dst_sel:DWORD dst_unused:UNUSED_PAD src0_sel:WORD_1 src1_sel:DWORD
	v_and_b32_sdwa v39, v34, v218 dst_sel:DWORD dst_unused:UNUSED_PAD src0_sel:WORD_1 src1_sel:DWORD
	v_add3_u32 v34, v34, v39, s80
	v_add3_u32 v35, v35, v38, s80
	v_and_b32_sdwa v38, v37, v218 dst_sel:DWORD dst_unused:UNUSED_PAD src0_sel:WORD_1 src1_sel:DWORD
	v_and_b32_sdwa v39, v36, v218 dst_sel:DWORD dst_unused:UNUSED_PAD src0_sel:WORD_1 src1_sel:DWORD
	v_add3_u32 v37, v37, v38, s80
	v_add3_u32 v36, v36, v39, s80
	v_and_b32_e32 v37, 0xffff0000, v37
	v_and_b32_e32 v36, 0xffff0000, v36
	v_or_b32_sdwa v35, v37, v35 dst_sel:DWORD dst_unused:UNUSED_PAD src0_sel:DWORD src1_sel:WORD_1
	v_or_b32_sdwa v34, v36, v34 dst_sel:DWORD dst_unused:UNUSED_PAD src0_sel:DWORD src1_sel:WORD_1
	global_store_dwordx2 v[32:33], v[34:35], off offset:16
.LBB0_259:
	s_or_b64 exec, exec, s[0:1]
	v_or3_b32 v32, v103, v104, 32
	v_lshrrev_b32_e32 v34, 4, v32
	s_and_saveexec_b64 s[0:1], s[2:3]
	s_cbranch_execz .LBB0_261
	v_mul_f32_e32 v35, 0x3d372713, v102
	v_mul_f32_e32 v35, v102, v35
	v_fma_f32 v35, v102, v35, v102
	v_mul_f32_e32 v35, 0x3f4c422a, v35
	v_add_f32_e32 v35, v35, v35
	v_mul_f32_e32 v35, 0x3fb8aa3b, v35
	v_exp_f32_e32 v38, v35
	v_mul_f32_e32 v35, 0x3d372713, v101
	v_mul_f32_e32 v35, v101, v35
	v_fma_f32 v35, v101, v35, v101
	v_mul_f32_e32 v35, 0x3f4c422a, v35
	v_add_f32_e32 v35, v35, v35
	v_mul_f32_e32 v35, 0x3fb8aa3b, v35
	v_exp_f32_e32 v40, v35
	v_mul_f32_e32 v35, 0x3d372713, v100
	v_mul_f32_e32 v35, v100, v35
	v_fma_f32 v35, v100, v35, v100
	v_mul_f32_e32 v35, 0x3f4c422a, v35
	v_add_f32_e32 v35, v35, v35
	v_mul_f32_e32 v35, 0x3fb8aa3b, v35
	v_exp_f32_e32 v39, v35
	v_mul_f32_e32 v35, 0x3d372713, v99
	v_mul_f32_e32 v35, v99, v35
	v_fma_f32 v35, v99, v35, v99
	v_mul_f32_e32 v35, 0x3f4c422a, v35
	v_add_f32_e32 v35, v35, v35
	v_mul_f32_e32 v35, 0x3fb8aa3b, v35
	v_pk_add_f32 v[38:39], v[38:39], 1.0 op_sel_hi:[1,0]
	v_exp_f32_e32 v41, v35
	v_rcp_f32_e32 v42, v39
	v_pk_add_f32 v[40:41], v[40:41], 1.0 op_sel_hi:[1,0]
	v_mad_i64_i32 v[32:33], s[2:3], s7, v215, v[64:65]
	v_mul_f32_e32 v39, 2.0, v42
	v_rcp_f32_e32 v42, v38
	v_or_b32_e32 v36, v32, v34
	v_mov_b32_e32 v37, v33
	v_readlane_b32 s8, v254, 3
	v_mul_f32_e32 v35, 2.0, v42
	v_mov_b32_e32 v42, v16
	v_mov_b32_e32 v43, v18
	v_rcp_f32_e32 v18, v41
	v_mov_b32_e32 v38, v35
	v_pk_add_f32 v[38:39], v[38:39], 1.0 op_sel_hi:[1,0] neg_lo:[1,0] neg_hi:[1,0]
	v_pk_mul_f32 v[42:43], v[42:43], 0.5 op_sel_hi:[1,0]
	v_pk_add_f32 v[38:39], v[38:39], 1.0 op_sel_hi:[1,0]
	v_pk_mul_f32 v[38:39], v[42:43], v[38:39]
	v_mul_f32_e32 v41, 2.0, v18
	v_rcp_f32_e32 v18, v40
	v_lshlrev_b64 v[36:37], 5, v[36:37]
	v_readlane_b32 s9, v254, 4
	v_mul_f32_e32 v40, 2.0, v18
	v_pk_add_f32 v[40:41], v[40:41], 1.0 op_sel_hi:[1,0] neg_lo:[1,0] neg_hi:[1,0]
	v_mov_b32_e32 v18, v17
	v_pk_mul_f32 v[16:17], v[18:19], 0.5 op_sel_hi:[1,0]
	v_pk_add_f32 v[18:19], v[40:41], 1.0 op_sel_hi:[1,0]
	v_lshl_add_u64 v[36:37], s[8:9], 0, v[36:37]
	v_pk_mul_f32 v[16:17], v[16:17], v[18:19]
	v_and_b32_sdwa v19, v38, v218 dst_sel:DWORD dst_unused:UNUSED_PAD src0_sel:WORD_1 src1_sel:DWORD
	v_add3_u32 v19, v38, v19, s80
	v_and_b32_sdwa v38, v16, v218 dst_sel:DWORD dst_unused:UNUSED_PAD src0_sel:WORD_1 src1_sel:DWORD
	v_add3_u32 v16, v16, v38, s80
	v_and_b32_e32 v16, 0xffff0000, v16
	v_or_b32_sdwa v16, v16, v19 dst_sel:DWORD dst_unused:UNUSED_PAD src0_sel:DWORD src1_sel:WORD_1
	v_mul_f32_e32 v19, 0x3d372713, v97
	v_mul_f32_e32 v19, v97, v19
	v_and_b32_sdwa v35, v17, v218 dst_sel:DWORD dst_unused:UNUSED_PAD src0_sel:WORD_1 src1_sel:DWORD
	v_fma_f32 v19, v97, v19, v97
	v_and_b32_sdwa v18, v39, v218 dst_sel:DWORD dst_unused:UNUSED_PAD src0_sel:WORD_1 src1_sel:DWORD
	v_add3_u32 v17, v17, v35, s80
	v_mul_f32_e32 v19, 0x3f4c422a, v19
	v_add3_u32 v18, v39, v18, s80
	v_and_b32_e32 v17, 0xffff0000, v17
	v_add_f32_e32 v19, v19, v19
	v_lshl_add_u64 v[36:37], v[36:37], 0, v[192:193]
	v_or_b32_sdwa v17, v17, v18 dst_sel:DWORD dst_unused:UNUSED_PAD src0_sel:DWORD src1_sel:WORD_1
	v_mul_f32_e32 v19, 0x3fb8aa3b, v19
	global_store_dwordx2 v[36:37], v[16:17], off
	v_mul_f32_e32 v18, 0x3d372713, v98
	v_exp_f32_e32 v36, v19
	v_mul_f32_e32 v19, 0x3d372713, v96
	v_mul_f32_e32 v18, v98, v18
	v_mul_f32_e32 v19, v96, v19
	v_fma_f32 v18, v98, v18, v98
	v_fma_f32 v19, v96, v19, v96
	v_or_b32_e32 v35, v82, v32
	v_mul_f32_e32 v18, 0x3f4c422a, v18
	v_mul_f32_e32 v19, 0x3f4c422a, v19
	v_or_b32_e32 v32, 2, v35
	v_add_f32_e32 v18, v18, v18
	v_add_f32_e32 v19, v19, v19
	v_lshlrev_b64 v[16:17], 5, v[32:33]
	v_mul_f32_e32 v18, 0x3fb8aa3b, v18
	v_mul_f32_e32 v19, 0x3fb8aa3b, v19
	v_mul_f32_e32 v32, 0x3d372713, v95
	v_exp_f32_e32 v18, v18
	v_exp_f32_e32 v19, v19
	v_mul_f32_e32 v32, v95, v32
	v_fma_f32 v32, v95, v32, v95
	v_mul_f32_e32 v32, 0x3f4c422a, v32
	v_add_f32_e32 v32, v32, v32
	v_mul_f32_e32 v32, 0x3fb8aa3b, v32
	v_pk_add_f32 v[18:19], v[18:19], 1.0 op_sel_hi:[1,0]
	v_exp_f32_e32 v37, v32
	v_rcp_f32_e32 v38, v19
	v_pk_add_f32 v[36:37], v[36:37], 1.0 op_sel_hi:[1,0]
	v_lshl_add_u64 v[16:17], s[8:9], 0, v[16:17]
	v_lshl_add_u64 v[16:17], v[16:17], 0, v[192:193]
	v_mul_f32_e32 v19, 2.0, v38
	v_rcp_f32_e32 v38, v18
	s_nop 0
	v_mul_f32_e32 v32, 2.0, v38
	v_mov_b32_e32 v38, v20
	v_mov_b32_e32 v39, v22
	v_rcp_f32_e32 v22, v37
	v_mov_b32_e32 v18, v32
	v_pk_add_f32 v[18:19], v[18:19], 1.0 op_sel_hi:[1,0] neg_lo:[1,0] neg_hi:[1,0]
	v_pk_mul_f32 v[38:39], v[38:39], 0.5 op_sel_hi:[1,0]
	v_pk_add_f32 v[18:19], v[18:19], 1.0 op_sel_hi:[1,0]
	v_pk_mul_f32 v[18:19], v[38:39], v[18:19]
	v_mul_f32_e32 v37, 2.0, v22
	v_rcp_f32_e32 v22, v36
	s_nop 0
	v_mul_f32_e32 v36, 2.0, v22
	v_pk_add_f32 v[36:37], v[36:37], 1.0 op_sel_hi:[1,0] neg_lo:[1,0] neg_hi:[1,0]
	v_mov_b32_e32 v22, v21
	v_pk_mul_f32 v[20:21], v[22:23], 0.5 op_sel_hi:[1,0]
	v_pk_add_f32 v[22:23], v[36:37], 1.0 op_sel_hi:[1,0]
	v_or_b32_e32 v32, 3, v35
	v_pk_mul_f32 v[20:21], v[20:21], v[22:23]
	v_and_b32_sdwa v22, v19, v218 dst_sel:DWORD dst_unused:UNUSED_PAD src0_sel:WORD_1 src1_sel:DWORD
	v_and_b32_sdwa v23, v18, v218 dst_sel:DWORD dst_unused:UNUSED_PAD src0_sel:WORD_1 src1_sel:DWORD
	v_add3_u32 v18, v18, v23, s80
	v_add3_u32 v19, v19, v22, s80
	v_and_b32_sdwa v22, v21, v218 dst_sel:DWORD dst_unused:UNUSED_PAD src0_sel:WORD_1 src1_sel:DWORD
	v_and_b32_sdwa v23, v20, v218 dst_sel:DWORD dst_unused:UNUSED_PAD src0_sel:WORD_1 src1_sel:DWORD
	v_add3_u32 v21, v21, v22, s80
	v_add3_u32 v20, v20, v23, s80
	v_and_b32_e32 v21, 0xffff0000, v21
	v_and_b32_e32 v20, 0xffff0000, v20
	v_or_b32_sdwa v19, v21, v19 dst_sel:DWORD dst_unused:UNUSED_PAD src0_sel:DWORD src1_sel:WORD_1
	v_or_b32_sdwa v18, v20, v18 dst_sel:DWORD dst_unused:UNUSED_PAD src0_sel:DWORD src1_sel:WORD_1
	global_store_dwordx2 v[16:17], v[18:19], off offset:16
	v_mul_f32_e32 v19, 0x3d372713, v93
	v_mul_f32_e32 v19, v93, v19
	v_fma_f32 v19, v93, v19, v93
	v_mul_f32_e32 v19, 0x3f4c422a, v19
	v_add_f32_e32 v19, v19, v19
	v_mul_f32_e32 v19, 0x3fb8aa3b, v19
	v_mul_f32_e32 v18, 0x3d372713, v94
	v_exp_f32_e32 v20, v19
	v_mul_f32_e32 v19, 0x3d372713, v92
	v_mul_f32_e32 v18, v94, v18
	v_mul_f32_e32 v19, v92, v19
	v_fma_f32 v18, v94, v18, v94
	v_fma_f32 v19, v92, v19, v92
	v_mul_f32_e32 v18, 0x3f4c422a, v18
	v_mul_f32_e32 v19, 0x3f4c422a, v19
	v_add_f32_e32 v18, v18, v18
	v_add_f32_e32 v19, v19, v19
	v_mul_f32_e32 v18, 0x3fb8aa3b, v18
	v_mul_f32_e32 v19, 0x3fb8aa3b, v19
	v_exp_f32_e32 v18, v18
	v_exp_f32_e32 v19, v19
	v_lshlrev_b64 v[16:17], 5, v[32:33]
	v_mul_f32_e32 v21, 0x3d372713, v91
	v_mul_f32_e32 v21, v91, v21
	v_pk_add_f32 v[18:19], v[18:19], 1.0 op_sel_hi:[1,0]
	v_fma_f32 v21, v91, v21, v91
	v_rcp_f32_e32 v23, v19
	v_mul_f32_e32 v21, 0x3f4c422a, v21
	v_add_f32_e32 v21, v21, v21
	v_mul_f32_e32 v21, 0x3fb8aa3b, v21
	v_mul_f32_e32 v19, 2.0, v23
	v_rcp_f32_e32 v23, v18
	v_exp_f32_e32 v21, v21
	v_lshl_add_u64 v[16:17], s[8:9], 0, v[16:17]
	v_lshl_add_u64 v[16:17], v[16:17], 0, v[192:193]
	v_mul_f32_e32 v18, 2.0, v23
	v_pk_add_f32 v[18:19], v[18:19], 1.0 op_sel_hi:[1,0] neg_lo:[1,0] neg_hi:[1,0]
	v_mov_b32_e32 v22, v24
	v_mov_b32_e32 v23, v26
	v_pk_mul_f32 v[22:23], v[22:23], 0.5 op_sel_hi:[1,0]
	v_pk_add_f32 v[18:19], v[18:19], 1.0 op_sel_hi:[1,0]
	v_pk_add_f32 v[20:21], v[20:21], 1.0 op_sel_hi:[1,0]
	v_pk_mul_f32 v[18:19], v[22:23], v[18:19]
	v_rcp_f32_e32 v23, v21
	s_nop 0
	v_mul_f32_e32 v21, 2.0, v23
	v_rcp_f32_e32 v23, v20
	s_nop 0
	v_mul_f32_e32 v20, 2.0, v23
	v_pk_add_f32 v[20:21], v[20:21], 1.0 op_sel_hi:[1,0] neg_lo:[1,0] neg_hi:[1,0]
	v_mov_b32_e32 v26, v25
	v_pk_mul_f32 v[22:23], v[26:27], 0.5 op_sel_hi:[1,0]
	v_pk_add_f32 v[20:21], v[20:21], 1.0 op_sel_hi:[1,0]
	s_nop 0
	v_pk_mul_f32 v[20:21], v[22:23], v[20:21]
	v_and_b32_sdwa v22, v19, v218 dst_sel:DWORD dst_unused:UNUSED_PAD src0_sel:WORD_1 src1_sel:DWORD
	v_and_b32_sdwa v23, v18, v218 dst_sel:DWORD dst_unused:UNUSED_PAD src0_sel:WORD_1 src1_sel:DWORD
	v_add3_u32 v18, v18, v23, s80
	v_add3_u32 v19, v19, v22, s80
	v_and_b32_sdwa v22, v21, v218 dst_sel:DWORD dst_unused:UNUSED_PAD src0_sel:WORD_1 src1_sel:DWORD
	v_and_b32_sdwa v23, v20, v218 dst_sel:DWORD dst_unused:UNUSED_PAD src0_sel:WORD_1 src1_sel:DWORD
	v_add3_u32 v21, v21, v22, s80
	v_add3_u32 v20, v20, v23, s80
	v_and_b32_e32 v21, 0xffff0000, v21
	v_and_b32_e32 v20, 0xffff0000, v20
	v_or_b32_sdwa v19, v21, v19 dst_sel:DWORD dst_unused:UNUSED_PAD src0_sel:DWORD src1_sel:WORD_1
	v_or_b32_sdwa v18, v20, v18 dst_sel:DWORD dst_unused:UNUSED_PAD src0_sel:DWORD src1_sel:WORD_1
	global_store_dwordx2 v[16:17], v[18:19], off
	v_mul_f32_e32 v19, 0x3d372713, v89
	v_mul_f32_e32 v19, v89, v19
	v_fma_f32 v19, v89, v19, v89
	v_mul_f32_e32 v19, 0x3f4c422a, v19
	v_add_f32_e32 v19, v19, v19
	v_mul_f32_e32 v19, 0x3fb8aa3b, v19
	v_mul_f32_e32 v18, 0x3d372713, v90
	v_exp_f32_e32 v20, v19
	v_mul_f32_e32 v19, 0x3d372713, v88
	v_mul_f32_e32 v18, v90, v18
	v_mul_f32_e32 v19, v88, v19
	v_fma_f32 v18, v90, v18, v90
	v_fma_f32 v19, v88, v19, v88
	v_mul_f32_e32 v18, 0x3f4c422a, v18
	v_mul_f32_e32 v19, 0x3f4c422a, v19
	v_add_f32_e32 v18, v18, v18
	v_add_f32_e32 v19, v19, v19
	v_mul_f32_e32 v18, 0x3fb8aa3b, v18
	v_mul_f32_e32 v19, 0x3fb8aa3b, v19
	v_exp_f32_e32 v18, v18
	v_exp_f32_e32 v19, v19
	v_mul_f32_e32 v21, 0x3d372713, v87
	v_mul_f32_e32 v21, v87, v21
	v_fma_f32 v21, v87, v21, v87
	v_pk_add_f32 v[18:19], v[18:19], 1.0 op_sel_hi:[1,0]
	v_mul_f32_e32 v21, 0x3f4c422a, v21
	v_rcp_f32_e32 v23, v19
	v_add_f32_e32 v21, v21, v21
	v_mul_f32_e32 v21, 0x3fb8aa3b, v21
	v_exp_f32_e32 v21, v21
	v_mul_f32_e32 v19, 2.0, v23
	v_rcp_f32_e32 v23, v18
	v_pk_add_f32 v[20:21], v[20:21], 1.0 op_sel_hi:[1,0]
	v_mul_f32_e32 v18, 2.0, v23
	v_pk_add_f32 v[18:19], v[18:19], 1.0 op_sel_hi:[1,0] neg_lo:[1,0] neg_hi:[1,0]
	v_mov_b32_e32 v22, v28
	v_mov_b32_e32 v23, v30
	v_pk_mul_f32 v[22:23], v[22:23], 0.5 op_sel_hi:[1,0]
	v_pk_add_f32 v[18:19], v[18:19], 1.0 op_sel_hi:[1,0]
	v_mov_b32_e32 v30, v29
	v_pk_mul_f32 v[18:19], v[22:23], v[18:19]
	v_rcp_f32_e32 v23, v21
	s_nop 0
	v_mul_f32_e32 v21, 2.0, v23
	v_rcp_f32_e32 v23, v20
	s_nop 0
	v_mul_f32_e32 v20, 2.0, v23
	v_pk_add_f32 v[20:21], v[20:21], 1.0 op_sel_hi:[1,0] neg_lo:[1,0] neg_hi:[1,0]
	v_pk_mul_f32 v[22:23], v[30:31], 0.5 op_sel_hi:[1,0]
	v_pk_add_f32 v[20:21], v[20:21], 1.0 op_sel_hi:[1,0]
	s_nop 0
	v_pk_mul_f32 v[20:21], v[22:23], v[20:21]
	v_and_b32_sdwa v22, v19, v218 dst_sel:DWORD dst_unused:UNUSED_PAD src0_sel:WORD_1 src1_sel:DWORD
	v_and_b32_sdwa v23, v18, v218 dst_sel:DWORD dst_unused:UNUSED_PAD src0_sel:WORD_1 src1_sel:DWORD
	v_add3_u32 v18, v18, v23, s80
	v_add3_u32 v19, v19, v22, s80
	v_and_b32_sdwa v22, v21, v218 dst_sel:DWORD dst_unused:UNUSED_PAD src0_sel:WORD_1 src1_sel:DWORD
	v_and_b32_sdwa v23, v20, v218 dst_sel:DWORD dst_unused:UNUSED_PAD src0_sel:WORD_1 src1_sel:DWORD
	v_add3_u32 v21, v21, v22, s80
	v_add3_u32 v20, v20, v23, s80
	v_and_b32_e32 v21, 0xffff0000, v21
	v_and_b32_e32 v20, 0xffff0000, v20
	v_or_b32_sdwa v19, v21, v19 dst_sel:DWORD dst_unused:UNUSED_PAD src0_sel:DWORD src1_sel:WORD_1
	v_or_b32_sdwa v18, v20, v18 dst_sel:DWORD dst_unused:UNUSED_PAD src0_sel:DWORD src1_sel:WORD_1
	global_store_dwordx2 v[16:17], v[18:19], off offset:16
.LBB0_261:
	s_or_b64 exec, exec, s[0:1]
	s_and_saveexec_b64 s[0:1], s[4:5]
	s_cbranch_execz .LBB0_248
	v_mul_f32_e32 v21, 0x3d372713, v85
	v_mul_f32_e32 v21, v85, v21
	v_fma_f32 v21, v85, v21, v85
	v_mul_f32_e32 v21, 0x3f4c422a, v21
	v_add_f32_e32 v21, v21, v21
	v_mul_f32_e32 v21, 0x3fb8aa3b, v21
	v_mul_f32_e32 v20, 0x3d372713, v86
	v_exp_f32_e32 v22, v21
	v_mul_f32_e32 v21, 0x3d372713, v84
	v_mul_f32_e32 v20, v86, v20
	v_mul_f32_e32 v21, v84, v21
	v_fma_f32 v20, v86, v20, v86
	v_fma_f32 v21, v84, v21, v84
	v_mul_f32_e32 v20, 0x3f4c422a, v20
	v_mul_f32_e32 v21, 0x3f4c422a, v21
	v_add_f32_e32 v20, v20, v20
	v_add_f32_e32 v21, v21, v21
	v_mul_f32_e32 v20, 0x3fb8aa3b, v20
	v_mul_f32_e32 v21, 0x3fb8aa3b, v21
	v_exp_f32_e32 v20, v20
	v_exp_f32_e32 v21, v21
	v_mul_f32_e32 v23, 0x3d372713, v83
	v_mul_f32_e32 v23, v83, v23
	v_fma_f32 v23, v83, v23, v83
	v_pk_add_f32 v[20:21], v[20:21], 1.0 op_sel_hi:[1,0]
	v_mul_f32_e32 v23, 0x3f4c422a, v23
	v_rcp_f32_e32 v25, v21
	v_add_f32_e32 v23, v23, v23
	v_mul_f32_e32 v23, 0x3fb8aa3b, v23
	v_exp_f32_e32 v23, v23
	v_mul_f32_e32 v21, 2.0, v25
	v_rcp_f32_e32 v25, v20
	v_pk_add_f32 v[22:23], v[22:23], 1.0 op_sel_hi:[1,0]
	v_mad_i64_i32 v[16:17], s[2:3], s7, v215, v[48:49]
	v_mul_f32_e32 v20, 2.0, v25
	v_mov_b32_e32 v24, v0
	v_mov_b32_e32 v25, v2
	v_rcp_f32_e32 v2, v23
	v_pk_add_f32 v[20:21], v[20:21], 1.0 op_sel_hi:[1,0] neg_lo:[1,0] neg_hi:[1,0]
	v_pk_mul_f32 v[24:25], v[24:25], 0.5 op_sel_hi:[1,0]
	v_pk_add_f32 v[20:21], v[20:21], 1.0 op_sel_hi:[1,0]
	v_or_b32_e32 v18, v16, v34
	v_pk_mul_f32 v[20:21], v[24:25], v[20:21]
	v_mul_f32_e32 v23, 2.0, v2
	v_rcp_f32_e32 v2, v22
	v_mov_b32_e32 v19, v17
	v_readlane_b32 s4, v254, 3
	v_lshlrev_b64 v[18:19], 5, v[18:19]
	v_mul_f32_e32 v22, 2.0, v2
	v_pk_add_f32 v[22:23], v[22:23], 1.0 op_sel_hi:[1,0] neg_lo:[1,0] neg_hi:[1,0]
	v_mov_b32_e32 v2, v1
	v_pk_mul_f32 v[0:1], v[2:3], 0.5 op_sel_hi:[1,0]
	v_pk_add_f32 v[2:3], v[22:23], 1.0 op_sel_hi:[1,0]
	v_readlane_b32 s5, v254, 4
	v_pk_mul_f32 v[0:1], v[0:1], v[2:3]
	v_and_b32_sdwa v2, v21, v218 dst_sel:DWORD dst_unused:UNUSED_PAD src0_sel:WORD_1 src1_sel:DWORD
	v_add3_u32 v2, v21, v2, s80
	v_and_b32_sdwa v21, v0, v218 dst_sel:DWORD dst_unused:UNUSED_PAD src0_sel:WORD_1 src1_sel:DWORD
	v_and_b32_sdwa v3, v20, v218 dst_sel:DWORD dst_unused:UNUSED_PAD src0_sel:WORD_1 src1_sel:DWORD
	v_add3_u32 v0, v0, v21, s80
	v_add3_u32 v3, v20, v3, s80
	v_and_b32_e32 v0, 0xffff0000, v0
	v_or_b32_sdwa v0, v0, v3 dst_sel:DWORD dst_unused:UNUSED_PAD src0_sel:DWORD src1_sel:WORD_1
	v_mul_f32_e32 v3, 0x3d372713, v80
	v_mul_f32_e32 v3, v80, v3
	v_and_b32_sdwa v20, v1, v218 dst_sel:DWORD dst_unused:UNUSED_PAD src0_sel:WORD_1 src1_sel:DWORD
	v_fma_f32 v3, v80, v3, v80
	v_add3_u32 v1, v1, v20, s80
	v_mul_f32_e32 v3, 0x3f4c422a, v3
	v_lshl_add_u64 v[18:19], s[4:5], 0, v[18:19]
	v_and_b32_e32 v1, 0xffff0000, v1
	v_add_f32_e32 v3, v3, v3
	v_lshl_add_u64 v[18:19], v[18:19], 0, v[192:193]
	v_or_b32_sdwa v1, v1, v2 dst_sel:DWORD dst_unused:UNUSED_PAD src0_sel:DWORD src1_sel:WORD_1
	v_mul_f32_e32 v3, 0x3fb8aa3b, v3
	global_store_dwordx2 v[18:19], v[0:1], off
	v_mul_f32_e32 v2, 0x3d372713, v81
	v_exp_f32_e32 v18, v3
	v_mul_f32_e32 v3, 0x3d372713, v79
	v_mul_f32_e32 v2, v81, v2
	v_mul_f32_e32 v3, v79, v3
	v_fma_f32 v2, v81, v2, v81
	v_fma_f32 v3, v79, v3, v79
	v_or_b32_e32 v22, v82, v16
	v_mul_f32_e32 v2, 0x3f4c422a, v2
	v_mul_f32_e32 v3, 0x3f4c422a, v3
	v_or_b32_e32 v16, 2, v22
	v_add_f32_e32 v2, v2, v2
	v_add_f32_e32 v3, v3, v3
	v_lshlrev_b64 v[0:1], 5, v[16:17]
	v_mul_f32_e32 v2, 0x3fb8aa3b, v2
	v_mul_f32_e32 v3, 0x3fb8aa3b, v3
	v_mul_f32_e32 v16, 0x3d372713, v78
	v_exp_f32_e32 v2, v2
	v_exp_f32_e32 v3, v3
	v_mul_f32_e32 v16, v78, v16
	v_fma_f32 v16, v78, v16, v78
	v_mul_f32_e32 v16, 0x3f4c422a, v16
	v_add_f32_e32 v16, v16, v16
	v_mul_f32_e32 v16, 0x3fb8aa3b, v16
	v_pk_add_f32 v[2:3], v[2:3], 1.0 op_sel_hi:[1,0]
	v_exp_f32_e32 v19, v16
	v_rcp_f32_e32 v20, v3
	v_pk_add_f32 v[18:19], v[18:19], 1.0 op_sel_hi:[1,0]
	v_lshl_add_u64 v[0:1], s[4:5], 0, v[0:1]
	v_lshl_add_u64 v[0:1], v[0:1], 0, v[192:193]
	v_mul_f32_e32 v3, 2.0, v20
	v_rcp_f32_e32 v20, v2
	s_nop 0
	v_mul_f32_e32 v16, 2.0, v20
	v_mov_b32_e32 v20, v4
	v_mov_b32_e32 v21, v6
	v_rcp_f32_e32 v6, v19
	v_mov_b32_e32 v2, v16
	v_pk_add_f32 v[2:3], v[2:3], 1.0 op_sel_hi:[1,0] neg_lo:[1,0] neg_hi:[1,0]
	v_pk_mul_f32 v[20:21], v[20:21], 0.5 op_sel_hi:[1,0]
	v_pk_add_f32 v[2:3], v[2:3], 1.0 op_sel_hi:[1,0]
	v_pk_mul_f32 v[2:3], v[20:21], v[2:3]
	v_mul_f32_e32 v19, 2.0, v6
	v_rcp_f32_e32 v6, v18
	s_nop 0
	v_mul_f32_e32 v18, 2.0, v6
	v_pk_add_f32 v[18:19], v[18:19], 1.0 op_sel_hi:[1,0] neg_lo:[1,0] neg_hi:[1,0]
	v_mov_b32_e32 v6, v5
	v_pk_mul_f32 v[4:5], v[6:7], 0.5 op_sel_hi:[1,0]
	v_pk_add_f32 v[6:7], v[18:19], 1.0 op_sel_hi:[1,0]
	v_or_b32_e32 v16, 3, v22
	v_pk_mul_f32 v[4:5], v[4:5], v[6:7]
	v_and_b32_sdwa v6, v3, v218 dst_sel:DWORD dst_unused:UNUSED_PAD src0_sel:WORD_1 src1_sel:DWORD
	v_and_b32_sdwa v7, v2, v218 dst_sel:DWORD dst_unused:UNUSED_PAD src0_sel:WORD_1 src1_sel:DWORD
	v_add3_u32 v2, v2, v7, s80
	v_add3_u32 v3, v3, v6, s80
	v_and_b32_sdwa v6, v5, v218 dst_sel:DWORD dst_unused:UNUSED_PAD src0_sel:WORD_1 src1_sel:DWORD
	v_and_b32_sdwa v7, v4, v218 dst_sel:DWORD dst_unused:UNUSED_PAD src0_sel:WORD_1 src1_sel:DWORD
	v_add3_u32 v5, v5, v6, s80
	v_add3_u32 v4, v4, v7, s80
	v_and_b32_e32 v5, 0xffff0000, v5
	v_and_b32_e32 v4, 0xffff0000, v4
	v_or_b32_sdwa v3, v5, v3 dst_sel:DWORD dst_unused:UNUSED_PAD src0_sel:DWORD src1_sel:WORD_1
	v_or_b32_sdwa v2, v4, v2 dst_sel:DWORD dst_unused:UNUSED_PAD src0_sel:DWORD src1_sel:WORD_1
	global_store_dwordx2 v[0:1], v[2:3], off offset:16
	v_mul_f32_e32 v3, 0x3d372713, v76
	v_mul_f32_e32 v3, v76, v3
	v_fma_f32 v3, v76, v3, v76
	v_mul_f32_e32 v3, 0x3f4c422a, v3
	v_add_f32_e32 v3, v3, v3
	v_mul_f32_e32 v3, 0x3fb8aa3b, v3
	v_mul_f32_e32 v2, 0x3d372713, v77
	v_exp_f32_e32 v4, v3
	v_mul_f32_e32 v3, 0x3d372713, v75
	v_mul_f32_e32 v2, v77, v2
	v_mul_f32_e32 v3, v75, v3
	v_fma_f32 v2, v77, v2, v77
	v_fma_f32 v3, v75, v3, v75
	v_mul_f32_e32 v2, 0x3f4c422a, v2
	v_mul_f32_e32 v3, 0x3f4c422a, v3
	v_add_f32_e32 v2, v2, v2
	v_add_f32_e32 v3, v3, v3
	v_mul_f32_e32 v2, 0x3fb8aa3b, v2
	v_mul_f32_e32 v3, 0x3fb8aa3b, v3
	v_exp_f32_e32 v2, v2
	v_exp_f32_e32 v3, v3
	v_lshlrev_b64 v[0:1], 5, v[16:17]
	v_mul_f32_e32 v5, 0x3d372713, v74
	v_mul_f32_e32 v5, v74, v5
	v_pk_add_f32 v[2:3], v[2:3], 1.0 op_sel_hi:[1,0]
	v_fma_f32 v5, v74, v5, v74
	v_rcp_f32_e32 v7, v3
	v_mul_f32_e32 v5, 0x3f4c422a, v5
	v_add_f32_e32 v5, v5, v5
	v_mul_f32_e32 v5, 0x3fb8aa3b, v5
	v_mul_f32_e32 v3, 2.0, v7
	v_rcp_f32_e32 v7, v2
	v_exp_f32_e32 v5, v5
	v_lshl_add_u64 v[0:1], s[4:5], 0, v[0:1]
	v_lshl_add_u64 v[0:1], v[0:1], 0, v[192:193]
	v_mul_f32_e32 v2, 2.0, v7
	v_pk_add_f32 v[2:3], v[2:3], 1.0 op_sel_hi:[1,0] neg_lo:[1,0] neg_hi:[1,0]
	v_mov_b32_e32 v6, v8
	v_mov_b32_e32 v7, v10
	v_pk_mul_f32 v[6:7], v[6:7], 0.5 op_sel_hi:[1,0]
	v_pk_add_f32 v[2:3], v[2:3], 1.0 op_sel_hi:[1,0]
	v_pk_add_f32 v[4:5], v[4:5], 1.0 op_sel_hi:[1,0]
	v_pk_mul_f32 v[2:3], v[6:7], v[2:3]
	v_rcp_f32_e32 v7, v5
	s_nop 0
	v_mul_f32_e32 v5, 2.0, v7
	v_rcp_f32_e32 v7, v4
	s_nop 0
	v_mul_f32_e32 v4, 2.0, v7
	v_pk_add_f32 v[4:5], v[4:5], 1.0 op_sel_hi:[1,0] neg_lo:[1,0] neg_hi:[1,0]
	v_mov_b32_e32 v10, v9
	v_pk_mul_f32 v[6:7], v[10:11], 0.5 op_sel_hi:[1,0]
	v_pk_add_f32 v[4:5], v[4:5], 1.0 op_sel_hi:[1,0]
	s_nop 0
	v_pk_mul_f32 v[4:5], v[6:7], v[4:5]
	v_and_b32_sdwa v6, v3, v218 dst_sel:DWORD dst_unused:UNUSED_PAD src0_sel:WORD_1 src1_sel:DWORD
	v_and_b32_sdwa v7, v2, v218 dst_sel:DWORD dst_unused:UNUSED_PAD src0_sel:WORD_1 src1_sel:DWORD
	v_add3_u32 v2, v2, v7, s80
	v_add3_u32 v3, v3, v6, s80
	v_and_b32_sdwa v6, v5, v218 dst_sel:DWORD dst_unused:UNUSED_PAD src0_sel:WORD_1 src1_sel:DWORD
	v_and_b32_sdwa v7, v4, v218 dst_sel:DWORD dst_unused:UNUSED_PAD src0_sel:WORD_1 src1_sel:DWORD
	v_add3_u32 v5, v5, v6, s80
	v_add3_u32 v4, v4, v7, s80
	v_and_b32_e32 v5, 0xffff0000, v5
	v_and_b32_e32 v4, 0xffff0000, v4
	v_or_b32_sdwa v3, v5, v3 dst_sel:DWORD dst_unused:UNUSED_PAD src0_sel:DWORD src1_sel:WORD_1
	v_or_b32_sdwa v2, v4, v2 dst_sel:DWORD dst_unused:UNUSED_PAD src0_sel:DWORD src1_sel:WORD_1
	global_store_dwordx2 v[0:1], v[2:3], off
	v_mul_f32_e32 v3, 0x3d372713, v72
	v_mul_f32_e32 v3, v72, v3
	v_fma_f32 v3, v72, v3, v72
	v_mul_f32_e32 v3, 0x3f4c422a, v3
	v_add_f32_e32 v3, v3, v3
	v_mul_f32_e32 v3, 0x3fb8aa3b, v3
	v_mul_f32_e32 v2, 0x3d372713, v73
	v_exp_f32_e32 v4, v3
	v_mul_f32_e32 v3, 0x3d372713, v71
	v_mul_f32_e32 v2, v73, v2
	v_mul_f32_e32 v3, v71, v3
	v_fma_f32 v2, v73, v2, v73
	v_fma_f32 v3, v71, v3, v71
	v_mul_f32_e32 v2, 0x3f4c422a, v2
	v_mul_f32_e32 v3, 0x3f4c422a, v3
	v_add_f32_e32 v2, v2, v2
	v_add_f32_e32 v3, v3, v3
	v_mul_f32_e32 v2, 0x3fb8aa3b, v2
	v_mul_f32_e32 v3, 0x3fb8aa3b, v3
	v_exp_f32_e32 v2, v2
	v_exp_f32_e32 v3, v3
	v_mul_f32_e32 v5, 0x3d372713, v70
	v_mul_f32_e32 v5, v70, v5
	v_fma_f32 v5, v70, v5, v70
	v_pk_add_f32 v[2:3], v[2:3], 1.0 op_sel_hi:[1,0]
	v_mul_f32_e32 v5, 0x3f4c422a, v5
	v_rcp_f32_e32 v7, v3
	v_add_f32_e32 v5, v5, v5
	v_mul_f32_e32 v5, 0x3fb8aa3b, v5
	v_exp_f32_e32 v5, v5
	v_mul_f32_e32 v3, 2.0, v7
	v_rcp_f32_e32 v7, v2
	v_pk_add_f32 v[4:5], v[4:5], 1.0 op_sel_hi:[1,0]
	v_mul_f32_e32 v2, 2.0, v7
	v_pk_add_f32 v[2:3], v[2:3], 1.0 op_sel_hi:[1,0] neg_lo:[1,0] neg_hi:[1,0]
	v_mov_b32_e32 v6, v12
	v_mov_b32_e32 v7, v14
	v_pk_mul_f32 v[6:7], v[6:7], 0.5 op_sel_hi:[1,0]
	v_pk_add_f32 v[2:3], v[2:3], 1.0 op_sel_hi:[1,0]
	v_mov_b32_e32 v14, v13
	v_pk_mul_f32 v[2:3], v[6:7], v[2:3]
	v_rcp_f32_e32 v7, v5
	s_nop 0
	v_mul_f32_e32 v5, 2.0, v7
	v_rcp_f32_e32 v7, v4
	s_nop 0
	v_mul_f32_e32 v4, 2.0, v7
	v_pk_add_f32 v[4:5], v[4:5], 1.0 op_sel_hi:[1,0] neg_lo:[1,0] neg_hi:[1,0]
	v_pk_mul_f32 v[6:7], v[14:15], 0.5 op_sel_hi:[1,0]
	v_pk_add_f32 v[4:5], v[4:5], 1.0 op_sel_hi:[1,0]
	s_nop 0
	v_pk_mul_f32 v[4:5], v[6:7], v[4:5]
	v_and_b32_sdwa v6, v3, v218 dst_sel:DWORD dst_unused:UNUSED_PAD src0_sel:WORD_1 src1_sel:DWORD
	v_and_b32_sdwa v7, v2, v218 dst_sel:DWORD dst_unused:UNUSED_PAD src0_sel:WORD_1 src1_sel:DWORD
	v_add3_u32 v2, v2, v7, s80
	v_add3_u32 v3, v3, v6, s80
	v_and_b32_sdwa v6, v5, v218 dst_sel:DWORD dst_unused:UNUSED_PAD src0_sel:WORD_1 src1_sel:DWORD
	v_and_b32_sdwa v7, v4, v218 dst_sel:DWORD dst_unused:UNUSED_PAD src0_sel:WORD_1 src1_sel:DWORD
	v_add3_u32 v5, v5, v6, s80
	v_add3_u32 v4, v4, v7, s80
	v_and_b32_e32 v5, 0xffff0000, v5
	v_and_b32_e32 v4, 0xffff0000, v4
	v_or_b32_sdwa v3, v5, v3 dst_sel:DWORD dst_unused:UNUSED_PAD src0_sel:DWORD src1_sel:WORD_1
	v_or_b32_sdwa v2, v4, v2 dst_sel:DWORD dst_unused:UNUSED_PAD src0_sel:DWORD src1_sel:WORD_1
	global_store_dwordx2 v[0:1], v[2:3], off offset:16
	s_branch .LBB0_248

.LBB0_363:
	v_cmp_lt_i32_e32 vcc, v212, v210
	s_waitcnt vmcnt(21)
	v_accvgpr_read_b32 v31, a3
	v_accvgpr_read_b32 v30, a2
	v_cndmask_b32_e32 v32, v209, v212, vcc
	v_lshlrev_b32_e32 v33, 2, v32
	ds_bpermute_b32 v32, v33, v88
	v_cmp_lt_i32_e32 vcc, v211, v210
	v_accvgpr_read_b32 v28, a0
	v_accvgpr_read_b32 v29, a1
	v_cndmask_b32_e32 v34, v209, v211, vcc
	s_waitcnt lgkmcnt(0)
	v_add_f32_e32 v32, v88, v32
	s_waitcnt vmcnt(11)
	v_lshlrev_b32_e32 v38, 2, v34
	ds_bpermute_b32 v34, v38, v32
	v_ashrrev_i32_e32 v83, 31, v82
	v_mov_b32_e32 v85, v193
	v_accvgpr_read_b32 v27, a7
	v_accvgpr_read_b32 v26, a6
	s_waitcnt lgkmcnt(0)
	v_add_f32_e32 v32, v32, v34
	v_rcp_f32_e32 v35, v32
	s_mov_b32 s0, 0x5780000
	v_accvgpr_read_b32 v24, a4
	v_accvgpr_read_b32 v25, a5
	v_mul_f32_e32 v32, 1.0, v35
	v_mov_b32_e32 v36, v28
	v_mov_b32_e32 v37, v30
	v_pk_mul_f32 v[36:37], v[36:37], v[32:33] op_sel_hi:[1,0]
	v_mov_b32_e32 v30, v29
	v_pk_mul_f32 v[28:29], v[30:31], v[32:33] op_sel_hi:[1,0]
	v_and_b32_sdwa v30, v37, v218 dst_sel:DWORD dst_unused:UNUSED_PAD src0_sel:WORD_1 src1_sel:DWORD
	v_and_b32_sdwa v31, v36, v218 dst_sel:DWORD dst_unused:UNUSED_PAD src0_sel:WORD_1 src1_sel:DWORD
	v_add3_u32 v31, v36, v31, s80
	v_add3_u32 v30, v37, v30, s80
	v_and_b32_sdwa v36, v29, v218 dst_sel:DWORD dst_unused:UNUSED_PAD src0_sel:WORD_1 src1_sel:DWORD
	v_and_b32_sdwa v37, v28, v218 dst_sel:DWORD dst_unused:UNUSED_PAD src0_sel:WORD_1 src1_sel:DWORD
	v_lshlrev_b64 v[34:35], 11, v[82:83]
	v_add3_u32 v29, v29, v36, s80
	v_add3_u32 v28, v28, v37, s80
	v_lshl_add_u64 v[34:35], s[90:91], 0, v[34:35]
	v_and_b32_e32 v29, 0xffff0000, v29
	v_and_b32_e32 v28, 0xffff0000, v28
	v_or_b32_sdwa v29, v29, v30 dst_sel:DWORD dst_unused:UNUSED_PAD src0_sel:DWORD src1_sel:WORD_1
	v_or_b32_sdwa v28, v28, v31 dst_sel:DWORD dst_unused:UNUSED_PAD src0_sel:DWORD src1_sel:WORD_1
	v_lshl_add_u64 v[30:31], s[2:3], 1, v[34:35]
	v_lshl_add_u64 v[30:31], v[30:31], 0, v[84:85]
	v_add_co_u32_e32 v34, vcc, s0, v30
	v_accvgpr_read_b32 v23, a11
	s_nop 0
	v_addc_co_u32_e32 v35, vcc, 0, v31, vcc
	global_store_dwordx2 v[34:35], v[28:29], off offset:1280
	v_mov_b32_e32 v28, v24
	v_mov_b32_e32 v29, v26
	v_pk_mul_f32 v[28:29], v[28:29], v[32:33] op_sel_hi:[1,0]
	v_mov_b32_e32 v26, v25
	v_pk_mul_f32 v[24:25], v[26:27], v[32:33] op_sel_hi:[1,0]
	v_and_b32_sdwa v26, v29, v218 dst_sel:DWORD dst_unused:UNUSED_PAD src0_sel:WORD_1 src1_sel:DWORD
	v_and_b32_sdwa v27, v28, v218 dst_sel:DWORD dst_unused:UNUSED_PAD src0_sel:WORD_1 src1_sel:DWORD
	v_add3_u32 v27, v28, v27, s80
	v_add3_u32 v26, v29, v26, s80
	v_and_b32_sdwa v28, v25, v218 dst_sel:DWORD dst_unused:UNUSED_PAD src0_sel:WORD_1 src1_sel:DWORD
	v_and_b32_sdwa v29, v24, v218 dst_sel:DWORD dst_unused:UNUSED_PAD src0_sel:WORD_1 src1_sel:DWORD
	v_add3_u32 v25, v25, v28, s80
	v_add3_u32 v24, v24, v29, s80
	v_and_b32_e32 v25, 0xffff0000, v25
	v_and_b32_e32 v24, 0xffff0000, v24
	v_accvgpr_read_b32 v22, a10
	v_accvgpr_read_b32 v20, a8
	v_or_b32_sdwa v25, v25, v26 dst_sel:DWORD dst_unused:UNUSED_PAD src0_sel:DWORD src1_sel:WORD_1
	v_or_b32_sdwa v24, v24, v27 dst_sel:DWORD dst_unused:UNUSED_PAD src0_sel:DWORD src1_sel:WORD_1
	v_accvgpr_read_b32 v21, a9
	global_store_dwordx2 v[34:35], v[24:25], off offset:1312
	v_mov_b32_e32 v24, v20
	v_mov_b32_e32 v25, v22
	v_pk_mul_f32 v[24:25], v[24:25], v[32:33] op_sel_hi:[1,0]
	v_mov_b32_e32 v22, v21
	v_pk_mul_f32 v[20:21], v[22:23], v[32:33] op_sel_hi:[1,0]
	v_and_b32_sdwa v22, v25, v218 dst_sel:DWORD dst_unused:UNUSED_PAD src0_sel:WORD_1 src1_sel:DWORD
	v_and_b32_sdwa v23, v24, v218 dst_sel:DWORD dst_unused:UNUSED_PAD src0_sel:WORD_1 src1_sel:DWORD
	v_add3_u32 v23, v24, v23, s80
	v_add3_u32 v22, v25, v22, s80
	v_and_b32_sdwa v24, v21, v218 dst_sel:DWORD dst_unused:UNUSED_PAD src0_sel:WORD_1 src1_sel:DWORD
	v_and_b32_sdwa v25, v20, v218 dst_sel:DWORD dst_unused:UNUSED_PAD src0_sel:WORD_1 src1_sel:DWORD
	v_add3_u32 v21, v21, v24, s80
	v_add3_u32 v20, v20, v25, s80
	v_accvgpr_read_b32 v19, a15
	v_and_b32_e32 v21, 0xffff0000, v21
	v_and_b32_e32 v20, 0xffff0000, v20
	v_accvgpr_read_b32 v18, a14
	v_accvgpr_read_b32 v16, a12
	v_or_b32_sdwa v21, v21, v22 dst_sel:DWORD dst_unused:UNUSED_PAD src0_sel:DWORD src1_sel:WORD_1
	v_or_b32_sdwa v20, v20, v23 dst_sel:DWORD dst_unused:UNUSED_PAD src0_sel:DWORD src1_sel:WORD_1
	v_accvgpr_read_b32 v17, a13
	global_store_dwordx2 v[34:35], v[20:21], off offset:1344
	v_mov_b32_e32 v20, v16
	v_mov_b32_e32 v21, v18
	v_pk_mul_f32 v[20:21], v[20:21], v[32:33] op_sel_hi:[1,0]
	v_mov_b32_e32 v18, v17
	v_pk_mul_f32 v[16:17], v[18:19], v[32:33] op_sel_hi:[1,0]
	v_and_b32_sdwa v18, v21, v218 dst_sel:DWORD dst_unused:UNUSED_PAD src0_sel:WORD_1 src1_sel:DWORD
	v_and_b32_sdwa v19, v20, v218 dst_sel:DWORD dst_unused:UNUSED_PAD src0_sel:WORD_1 src1_sel:DWORD
	v_add3_u32 v19, v20, v19, s80
	v_add3_u32 v18, v21, v18, s80
	v_and_b32_sdwa v20, v17, v218 dst_sel:DWORD dst_unused:UNUSED_PAD src0_sel:WORD_1 src1_sel:DWORD
	v_and_b32_sdwa v21, v16, v218 dst_sel:DWORD dst_unused:UNUSED_PAD src0_sel:WORD_1 src1_sel:DWORD
	v_add3_u32 v17, v17, v20, s80
	v_add3_u32 v16, v16, v21, s80
	v_and_b32_e32 v17, 0xffff0000, v17
	v_and_b32_e32 v16, 0xffff0000, v16
	v_or_b32_sdwa v17, v17, v18 dst_sel:DWORD dst_unused:UNUSED_PAD src0_sel:DWORD src1_sel:WORD_1
	v_or_b32_sdwa v16, v16, v19 dst_sel:DWORD dst_unused:UNUSED_PAD src0_sel:DWORD src1_sel:WORD_1
	global_store_dwordx2 v[34:35], v[16:17], off offset:1376
	ds_bpermute_b32 v16, v33, v89
	s_waitcnt vmcnt(4)
	v_accvgpr_read_b32 v12, a16
	v_accvgpr_read_b32 v13, a17
	v_accvgpr_read_b32 v14, a18
	v_accvgpr_read_b32 v15, a19
	s_waitcnt lgkmcnt(0)
	v_add_f32_e32 v16, v89, v16
	ds_bpermute_b32 v17, v38, v16
	v_accvgpr_read_b32 v8, a20
	v_accvgpr_read_b32 v10, a22
	v_accvgpr_read_b32 v9, a21
	v_accvgpr_read_b32 v11, a23
	s_waitcnt lgkmcnt(0)
	v_add_f32_e32 v16, v16, v17
	v_div_scale_f32 v17, s[0:1], v16, v16, 1.0
	v_rcp_f32_e32 v18, v17
	s_mov_b32 s0, 0x57a0000
	v_accvgpr_read_b32 v4, a24
	v_accvgpr_read_b32 v6, a26
	v_fma_f32 v19, -v17, v18, 1.0
	v_fmac_f32_e32 v18, v19, v18
	v_div_scale_f32 v19, vcc, 1.0, v16, 1.0
	v_mul_f32_e32 v20, v19, v18
	v_fma_f32 v21, -v17, v20, v19
	v_fmac_f32_e32 v20, v21, v18
	v_fma_f32 v17, -v17, v20, v19
	v_div_fmas_f32 v17, v17, v18, v20
	v_div_fixup_f32 v16, v17, v16, 1.0
	v_mov_b32_e32 v18, v12
	v_mov_b32_e32 v19, v14
	v_mov_b32_e32 v14, v13
	v_pk_mul_f32 v[18:19], v[18:19], v[16:17] op_sel_hi:[1,0]
	v_pk_mul_f32 v[12:13], v[14:15], v[16:17] op_sel_hi:[1,0]
	v_and_b32_sdwa v15, v18, v218 dst_sel:DWORD dst_unused:UNUSED_PAD src0_sel:WORD_1 src1_sel:DWORD
	v_and_b32_sdwa v17, v13, v218 dst_sel:DWORD dst_unused:UNUSED_PAD src0_sel:WORD_1 src1_sel:DWORD
	v_and_b32_sdwa v14, v19, v218 dst_sel:DWORD dst_unused:UNUSED_PAD src0_sel:WORD_1 src1_sel:DWORD
	v_add3_u32 v15, v18, v15, s80
	v_and_b32_sdwa v18, v12, v218 dst_sel:DWORD dst_unused:UNUSED_PAD src0_sel:WORD_1 src1_sel:DWORD
	v_add3_u32 v13, v13, v17, s80
	v_add3_u32 v14, v19, v14, s80
	v_add3_u32 v12, v12, v18, s80
	v_and_b32_e32 v13, 0xffff0000, v13
	v_and_b32_e32 v12, 0xffff0000, v12
	v_or_b32_sdwa v13, v13, v14 dst_sel:DWORD dst_unused:UNUSED_PAD src0_sel:DWORD src1_sel:WORD_1
	v_add_co_u32_e32 v14, vcc, s0, v30
	v_or_b32_sdwa v12, v12, v15 dst_sel:DWORD dst_unused:UNUSED_PAD src0_sel:DWORD src1_sel:WORD_1
	s_nop 0
	v_addc_co_u32_e32 v15, vcc, 0, v31, vcc
	global_store_dwordx2 v[14:15], v[12:13], off offset:1280
	v_mov_b32_e32 v12, v8
	v_mov_b32_e32 v13, v10
	v_pk_mul_f32 v[12:13], v[12:13], v[16:17] op_sel_hi:[1,0]
	v_mov_b32_e32 v10, v9
	v_pk_mul_f32 v[8:9], v[10:11], v[16:17] op_sel_hi:[1,0]
	v_and_b32_sdwa v10, v13, v218 dst_sel:DWORD dst_unused:UNUSED_PAD src0_sel:WORD_1 src1_sel:DWORD
	v_and_b32_sdwa v11, v12, v218 dst_sel:DWORD dst_unused:UNUSED_PAD src0_sel:WORD_1 src1_sel:DWORD
	v_add3_u32 v11, v12, v11, s80
	v_add3_u32 v10, v13, v10, s80
	v_and_b32_sdwa v12, v9, v218 dst_sel:DWORD dst_unused:UNUSED_PAD src0_sel:WORD_1 src1_sel:DWORD
	v_and_b32_sdwa v13, v8, v218 dst_sel:DWORD dst_unused:UNUSED_PAD src0_sel:WORD_1 src1_sel:DWORD
	v_add3_u32 v9, v9, v12, s80
	v_add3_u32 v8, v8, v13, s80
	v_and_b32_e32 v9, 0xffff0000, v9
	v_and_b32_e32 v8, 0xffff0000, v8
	v_or_b32_sdwa v9, v9, v10 dst_sel:DWORD dst_unused:UNUSED_PAD src0_sel:DWORD src1_sel:WORD_1
	v_or_b32_sdwa v8, v8, v11 dst_sel:DWORD dst_unused:UNUSED_PAD src0_sel:DWORD src1_sel:WORD_1
	v_accvgpr_read_b32 v5, a25
	global_store_dwordx2 v[14:15], v[8:9], off offset:1312
	v_mov_b32_e32 v8, v4
	v_mov_b32_e32 v9, v6
	v_accvgpr_read_b32 v7, a27
	v_pk_mul_f32 v[8:9], v[8:9], v[16:17] op_sel_hi:[1,0]
	v_mov_b32_e32 v6, v5
	v_pk_mul_f32 v[4:5], v[6:7], v[16:17] op_sel_hi:[1,0]
	v_and_b32_sdwa v6, v9, v218 dst_sel:DWORD dst_unused:UNUSED_PAD src0_sel:WORD_1 src1_sel:DWORD
	v_and_b32_sdwa v7, v8, v218 dst_sel:DWORD dst_unused:UNUSED_PAD src0_sel:WORD_1 src1_sel:DWORD
	v_add3_u32 v7, v8, v7, s80
	v_add3_u32 v6, v9, v6, s80
	v_and_b32_sdwa v8, v5, v218 dst_sel:DWORD dst_unused:UNUSED_PAD src0_sel:WORD_1 src1_sel:DWORD
	v_and_b32_sdwa v9, v4, v218 dst_sel:DWORD dst_unused:UNUSED_PAD src0_sel:WORD_1 src1_sel:DWORD
	v_add3_u32 v5, v5, v8, s80
	v_add3_u32 v4, v4, v9, s80
	v_accvgpr_read_b32 v0, a28
	v_and_b32_e32 v5, 0xffff0000, v5
	v_and_b32_e32 v4, 0xffff0000, v4
	v_accvgpr_read_b32 v2, a30
	v_or_b32_sdwa v5, v5, v6 dst_sel:DWORD dst_unused:UNUSED_PAD src0_sel:DWORD src1_sel:WORD_1
	v_or_b32_sdwa v4, v4, v7 dst_sel:DWORD dst_unused:UNUSED_PAD src0_sel:DWORD src1_sel:WORD_1
	v_accvgpr_read_b32 v1, a29
	global_store_dwordx2 v[14:15], v[4:5], off offset:1344
	v_mov_b32_e32 v4, v0
	v_mov_b32_e32 v5, v2
	v_accvgpr_read_b32 v3, a31
	v_pk_mul_f32 v[4:5], v[4:5], v[16:17] op_sel_hi:[1,0]
	v_mov_b32_e32 v2, v1
	v_pk_mul_f32 v[0:1], v[2:3], v[16:17] op_sel_hi:[1,0]
	v_and_b32_sdwa v2, v5, v218 dst_sel:DWORD dst_unused:UNUSED_PAD src0_sel:WORD_1 src1_sel:DWORD
	v_and_b32_sdwa v3, v4, v218 dst_sel:DWORD dst_unused:UNUSED_PAD src0_sel:WORD_1 src1_sel:DWORD
	v_add3_u32 v3, v4, v3, s80
	v_add3_u32 v2, v5, v2, s80
	v_and_b32_sdwa v4, v1, v218 dst_sel:DWORD dst_unused:UNUSED_PAD src0_sel:WORD_1 src1_sel:DWORD
	v_and_b32_sdwa v5, v0, v218 dst_sel:DWORD dst_unused:UNUSED_PAD src0_sel:WORD_1 src1_sel:DWORD
	v_add3_u32 v1, v1, v4, s80
	v_add3_u32 v0, v0, v5, s80
	v_and_b32_e32 v1, 0xffff0000, v1
	v_and_b32_e32 v0, 0xffff0000, v0
	v_or_b32_sdwa v1, v1, v2 dst_sel:DWORD dst_unused:UNUSED_PAD src0_sel:DWORD src1_sel:WORD_1
	v_or_b32_sdwa v0, v0, v3 dst_sel:DWORD dst_unused:UNUSED_PAD src0_sel:DWORD src1_sel:WORD_1
	global_store_dwordx2 v[14:15], v[0:1], off offset:1376

.LBB0_773:
	v_mov_b32_e32 v90, 0
	v_mov_b32_e32 v91, 0
	v_mov_b32_e32 v92, 0
	v_mov_b32_e32 v93, 0
	v_mov_b32_e32 v194, 0
	v_mov_b32_e32 v195, 0
	v_mov_b32_e32 v196, 0
	v_mov_b32_e32 v197, 0
	v_mov_b32_e32 v198, 0
	v_mov_b32_e32 v199, 0
	v_mov_b32_e32 v200, 0
	v_mov_b32_e32 v201, 0
	v_mov_b32_e32 v202, 0
	v_mov_b32_e32 v203, 0
	v_mov_b32_e32 v204, 0
	v_mov_b32_e32 v205, 0
	s_nop 1
.Lrs5_top:
	s_add_i32 s4, s3, 64
	s_min_u32 s5, s4, 0x3e0
	s_lshl_b32 s78, s5, 1
	ds_read_b128 v[44:47], v78 offset:0
	ds_read_b128 v[40:43], v78 offset:0x800
	ds_read_b128 v[60:63], v76 offset:0
	v_mfma_f32_32x32x16_bf16 a[48:63], v[90:93], v[202:205], a[48:63]
	ds_read_b128 v[56:59], v76 offset:0x800
	v_mfma_f32_32x32x16_bf16 a[16:31], v[90:93], v[194:197], a[16:31]
	ds_read_b128 v[52:55], v76 offset:0x1000
	v_lshl_add_u64 v[106:107], v[64:65], 0, s[78:79]
	global_load_dwordx4 v[106:109], v[106:107], off
	v_mfma_f32_32x32x16_bf16 a[0:15], v[198:201], v[202:205], a[0:15]
	ds_read_b128 v[48:51], v76 offset:0x1800
	v_lshl_add_u64 v[110:111], v[68:69], 0, s[78:79]
	global_load_dwordx4 v[110:113], v[110:111], off
	v_mfma_f32_32x32x16_bf16 a[128:143], v[198:201], v[194:197], a[128:143]
	v_lshl_add_u64 v[114:115], v[70:71], 0, s[78:79]
	global_load_dwordx4 v[114:117], v[114:115], off
	s_waitcnt lgkmcnt(3)
	v_mfma_f32_32x32x16_bf16 a[112:127], v[60:63], v[44:47], a[112:127]
	ds_read_b128 v[82:85], v79 offset:0
	v_mfma_f32_32x32x16_bf16 a[96:111], v[60:63], v[40:43], a[96:111]
	v_lshl_add_u64 v[118:119], v[72:73], 0, s[78:79]
	global_load_dwordx4 v[118:121], v[118:119], off
	s_waitcnt lgkmcnt(3)
	v_mfma_f32_32x32x16_bf16 a[80:95], v[56:59], v[44:47], a[80:95]
	ds_read_b128 v[86:89], v79 offset:0x800
	v_mfma_f32_32x32x16_bf16 a[64:79], v[56:59], v[40:43], a[64:79]
	v_lshl_add_u64 v[122:123], v[66:67], 0, s[78:79]
	global_load_dwordx4 v[122:125], v[122:123], off
	s_waitcnt lgkmcnt(3)
	v_mfma_f32_32x32x16_bf16 a[48:63], v[52:55], v[44:47], a[48:63]
	ds_read_b128 v[90:93], v77 offset:0
	v_mfma_f32_32x32x16_bf16 a[16:31], v[52:55], v[40:43], a[16:31]
	v_lshl_add_u64 v[126:127], v[74:75], 0, s[78:79]
	global_load_dwordx4 v[126:129], v[126:127], off
	s_waitcnt vmcnt(11)
	ds_write_b128 v80, v[4:7] offset:0x8000
	s_waitcnt lgkmcnt(4)
	v_mfma_f32_32x32x16_bf16 a[0:15], v[48:51], v[44:47], a[0:15]
	ds_read_b128 v[94:97], v77 offset:0x800
	s_min_u32 s3, s3, 0x380
	s_lshl_b32 s78, s3, 1
	s_waitcnt vmcnt(10)
	ds_write_b128 v80, v[8:11] offset:0x9000
	v_mfma_f32_32x32x16_bf16 a[128:143], v[48:51], v[40:43], a[128:143]
	ds_read_b128 v[98:101], v77 offset:0x1000
	s_add_i32 s6, s78, 0xc0
	s_mov_b32 s7, s79
	s_waitcnt vmcnt(9)
	ds_write_b128 v80, v[12:15] offset:0xa000
	s_waitcnt lgkmcnt(5)
	v_mfma_f32_32x32x16_bf16 a[112:127], v[90:93], v[82:85], a[112:127]
	ds_read_b128 v[102:105], v77 offset:0x1800
	s_add_i32 s2, s2, 2
	s_cmp_gt_u32 s2, 29
	s_waitcnt vmcnt(8)
	ds_write_b128 v80, v[16:19] offset:0xb000
	v_mfma_f32_32x32x16_bf16 a[96:111], v[90:93], v[86:89], a[96:111]
	s_waitcnt vmcnt(7)
	ds_write_b128 v80, v[20:23] offset:0xc000
	s_waitcnt lgkmcnt(6)
	v_mfma_f32_32x32x16_bf16 a[80:95], v[94:97], v[82:85], a[80:95]
	s_waitcnt vmcnt(6)
	ds_write_b128 v80, v[24:27] offset:0xd000
	v_mfma_f32_32x32x16_bf16 a[64:79], v[94:97], v[86:89], a[64:79]
	v_lshl_add_u64 v[4:5], v[64:65], 0, s[78:79]
	v_lshl_add_u64 v[8:9], v[68:69], 0, s[6:7]
	v_lshl_add_u64 v[12:13], v[70:71], 0, s[6:7]
	v_lshl_add_u64 v[16:17], v[72:73], 0, s[6:7]
	v_lshl_add_u64 v[20:21], v[66:67], 0, s[78:79]
	v_lshl_add_u64 v[24:25], v[74:75], 0, s[6:7]
	s_waitcnt lgkmcnt(0)
	s_barrier
	ds_read_b128 v[40:43], v78 offset:0x8000
	ds_read_b128 v[44:47], v78 offset:0x8800
	ds_read_b128 v[48:51], v76 offset:0x8000
	v_mfma_f32_32x32x16_bf16 a[48:63], v[98:101], v[82:85], a[48:63]
	ds_read_b128 v[52:55], v76 offset:0x8800
	v_mfma_f32_32x32x16_bf16 a[16:31], v[98:101], v[86:89], a[16:31]
	ds_read_b128 v[56:59], v76 offset:0x9000
	global_load_dwordx4 v[4:7], v[4:5], off offset:192
	v_mfma_f32_32x32x16_bf16 a[0:15], v[102:105], v[82:85], a[0:15]
	ds_read_b128 v[60:63], v76 offset:0x9800
	global_load_dwordx4 v[8:11], v[8:9], off
	v_mfma_f32_32x32x16_bf16 a[128:143], v[102:105], v[86:89], a[128:143]
	global_load_dwordx4 v[12:15], v[12:13], off
	s_waitcnt lgkmcnt(3)
	v_mfma_f32_32x32x16_bf16 a[112:127], v[48:51], v[40:43], a[112:127]
	ds_read_b128 v[202:205], v79 offset:0x8000
	v_mfma_f32_32x32x16_bf16 a[96:111], v[48:51], v[44:47], a[96:111]
	global_load_dwordx4 v[16:19], v[16:17], off
	s_waitcnt lgkmcnt(3)
	v_mfma_f32_32x32x16_bf16 a[80:95], v[52:55], v[40:43], a[80:95]
	ds_read_b128 v[194:197], v79 offset:0x8800
	v_mfma_f32_32x32x16_bf16 a[64:79], v[52:55], v[44:47], a[64:79]
	global_load_dwordx4 v[20:23], v[20:21], off offset:192
	s_waitcnt lgkmcnt(3)
	v_mfma_f32_32x32x16_bf16 a[48:63], v[56:59], v[40:43], a[48:63]
	ds_read_b128 v[82:85], v77 offset:0x8000
	v_mfma_f32_32x32x16_bf16 a[16:31], v[56:59], v[44:47], a[16:31]
	global_load_dwordx4 v[24:27], v[24:25], off
	s_waitcnt vmcnt(11)
	ds_write_b128 v80, v[106:109] offset:0
	s_waitcnt lgkmcnt(4)
	v_mfma_f32_32x32x16_bf16 a[0:15], v[60:63], v[40:43], a[0:15]
	ds_read_b128 v[86:89], v77 offset:0x8800
	s_waitcnt vmcnt(10)
	ds_write_b128 v80, v[110:113] offset:0x1000
	v_mfma_f32_32x32x16_bf16 a[128:143], v[60:63], v[44:47], a[128:143]
	ds_read_b128 v[90:93], v77 offset:0x9000
	s_waitcnt vmcnt(9)
	ds_write_b128 v80, v[114:117] offset:0x2000
	s_waitcnt lgkmcnt(5)
	v_mfma_f32_32x32x16_bf16 a[112:127], v[82:85], v[202:205], a[112:127]
	ds_read_b128 v[198:201], v77 offset:0x9800
	s_waitcnt vmcnt(8)
	ds_write_b128 v80, v[118:121] offset:0x3000
	v_mfma_f32_32x32x16_bf16 a[96:111], v[82:85], v[194:197], a[96:111]
	s_waitcnt vmcnt(7)
	ds_write_b128 v80, v[122:125] offset:0x4000
	s_waitcnt lgkmcnt(6)
	v_mfma_f32_32x32x16_bf16 a[80:95], v[86:89], v[202:205], a[80:95]
	s_waitcnt vmcnt(6)
	ds_write_b128 v80, v[126:129] offset:0x5000
	v_mfma_f32_32x32x16_bf16 a[64:79], v[86:89], v[194:197], a[64:79]
	s_waitcnt lgkmcnt(0)
	s_barrier
	s_cbranch_scc1 .Lrs5_exit
	s_mov_b32 s3, s4
	s_branch .Lrs5_top
.Lrs5_exit:
	v_mfma_f32_32x32x16_bf16 a[48:63], v[90:93], v[202:205], a[48:63]
	v_mfma_f32_32x32x16_bf16 a[16:31], v[90:93], v[194:197], a[16:31]
	s_nop 7
	s_nop 3
	s_branch .LBB0_777

.LBB0_1146:
	v_and_b32_e32 v4, 0x3ff, v3
	v_lshlrev_b32_e32 v192, 2, v4
	s_movk_i32 s4, 0x800
	v_lshl_add_u64 v[4:5], s[42:43], 0, v[192:193]
	v_cmp_gt_i32_e32 vcc, s4, v3
	s_movk_i32 s4, 0xaff
	s_nop 0
	v_cndmask_b32_e32 v5, v5, v1, vcc
	v_cndmask_b32_e32 v4, v4, v0, vcc
	global_load_dword v4, v[4:5], off
	v_add_u32_e32 v5, 0x100, v3
	v_cmp_lt_i32_e32 vcc, s4, v3
	v_mov_b32_e32 v3, v5
	s_mov_b64 s[4:5], 0x400
	v_lshl_add_u64 v[0:1], v[0:1], 0, s[4:5]
	s_or_b64 s[2:3], vcc, s[2:3]
	s_waitcnt vmcnt(0)
	v_mul_f32_e32 v5, 0xbfb8aa3b, v4
	v_exp_f32_e32 v5, v5
	s_nop 0
	v_add_f32_e32 v5, 1.0, v5
	v_rcp_f32_e32 v7, v5
	s_nop 0
	v_mul_f32_e32 v4, v4, v7
	ds_write_b32 v2, v4
	v_add_u32_e32 v2, 0x400, v2
	s_andn2_b64 exec, exec, s[2:3]
	s_cbranch_execnz .LBB0_1146
